# ping-pong roles swapped (waves 4-7 lead the K-loop, waves 0-3 trail), on top of nomidprio
# speedup vs baseline: 1.0005x; 1.0005x over previous
.LBB0_539:
	v_readlane_b32 s8, v255, 41
	s_lshl_b32 s8, s8, 22
	s_andn2_b64 vcc, exec, s[24:25]
	s_cbranch_vccnz .LBB0_719
	v_ashrrev_i32_e32 v3, 31, v11
	v_lshrrev_b32_e32 v3, 26, v3
	v_add_u32_e32 v3, v11, v3
	v_ashrrev_i32_e32 v10, 6, v3
	v_bfe_i32 v3, v11, 27, 1
	v_lshlrev_b32_e32 v2, 4, v11
	v_lshrrev_b32_e32 v3, 22, v3
	v_add_u32_e32 v3, v2, v3
	v_and_b32_e32 v3, 0xfffffc00, v3
	v_sub_u32_e32 v3, v2, v3
	v_lshrrev_b32_e32 v4, 4, v3
	v_bitop3_b32 v3, v4, v3, 32 bitop3:0x6c
	v_ashrrev_i32_e32 v5, 31, v3
	v_lshrrev_b32_e32 v5, 26, v5
	v_add_u32_e32 v5, v3, v5
	v_lshlrev_b32_e32 v4, 3, v10
	v_ashrrev_i32_e32 v12, 6, v5
	v_and_b32_e32 v5, 0xc0, v5
	v_and_b32_e32 v4, -16, v4
	v_sub_u32_e32 v3, v3, v5
	v_add_u32_e32 v4, v12, v4
	v_ashrrev_i16_sdwa v3, v224, sext(v3) dst_sel:DWORD dst_unused:UNUSED_PAD src0_sel:DWORD src1_sel:BYTE_0
	v_lshlrev_b32_e32 v6, 5, v10
	v_bfe_i32 v13, v3, 0, 16
	v_lshlrev_b32_e32 v3, 1, v4
	v_lshrrev_b32_e32 v5, 2, v4
	v_and_b32_e32 v7, 3, v12
	s_mov_b32 s9, 0xfffe0
	v_and_b32_e32 v6, 32, v6
	v_and_b32_e32 v3, 24, v3
	v_and_b32_e32 v5, 4, v5
	v_and_or_b32 v7, v4, s9, v7
	v_or3_b32 v3, v7, v5, v3
	v_add_lshl_u32 v5, v6, v13, 1
	v_add_u32_e32 v2, 0x2000, v2
	s_waitcnt vmcnt(0)
	v_lshl_add_u32 v134, v3, 12, v5
	v_ashrrev_i32_e32 v3, 31, v2
	v_lshrrev_b32_e32 v3, 22, v3
	v_add_u32_e32 v3, v2, v3
	v_ashrrev_i32_e32 v14, 10, v3
	v_mul_i32_i24_e32 v3, 0x400, v14
	v_sub_u32_e32 v2, v2, v3
	v_lshrrev_b32_e32 v3, 4, v2
	v_bitop3_b32 v2, v3, v2, 32 bitop3:0x6c
	v_lshl_add_u32 v132, v4, 12, v5
	v_ashrrev_i32_e32 v4, 31, v2
	v_lshrrev_b32_e32 v4, 26, v4
	v_lshlrev_b32_e32 v3, 3, v14
	v_add_u32_e32 v4, v2, v4
	v_and_b32_e32 v3, -16, v3
	v_ashrrev_i32_e32 v15, 6, v4
	v_add_u32_e32 v3, v15, v3
	v_and_b32_e32 v6, 3, v15
	s_ashr_i32 s34, s30, 6
	s_ashr_i32 s31, s30, 8
	v_and_or_b32 v6, v3, s9, v6
	s_lshl_b32 s9, s34, 10
	s_add_u32 s12, s28, 0x1de00000
	v_and_b32_e32 v4, 0xc0, v4
	s_addc_u32 s21, s29, 0
	s_ashr_i32 s43, s42, 31
	s_ashr_i32 s41, s40, 31
	v_sub_u32_e32 v2, v2, v4
	s_lshl_b64 s[26:27], s[42:43], 20
	s_lshl_b64 s[38:39], s[40:41], 20
	v_ashrrev_i16_sdwa v2, v224, sext(v2) dst_sel:DWORD dst_unused:UNUSED_PAD src0_sel:DWORD src1_sel:BYTE_0
	s_add_u32 s54, s18, s38
	v_lshlrev_b32_e32 v5, 5, v14
	v_bfe_i32 v16, v2, 0, 16
	v_lshlrev_b32_e32 v2, 1, v3
	v_lshrrev_b32_e32 v4, 2, v3
	s_addc_u32 s55, s19, s39
	s_add_i32 s58, s9, 0
	v_and_b32_e32 v5, 32, v5
	v_and_b32_e32 v2, 24, v2
	v_and_b32_e32 v4, 4, v4
	s_add_i32 m0, s58, 0x10000
	v_or3_b32 v2, v6, v4, v2
	v_add_lshl_u32 v4, v5, v16, 1
	global_load_lds_dwordx4 v134, s[54:55]
	s_add_i32 m0, s58, 0x12000
	v_lshl_add_u32 v138, v2, 12, v4
	s_add_u32 s38, s54, 0x80000
	global_load_lds_dwordx4 v138, s[54:55]
	s_addc_u32 s39, s55, 0
	s_add_i32 m0, s58, 0x14000
	v_lshl_add_u32 v136, v3, 12, v4
	global_load_lds_dwordx4 v134, s[38:39]
	s_add_i32 m0, s58, 0x16000
	s_add_u32 s44, s12, s26
	s_addc_u32 s45, s21, s27
	s_add_i32 s59, s58, 0x2000
	global_load_lds_dwordx4 v138, s[38:39]
	s_mov_b32 m0, s58
	s_add_u32 s26, s44, 0x80000
	global_load_lds_dwordx4 v132, s[44:45]
	s_mov_b32 m0, s59
	s_addc_u32 s27, s45, 0
	s_add_i32 s60, s58, 0x4000
	global_load_lds_dwordx4 v136, s[44:45]
	s_mov_b32 m0, s60
	s_add_i32 s61, s58, 0x6000
	global_load_lds_dwordx4 v132, s[26:27]
	s_mov_b32 m0, s61
	v_mov_b32_e32 v135, v181
	global_load_lds_dwordx4 v136, s[26:27]
	v_mov_b32_e32 v139, v181
	v_mov_b32_e32 v133, v181
	v_mov_b32_e32 v137, v181
	s_cmp_eq_u32 s31, 1
	v_lshl_add_u64 v[8:9], s[54:55], 0, v[134:135]
	v_lshl_add_u64 v[6:7], s[54:55], 0, v[138:139]
	v_lshl_add_u64 v[2:3], s[44:45], 0, v[132:133]
	s_cselect_b64 s[26:27], -1, 0
	s_cmp_lg_u32 s31, 1
	v_lshl_add_u64 v[4:5], s[44:45], 0, v[136:137]
	s_cbranch_scc0 .LBB0_542
	s_barrier

.LBB0_552:
	s_add_u32 s54, s44, 0xfff80080
	s_addc_u32 s55, s45, -1
	s_waitcnt lgkmcnt(0)
	s_add_i32 s82, 0, 0x10000
	s_cmp_eq_u32 s76, 28
	s_cselect_b32 s57, s41, s55
	s_cselect_b32 s56, s43, s54
	v_add_u32_e32 v161, s82, v159
	s_cselect_b32 s55, s35, s75
	s_cselect_b32 s54, s47, s74
	s_add_i32 vcc_lo, 0, 0x14000
	ds_read_b128 v[144:147], v161
	ds_read_b128 v[148:151], v161 offset:1024
	ds_read_b128 v[152:155], v161 offset:2048
	ds_read_b128 v[162:165], v161 offset:3072
	v_add_u32_e32 v161, vcc_lo, v159
	ds_read_b128 v[166:169], v161
	ds_read_b128 v[170:173], v161 offset:1024
	ds_read_b128 v[174:177], v161 offset:2048
	ds_read_b128 v[190:193], v161 offset:3072
	v_lshl_add_u64 v[178:179], s[44:45], 0, v[140:141]
	s_add_i32 m0, s58, 0xc000
	ds_read_b128 v[194:197], v160
	ds_read_b128 v[198:201], v160 offset:1024
	ds_read_b128 v[202:205], v160 offset:2048
	ds_read_b128 v[206:209], v160 offset:3072
	ds_read_b128 v[210:213], v160 offset:4096
	ds_read_b128 v[214:217], v160 offset:5120
	ds_read_b128 v[218:221], v160 offset:6144
	ds_read_b128 v[238:241], v160 offset:7168
	global_load_lds_dwordx4 v[178:179], off
	v_lshl_add_u64 v[178:179], s[44:45], 0, v[142:143]
	s_add_i32 m0, s58, 0xe000
	s_nop 0
	global_load_lds_dwordx4 v[178:179], off
	s_waitcnt vmcnt(8)
	s_waitcnt lgkmcnt(0)
	s_barrier
	s_setprio 1
	s_waitcnt lgkmcnt(0)
	v_mfma_f32_16x16x32_bf16 v[126:129], v[144:147], v[194:197], v[126:129]
	v_mfma_f32_16x16x32_bf16 v[122:125], v[152:155], v[194:197], v[122:125]
	v_mfma_f32_16x16x32_bf16 v[110:113], v[144:147], v[202:205], v[110:113]
	v_mfma_f32_16x16x32_bf16 v[106:109], v[152:155], v[202:205], v[106:109]
	v_mfma_f32_16x16x32_bf16 v[94:97], v[144:147], v[210:213], v[94:97]
	v_mfma_f32_16x16x32_bf16 v[90:93], v[152:155], v[210:213], v[90:93]
	v_mfma_f32_16x16x32_bf16 v[78:81], v[144:147], v[218:221], v[78:81]
	v_mfma_f32_16x16x32_bf16 v[74:77], v[152:155], v[218:221], v[74:77]
	v_mfma_f32_16x16x32_bf16 v[126:129], v[148:151], v[198:201], v[126:129]
	v_mfma_f32_16x16x32_bf16 v[122:125], v[162:165], v[198:201], v[122:125]
	v_mfma_f32_16x16x32_bf16 v[110:113], v[148:151], v[206:209], v[110:113]
	v_mfma_f32_16x16x32_bf16 v[106:109], v[162:165], v[206:209], v[106:109]
	v_mfma_f32_16x16x32_bf16 v[94:97], v[148:151], v[214:217], v[94:97]
	v_mfma_f32_16x16x32_bf16 v[90:93], v[162:165], v[214:217], v[90:93]
	v_mfma_f32_16x16x32_bf16 v[78:81], v[148:151], v[238:241], v[78:81]
	v_mfma_f32_16x16x32_bf16 v[74:77], v[162:165], v[238:241], v[74:77]
	v_mfma_f32_16x16x32_bf16 v[118:121], v[166:169], v[194:197], v[118:121]
	v_mfma_f32_16x16x32_bf16 v[114:117], v[174:177], v[194:197], v[114:117]
	v_mfma_f32_16x16x32_bf16 v[102:105], v[166:169], v[202:205], v[102:105]
	v_mfma_f32_16x16x32_bf16 v[98:101], v[174:177], v[202:205], v[98:101]
	v_mfma_f32_16x16x32_bf16 v[86:89], v[166:169], v[210:213], v[86:89]
	v_mfma_f32_16x16x32_bf16 v[82:85], v[174:177], v[210:213], v[82:85]
	v_mfma_f32_16x16x32_bf16 v[70:73], v[166:169], v[218:221], v[70:73]
	v_mfma_f32_16x16x32_bf16 v[66:69], v[174:177], v[218:221], v[66:69]
	v_mfma_f32_16x16x32_bf16 v[118:121], v[170:173], v[198:201], v[118:121]
	v_mfma_f32_16x16x32_bf16 v[114:117], v[190:193], v[198:201], v[114:117]
	v_mfma_f32_16x16x32_bf16 v[102:105], v[170:173], v[206:209], v[102:105]
	v_mfma_f32_16x16x32_bf16 v[98:101], v[190:193], v[206:209], v[98:101]
	v_mfma_f32_16x16x32_bf16 v[86:89], v[170:173], v[214:217], v[86:89]
	v_mfma_f32_16x16x32_bf16 v[82:85], v[190:193], v[214:217], v[82:85]
	v_mfma_f32_16x16x32_bf16 v[70:73], v[170:173], v[238:241], v[70:73]
	v_mfma_f32_16x16x32_bf16 v[66:69], v[190:193], v[238:241], v[66:69]
	s_setprio 0
	s_barrier
	s_add_i32 s82, s82, s9
	v_lshl_add_u64 v[178:179], s[54:55], 0, v[134:135]
	s_mov_b32 m0, s82
	ds_read_b128 v[194:197], v160 offset:16384
	ds_read_b128 v[198:201], v160 offset:17408
	ds_read_b128 v[202:205], v160 offset:18432
	ds_read_b128 v[206:209], v160 offset:19456
	ds_read_b128 v[210:213], v160 offset:20480
	ds_read_b128 v[214:217], v160 offset:21504
	ds_read_b128 v[218:221], v160 offset:22528
	ds_read_b128 v[238:241], v160 offset:23552
	global_load_lds_dwordx4 v[178:179], off
	s_add_i32 m0, s82, 0x2000
	s_add_u32 s82, s54, 0x80000
	v_lshl_add_u64 v[222:223], s[54:55], 0, v[138:139]
	s_addc_u32 s83, s55, 0
	s_add_i32 vcc_lo, vcc_lo, s9
	global_load_lds_dwordx4 v[222:223], off
	v_lshl_add_u64 v[242:243], s[82:83], 0, v[134:135]
	s_mov_b32 m0, vcc_lo
	v_lshl_add_u64 v[244:245], s[56:57], 0, v[136:137]
	global_load_lds_dwordx4 v[242:243], off
	v_lshl_add_u64 v[242:243], s[82:83], 0, v[138:139]
	s_add_i32 m0, vcc_lo, 0x2000
	s_nop 0
	global_load_lds_dwordx4 v[242:243], off
	v_lshl_add_u64 v[242:243], s[56:57], 0, v[132:133]
	s_mov_b32 m0, s58
	s_nop 0
	global_load_lds_dwordx4 v[242:243], off
	s_mov_b32 m0, s59
	s_nop 0
	global_load_lds_dwordx4 v[244:245], off
	s_waitcnt vmcnt(8)
	s_waitcnt lgkmcnt(0)
	s_barrier
	s_setprio 1
	s_waitcnt lgkmcnt(0)
	v_mfma_f32_16x16x32_bf16 v[62:65], v[144:147], v[194:197], v[62:65]
	v_mfma_f32_16x16x32_bf16 v[58:61], v[152:155], v[194:197], v[58:61]
	v_mfma_f32_16x16x32_bf16 v[46:49], v[144:147], v[202:205], v[46:49]
	v_mfma_f32_16x16x32_bf16 v[42:45], v[152:155], v[202:205], v[42:45]
	v_mfma_f32_16x16x32_bf16 v[30:33], v[144:147], v[210:213], v[30:33]
	v_mfma_f32_16x16x32_bf16 v[26:29], v[152:155], v[210:213], v[26:29]
	v_mfma_f32_16x16x32_bf16 v[14:17], v[144:147], v[218:221], v[14:17]
	v_mfma_f32_16x16x32_bf16 v[10:13], v[152:155], v[218:221], v[10:13]
	v_mfma_f32_16x16x32_bf16 v[62:65], v[148:151], v[198:201], v[62:65]
	v_mfma_f32_16x16x32_bf16 v[58:61], v[162:165], v[198:201], v[58:61]
	v_mfma_f32_16x16x32_bf16 v[46:49], v[148:151], v[206:209], v[46:49]
	v_mfma_f32_16x16x32_bf16 v[42:45], v[162:165], v[206:209], v[42:45]
	v_mfma_f32_16x16x32_bf16 v[30:33], v[148:151], v[214:217], v[30:33]
	v_mfma_f32_16x16x32_bf16 v[26:29], v[162:165], v[214:217], v[26:29]
	v_mfma_f32_16x16x32_bf16 v[14:17], v[148:151], v[238:241], v[14:17]
	v_mfma_f32_16x16x32_bf16 v[10:13], v[162:165], v[238:241], v[10:13]
	v_mfma_f32_16x16x32_bf16 v[54:57], v[166:169], v[194:197], v[54:57]
	v_mfma_f32_16x16x32_bf16 v[50:53], v[174:177], v[194:197], v[50:53]
	v_mfma_f32_16x16x32_bf16 v[38:41], v[166:169], v[202:205], v[38:41]
	v_mfma_f32_16x16x32_bf16 v[34:37], v[174:177], v[202:205], v[34:37]
	v_mfma_f32_16x16x32_bf16 v[22:25], v[166:169], v[210:213], v[22:25]
	v_mfma_f32_16x16x32_bf16 v[18:21], v[174:177], v[210:213], v[18:21]
	v_mfma_f32_16x16x32_bf16 v[6:9], v[166:169], v[218:221], v[6:9]
	v_mfma_f32_16x16x32_bf16 v[2:5], v[174:177], v[218:221], v[2:5]
	v_mfma_f32_16x16x32_bf16 v[54:57], v[170:173], v[198:201], v[54:57]
	v_mfma_f32_16x16x32_bf16 v[50:53], v[190:193], v[198:201], v[50:53]
	v_mfma_f32_16x16x32_bf16 v[38:41], v[170:173], v[206:209], v[38:41]
	v_mfma_f32_16x16x32_bf16 v[34:37], v[190:193], v[206:209], v[34:37]
	v_mfma_f32_16x16x32_bf16 v[22:25], v[170:173], v[214:217], v[22:25]
	v_mfma_f32_16x16x32_bf16 v[18:21], v[190:193], v[214:217], v[18:21]
	v_mfma_f32_16x16x32_bf16 v[6:9], v[170:173], v[238:241], v[6:9]
	v_mfma_f32_16x16x32_bf16 v[2:5], v[190:193], v[238:241], v[2:5]
	s_setprio 0
	s_barrier
	s_add_i32 s82, 0, 0x18000
	v_add_u32_e32 v161, s82, v159
	s_add_i32 s83, 0, 0x1c000
	ds_read_b128 v[144:147], v161
	ds_read_b128 v[148:151], v161 offset:1024
	ds_read_b128 v[152:155], v161 offset:2048
	ds_read_b128 v[162:165], v161 offset:3072
	v_add_u32_e32 v161, s83, v159
	ds_read_b128 v[166:169], v161
	ds_read_b128 v[170:173], v161 offset:1024
	ds_read_b128 v[174:177], v161 offset:2048
	ds_read_b128 v[190:193], v161 offset:3072
	s_add_u32 s56, s56, 0x80000
	s_addc_u32 s57, s57, 0
	s_mov_b32 m0, s60
	v_lshl_add_u64 v[246:247], s[56:57], 0, v[132:133]
	ds_read_b128 v[194:197], v160 offset:32768
	ds_read_b128 v[198:201], v160 offset:33792
	ds_read_b128 v[202:205], v160 offset:34816
	ds_read_b128 v[206:209], v160 offset:35840
	ds_read_b128 v[210:213], v160 offset:36864
	ds_read_b128 v[214:217], v160 offset:37888
	ds_read_b128 v[218:221], v160 offset:38912
	ds_read_b128 v[238:241], v160 offset:39936
	global_load_lds_dwordx4 v[246:247], off
	v_lshl_add_u64 v[246:247], s[56:57], 0, v[136:137]
	s_mov_b32 m0, s61
	s_nop 0
	global_load_lds_dwordx4 v[246:247], off
	s_waitcnt vmcnt(8)
	s_waitcnt lgkmcnt(0)
	s_barrier
	s_setprio 1
	s_waitcnt lgkmcnt(0)
	v_mfma_f32_16x16x32_bf16 v[126:129], v[144:147], v[194:197], v[126:129]
	v_mfma_f32_16x16x32_bf16 v[122:125], v[152:155], v[194:197], v[122:125]
	v_mfma_f32_16x16x32_bf16 v[110:113], v[144:147], v[202:205], v[110:113]
	v_mfma_f32_16x16x32_bf16 v[106:109], v[152:155], v[202:205], v[106:109]
	v_mfma_f32_16x16x32_bf16 v[94:97], v[144:147], v[210:213], v[94:97]
	v_mfma_f32_16x16x32_bf16 v[90:93], v[152:155], v[210:213], v[90:93]
	v_mfma_f32_16x16x32_bf16 v[78:81], v[144:147], v[218:221], v[78:81]
	v_mfma_f32_16x16x32_bf16 v[74:77], v[152:155], v[218:221], v[74:77]
	v_mfma_f32_16x16x32_bf16 v[126:129], v[148:151], v[198:201], v[126:129]
	v_mfma_f32_16x16x32_bf16 v[122:125], v[162:165], v[198:201], v[122:125]
	v_mfma_f32_16x16x32_bf16 v[110:113], v[148:151], v[206:209], v[110:113]
	v_mfma_f32_16x16x32_bf16 v[106:109], v[162:165], v[206:209], v[106:109]
	v_mfma_f32_16x16x32_bf16 v[94:97], v[148:151], v[214:217], v[94:97]
	v_mfma_f32_16x16x32_bf16 v[90:93], v[162:165], v[214:217], v[90:93]
	v_mfma_f32_16x16x32_bf16 v[78:81], v[148:151], v[238:241], v[78:81]
	v_mfma_f32_16x16x32_bf16 v[74:77], v[162:165], v[238:241], v[74:77]
	v_mfma_f32_16x16x32_bf16 v[118:121], v[166:169], v[194:197], v[118:121]
	v_mfma_f32_16x16x32_bf16 v[114:117], v[174:177], v[194:197], v[114:117]
	v_mfma_f32_16x16x32_bf16 v[102:105], v[166:169], v[202:205], v[102:105]
	v_mfma_f32_16x16x32_bf16 v[98:101], v[174:177], v[202:205], v[98:101]
	v_mfma_f32_16x16x32_bf16 v[86:89], v[166:169], v[210:213], v[86:89]
	v_mfma_f32_16x16x32_bf16 v[82:85], v[174:177], v[210:213], v[82:85]
	v_mfma_f32_16x16x32_bf16 v[70:73], v[166:169], v[218:221], v[70:73]
	v_mfma_f32_16x16x32_bf16 v[66:69], v[174:177], v[218:221], v[66:69]
	v_mfma_f32_16x16x32_bf16 v[118:121], v[170:173], v[198:201], v[118:121]
	v_mfma_f32_16x16x32_bf16 v[114:117], v[190:193], v[198:201], v[114:117]
	v_mfma_f32_16x16x32_bf16 v[102:105], v[170:173], v[206:209], v[102:105]
	v_mfma_f32_16x16x32_bf16 v[98:101], v[190:193], v[206:209], v[98:101]
	v_mfma_f32_16x16x32_bf16 v[86:89], v[170:173], v[214:217], v[86:89]
	v_mfma_f32_16x16x32_bf16 v[82:85], v[190:193], v[214:217], v[82:85]
	v_mfma_f32_16x16x32_bf16 v[70:73], v[170:173], v[238:241], v[70:73]
	v_mfma_f32_16x16x32_bf16 v[66:69], v[190:193], v[238:241], v[66:69]
	s_setprio 0
	s_barrier
	s_add_i32 s56, s82, s9
	v_lshl_add_u64 v[178:179], v[178:179], 0, s[16:17]
	s_mov_b32 m0, s56
	ds_read_b128 v[194:197], v160 offset:49152
	ds_read_b128 v[198:201], v160 offset:50176
	ds_read_b128 v[202:205], v160 offset:51200
	ds_read_b128 v[206:209], v160 offset:52224
	ds_read_b128 v[210:213], v160 offset:53248
	ds_read_b128 v[214:217], v160 offset:54272
	ds_read_b128 v[218:221], v160 offset:55296
	ds_read_b128 v[238:241], v160 offset:56320
	global_load_lds_dwordx4 v[178:179], off
	s_add_i32 m0, s56, 0x2000
	s_add_u32 s54, s54, 0x80080
	v_lshl_add_u64 v[178:179], v[222:223], 0, s[16:17]
	s_addc_u32 s55, s55, 0
	s_add_i32 s56, s83, s9
	global_load_lds_dwordx4 v[178:179], off
	v_lshl_add_u64 v[178:179], s[54:55], 0, v[134:135]
	s_mov_b32 m0, s56
	s_nop 0
	global_load_lds_dwordx4 v[178:179], off
	v_lshl_add_u64 v[178:179], s[54:55], 0, v[138:139]
	s_add_i32 m0, s56, 0x2000
	s_nop 0
	global_load_lds_dwordx4 v[178:179], off
	v_lshl_add_u64 v[178:179], v[242:243], 0, s[16:17]
	s_mov_b32 m0, s64
	s_nop 0
	global_load_lds_dwordx4 v[178:179], off
	v_lshl_add_u64 v[178:179], v[244:245], 0, s[16:17]
	s_mov_b32 m0, s69
	s_nop 0
	global_load_lds_dwordx4 v[178:179], off
	s_waitcnt vmcnt(8)
	s_waitcnt lgkmcnt(0)
	s_barrier
	s_setprio 1
	s_waitcnt lgkmcnt(0)
	v_mfma_f32_16x16x32_bf16 v[62:65], v[144:147], v[194:197], v[62:65]
	v_mfma_f32_16x16x32_bf16 v[58:61], v[152:155], v[194:197], v[58:61]
	v_mfma_f32_16x16x32_bf16 v[46:49], v[144:147], v[202:205], v[46:49]
	v_mfma_f32_16x16x32_bf16 v[42:45], v[152:155], v[202:205], v[42:45]
	v_mfma_f32_16x16x32_bf16 v[30:33], v[144:147], v[210:213], v[30:33]
	v_mfma_f32_16x16x32_bf16 v[26:29], v[152:155], v[210:213], v[26:29]
	v_mfma_f32_16x16x32_bf16 v[14:17], v[144:147], v[218:221], v[14:17]
	v_mfma_f32_16x16x32_bf16 v[10:13], v[152:155], v[218:221], v[10:13]
	v_mfma_f32_16x16x32_bf16 v[62:65], v[148:151], v[198:201], v[62:65]
	v_mfma_f32_16x16x32_bf16 v[58:61], v[162:165], v[198:201], v[58:61]
	v_mfma_f32_16x16x32_bf16 v[46:49], v[148:151], v[206:209], v[46:49]
	v_mfma_f32_16x16x32_bf16 v[42:45], v[162:165], v[206:209], v[42:45]
	v_mfma_f32_16x16x32_bf16 v[30:33], v[148:151], v[214:217], v[30:33]
	v_mfma_f32_16x16x32_bf16 v[26:29], v[162:165], v[214:217], v[26:29]
	v_mfma_f32_16x16x32_bf16 v[14:17], v[148:151], v[238:241], v[14:17]
	v_mfma_f32_16x16x32_bf16 v[10:13], v[162:165], v[238:241], v[10:13]
	v_mfma_f32_16x16x32_bf16 v[54:57], v[166:169], v[194:197], v[54:57]
	v_mfma_f32_16x16x32_bf16 v[50:53], v[174:177], v[194:197], v[50:53]
	v_mfma_f32_16x16x32_bf16 v[38:41], v[166:169], v[202:205], v[38:41]
	v_mfma_f32_16x16x32_bf16 v[34:37], v[174:177], v[202:205], v[34:37]
	v_mfma_f32_16x16x32_bf16 v[22:25], v[166:169], v[210:213], v[22:25]
	v_mfma_f32_16x16x32_bf16 v[18:21], v[174:177], v[210:213], v[18:21]
	v_mfma_f32_16x16x32_bf16 v[6:9], v[166:169], v[218:221], v[6:9]
	v_mfma_f32_16x16x32_bf16 v[2:5], v[174:177], v[218:221], v[2:5]
	v_mfma_f32_16x16x32_bf16 v[54:57], v[170:173], v[198:201], v[54:57]
	v_mfma_f32_16x16x32_bf16 v[50:53], v[190:193], v[198:201], v[50:53]
	v_mfma_f32_16x16x32_bf16 v[38:41], v[170:173], v[206:209], v[38:41]
	v_mfma_f32_16x16x32_bf16 v[34:37], v[190:193], v[206:209], v[34:37]
	v_mfma_f32_16x16x32_bf16 v[22:25], v[170:173], v[214:217], v[22:25]
	v_mfma_f32_16x16x32_bf16 v[18:21], v[190:193], v[214:217], v[18:21]
	v_mfma_f32_16x16x32_bf16 v[6:9], v[170:173], v[238:241], v[6:9]
	v_mfma_f32_16x16x32_bf16 v[2:5], v[190:193], v[238:241], v[2:5]
	s_setprio 0
	s_barrier
	s_add_i32 s76, s76, 2
	s_add_u32 s44, s44, 0x100
	s_addc_u32 s45, s45, 0
	s_add_u32 s74, s74, 0x100
	s_addc_u32 s75, s75, 0
	s_cmp_gt_u32 s76, 29
	s_cbranch_scc0 .LBB0_552
	s_and_b64 vcc, exec, s[30:31]
	s_cbranch_vccnz .LBB0_555
	s_barrier

.LBB0_715:
	s_andn2_b64 vcc, exec, s[38:39]
	s_mov_b64 s[38:39], -1
	s_cbranch_vccnz .LBB0_544
	s_andn2_b64 vcc, exec, s[26:27]
	s_cbranch_vccz .LBB0_543
	s_barrier
	s_branch .LBB0_543

.LBB0_812:
	s_add_u32 s14, s0, s54
	s_movk_i32 s24, 0x180
	s_addc_u32 s15, s1, 0
	s_load_dwordx2 s[22:23], s[14:15], 0x118
	v_mov_b32_e32 v14, v0
	s_andn2_b64 vcc, exec, s[10:11]
	v_readfirstlane_b32 s26, v14
	s_cbranch_vccnz .LBB0_832
	v_lshlrev_b32_e32 v2, 4, v14
	v_add_u32_e32 v3, 0x2000, v2
	v_ashrrev_i32_e32 v4, 31, v3
	v_lshrrev_b32_e32 v4, 22, v4
	v_add_u32_e32 v4, v3, v4
	v_ashrrev_i32_e32 v4, 10, v4
	v_mul_i32_i24_e32 v5, 0x400, v4
	v_sub_u32_e32 v3, v3, v5
	v_lshrrev_b32_e32 v5, 4, v3
	v_bitop3_b32 v3, v5, v3, 32 bitop3:0x6c
	v_ashrrev_i32_e32 v5, 31, v3
	v_lshrrev_b32_e32 v5, 26, v5
	v_add_u32_e32 v5, v3, v5
	v_lshlrev_b32_e32 v7, 3, v4
	v_ashrrev_i32_e32 v6, 6, v5
	v_and_b32_e32 v7, -16, v7
	v_lshlrev_b32_e32 v4, 5, v4
	v_add_u32_e32 v7, v6, v7
	v_and_b32_e32 v15, 32, v4
	v_and_b32_e32 v4, 0xc0, v5
	v_and_b32_e32 v6, 3, v6
	s_mov_b32 s18, 0x7fffffe0
	v_lshrrev_b32_e32 v8, 2, v7
	v_lshlrev_b32_e32 v9, 1, v7
	v_sub_u32_e32 v3, v3, v4
	v_and_or_b32 v6, v7, s18, v6
	v_and_b32_e32 v8, 4, v8
	v_and_b32_e32 v9, 24, v9
	v_ashrrev_i16_sdwa v3, v224, sext(v3) dst_sel:DWORD dst_unused:UNUSED_PAD src0_sel:DWORD src1_sel:BYTE_0
	v_or3_b32 v6, v6, v8, v9
	v_bfe_i32 v16, v3, 0, 16
	v_mul_lo_u32 v6, v6, s24
	v_add_u32_e32 v3, v15, v16
	v_mul_lo_u32 v17, v7, s24
	s_waitcnt vmcnt(0)
	v_add_lshl_u32 v132, v6, v3, 1
	v_add_lshl_u32 v134, v3, v17, 1
	v_bfe_i32 v3, v14, 27, 1
	v_lshrrev_b32_e32 v3, 22, v3
	v_add_u32_e32 v3, v2, v3
	v_and_b32_e32 v3, 0xfffffc00, v3
	v_sub_u32_e32 v2, v2, v3
	v_lshrrev_b32_e32 v3, 4, v2
	v_ashrrev_i32_e32 v5, 31, v14
	s_waitcnt lgkmcnt(0)
	s_add_u32 s9, s22, 0x37200000
	v_bitop3_b32 v2, v3, v2, 32 bitop3:0x6c
	v_lshrrev_b32_e32 v5, 26, v5
	s_mul_i32 s11, s12, 0x30000
	s_addc_u32 s21, s23, 0
	v_ashrrev_i32_e32 v3, 31, v2
	v_add_u32_e32 v5, v14, v5
	s_mul_hi_u32 s10, s12, 0x30000
	s_add_u32 s11, s22, s11
	v_lshrrev_b32_e32 v3, 26, v3
	v_ashrrev_i32_e32 v5, 6, v5
	s_addc_u32 s10, s23, s10
	v_add_u32_e32 v3, v2, v3
	v_lshlrev_b32_e32 v6, 3, v5
	s_add_u32 s42, s11, 0x16900000
	v_ashrrev_i32_e32 v4, 6, v3
	v_and_b32_e32 v6, -16, v6
	s_addc_u32 s43, s10, 0
	s_ashr_i32 s25, s24, 31
	v_add_u32_e32 v6, v4, v6
	v_and_b32_e32 v4, 3, v4
	s_lshl_b64 s[14:15], s[24:25], 9
	v_and_or_b32 v4, v6, s18, v4
	s_ashr_i32 s18, s6, 31
	s_mul_i32 s18, s14, s18
	s_mul_hi_u32 s19, s14, s6
	s_add_i32 s29, s19, s18
	s_lshr_b64 s[18:19], s[24:25], 23
	s_mul_i32 s19, s18, s6
	s_add_i32 s29, s29, s19
	s_ashr_i32 s19, s8, 31
	v_and_b32_e32 v3, 0xc0, v3
	s_mul_i32 s19, s14, s19
	s_mul_hi_u32 s31, s14, s8
	s_ashr_i32 s27, s26, 6
	v_lshrrev_b32_e32 v7, 2, v6
	v_lshlrev_b32_e32 v8, 1, v6
	v_sub_u32_e32 v2, v2, v3
	s_add_i32 s19, s31, s19
	s_mul_i32 s18, s18, s8
	s_ashr_i32 s28, s26, 8
	s_lshl_b64 s[10:11], s[24:25], 8
	s_lshl_b32 s44, s27, 10
	v_and_b32_e32 v7, 4, v7
	v_and_b32_e32 v8, 24, v8
	v_lshlrev_b32_e32 v5, 5, v5
	v_ashrrev_i16_sdwa v2, v224, sext(v2) dst_sel:DWORD dst_unused:UNUSED_PAD src0_sel:DWORD src1_sel:BYTE_0
	s_add_i32 s19, s19, s18
	s_mul_i32 s18, s14, s8
	v_or3_b32 v4, v4, v7, v8
	v_and_b32_e32 v18, 32, v5
	v_bfe_i32 v19, v2, 0, 16
	s_add_u32 s40, s42, s18
	v_mul_lo_u32 v4, v4, s24
	v_add_u32_e32 v2, v18, v19
	s_addc_u32 s41, s43, s19
	s_add_i32 s45, s44, 0
	v_add_lshl_u32 v136, v4, v2, 1
	s_add_i32 m0, s45, 0x10000
	s_mul_i32 s30, s14, s6
	global_load_lds_dwordx4 v136, s[40:41]
	s_add_i32 m0, s45, 0x12000
	s_add_u32 s18, s40, s10
	global_load_lds_dwordx4 v132, s[40:41]
	s_addc_u32 s19, s41, s11
	s_add_i32 m0, s45, 0x14000
	v_mul_lo_u32 v20, v6, s24
	global_load_lds_dwordx4 v136, s[18:19]
	s_add_i32 m0, s45, 0x16000
	s_add_u32 s34, s9, s30
	v_mov_b32_e32 v137, v181
	v_mov_b32_e32 v133, v181
	s_addc_u32 s35, s21, s29
	s_add_i32 s46, s45, 0x2000
	v_add_lshl_u32 v138, v2, v20, 1
	v_lshl_add_u64 v[6:7], s[18:19], 0, v[136:137]
	v_lshl_add_u64 v[8:9], s[18:19], 0, v[132:133]
	global_load_lds_dwordx4 v132, s[18:19]
	s_mov_b32 m0, s45
	s_add_u32 s18, s34, s10
	global_load_lds_dwordx4 v138, s[34:35]
	s_mov_b32 m0, s46
	s_addc_u32 s19, s35, s11
	s_add_i32 s47, s45, 0x4000
	global_load_lds_dwordx4 v134, s[34:35]
	s_mov_b32 m0, s47
	s_add_i32 s48, s45, 0x6000
	global_load_lds_dwordx4 v138, s[18:19]
	s_mov_b32 m0, s48
	v_mov_b32_e32 v139, v181
	global_load_lds_dwordx4 v134, s[18:19]
	v_mov_b32_e32 v135, v181
	s_cmp_eq_u32 s28, 1
	v_lshl_add_u64 v[2:3], s[40:41], 0, v[136:137]
	v_lshl_add_u64 v[4:5], s[40:41], 0, v[132:133]
	v_lshl_add_u64 v[10:11], s[34:35], 0, v[138:139]
	v_lshl_add_u64 v[12:13], s[34:35], 0, v[134:135]
	s_cselect_b64 s[18:19], -1, 0
	s_cmp_lg_u32 s28, 1
	s_cbranch_scc0 .LBB0_815
	s_barrier

.LBB0_826:
	s_and_b64 vcc, exec, s[26:27]
	s_cbranch_vccnz .LBB0_828
	s_barrier
.LBB0_828:
	v_mul_f32_e32 v155, 0x3dd2d3e8, v126
	v_fma_f32 v155, -v126, v155, s79
	v_mul_f32_e32 v155, v126, v155
	v_exp_f32_e32 v155, v155
	s_lshl_b32 s35, s8, 9
	v_mov_b32_e32 v151, v144
	v_mov_b32_e32 v149, v145
	v_add_f32_e32 v155, 1.0, v155
	v_rcp_f32_e32 v155, v155
	s_lshl_b32 s34, s61, 8
	s_sub_i32 s35, s55, s35
	v_mul_f32_e32 v126, v126, v155
	v_mul_f32_e32 v155, 0x3dd2d3e8, v127
	v_fma_f32 v155, -v127, v155, s79
	v_mul_f32_e32 v155, v127, v155
	v_exp_f32_e32 v155, v155
	s_add_i32 s40, s35, s34
	v_lshl_add_u32 v154, v151, 3, s56
	s_lshl_b32 s34, s8, 4
	v_add_f32_e32 v155, 1.0, v155
	v_rcp_f32_e32 v155, v155
	v_ashrrev_i32_e32 v148, 4, v154
	v_add_lshl_u32 v149, s40, v149, 4
	s_ashr_i32 s35, s34, 31
	v_mul_f32_e32 v127, v127, v155
	v_mul_f32_e32 v155, 0x3dd2d3e8, v128
	v_fma_f32 v155, -v128, v155, s79
	v_mul_f32_e32 v155, v128, v155
	v_exp_f32_e32 v155, v155
	s_lshl_b64 s[34:35], s[34:35], 1
	v_lshlrev_b32_e32 v151, 4, v151
	v_and_b32_e32 v180, 16, v151
	v_add_f32_e32 v155, 1.0, v155
	v_rcp_f32_e32 v155, v155
	s_nop 0
	v_mul_f32_e32 v128, v128, v155
	v_mul_f32_e32 v155, 0x3dd2d3e8, v129
	v_fma_f32 v155, -v129, v155, s79
	v_mul_f32_e32 v155, v129, v155
	v_exp_f32_e32 v155, v155
	s_nop 0
	v_add_f32_e32 v155, 1.0, v155
	v_rcp_f32_e32 v155, v155
	s_nop 0
	v_mul_f32_e32 v129, v129, v155
	v_mul_f32_e32 v155, 0x3dd2d3e8, v122
	v_fma_f32 v155, -v122, v155, s79
	v_mul_f32_e32 v155, v122, v155
	v_exp_f32_e32 v155, v155
	s_nop 0
	v_add_f32_e32 v155, 1.0, v155
	v_rcp_f32_e32 v155, v155
	s_nop 0
	v_mul_f32_e32 v122, v122, v155
	v_mul_f32_e32 v155, 0x3dd2d3e8, v123
	v_fma_f32 v155, -v123, v155, s79
	v_mul_f32_e32 v155, v123, v155
	v_exp_f32_e32 v155, v155
	s_nop 0
	v_add_f32_e32 v155, 1.0, v155
	v_rcp_f32_e32 v155, v155
	s_nop 0
	v_mul_f32_e32 v123, v123, v155
	v_mul_f32_e32 v155, 0x3dd2d3e8, v124
	v_fma_f32 v155, -v124, v155, s79
	v_mul_f32_e32 v155, v124, v155
	v_exp_f32_e32 v155, v155
	s_nop 0
	v_add_f32_e32 v155, 1.0, v155
	v_rcp_f32_e32 v155, v155
	s_nop 0
	v_mul_f32_e32 v155, v124, v155
	v_mul_f32_e32 v124, 0x3dd2d3e8, v125
	v_fma_f32 v124, -v125, v124, s79
	v_mul_f32_e32 v124, v125, v124
	v_exp_f32_e32 v124, v124
	s_nop 0
	v_add_f32_e32 v124, 1.0, v124
	v_rcp_f32_e32 v124, v124
	s_nop 0
	v_mul_f32_e32 v156, v125, v124
	v_cvt_pk_bf16_f32 v124, v126, v127
	v_cvt_pk_bf16_f32 v125, v128, v129
	v_cvt_pk_bf16_f32 v126, v122, v123
	v_add_u32_e32 v128, v148, v149
	v_mov_b64_e32 v[122:123], s[22:23]
	v_mad_i64_i32 v[128:129], s[40:41], v128, s80, v[122:123]
	v_lshl_add_u64 v[128:129], v[128:129], 0, s[34:35]
	v_lshl_add_u64 v[128:129], v[128:129], 0, v[180:181]
	v_cvt_pk_bf16_f32 v127, v155, v156
	global_store_dwordx4 v[128:129], v[124:127], off
	s_nop 1
	v_mul_f32_e32 v125, 0x3dd2d3e8, v118
	v_fma_f32 v125, -v118, v125, s79
	v_mul_f32_e32 v125, v118, v125
	v_exp_f32_e32 v125, v125
	v_add_u32_e32 v124, 0x80, v154
	v_ashrrev_i32_e32 v124, 4, v124
	v_add_f32_e32 v125, 1.0, v125
	v_rcp_f32_e32 v125, v125
	s_nop 0
	v_mul_f32_e32 v118, v118, v125
	v_mul_f32_e32 v125, 0x3dd2d3e8, v119
	v_fma_f32 v125, -v119, v125, s79
	v_mul_f32_e32 v125, v119, v125
	v_exp_f32_e32 v125, v125
	s_nop 0
	v_add_f32_e32 v125, 1.0, v125
	v_rcp_f32_e32 v125, v125
	s_nop 0
	v_mul_f32_e32 v119, v119, v125
	v_mul_f32_e32 v125, 0x3dd2d3e8, v120
	v_fma_f32 v125, -v120, v125, s79
	v_mul_f32_e32 v125, v120, v125
	v_exp_f32_e32 v125, v125
	s_nop 0
	v_add_f32_e32 v125, 1.0, v125
	v_rcp_f32_e32 v125, v125
	s_nop 0
	v_mul_f32_e32 v120, v120, v125
	v_mul_f32_e32 v125, 0x3dd2d3e8, v121
	v_fma_f32 v125, -v121, v125, s79
	v_mul_f32_e32 v125, v121, v125
	v_exp_f32_e32 v125, v125
	s_nop 0
	v_add_f32_e32 v125, 1.0, v125
	v_rcp_f32_e32 v125, v125
	s_nop 0
	v_mul_f32_e32 v121, v121, v125
	v_mul_f32_e32 v125, 0x3dd2d3e8, v114
	v_fma_f32 v125, -v114, v125, s79
	v_mul_f32_e32 v125, v114, v125
	v_exp_f32_e32 v125, v125
	s_nop 0
	v_add_f32_e32 v125, 1.0, v125
	v_rcp_f32_e32 v125, v125
	s_nop 0
	v_mul_f32_e32 v125, v114, v125
	v_mul_f32_e32 v114, 0x3dd2d3e8, v115
	v_fma_f32 v114, -v115, v114, s79
	v_mul_f32_e32 v114, v115, v114
	v_exp_f32_e32 v114, v114
	s_nop 0
	v_add_f32_e32 v114, 1.0, v114
	v_rcp_f32_e32 v114, v114
	s_nop 0
	v_mul_f32_e32 v126, v115, v114
	v_mul_f32_e32 v114, 0x3dd2d3e8, v116
	v_fma_f32 v114, -v116, v114, s79
	v_mul_f32_e32 v114, v116, v114
	v_exp_f32_e32 v114, v114
	s_nop 0
	v_add_f32_e32 v114, 1.0, v114
	v_rcp_f32_e32 v114, v114
	s_nop 0
	v_mul_f32_e32 v127, v116, v114
	v_mul_f32_e32 v114, 0x3dd2d3e8, v117
	v_fma_f32 v114, -v117, v114, s79
	v_mul_f32_e32 v114, v117, v114
	v_exp_f32_e32 v114, v114
	s_nop 0
	v_add_f32_e32 v114, 1.0, v114
	v_rcp_f32_e32 v114, v114
	s_nop 0
	v_mul_f32_e32 v117, v117, v114
	v_cvt_pk_bf16_f32 v114, v118, v119
	v_add_u32_e32 v118, v124, v149
	v_mad_i64_i32 v[118:119], s[40:41], v118, s80, v[122:123]
	v_lshl_add_u64 v[118:119], v[118:119], 0, s[34:35]
	v_lshl_add_u64 v[118:119], v[118:119], 0, v[180:181]
	v_cvt_pk_bf16_f32 v115, v120, v121
	v_cvt_pk_bf16_f32 v116, v125, v126
	v_cvt_pk_bf16_f32 v117, v127, v117
	global_store_dwordx4 v[118:119], v[114:117], off
	s_nop 1
	v_mul_f32_e32 v115, 0x3dd2d3e8, v110
	v_fma_f32 v115, -v110, v115, s79
	v_mul_f32_e32 v115, v110, v115
	v_exp_f32_e32 v115, v115
	v_add_u32_e32 v114, 0x100, v149
	v_add_f32_e32 v115, 1.0, v115
	v_rcp_f32_e32 v115, v115
	s_nop 0
	v_mul_f32_e32 v110, v110, v115
	v_mul_f32_e32 v115, 0x3dd2d3e8, v111
	v_fma_f32 v115, -v111, v115, s79
	v_mul_f32_e32 v115, v111, v115
	v_exp_f32_e32 v115, v115
	s_nop 0
	v_add_f32_e32 v115, 1.0, v115
	v_rcp_f32_e32 v115, v115
	s_nop 0
	v_mul_f32_e32 v111, v111, v115
	v_mul_f32_e32 v115, 0x3dd2d3e8, v112
	v_fma_f32 v115, -v112, v115, s79
	v_mul_f32_e32 v115, v112, v115
	v_exp_f32_e32 v115, v115
	s_nop 0
	v_add_f32_e32 v115, 1.0, v115
	v_rcp_f32_e32 v115, v115
	s_nop 0
	v_mul_f32_e32 v112, v112, v115
	v_mul_f32_e32 v115, 0x3dd2d3e8, v113
	v_fma_f32 v115, -v113, v115, s79
	v_mul_f32_e32 v115, v113, v115
	v_exp_f32_e32 v115, v115
	s_nop 0
	v_add_f32_e32 v115, 1.0, v115
	v_rcp_f32_e32 v115, v115
	s_nop 0
	v_mul_f32_e32 v113, v113, v115
	v_mul_f32_e32 v115, 0x3dd2d3e8, v106
	v_fma_f32 v115, -v106, v115, s79
	v_mul_f32_e32 v115, v106, v115
	v_exp_f32_e32 v115, v115
	s_nop 0
	v_add_f32_e32 v115, 1.0, v115
	v_rcp_f32_e32 v115, v115
	s_nop 0
	v_mul_f32_e32 v115, v106, v115
	v_mul_f32_e32 v106, 0x3dd2d3e8, v107
	v_fma_f32 v106, -v107, v106, s79
	v_mul_f32_e32 v106, v107, v106
	v_exp_f32_e32 v106, v106
	s_nop 0
	v_add_f32_e32 v106, 1.0, v106
	v_rcp_f32_e32 v106, v106
	s_nop 0
	v_mul_f32_e32 v116, v107, v106
	v_mul_f32_e32 v106, 0x3dd2d3e8, v108
	v_fma_f32 v106, -v108, v106, s79
	v_mul_f32_e32 v106, v108, v106
	v_exp_f32_e32 v106, v106
	s_nop 0
	v_add_f32_e32 v106, 1.0, v106
	v_rcp_f32_e32 v106, v106
	s_nop 0
	v_mul_f32_e32 v117, v108, v106
	v_mul_f32_e32 v106, 0x3dd2d3e8, v109
	v_fma_f32 v106, -v109, v106, s79
	v_mul_f32_e32 v106, v109, v106
	v_exp_f32_e32 v106, v106
	s_nop 0
	v_add_f32_e32 v106, 1.0, v106
	v_rcp_f32_e32 v106, v106
	s_nop 0
	v_mul_f32_e32 v109, v109, v106
	v_cvt_pk_bf16_f32 v106, v110, v111
	v_add_u32_e32 v110, v148, v114
	v_mad_i64_i32 v[110:111], s[40:41], v110, s80, v[122:123]
	v_lshl_add_u64 v[110:111], v[110:111], 0, s[34:35]
	v_lshl_add_u64 v[110:111], v[110:111], 0, v[180:181]
	v_cvt_pk_bf16_f32 v107, v112, v113
	v_cvt_pk_bf16_f32 v108, v115, v116
	v_cvt_pk_bf16_f32 v109, v117, v109
	global_store_dwordx4 v[110:111], v[106:109], off
	s_nop 1
	v_mul_f32_e32 v106, 0x3dd2d3e8, v102
	v_fma_f32 v106, -v102, v106, s79
	v_mul_f32_e32 v106, v102, v106
	v_exp_f32_e32 v106, v106
	s_nop 0
	v_add_f32_e32 v106, 1.0, v106
	v_rcp_f32_e32 v106, v106
	s_nop 0
	v_mul_f32_e32 v102, v102, v106
	v_mul_f32_e32 v106, 0x3dd2d3e8, v103
	v_fma_f32 v106, -v103, v106, s79
	v_mul_f32_e32 v106, v103, v106
	v_exp_f32_e32 v106, v106
	s_nop 0
	v_add_f32_e32 v106, 1.0, v106
	v_rcp_f32_e32 v106, v106
	s_nop 0
	v_mul_f32_e32 v103, v103, v106
	v_mul_f32_e32 v106, 0x3dd2d3e8, v104
	v_fma_f32 v106, -v104, v106, s79
	v_mul_f32_e32 v106, v104, v106
	v_exp_f32_e32 v106, v106
	s_nop 0
	v_add_f32_e32 v106, 1.0, v106
	v_rcp_f32_e32 v106, v106
	s_nop 0
	v_mul_f32_e32 v104, v104, v106
	v_mul_f32_e32 v106, 0x3dd2d3e8, v105
	v_fma_f32 v106, -v105, v106, s79
	v_mul_f32_e32 v106, v105, v106
	v_exp_f32_e32 v106, v106
	s_nop 0
	v_add_f32_e32 v106, 1.0, v106
	v_rcp_f32_e32 v106, v106
	s_nop 0
	v_mul_f32_e32 v105, v105, v106
	v_mul_f32_e32 v106, 0x3dd2d3e8, v98
	v_fma_f32 v106, -v98, v106, s79
	v_mul_f32_e32 v106, v98, v106
	v_exp_f32_e32 v106, v106
	s_nop 0
	v_add_f32_e32 v106, 1.0, v106
	v_rcp_f32_e32 v106, v106
	s_nop 0
	v_mul_f32_e32 v106, v98, v106
	v_mul_f32_e32 v98, 0x3dd2d3e8, v99
	v_fma_f32 v98, -v99, v98, s79
	v_mul_f32_e32 v98, v99, v98
	v_exp_f32_e32 v98, v98
	s_nop 0
	v_add_f32_e32 v98, 1.0, v98
	v_rcp_f32_e32 v98, v98
	s_nop 0
	v_mul_f32_e32 v107, v99, v98
	v_mul_f32_e32 v98, 0x3dd2d3e8, v100
	v_fma_f32 v98, -v100, v98, s79
	v_mul_f32_e32 v98, v100, v98
	v_exp_f32_e32 v98, v98
	s_nop 0
	v_add_f32_e32 v98, 1.0, v98
	v_rcp_f32_e32 v98, v98
	s_nop 0
	v_mul_f32_e32 v108, v100, v98
	v_mul_f32_e32 v98, 0x3dd2d3e8, v101
	v_fma_f32 v98, -v101, v98, s79
	v_mul_f32_e32 v98, v101, v98
	v_exp_f32_e32 v98, v98
	s_nop 0
	v_add_f32_e32 v98, 1.0, v98
	v_rcp_f32_e32 v98, v98
	s_nop 0
	v_mul_f32_e32 v101, v101, v98
	v_cvt_pk_bf16_f32 v98, v102, v103
	v_add_u32_e32 v102, v124, v114
	v_mad_i64_i32 v[102:103], s[40:41], v102, s80, v[122:123]
	v_lshl_add_u64 v[102:103], v[102:103], 0, s[34:35]
	v_lshl_add_u64 v[102:103], v[102:103], 0, v[180:181]
	v_cvt_pk_bf16_f32 v99, v104, v105
	v_cvt_pk_bf16_f32 v100, v106, v107
	v_cvt_pk_bf16_f32 v101, v108, v101
	global_store_dwordx4 v[102:103], v[98:101], off
	s_nop 1
	v_mul_f32_e32 v99, 0x3dd2d3e8, v94
	v_fma_f32 v99, -v94, v99, s79
	v_mul_f32_e32 v99, v94, v99
	v_exp_f32_e32 v99, v99
	v_add_u32_e32 v98, 0x200, v149
	v_add_f32_e32 v99, 1.0, v99
	v_rcp_f32_e32 v99, v99
	s_nop 0
	v_mul_f32_e32 v94, v94, v99
	v_mul_f32_e32 v99, 0x3dd2d3e8, v95
	v_fma_f32 v99, -v95, v99, s79
	v_mul_f32_e32 v99, v95, v99
	v_exp_f32_e32 v99, v99
	s_nop 0
	v_add_f32_e32 v99, 1.0, v99
	v_rcp_f32_e32 v99, v99
	s_nop 0
	v_mul_f32_e32 v95, v95, v99
	v_mul_f32_e32 v99, 0x3dd2d3e8, v96
	v_fma_f32 v99, -v96, v99, s79
	v_mul_f32_e32 v99, v96, v99
	v_exp_f32_e32 v99, v99
	s_nop 0
	v_add_f32_e32 v99, 1.0, v99
	v_rcp_f32_e32 v99, v99
	s_nop 0
	v_mul_f32_e32 v96, v96, v99
	v_mul_f32_e32 v99, 0x3dd2d3e8, v97
	v_fma_f32 v99, -v97, v99, s79
	v_mul_f32_e32 v99, v97, v99
	v_exp_f32_e32 v99, v99
	s_nop 0
	v_add_f32_e32 v99, 1.0, v99
	v_rcp_f32_e32 v99, v99
	s_nop 0
	v_mul_f32_e32 v97, v97, v99
	v_mul_f32_e32 v99, 0x3dd2d3e8, v90
	v_fma_f32 v99, -v90, v99, s79
	v_mul_f32_e32 v99, v90, v99
	v_exp_f32_e32 v99, v99
	s_nop 0
	v_add_f32_e32 v99, 1.0, v99
	v_rcp_f32_e32 v99, v99
	s_nop 0
	v_mul_f32_e32 v99, v90, v99
	v_mul_f32_e32 v90, 0x3dd2d3e8, v91
	v_fma_f32 v90, -v91, v90, s79
	v_mul_f32_e32 v90, v91, v90
	v_exp_f32_e32 v90, v90
	s_nop 0
	v_add_f32_e32 v90, 1.0, v90
	v_rcp_f32_e32 v90, v90
	s_nop 0
	v_mul_f32_e32 v100, v91, v90
	v_mul_f32_e32 v90, 0x3dd2d3e8, v92
	v_fma_f32 v90, -v92, v90, s79
	v_mul_f32_e32 v90, v92, v90
	v_exp_f32_e32 v90, v90
	s_nop 0
	v_add_f32_e32 v90, 1.0, v90
	v_rcp_f32_e32 v90, v90
	s_nop 0
	v_mul_f32_e32 v101, v92, v90
	v_mul_f32_e32 v90, 0x3dd2d3e8, v93
	v_fma_f32 v90, -v93, v90, s79
	v_mul_f32_e32 v90, v93, v90
	v_exp_f32_e32 v90, v90
	s_nop 0
	v_add_f32_e32 v90, 1.0, v90
	v_rcp_f32_e32 v90, v90
	s_nop 0
	v_mul_f32_e32 v93, v93, v90
	v_cvt_pk_bf16_f32 v90, v94, v95
	v_add_u32_e32 v94, v148, v98
	v_mad_i64_i32 v[94:95], s[40:41], v94, s80, v[122:123]
	v_lshl_add_u64 v[94:95], v[94:95], 0, s[34:35]
	v_lshl_add_u64 v[94:95], v[94:95], 0, v[180:181]
	v_cvt_pk_bf16_f32 v91, v96, v97
	v_cvt_pk_bf16_f32 v92, v99, v100
	v_cvt_pk_bf16_f32 v93, v101, v93
	global_store_dwordx4 v[94:95], v[90:93], off
	s_nop 1
	v_mul_f32_e32 v90, 0x3dd2d3e8, v86
	v_fma_f32 v90, -v86, v90, s79
	v_mul_f32_e32 v90, v86, v90
	v_exp_f32_e32 v90, v90
	s_nop 0
	v_add_f32_e32 v90, 1.0, v90
	v_rcp_f32_e32 v90, v90
	s_nop 0
	v_mul_f32_e32 v86, v86, v90
	v_mul_f32_e32 v90, 0x3dd2d3e8, v87
	v_fma_f32 v90, -v87, v90, s79
	v_mul_f32_e32 v90, v87, v90
	v_exp_f32_e32 v90, v90
	s_nop 0
	v_add_f32_e32 v90, 1.0, v90
	v_rcp_f32_e32 v90, v90
	s_nop 0
	v_mul_f32_e32 v87, v87, v90
	v_mul_f32_e32 v90, 0x3dd2d3e8, v88
	v_fma_f32 v90, -v88, v90, s79
	v_mul_f32_e32 v90, v88, v90
	v_exp_f32_e32 v90, v90
	s_nop 0
	v_add_f32_e32 v90, 1.0, v90
	v_rcp_f32_e32 v90, v90
	s_nop 0
	v_mul_f32_e32 v88, v88, v90
	v_mul_f32_e32 v90, 0x3dd2d3e8, v89
	v_fma_f32 v90, -v89, v90, s79
	v_mul_f32_e32 v90, v89, v90
	v_exp_f32_e32 v90, v90
	s_nop 0
	v_add_f32_e32 v90, 1.0, v90
	v_rcp_f32_e32 v90, v90
	s_nop 0
	v_mul_f32_e32 v89, v89, v90
	v_mul_f32_e32 v90, 0x3dd2d3e8, v82
	v_fma_f32 v90, -v82, v90, s79
	v_mul_f32_e32 v90, v82, v90
	v_exp_f32_e32 v90, v90
	s_nop 0
	v_add_f32_e32 v90, 1.0, v90
	v_rcp_f32_e32 v90, v90
	s_nop 0
	v_mul_f32_e32 v90, v82, v90
	v_mul_f32_e32 v82, 0x3dd2d3e8, v83
	v_fma_f32 v82, -v83, v82, s79
	v_mul_f32_e32 v82, v83, v82
	v_exp_f32_e32 v82, v82
	s_nop 0
	v_add_f32_e32 v82, 1.0, v82
	v_rcp_f32_e32 v82, v82
	s_nop 0
	v_mul_f32_e32 v91, v83, v82
	v_mul_f32_e32 v82, 0x3dd2d3e8, v84
	v_fma_f32 v82, -v84, v82, s79
	v_mul_f32_e32 v82, v84, v82
	v_exp_f32_e32 v82, v82
	s_nop 0
	v_add_f32_e32 v82, 1.0, v82
	v_rcp_f32_e32 v82, v82
	s_nop 0
	v_mul_f32_e32 v92, v84, v82
	v_mul_f32_e32 v82, 0x3dd2d3e8, v85
	v_fma_f32 v82, -v85, v82, s79
	v_mul_f32_e32 v82, v85, v82
	v_exp_f32_e32 v82, v82
	s_nop 0
	v_add_f32_e32 v82, 1.0, v82
	v_rcp_f32_e32 v82, v82
	s_nop 0
	v_mul_f32_e32 v85, v85, v82
	v_cvt_pk_bf16_f32 v82, v86, v87
	v_add_u32_e32 v86, v124, v98
	v_mad_i64_i32 v[86:87], s[40:41], v86, s80, v[122:123]
	v_lshl_add_u64 v[86:87], v[86:87], 0, s[34:35]
	v_lshl_add_u64 v[86:87], v[86:87], 0, v[180:181]
	v_cvt_pk_bf16_f32 v83, v88, v89
	v_cvt_pk_bf16_f32 v84, v90, v91
	v_cvt_pk_bf16_f32 v85, v92, v85
	global_store_dwordx4 v[86:87], v[82:85], off
	s_nop 1
	v_mul_f32_e32 v83, 0x3dd2d3e8, v78
	v_fma_f32 v83, -v78, v83, s79
	v_mul_f32_e32 v83, v78, v83
	v_exp_f32_e32 v83, v83
	v_add_u32_e32 v82, 0x300, v149
	v_add_f32_e32 v83, 1.0, v83
	v_rcp_f32_e32 v83, v83
	s_nop 0
	v_mul_f32_e32 v78, v78, v83
	v_mul_f32_e32 v83, 0x3dd2d3e8, v79
	v_fma_f32 v83, -v79, v83, s79
	v_mul_f32_e32 v83, v79, v83
	v_exp_f32_e32 v83, v83
	s_nop 0
	v_add_f32_e32 v83, 1.0, v83
	v_rcp_f32_e32 v83, v83
	s_nop 0
	v_mul_f32_e32 v79, v79, v83
	v_mul_f32_e32 v83, 0x3dd2d3e8, v80
	v_fma_f32 v83, -v80, v83, s79
	v_mul_f32_e32 v83, v80, v83
	v_exp_f32_e32 v83, v83
	s_nop 0
	v_add_f32_e32 v83, 1.0, v83
	v_rcp_f32_e32 v83, v83
	s_nop 0
	v_mul_f32_e32 v80, v80, v83
	v_mul_f32_e32 v83, 0x3dd2d3e8, v81
	v_fma_f32 v83, -v81, v83, s79
	v_mul_f32_e32 v83, v81, v83
	v_exp_f32_e32 v83, v83
	s_nop 0
	v_add_f32_e32 v83, 1.0, v83
	v_rcp_f32_e32 v83, v83
	s_nop 0
	v_mul_f32_e32 v81, v81, v83
	v_mul_f32_e32 v83, 0x3dd2d3e8, v74
	v_fma_f32 v83, -v74, v83, s79
	v_mul_f32_e32 v83, v74, v83
	v_exp_f32_e32 v83, v83
	s_nop 0
	v_add_f32_e32 v83, 1.0, v83
	v_rcp_f32_e32 v83, v83
	s_nop 0
	v_mul_f32_e32 v83, v74, v83
	v_mul_f32_e32 v74, 0x3dd2d3e8, v75
	v_fma_f32 v74, -v75, v74, s79
	v_mul_f32_e32 v74, v75, v74
	v_exp_f32_e32 v74, v74
	s_nop 0
	v_add_f32_e32 v74, 1.0, v74
	v_rcp_f32_e32 v74, v74
	s_nop 0
	v_mul_f32_e32 v84, v75, v74
	v_mul_f32_e32 v74, 0x3dd2d3e8, v76
	v_fma_f32 v74, -v76, v74, s79
	v_mul_f32_e32 v74, v76, v74
	v_exp_f32_e32 v74, v74
	s_nop 0
	v_add_f32_e32 v74, 1.0, v74
	v_rcp_f32_e32 v74, v74
	s_nop 0
	v_mul_f32_e32 v85, v76, v74
	v_mul_f32_e32 v74, 0x3dd2d3e8, v77
	v_fma_f32 v74, -v77, v74, s79
	v_mul_f32_e32 v74, v77, v74
	v_exp_f32_e32 v74, v74
	s_nop 0
	v_add_f32_e32 v74, 1.0, v74
	v_rcp_f32_e32 v74, v74
	s_nop 0
	v_mul_f32_e32 v77, v77, v74
	v_cvt_pk_bf16_f32 v74, v78, v79
	v_add_u32_e32 v78, v148, v82
	v_mad_i64_i32 v[78:79], s[40:41], v78, s80, v[122:123]
	v_lshl_add_u64 v[78:79], v[78:79], 0, s[34:35]
	v_lshl_add_u64 v[78:79], v[78:79], 0, v[180:181]
	v_cvt_pk_bf16_f32 v75, v80, v81
	v_cvt_pk_bf16_f32 v76, v83, v84
	v_cvt_pk_bf16_f32 v77, v85, v77
	global_store_dwordx4 v[78:79], v[74:77], off
	s_nop 1
	v_mul_f32_e32 v74, 0x3dd2d3e8, v70
	v_fma_f32 v74, -v70, v74, s79
	v_mul_f32_e32 v74, v70, v74
	v_exp_f32_e32 v74, v74
	s_nop 0
	v_add_f32_e32 v74, 1.0, v74
	v_rcp_f32_e32 v74, v74
	s_nop 0
	v_mul_f32_e32 v70, v70, v74
	v_mul_f32_e32 v74, 0x3dd2d3e8, v71
	v_fma_f32 v74, -v71, v74, s79
	v_mul_f32_e32 v74, v71, v74
	v_exp_f32_e32 v74, v74
	s_nop 0
	v_add_f32_e32 v74, 1.0, v74
	v_rcp_f32_e32 v74, v74
	s_nop 0
	v_mul_f32_e32 v71, v71, v74
	v_mul_f32_e32 v74, 0x3dd2d3e8, v72
	v_fma_f32 v74, -v72, v74, s79
	v_mul_f32_e32 v74, v72, v74
	v_exp_f32_e32 v74, v74
	s_nop 0
	v_add_f32_e32 v74, 1.0, v74
	v_rcp_f32_e32 v74, v74
	s_nop 0
	v_mul_f32_e32 v72, v72, v74
	v_mul_f32_e32 v74, 0x3dd2d3e8, v73
	v_fma_f32 v74, -v73, v74, s79
	v_mul_f32_e32 v74, v73, v74
	v_exp_f32_e32 v74, v74
	s_nop 0
	v_add_f32_e32 v74, 1.0, v74
	v_rcp_f32_e32 v74, v74
	s_nop 0
	v_mul_f32_e32 v73, v73, v74
	v_mul_f32_e32 v74, 0x3dd2d3e8, v66
	v_fma_f32 v74, -v66, v74, s79
	v_mul_f32_e32 v74, v66, v74
	v_exp_f32_e32 v74, v74
	s_nop 0
	v_add_f32_e32 v74, 1.0, v74
	v_rcp_f32_e32 v74, v74
	s_nop 0
	v_mul_f32_e32 v74, v66, v74
	v_mul_f32_e32 v66, 0x3dd2d3e8, v67
	v_fma_f32 v66, -v67, v66, s79
	v_mul_f32_e32 v66, v67, v66
	v_exp_f32_e32 v66, v66
	s_nop 0
	v_add_f32_e32 v66, 1.0, v66
	v_rcp_f32_e32 v66, v66
	s_nop 0
	v_mul_f32_e32 v75, v67, v66
	v_mul_f32_e32 v66, 0x3dd2d3e8, v68
	v_fma_f32 v66, -v68, v66, s79
	v_mul_f32_e32 v66, v68, v66
	v_exp_f32_e32 v66, v66
	s_nop 0
	v_add_f32_e32 v66, 1.0, v66
	v_rcp_f32_e32 v66, v66
	s_nop 0
	v_mul_f32_e32 v76, v68, v66
	v_mul_f32_e32 v66, 0x3dd2d3e8, v69
	v_fma_f32 v66, -v69, v66, s79
	v_mul_f32_e32 v66, v69, v66
	v_exp_f32_e32 v66, v66
	s_nop 0
	v_add_f32_e32 v66, 1.0, v66
	v_rcp_f32_e32 v66, v66
	s_nop 0
	v_mul_f32_e32 v69, v69, v66
	v_cvt_pk_bf16_f32 v66, v70, v71
	v_add_u32_e32 v70, v124, v82
	v_mad_i64_i32 v[70:71], s[40:41], v70, s80, v[122:123]
	v_lshl_add_u64 v[70:71], v[70:71], 0, s[34:35]
	v_lshl_add_u64 v[70:71], v[70:71], 0, v[180:181]
	v_cvt_pk_bf16_f32 v67, v72, v73
	v_cvt_pk_bf16_f32 v68, v74, v75
	v_cvt_pk_bf16_f32 v69, v76, v69
	global_store_dwordx4 v[70:71], v[66:69], off
	s_nop 1
	v_mul_f32_e32 v67, 0x3dd2d3e8, v62
	v_fma_f32 v67, -v62, v67, s79
	v_mul_f32_e32 v67, v62, v67
	v_exp_f32_e32 v67, v67
	v_add_u32_e32 v66, 0x800, v149
	v_add_f32_e32 v67, 1.0, v67
	v_rcp_f32_e32 v67, v67
	s_nop 0
	v_mul_f32_e32 v62, v62, v67
	v_mul_f32_e32 v67, 0x3dd2d3e8, v63
	v_fma_f32 v67, -v63, v67, s79
	v_mul_f32_e32 v67, v63, v67
	v_exp_f32_e32 v67, v67
	s_nop 0
	v_add_f32_e32 v67, 1.0, v67
	v_rcp_f32_e32 v67, v67
	s_nop 0
	v_mul_f32_e32 v63, v63, v67
	v_mul_f32_e32 v67, 0x3dd2d3e8, v64
	v_fma_f32 v67, -v64, v67, s79
	v_mul_f32_e32 v67, v64, v67
	v_exp_f32_e32 v67, v67
	s_nop 0
	v_add_f32_e32 v67, 1.0, v67
	v_rcp_f32_e32 v67, v67
	s_nop 0
	v_mul_f32_e32 v64, v64, v67
	v_mul_f32_e32 v67, 0x3dd2d3e8, v65
	v_fma_f32 v67, -v65, v67, s79
	v_mul_f32_e32 v67, v65, v67
	v_exp_f32_e32 v67, v67
	s_nop 0
	v_add_f32_e32 v67, 1.0, v67
	v_rcp_f32_e32 v67, v67
	s_nop 0
	v_mul_f32_e32 v65, v65, v67
	v_mul_f32_e32 v67, 0x3dd2d3e8, v58
	v_fma_f32 v67, -v58, v67, s79
	v_mul_f32_e32 v67, v58, v67
	v_exp_f32_e32 v67, v67
	s_nop 0
	v_add_f32_e32 v67, 1.0, v67
	v_rcp_f32_e32 v67, v67
	s_nop 0
	v_mul_f32_e32 v67, v58, v67
	v_mul_f32_e32 v58, 0x3dd2d3e8, v59
	v_fma_f32 v58, -v59, v58, s79
	v_mul_f32_e32 v58, v59, v58
	v_exp_f32_e32 v58, v58
	s_nop 0
	v_add_f32_e32 v58, 1.0, v58
	v_rcp_f32_e32 v58, v58
	s_nop 0
	v_mul_f32_e32 v68, v59, v58
	v_mul_f32_e32 v58, 0x3dd2d3e8, v60
	v_fma_f32 v58, -v60, v58, s79
	v_mul_f32_e32 v58, v60, v58
	v_exp_f32_e32 v58, v58
	s_nop 0
	v_add_f32_e32 v58, 1.0, v58
	v_rcp_f32_e32 v58, v58
	s_nop 0
	v_mul_f32_e32 v69, v60, v58
	v_mul_f32_e32 v58, 0x3dd2d3e8, v61
	v_fma_f32 v58, -v61, v58, s79
	v_mul_f32_e32 v58, v61, v58
	v_exp_f32_e32 v58, v58
	s_nop 0
	v_add_f32_e32 v58, 1.0, v58
	v_rcp_f32_e32 v58, v58
	s_nop 0
	v_mul_f32_e32 v61, v61, v58
	v_cvt_pk_bf16_f32 v58, v62, v63
	v_add_u32_e32 v62, v148, v66
	v_mad_i64_i32 v[62:63], s[40:41], v62, s80, v[122:123]
	v_lshl_add_u64 v[62:63], v[62:63], 0, s[34:35]
	v_lshl_add_u64 v[62:63], v[62:63], 0, v[180:181]
	v_cvt_pk_bf16_f32 v59, v64, v65
	v_cvt_pk_bf16_f32 v60, v67, v68
	v_cvt_pk_bf16_f32 v61, v69, v61
	global_store_dwordx4 v[62:63], v[58:61], off
	s_nop 1
	v_mul_f32_e32 v58, 0x3dd2d3e8, v54
	v_fma_f32 v58, -v54, v58, s79
	v_mul_f32_e32 v58, v54, v58
	v_exp_f32_e32 v58, v58
	s_nop 0
	v_add_f32_e32 v58, 1.0, v58
	v_rcp_f32_e32 v58, v58
	s_nop 0
	v_mul_f32_e32 v54, v54, v58
	v_mul_f32_e32 v58, 0x3dd2d3e8, v55
	v_fma_f32 v58, -v55, v58, s79
	v_mul_f32_e32 v58, v55, v58
	v_exp_f32_e32 v58, v58
	s_nop 0
	v_add_f32_e32 v58, 1.0, v58
	v_rcp_f32_e32 v58, v58
	s_nop 0
	v_mul_f32_e32 v55, v55, v58
	v_mul_f32_e32 v58, 0x3dd2d3e8, v56
	v_fma_f32 v58, -v56, v58, s79
	v_mul_f32_e32 v58, v56, v58
	v_exp_f32_e32 v58, v58
	s_nop 0
	v_add_f32_e32 v58, 1.0, v58
	v_rcp_f32_e32 v58, v58
	s_nop 0
	v_mul_f32_e32 v56, v56, v58
	v_mul_f32_e32 v58, 0x3dd2d3e8, v57
	v_fma_f32 v58, -v57, v58, s79
	v_mul_f32_e32 v58, v57, v58
	v_exp_f32_e32 v58, v58
	s_nop 0
	v_add_f32_e32 v58, 1.0, v58
	v_rcp_f32_e32 v58, v58
	s_nop 0
	v_mul_f32_e32 v57, v57, v58
	v_mul_f32_e32 v58, 0x3dd2d3e8, v50
	v_fma_f32 v58, -v50, v58, s79
	v_mul_f32_e32 v58, v50, v58
	v_exp_f32_e32 v58, v58
	s_nop 0
	v_add_f32_e32 v58, 1.0, v58
	v_rcp_f32_e32 v58, v58
	s_nop 0
	v_mul_f32_e32 v58, v50, v58
	v_mul_f32_e32 v50, 0x3dd2d3e8, v51
	v_fma_f32 v50, -v51, v50, s79
	v_mul_f32_e32 v50, v51, v50
	v_exp_f32_e32 v50, v50
	s_nop 0
	v_add_f32_e32 v50, 1.0, v50
	v_rcp_f32_e32 v50, v50
	s_nop 0
	v_mul_f32_e32 v59, v51, v50
	v_mul_f32_e32 v50, 0x3dd2d3e8, v52
	v_fma_f32 v50, -v52, v50, s79
	v_mul_f32_e32 v50, v52, v50
	v_exp_f32_e32 v50, v50
	s_nop 0
	v_add_f32_e32 v50, 1.0, v50
	v_rcp_f32_e32 v50, v50
	s_nop 0
	v_mul_f32_e32 v60, v52, v50
	v_mul_f32_e32 v50, 0x3dd2d3e8, v53
	v_fma_f32 v50, -v53, v50, s79
	v_mul_f32_e32 v50, v53, v50
	v_exp_f32_e32 v50, v50
	s_nop 0
	v_add_f32_e32 v50, 1.0, v50
	v_rcp_f32_e32 v50, v50
	s_nop 0
	v_mul_f32_e32 v53, v53, v50
	v_cvt_pk_bf16_f32 v50, v54, v55
	v_add_u32_e32 v54, v124, v66
	v_mad_i64_i32 v[54:55], s[40:41], v54, s80, v[122:123]
	v_lshl_add_u64 v[54:55], v[54:55], 0, s[34:35]
	v_lshl_add_u64 v[54:55], v[54:55], 0, v[180:181]
	v_cvt_pk_bf16_f32 v51, v56, v57
	v_cvt_pk_bf16_f32 v52, v58, v59
	v_cvt_pk_bf16_f32 v53, v60, v53
	global_store_dwordx4 v[54:55], v[50:53], off
	s_nop 1
	v_mul_f32_e32 v51, 0x3dd2d3e8, v46
	v_fma_f32 v51, -v46, v51, s79
	v_mul_f32_e32 v51, v46, v51
	v_exp_f32_e32 v51, v51
	v_add_u32_e32 v50, 0x900, v149
	v_add_f32_e32 v51, 1.0, v51
	v_rcp_f32_e32 v51, v51
	s_nop 0
	v_mul_f32_e32 v46, v46, v51
	v_mul_f32_e32 v51, 0x3dd2d3e8, v47
	v_fma_f32 v51, -v47, v51, s79
	v_mul_f32_e32 v51, v47, v51
	v_exp_f32_e32 v51, v51
	s_nop 0
	v_add_f32_e32 v51, 1.0, v51
	v_rcp_f32_e32 v51, v51
	s_nop 0
	v_mul_f32_e32 v47, v47, v51
	v_mul_f32_e32 v51, 0x3dd2d3e8, v48
	v_fma_f32 v51, -v48, v51, s79
	v_mul_f32_e32 v51, v48, v51
	v_exp_f32_e32 v51, v51
	s_nop 0
	v_add_f32_e32 v51, 1.0, v51
	v_rcp_f32_e32 v51, v51
	s_nop 0
	v_mul_f32_e32 v48, v48, v51
	v_mul_f32_e32 v51, 0x3dd2d3e8, v49
	v_fma_f32 v51, -v49, v51, s79
	v_mul_f32_e32 v51, v49, v51
	v_exp_f32_e32 v51, v51
	s_nop 0
	v_add_f32_e32 v51, 1.0, v51
	v_rcp_f32_e32 v51, v51
	s_nop 0
	v_mul_f32_e32 v49, v49, v51
	v_mul_f32_e32 v51, 0x3dd2d3e8, v42
	v_fma_f32 v51, -v42, v51, s79
	v_mul_f32_e32 v51, v42, v51
	v_exp_f32_e32 v51, v51
	s_nop 0
	v_add_f32_e32 v51, 1.0, v51
	v_rcp_f32_e32 v51, v51
	s_nop 0
	v_mul_f32_e32 v51, v42, v51
	v_mul_f32_e32 v42, 0x3dd2d3e8, v43
	v_fma_f32 v42, -v43, v42, s79
	v_mul_f32_e32 v42, v43, v42
	v_exp_f32_e32 v42, v42
	s_nop 0
	v_add_f32_e32 v42, 1.0, v42
	v_rcp_f32_e32 v42, v42
	s_nop 0
	v_mul_f32_e32 v52, v43, v42
	v_mul_f32_e32 v42, 0x3dd2d3e8, v44
	v_fma_f32 v42, -v44, v42, s79
	v_mul_f32_e32 v42, v44, v42
	v_exp_f32_e32 v42, v42
	s_nop 0
	v_add_f32_e32 v42, 1.0, v42
	v_rcp_f32_e32 v42, v42
	s_nop 0
	v_mul_f32_e32 v53, v44, v42
	v_mul_f32_e32 v42, 0x3dd2d3e8, v45
	v_fma_f32 v42, -v45, v42, s79
	v_mul_f32_e32 v42, v45, v42
	v_exp_f32_e32 v42, v42
	s_nop 0
	v_add_f32_e32 v42, 1.0, v42
	v_rcp_f32_e32 v42, v42
	s_nop 0
	v_mul_f32_e32 v45, v45, v42
	v_cvt_pk_bf16_f32 v42, v46, v47
	v_add_u32_e32 v46, v148, v50
	v_mad_i64_i32 v[46:47], s[40:41], v46, s80, v[122:123]
	v_lshl_add_u64 v[46:47], v[46:47], 0, s[34:35]
	v_lshl_add_u64 v[46:47], v[46:47], 0, v[180:181]
	v_cvt_pk_bf16_f32 v43, v48, v49
	v_cvt_pk_bf16_f32 v44, v51, v52
	v_cvt_pk_bf16_f32 v45, v53, v45
	global_store_dwordx4 v[46:47], v[42:45], off
	s_nop 1
	v_mul_f32_e32 v42, 0x3dd2d3e8, v38
	v_fma_f32 v42, -v38, v42, s79
	v_mul_f32_e32 v42, v38, v42
	v_exp_f32_e32 v42, v42
	s_nop 0
	v_add_f32_e32 v42, 1.0, v42
	v_rcp_f32_e32 v42, v42
	s_nop 0
	v_mul_f32_e32 v38, v38, v42
	v_mul_f32_e32 v42, 0x3dd2d3e8, v39
	v_fma_f32 v42, -v39, v42, s79
	v_mul_f32_e32 v42, v39, v42
	v_exp_f32_e32 v42, v42
	s_nop 0
	v_add_f32_e32 v42, 1.0, v42
	v_rcp_f32_e32 v42, v42
	s_nop 0
	v_mul_f32_e32 v39, v39, v42
	v_mul_f32_e32 v42, 0x3dd2d3e8, v40
	v_fma_f32 v42, -v40, v42, s79
	v_mul_f32_e32 v42, v40, v42
	v_exp_f32_e32 v42, v42
	s_nop 0
	v_add_f32_e32 v42, 1.0, v42
	v_rcp_f32_e32 v42, v42
	s_nop 0
	v_mul_f32_e32 v40, v40, v42
	v_mul_f32_e32 v42, 0x3dd2d3e8, v41
	v_fma_f32 v42, -v41, v42, s79
	v_mul_f32_e32 v42, v41, v42
	v_exp_f32_e32 v42, v42
	s_nop 0
	v_add_f32_e32 v42, 1.0, v42
	v_rcp_f32_e32 v42, v42
	s_nop 0
	v_mul_f32_e32 v41, v41, v42
	v_mul_f32_e32 v42, 0x3dd2d3e8, v34
	v_fma_f32 v42, -v34, v42, s79
	v_mul_f32_e32 v42, v34, v42
	v_exp_f32_e32 v42, v42
	s_nop 0
	v_add_f32_e32 v42, 1.0, v42
	v_rcp_f32_e32 v42, v42
	s_nop 0
	v_mul_f32_e32 v42, v34, v42
	v_mul_f32_e32 v34, 0x3dd2d3e8, v35
	v_fma_f32 v34, -v35, v34, s79
	v_mul_f32_e32 v34, v35, v34
	v_exp_f32_e32 v34, v34
	s_nop 0
	v_add_f32_e32 v34, 1.0, v34
	v_rcp_f32_e32 v34, v34
	s_nop 0
	v_mul_f32_e32 v43, v35, v34
	v_mul_f32_e32 v34, 0x3dd2d3e8, v36
	v_fma_f32 v34, -v36, v34, s79
	v_mul_f32_e32 v34, v36, v34
	v_exp_f32_e32 v34, v34
	s_nop 0
	v_add_f32_e32 v34, 1.0, v34
	v_rcp_f32_e32 v34, v34
	s_nop 0
	v_mul_f32_e32 v44, v36, v34
	v_mul_f32_e32 v34, 0x3dd2d3e8, v37
	v_fma_f32 v34, -v37, v34, s79
	v_mul_f32_e32 v34, v37, v34
	v_exp_f32_e32 v34, v34
	s_nop 0
	v_add_f32_e32 v34, 1.0, v34
	v_rcp_f32_e32 v34, v34
	s_nop 0
	v_mul_f32_e32 v37, v37, v34
	v_cvt_pk_bf16_f32 v34, v38, v39
	v_add_u32_e32 v38, v124, v50
	v_mad_i64_i32 v[38:39], s[40:41], v38, s80, v[122:123]
	v_lshl_add_u64 v[38:39], v[38:39], 0, s[34:35]
	v_lshl_add_u64 v[38:39], v[38:39], 0, v[180:181]
	v_cvt_pk_bf16_f32 v35, v40, v41
	v_cvt_pk_bf16_f32 v36, v42, v43
	v_cvt_pk_bf16_f32 v37, v44, v37
	global_store_dwordx4 v[38:39], v[34:37], off
	s_nop 1
	v_mul_f32_e32 v35, 0x3dd2d3e8, v30
	v_fma_f32 v35, -v30, v35, s79
	v_mul_f32_e32 v35, v30, v35
	v_exp_f32_e32 v35, v35
	v_add_u32_e32 v34, 0xa00, v149
	v_add_f32_e32 v35, 1.0, v35
	v_rcp_f32_e32 v35, v35
	s_nop 0
	v_mul_f32_e32 v30, v30, v35
	v_mul_f32_e32 v35, 0x3dd2d3e8, v31
	v_fma_f32 v35, -v31, v35, s79
	v_mul_f32_e32 v35, v31, v35
	v_exp_f32_e32 v35, v35
	s_nop 0
	v_add_f32_e32 v35, 1.0, v35
	v_rcp_f32_e32 v35, v35
	s_nop 0
	v_mul_f32_e32 v31, v31, v35
	v_mul_f32_e32 v35, 0x3dd2d3e8, v32
	v_fma_f32 v35, -v32, v35, s79
	v_mul_f32_e32 v35, v32, v35
	v_exp_f32_e32 v35, v35
	s_nop 0
	v_add_f32_e32 v35, 1.0, v35
	v_rcp_f32_e32 v35, v35
	s_nop 0
	v_mul_f32_e32 v32, v32, v35
	v_mul_f32_e32 v35, 0x3dd2d3e8, v33
	v_fma_f32 v35, -v33, v35, s79
	v_mul_f32_e32 v35, v33, v35
	v_exp_f32_e32 v35, v35
	s_nop 0
	v_add_f32_e32 v35, 1.0, v35
	v_rcp_f32_e32 v35, v35
	s_nop 0
	v_mul_f32_e32 v33, v33, v35
	v_mul_f32_e32 v35, 0x3dd2d3e8, v26
	v_fma_f32 v35, -v26, v35, s79
	v_mul_f32_e32 v35, v26, v35
	v_exp_f32_e32 v35, v35
	s_nop 0
	v_add_f32_e32 v35, 1.0, v35
	v_rcp_f32_e32 v35, v35
	s_nop 0
	v_mul_f32_e32 v35, v26, v35
	v_mul_f32_e32 v26, 0x3dd2d3e8, v27
	v_fma_f32 v26, -v27, v26, s79
	v_mul_f32_e32 v26, v27, v26
	v_exp_f32_e32 v26, v26
	s_nop 0
	v_add_f32_e32 v26, 1.0, v26
	v_rcp_f32_e32 v26, v26
	s_nop 0
	v_mul_f32_e32 v36, v27, v26
	v_mul_f32_e32 v26, 0x3dd2d3e8, v28
	v_fma_f32 v26, -v28, v26, s79
	v_mul_f32_e32 v26, v28, v26
	v_exp_f32_e32 v26, v26
	s_nop 0
	v_add_f32_e32 v26, 1.0, v26
	v_rcp_f32_e32 v26, v26
	s_nop 0
	v_mul_f32_e32 v37, v28, v26
	v_mul_f32_e32 v26, 0x3dd2d3e8, v29
	v_fma_f32 v26, -v29, v26, s79
	v_mul_f32_e32 v26, v29, v26
	v_exp_f32_e32 v26, v26
	s_nop 0
	v_add_f32_e32 v26, 1.0, v26
	v_rcp_f32_e32 v26, v26
	s_nop 0
	v_mul_f32_e32 v29, v29, v26
	v_cvt_pk_bf16_f32 v26, v30, v31
	v_add_u32_e32 v30, v148, v34
	v_mad_i64_i32 v[30:31], s[40:41], v30, s80, v[122:123]
	v_lshl_add_u64 v[30:31], v[30:31], 0, s[34:35]
	v_lshl_add_u64 v[30:31], v[30:31], 0, v[180:181]
	v_cvt_pk_bf16_f32 v27, v32, v33
	v_cvt_pk_bf16_f32 v28, v35, v36
	v_cvt_pk_bf16_f32 v29, v37, v29
	global_store_dwordx4 v[30:31], v[26:29], off
	s_nop 1
	v_mul_f32_e32 v26, 0x3dd2d3e8, v22
	v_fma_f32 v26, -v22, v26, s79
	v_mul_f32_e32 v26, v22, v26
	v_exp_f32_e32 v26, v26
	s_nop 0
	v_add_f32_e32 v26, 1.0, v26
	v_rcp_f32_e32 v26, v26
	s_nop 0
	v_mul_f32_e32 v22, v22, v26
	v_mul_f32_e32 v26, 0x3dd2d3e8, v23
	v_fma_f32 v26, -v23, v26, s79
	v_mul_f32_e32 v26, v23, v26
	v_exp_f32_e32 v26, v26
	s_nop 0
	v_add_f32_e32 v26, 1.0, v26
	v_rcp_f32_e32 v26, v26
	s_nop 0
	v_mul_f32_e32 v23, v23, v26
	v_mul_f32_e32 v26, 0x3dd2d3e8, v24
	v_fma_f32 v26, -v24, v26, s79
	v_mul_f32_e32 v26, v24, v26
	v_exp_f32_e32 v26, v26
	s_nop 0
	v_add_f32_e32 v26, 1.0, v26
	v_rcp_f32_e32 v26, v26
	s_nop 0
	v_mul_f32_e32 v24, v24, v26
	v_mul_f32_e32 v26, 0x3dd2d3e8, v25
	v_fma_f32 v26, -v25, v26, s79
	v_mul_f32_e32 v26, v25, v26
	v_exp_f32_e32 v26, v26
	s_nop 0
	v_add_f32_e32 v26, 1.0, v26
	v_rcp_f32_e32 v26, v26
	s_nop 0
	v_mul_f32_e32 v25, v25, v26
	v_mul_f32_e32 v26, 0x3dd2d3e8, v18
	v_fma_f32 v26, -v18, v26, s79
	v_mul_f32_e32 v26, v18, v26
	v_exp_f32_e32 v26, v26
	s_nop 0
	v_add_f32_e32 v26, 1.0, v26
	v_rcp_f32_e32 v26, v26
	s_nop 0
	v_mul_f32_e32 v26, v18, v26
	v_mul_f32_e32 v18, 0x3dd2d3e8, v19
	v_fma_f32 v18, -v19, v18, s79
	v_mul_f32_e32 v18, v19, v18
	v_exp_f32_e32 v18, v18
	s_nop 0
	v_add_f32_e32 v18, 1.0, v18
	v_rcp_f32_e32 v18, v18
	s_nop 0
	v_mul_f32_e32 v27, v19, v18
	v_mul_f32_e32 v18, 0x3dd2d3e8, v20
	v_fma_f32 v18, -v20, v18, s79
	v_mul_f32_e32 v18, v20, v18
	v_exp_f32_e32 v18, v18
	s_nop 0
	v_add_f32_e32 v18, 1.0, v18
	v_rcp_f32_e32 v18, v18
	s_nop 0
	v_mul_f32_e32 v28, v20, v18
	v_mul_f32_e32 v18, 0x3dd2d3e8, v21
	v_fma_f32 v18, -v21, v18, s79
	v_mul_f32_e32 v18, v21, v18
	v_exp_f32_e32 v18, v18
	s_nop 0
	v_add_f32_e32 v18, 1.0, v18
	v_rcp_f32_e32 v18, v18
	s_nop 0
	v_mul_f32_e32 v21, v21, v18
	v_cvt_pk_bf16_f32 v18, v22, v23
	v_add_u32_e32 v22, v124, v34
	v_mad_i64_i32 v[22:23], s[40:41], v22, s80, v[122:123]
	v_lshl_add_u64 v[22:23], v[22:23], 0, s[34:35]
	v_lshl_add_u64 v[22:23], v[22:23], 0, v[180:181]
	v_cvt_pk_bf16_f32 v19, v24, v25
	v_cvt_pk_bf16_f32 v20, v26, v27
	v_cvt_pk_bf16_f32 v21, v28, v21
	global_store_dwordx4 v[22:23], v[18:21], off
	s_nop 1
	v_mul_f32_e32 v19, 0x3dd2d3e8, v14
	v_fma_f32 v19, -v14, v19, s79
	v_mul_f32_e32 v19, v14, v19
	v_exp_f32_e32 v19, v19
	v_add_u32_e32 v18, 0xb00, v149
	v_add_f32_e32 v19, 1.0, v19
	v_rcp_f32_e32 v19, v19
	s_nop 0
	v_mul_f32_e32 v14, v14, v19
	v_mul_f32_e32 v19, 0x3dd2d3e8, v15
	v_fma_f32 v19, -v15, v19, s79
	v_mul_f32_e32 v19, v15, v19
	v_exp_f32_e32 v19, v19
	s_nop 0
	v_add_f32_e32 v19, 1.0, v19
	v_rcp_f32_e32 v19, v19
	s_nop 0
	v_mul_f32_e32 v15, v15, v19
	v_mul_f32_e32 v19, 0x3dd2d3e8, v16
	v_fma_f32 v19, -v16, v19, s79
	v_mul_f32_e32 v19, v16, v19
	v_exp_f32_e32 v19, v19
	s_nop 0
	v_add_f32_e32 v19, 1.0, v19
	v_rcp_f32_e32 v19, v19
	s_nop 0
	v_mul_f32_e32 v16, v16, v19
	v_mul_f32_e32 v19, 0x3dd2d3e8, v17
	v_fma_f32 v19, -v17, v19, s79
	v_mul_f32_e32 v19, v17, v19
	v_exp_f32_e32 v19, v19
	s_nop 0
	v_add_f32_e32 v19, 1.0, v19
	v_rcp_f32_e32 v19, v19
	s_nop 0
	v_mul_f32_e32 v17, v17, v19
	v_mul_f32_e32 v19, 0x3dd2d3e8, v10
	v_fma_f32 v19, -v10, v19, s79
	v_mul_f32_e32 v19, v10, v19
	v_exp_f32_e32 v19, v19
	s_nop 0
	v_add_f32_e32 v19, 1.0, v19
	v_rcp_f32_e32 v19, v19
	s_nop 0
	v_mul_f32_e32 v19, v10, v19
	v_mul_f32_e32 v10, 0x3dd2d3e8, v11
	v_fma_f32 v10, -v11, v10, s79
	v_mul_f32_e32 v10, v11, v10
	v_exp_f32_e32 v10, v10
	s_nop 0
	v_add_f32_e32 v10, 1.0, v10
	v_rcp_f32_e32 v10, v10
	s_nop 0
	v_mul_f32_e32 v20, v11, v10
	v_mul_f32_e32 v10, 0x3dd2d3e8, v12
	v_fma_f32 v10, -v12, v10, s79
	v_mul_f32_e32 v10, v12, v10
	v_exp_f32_e32 v10, v10
	s_nop 0
	v_add_f32_e32 v10, 1.0, v10
	v_rcp_f32_e32 v10, v10
	s_nop 0
	v_mul_f32_e32 v21, v12, v10
	v_mul_f32_e32 v10, 0x3dd2d3e8, v13
	v_fma_f32 v10, -v13, v10, s79
	v_mul_f32_e32 v10, v13, v10
	v_exp_f32_e32 v10, v10
	s_nop 0
	v_add_f32_e32 v10, 1.0, v10
	v_rcp_f32_e32 v10, v10
	s_nop 0
	v_mul_f32_e32 v13, v13, v10
	v_cvt_pk_bf16_f32 v10, v14, v15
	v_add_u32_e32 v14, v148, v18
	v_mad_i64_i32 v[14:15], s[40:41], v14, s80, v[122:123]
	v_lshl_add_u64 v[14:15], v[14:15], 0, s[34:35]
	v_lshl_add_u64 v[14:15], v[14:15], 0, v[180:181]
	v_cvt_pk_bf16_f32 v11, v16, v17
	v_cvt_pk_bf16_f32 v12, v19, v20
	v_cvt_pk_bf16_f32 v13, v21, v13
	global_store_dwordx4 v[14:15], v[10:13], off
	s_nop 1
	v_mul_f32_e32 v10, 0x3dd2d3e8, v6
	v_fma_f32 v10, -v6, v10, s79
	v_mul_f32_e32 v10, v6, v10
	v_exp_f32_e32 v10, v10
	s_nop 0
	v_add_f32_e32 v10, 1.0, v10
	v_rcp_f32_e32 v10, v10
	s_nop 0
	v_mul_f32_e32 v6, v6, v10
	v_mul_f32_e32 v10, 0x3dd2d3e8, v7
	v_fma_f32 v10, -v7, v10, s79
	v_mul_f32_e32 v10, v7, v10
	v_exp_f32_e32 v10, v10
	s_nop 0
	v_add_f32_e32 v10, 1.0, v10
	v_rcp_f32_e32 v10, v10
	s_nop 0
	v_mul_f32_e32 v7, v7, v10
	v_mul_f32_e32 v10, 0x3dd2d3e8, v8
	v_fma_f32 v10, -v8, v10, s79
	v_mul_f32_e32 v10, v8, v10
	v_exp_f32_e32 v10, v10
	s_nop 0
	v_add_f32_e32 v10, 1.0, v10
	v_rcp_f32_e32 v10, v10
	s_nop 0
	v_mul_f32_e32 v8, v8, v10
	v_mul_f32_e32 v10, 0x3dd2d3e8, v9
	v_fma_f32 v10, -v9, v10, s79
	v_mul_f32_e32 v10, v9, v10
	v_exp_f32_e32 v10, v10
	s_nop 0
	v_add_f32_e32 v10, 1.0, v10
	v_rcp_f32_e32 v10, v10
	s_nop 0
	v_mul_f32_e32 v9, v9, v10
	v_mul_f32_e32 v10, 0x3dd2d3e8, v2
	v_fma_f32 v10, -v2, v10, s79
	v_mul_f32_e32 v10, v2, v10
	v_exp_f32_e32 v10, v10
	s_nop 0
	v_add_f32_e32 v10, 1.0, v10
	v_rcp_f32_e32 v10, v10
	s_nop 0
	v_mul_f32_e32 v10, v2, v10
	v_mul_f32_e32 v2, 0x3dd2d3e8, v3
	v_fma_f32 v2, -v3, v2, s79
	v_mul_f32_e32 v2, v3, v2
	v_exp_f32_e32 v2, v2
	s_nop 0
	v_add_f32_e32 v2, 1.0, v2
	v_rcp_f32_e32 v2, v2
	s_nop 0
	v_mul_f32_e32 v11, v3, v2
	v_mul_f32_e32 v2, 0x3dd2d3e8, v4
	v_fma_f32 v2, -v4, v2, s79
	v_mul_f32_e32 v2, v4, v2
	v_exp_f32_e32 v2, v2
	s_nop 0
	v_add_f32_e32 v2, 1.0, v2
	v_rcp_f32_e32 v2, v2
	s_nop 0
	v_mul_f32_e32 v12, v4, v2
	v_mul_f32_e32 v2, 0x3dd2d3e8, v5
	v_fma_f32 v2, -v5, v2, s79
	v_mul_f32_e32 v2, v5, v2
	v_exp_f32_e32 v2, v2
	s_nop 0
	v_add_f32_e32 v2, 1.0, v2
	v_rcp_f32_e32 v2, v2
	s_nop 0
	v_mul_f32_e32 v5, v5, v2
	v_cvt_pk_bf16_f32 v2, v6, v7
	v_add_u32_e32 v6, v124, v18
	v_mad_i64_i32 v[6:7], s[40:41], v6, s80, v[122:123]
	v_lshl_add_u64 v[6:7], v[6:7], 0, s[34:35]
	v_lshl_add_u64 v[6:7], v[6:7], 0, v[180:181]
	v_cvt_pk_bf16_f32 v3, v8, v9
	v_cvt_pk_bf16_f32 v4, v10, v11
	v_cvt_pk_bf16_f32 v5, v12, v5
	global_store_dwordx4 v[6:7], v[2:5], off
	s_and_b64 vcc, exec, s[38:39]
	s_mov_b64 s[34:35], -1
	s_cbranch_vccnz .LBB0_817
	s_andn2_b64 vcc, exec, s[18:19]
	s_cbranch_vccz .LBB0_816
	s_barrier
	s_branch .LBB0_816

.LBB0_921:
	v_ashrrev_i32_e32 v3, 31, v15
	v_lshrrev_b32_e32 v3, 26, v3
	v_add_u32_e32 v3, v15, v3
	v_ashrrev_i32_e32 v10, 6, v3
	v_bfe_i32 v3, v15, 27, 1
	v_lshlrev_b32_e32 v2, 4, v15
	v_lshrrev_b32_e32 v3, 22, v3
	v_add_u32_e32 v3, v2, v3
	v_and_b32_e32 v3, 0xfffffc00, v3
	v_sub_u32_e32 v3, v2, v3
	v_lshrrev_b32_e32 v4, 4, v3
	v_bitop3_b32 v3, v4, v3, 32 bitop3:0x6c
	v_ashrrev_i32_e32 v5, 31, v3
	v_lshrrev_b32_e32 v5, 26, v5
	v_lshlrev_b32_e32 v4, 3, v10
	v_add_u32_e32 v5, v3, v5
	v_and_b32_e32 v4, -16, v4
	v_ashrrev_i32_e32 v12, 6, v5
	v_and_b32_e32 v5, 0xc0, v5
	v_readlane_b32 s8, v255, 41
	v_add_u32_e32 v4, v12, v4
	v_lshlrev_b32_e32 v6, 5, v10
	v_sub_u32_e32 v3, v3, v5
	s_mul_i32 s12, s8, 0x240000
	s_waitcnt lgkmcnt(0)
	s_add_u32 s10, s22, 0x39600000
	v_and_b32_e32 v11, 32, v6
	v_ashrrev_i16_sdwa v3, v224, sext(v3) dst_sel:DWORD dst_unused:UNUSED_PAD src0_sel:DWORD src1_sel:BYTE_0
	v_lshlrev_b32_e32 v5, 1, v4
	v_lshrrev_b32_e32 v6, 2, v4
	v_and_b32_e32 v7, 3, v12
	s_mov_b32 s21, 0x7fffe0
	s_addc_u32 s11, s23, 0
	s_lshl_b64 s[8:9], s[12:13], 1
	v_bfe_i32 v13, v3, 0, 16
	v_and_b32_e32 v5, 24, v5
	v_and_b32_e32 v6, 4, v6
	v_and_or_b32 v7, v4, s21, v7
	s_movk_i32 s12, 0x600
	v_add_u32_e32 v3, v11, v13
	v_or3_b32 v5, v7, v6, v5
	v_mul_lo_u32 v4, v4, s12
	s_waitcnt vmcnt(1)
	v_add_lshl_u32 v130, v3, v4, 1
	v_mul_u32_u24_e32 v4, 0x600, v5
	v_add_u32_e32 v2, 0x2000, v2
	v_add_lshl_u32 v180, v4, v3, 1
	v_ashrrev_i32_e32 v3, 31, v2
	v_lshrrev_b32_e32 v3, 22, v3
	v_add_u32_e32 v3, v2, v3
	v_ashrrev_i32_e32 v14, 10, v3
	v_mul_i32_i24_e32 v3, 0x400, v14
	v_sub_u32_e32 v2, v2, v3
	v_lshrrev_b32_e32 v3, 4, v2
	v_bitop3_b32 v2, v3, v2, 32 bitop3:0x6c
	v_ashrrev_i32_e32 v4, 31, v2
	v_lshrrev_b32_e32 v4, 26, v4
	s_add_u32 s8, s22, s8
	v_lshlrev_b32_e32 v3, 3, v14
	v_add_u32_e32 v4, v2, v4
	s_addc_u32 s9, s23, s9
	v_and_b32_e32 v3, -16, v3
	v_ashrrev_i32_e32 v17, 6, v4
	s_add_u32 s8, s8, 0x4d00000
	v_add_u32_e32 v3, v17, v3
	v_lshlrev_b32_e32 v5, 5, v14
	v_and_b32_e32 v4, 0xc0, v4
	v_and_b32_e32 v6, 3, v17
	s_addc_u32 s9, s9, 0
	v_and_b32_e32 v16, 32, v5
	v_sub_u32_e32 v2, v2, v4
	v_lshlrev_b32_e32 v4, 1, v3
	v_lshrrev_b32_e32 v5, 2, v3
	v_and_or_b32 v6, v3, s21, v6
	v_mul_lo_u32 v3, v3, s12
	s_add_i32 s12, s14, s15
	s_mul_hi_i32 s14, s12, 0x2aaaaaab
	s_lshr_b32 s15, s14, 31
	s_ashr_i32 s14, s14, 3
	v_ashrrev_i16_sdwa v2, v224, sext(v2) dst_sel:DWORD dst_unused:UNUSED_PAD src0_sel:DWORD src1_sel:BYTE_0
	s_add_i32 s14, s14, s15
	v_bfe_i32 v18, v2, 0, 16
	v_and_b32_e32 v4, 24, v4
	v_and_b32_e32 v5, 4, v5
	s_lshl_b32 s27, s14, 3
	v_add_u32_e32 v2, v16, v18
	v_or3_b32 v4, v6, v5, v4
	s_sub_i32 s15, 33, s27
	s_waitcnt vmcnt(0)
	v_add_lshl_u32 v132, v2, v3, 1
	v_mul_u32_u24_e32 v3, 0x600, v4
	s_min_u32 s28, s15, 8
	s_mul_i32 s14, s14, 48
	v_add_lshl_u32 v134, v3, v2, 1
	s_sub_i32 s29, s12, s14
	v_cvt_f32_ubyte0_e32 v3, s28
	v_cvt_f32_i32_e32 v2, s29
	v_rcp_iflag_f32_e32 v4, v3
	s_ashr_i32 s26, s24, 6
	s_ashr_i32 s12, s29, 30
	s_ashr_i32 s25, s24, 8
	v_mul_f32_e32 v4, v2, v4
	v_trunc_f32_e32 v4, v4
	v_fma_f32 v2, -v4, v3, v2
	v_cvt_i32_f32_e32 v4, v4
	s_lshl_b32 s21, s26, 10
	s_or_b32 s12, s12, 1
	v_cmp_ge_f32_e64 s[14:15], |v2|, v3
	s_and_b64 s[14:15], s[14:15], exec
	s_cselect_b32 s12, s12, 0
	v_readfirstlane_b32 s14, v4
	s_add_i32 s12, s14, s12
	s_mul_i32 s14, s12, s28
	s_sub_i32 s14, s29, s14
	s_sext_i32_i8 s14, s14
	s_add_i32 s56, s27, s14
	s_bfe_i64 s[14:15], s[12:13], 0x80000
	s_mul_hi_i32 s15, s14, 0xc0000
	s_mul_i32 s14, s14, 0xc0000
	s_add_u32 s34, s8, s14
	s_addc_u32 s35, s9, s15
	s_add_i32 s44, s21, 0
	s_add_i32 m0, s44, 0x10000
	s_mul_i32 s28, s56, 0xc0000
	global_load_lds_dwordx4 v180, s[34:35]
	s_add_i32 m0, s44, 0x12000
	s_add_u32 s14, s34, 0x60000
	global_load_lds_dwordx4 v134, s[34:35]
	s_addc_u32 s15, s35, 0
	s_add_i32 m0, s44, 0x14000
	s_mul_hi_i32 s27, s56, 0xc0000
	global_load_lds_dwordx4 v180, s[14:15]
	s_add_i32 m0, s44, 0x16000
	s_add_u32 s30, s10, s28
	s_addc_u32 s31, s11, s27
	s_add_i32 s45, s44, 0x2000
	global_load_lds_dwordx4 v134, s[14:15]
	s_mov_b32 m0, s44
	s_add_u32 s14, s30, 0x60000
	global_load_lds_dwordx4 v130, s[30:31]
	s_mov_b32 m0, s45
	s_addc_u32 s15, s31, 0
	s_add_i32 s46, s44, 0x4000
	global_load_lds_dwordx4 v132, s[30:31]
	s_mov_b32 m0, s46
	s_add_i32 s47, s44, 0x6000
	global_load_lds_dwordx4 v130, s[14:15]
	s_mov_b32 m0, s47
	v_mov_b32_e32 v135, v181
	global_load_lds_dwordx4 v132, s[14:15]
	v_mov_b32_e32 v131, v181
	v_mov_b32_e32 v133, v181
	s_cmp_eq_u32 s25, 1
	v_lshl_add_u64 v[8:9], s[34:35], 0, v[180:181]
	v_lshl_add_u64 v[6:7], s[34:35], 0, v[134:135]
	v_lshl_add_u64 v[2:3], s[30:31], 0, v[130:131]
	s_cselect_b64 s[14:15], -1, 0
	s_cmp_lg_u32 s25, 1
	v_lshl_add_u64 v[4:5], s[30:31], 0, v[132:133]
	s_cbranch_scc0 .LBB0_923
	s_barrier

.LBB0_937:
	s_add_u32 s34, s30, 0x100
	s_addc_u32 s35, s31, 0
	s_add_i32 s61, 0, 0x10000
	s_cmp_eq_u32 s60, 20
	s_cselect_b32 s43, s27, s35
	s_cselect_b32 s42, s26, s34
	s_cselect_b32 s41, s29, s59
	s_cselect_b32 s40, s28, s58
	s_add_i32 s62, 0, 0x14000
	v_add_u32_e32 v156, s61, v150
	v_add_u32_e32 v172, s62, v150
	ds_read_b128 v[140:143], v156
	ds_read_b128 v[144:147], v156 offset:1024
	ds_read_b128 v[152:155], v156 offset:2048
	ds_read_b128 v[156:159], v156 offset:3072
	ds_read_b128 v[160:163], v172
	ds_read_b128 v[164:167], v172 offset:1024
	ds_read_b128 v[168:171], v172 offset:2048
	ds_read_b128 v[172:175], v172 offset:3072
	v_lshl_add_u64 v[218:219], s[30:31], 0, v[136:137]
	s_add_i32 m0, s44, 0xc000
	ds_read_b128 v[176:179], v151
	ds_read_b128 v[190:193], v151 offset:1024
	ds_read_b128 v[194:197], v151 offset:2048
	ds_read_b128 v[198:201], v151 offset:3072
	ds_read_b128 v[202:205], v151 offset:4096
	ds_read_b128 v[206:209], v151 offset:5120
	ds_read_b128 v[210:213], v151 offset:6144
	ds_read_b128 v[214:217], v151 offset:7168
	global_load_lds_dwordx4 v[218:219], off
	v_lshl_add_u64 v[218:219], s[30:31], 0, v[138:139]
	s_add_i32 m0, s44, 0xe000
	s_nop 0
	global_load_lds_dwordx4 v[218:219], off
	s_waitcnt vmcnt(8)
	s_waitcnt lgkmcnt(0)
	s_barrier
	s_setprio 1
	s_waitcnt lgkmcnt(0)
	v_mfma_f32_16x16x32_bf16 v[126:129], v[140:143], v[176:179], v[126:129]
	v_mfma_f32_16x16x32_bf16 v[122:125], v[152:155], v[176:179], v[122:125]
	v_mfma_f32_16x16x32_bf16 v[110:113], v[140:143], v[194:197], v[110:113]
	v_mfma_f32_16x16x32_bf16 v[106:109], v[152:155], v[194:197], v[106:109]
	v_mfma_f32_16x16x32_bf16 v[94:97], v[140:143], v[202:205], v[94:97]
	v_mfma_f32_16x16x32_bf16 v[90:93], v[152:155], v[202:205], v[90:93]
	v_mfma_f32_16x16x32_bf16 v[78:81], v[140:143], v[210:213], v[78:81]
	v_mfma_f32_16x16x32_bf16 v[74:77], v[152:155], v[210:213], v[74:77]
	v_mfma_f32_16x16x32_bf16 v[126:129], v[144:147], v[190:193], v[126:129]
	v_mfma_f32_16x16x32_bf16 v[122:125], v[156:159], v[190:193], v[122:125]
	v_mfma_f32_16x16x32_bf16 v[110:113], v[144:147], v[198:201], v[110:113]
	v_mfma_f32_16x16x32_bf16 v[106:109], v[156:159], v[198:201], v[106:109]
	v_mfma_f32_16x16x32_bf16 v[94:97], v[144:147], v[206:209], v[94:97]
	v_mfma_f32_16x16x32_bf16 v[90:93], v[156:159], v[206:209], v[90:93]
	v_mfma_f32_16x16x32_bf16 v[78:81], v[144:147], v[214:217], v[78:81]
	v_mfma_f32_16x16x32_bf16 v[74:77], v[156:159], v[214:217], v[74:77]
	v_mfma_f32_16x16x32_bf16 v[118:121], v[160:163], v[176:179], v[118:121]
	v_mfma_f32_16x16x32_bf16 v[114:117], v[168:171], v[176:179], v[114:117]
	v_mfma_f32_16x16x32_bf16 v[102:105], v[160:163], v[194:197], v[102:105]
	v_mfma_f32_16x16x32_bf16 v[98:101], v[168:171], v[194:197], v[98:101]
	v_mfma_f32_16x16x32_bf16 v[86:89], v[160:163], v[202:205], v[86:89]
	v_mfma_f32_16x16x32_bf16 v[82:85], v[168:171], v[202:205], v[82:85]
	v_mfma_f32_16x16x32_bf16 v[70:73], v[160:163], v[210:213], v[70:73]
	v_mfma_f32_16x16x32_bf16 v[66:69], v[168:171], v[210:213], v[66:69]
	v_mfma_f32_16x16x32_bf16 v[118:121], v[164:167], v[190:193], v[118:121]
	v_mfma_f32_16x16x32_bf16 v[114:117], v[172:175], v[190:193], v[114:117]
	v_mfma_f32_16x16x32_bf16 v[102:105], v[164:167], v[198:201], v[102:105]
	v_mfma_f32_16x16x32_bf16 v[98:101], v[172:175], v[198:201], v[98:101]
	v_mfma_f32_16x16x32_bf16 v[86:89], v[164:167], v[206:209], v[86:89]
	v_mfma_f32_16x16x32_bf16 v[82:85], v[172:175], v[206:209], v[82:85]
	v_mfma_f32_16x16x32_bf16 v[70:73], v[164:167], v[214:217], v[70:73]
	v_mfma_f32_16x16x32_bf16 v[66:69], v[172:175], v[214:217], v[66:69]
	s_setprio 0
	s_barrier
	s_add_i32 s30, s61, s21
	v_lshl_add_u64 v[218:219], s[40:41], 0, v[180:181]
	s_mov_b32 m0, s30
	ds_read_b128 v[176:179], v151 offset:16384
	ds_read_b128 v[190:193], v151 offset:17408
	ds_read_b128 v[194:197], v151 offset:18432
	ds_read_b128 v[198:201], v151 offset:19456
	ds_read_b128 v[202:205], v151 offset:20480
	ds_read_b128 v[206:209], v151 offset:21504
	ds_read_b128 v[210:213], v151 offset:22528
	ds_read_b128 v[214:217], v151 offset:23552
	global_load_lds_dwordx4 v[218:219], off
	s_add_i32 m0, s30, 0x2000
	s_add_u32 s30, s40, 0x60000
	v_lshl_add_u64 v[220:221], s[40:41], 0, v[134:135]
	s_addc_u32 s31, s41, 0
	s_add_i32 s61, s62, s21
	global_load_lds_dwordx4 v[220:221], off
	v_lshl_add_u64 v[222:223], s[30:31], 0, v[180:181]
	s_mov_b32 m0, s61
	v_lshl_add_u64 v[238:239], s[42:43], 0, v[132:133]
	global_load_lds_dwordx4 v[222:223], off
	v_lshl_add_u64 v[222:223], s[30:31], 0, v[134:135]
	s_add_i32 m0, s61, 0x2000
	s_nop 0
	global_load_lds_dwordx4 v[222:223], off
	v_lshl_add_u64 v[222:223], s[42:43], 0, v[130:131]
	s_mov_b32 m0, s44
	s_nop 0
	global_load_lds_dwordx4 v[222:223], off
	s_mov_b32 m0, s45
	s_nop 0
	global_load_lds_dwordx4 v[238:239], off
	s_waitcnt vmcnt(8)
	s_waitcnt lgkmcnt(0)
	s_barrier
	s_setprio 1
	s_waitcnt lgkmcnt(0)
	v_mfma_f32_16x16x32_bf16 v[62:65], v[140:143], v[176:179], v[62:65]
	v_mfma_f32_16x16x32_bf16 v[58:61], v[152:155], v[176:179], v[58:61]
	v_mfma_f32_16x16x32_bf16 v[46:49], v[140:143], v[194:197], v[46:49]
	v_mfma_f32_16x16x32_bf16 v[42:45], v[152:155], v[194:197], v[42:45]
	v_mfma_f32_16x16x32_bf16 v[30:33], v[140:143], v[202:205], v[30:33]
	v_mfma_f32_16x16x32_bf16 v[26:29], v[152:155], v[202:205], v[26:29]
	v_mfma_f32_16x16x32_bf16 v[14:17], v[140:143], v[210:213], v[14:17]
	v_mfma_f32_16x16x32_bf16 v[10:13], v[152:155], v[210:213], v[10:13]
	v_mfma_f32_16x16x32_bf16 v[62:65], v[144:147], v[190:193], v[62:65]
	v_mfma_f32_16x16x32_bf16 v[58:61], v[156:159], v[190:193], v[58:61]
	v_mfma_f32_16x16x32_bf16 v[46:49], v[144:147], v[198:201], v[46:49]
	v_mfma_f32_16x16x32_bf16 v[42:45], v[156:159], v[198:201], v[42:45]
	v_mfma_f32_16x16x32_bf16 v[30:33], v[144:147], v[206:209], v[30:33]
	v_mfma_f32_16x16x32_bf16 v[26:29], v[156:159], v[206:209], v[26:29]
	v_mfma_f32_16x16x32_bf16 v[14:17], v[144:147], v[214:217], v[14:17]
	v_mfma_f32_16x16x32_bf16 v[10:13], v[156:159], v[214:217], v[10:13]
	v_mfma_f32_16x16x32_bf16 v[54:57], v[160:163], v[176:179], v[54:57]
	v_mfma_f32_16x16x32_bf16 v[50:53], v[168:171], v[176:179], v[50:53]
	v_mfma_f32_16x16x32_bf16 v[38:41], v[160:163], v[194:197], v[38:41]
	v_mfma_f32_16x16x32_bf16 v[34:37], v[168:171], v[194:197], v[34:37]
	v_mfma_f32_16x16x32_bf16 v[22:25], v[160:163], v[202:205], v[22:25]
	v_mfma_f32_16x16x32_bf16 v[18:21], v[168:171], v[202:205], v[18:21]
	v_mfma_f32_16x16x32_bf16 v[6:9], v[160:163], v[210:213], v[6:9]
	v_mfma_f32_16x16x32_bf16 v[2:5], v[168:171], v[210:213], v[2:5]
	v_mfma_f32_16x16x32_bf16 v[54:57], v[164:167], v[190:193], v[54:57]
	v_mfma_f32_16x16x32_bf16 v[50:53], v[172:175], v[190:193], v[50:53]
	v_mfma_f32_16x16x32_bf16 v[38:41], v[164:167], v[198:201], v[38:41]
	v_mfma_f32_16x16x32_bf16 v[34:37], v[172:175], v[198:201], v[34:37]
	v_mfma_f32_16x16x32_bf16 v[22:25], v[164:167], v[206:209], v[22:25]
	v_mfma_f32_16x16x32_bf16 v[18:21], v[172:175], v[206:209], v[18:21]
	v_mfma_f32_16x16x32_bf16 v[6:9], v[164:167], v[214:217], v[6:9]
	v_mfma_f32_16x16x32_bf16 v[2:5], v[172:175], v[214:217], v[2:5]
	s_setprio 0
	s_barrier
	s_add_i32 s61, 0, 0x18000
	s_add_i32 s62, 0, 0x1c000
	v_add_u32_e32 v156, s61, v150
	v_add_u32_e32 v172, s62, v150
	ds_read_b128 v[140:143], v156
	ds_read_b128 v[144:147], v156 offset:1024
	ds_read_b128 v[152:155], v156 offset:2048
	ds_read_b128 v[156:159], v156 offset:3072
	ds_read_b128 v[160:163], v172
	ds_read_b128 v[164:167], v172 offset:1024
	ds_read_b128 v[168:171], v172 offset:2048
	ds_read_b128 v[172:175], v172 offset:3072
	s_add_u32 s30, s42, 0x60000
	s_addc_u32 s31, s43, 0
	s_mov_b32 m0, s46
	v_lshl_add_u64 v[240:241], s[30:31], 0, v[130:131]
	ds_read_b128 v[176:179], v151 offset:32768
	ds_read_b128 v[190:193], v151 offset:33792
	ds_read_b128 v[194:197], v151 offset:34816
	ds_read_b128 v[198:201], v151 offset:35840
	ds_read_b128 v[202:205], v151 offset:36864
	ds_read_b128 v[206:209], v151 offset:37888
	ds_read_b128 v[210:213], v151 offset:38912
	ds_read_b128 v[214:217], v151 offset:39936
	global_load_lds_dwordx4 v[240:241], off
	v_lshl_add_u64 v[240:241], s[30:31], 0, v[132:133]
	s_mov_b32 m0, s47
	s_nop 0
	global_load_lds_dwordx4 v[240:241], off
	s_waitcnt vmcnt(8)
	s_waitcnt lgkmcnt(0)
	s_barrier
	s_setprio 1
	s_waitcnt lgkmcnt(0)
	v_mfma_f32_16x16x32_bf16 v[126:129], v[140:143], v[176:179], v[126:129]
	v_mfma_f32_16x16x32_bf16 v[122:125], v[152:155], v[176:179], v[122:125]
	v_mfma_f32_16x16x32_bf16 v[110:113], v[140:143], v[194:197], v[110:113]
	v_mfma_f32_16x16x32_bf16 v[106:109], v[152:155], v[194:197], v[106:109]
	v_mfma_f32_16x16x32_bf16 v[94:97], v[140:143], v[202:205], v[94:97]
	v_mfma_f32_16x16x32_bf16 v[90:93], v[152:155], v[202:205], v[90:93]
	v_mfma_f32_16x16x32_bf16 v[78:81], v[140:143], v[210:213], v[78:81]
	v_mfma_f32_16x16x32_bf16 v[74:77], v[152:155], v[210:213], v[74:77]
	v_mfma_f32_16x16x32_bf16 v[126:129], v[144:147], v[190:193], v[126:129]
	v_mfma_f32_16x16x32_bf16 v[122:125], v[156:159], v[190:193], v[122:125]
	v_mfma_f32_16x16x32_bf16 v[110:113], v[144:147], v[198:201], v[110:113]
	v_mfma_f32_16x16x32_bf16 v[106:109], v[156:159], v[198:201], v[106:109]
	v_mfma_f32_16x16x32_bf16 v[94:97], v[144:147], v[206:209], v[94:97]
	v_mfma_f32_16x16x32_bf16 v[90:93], v[156:159], v[206:209], v[90:93]
	v_mfma_f32_16x16x32_bf16 v[78:81], v[144:147], v[214:217], v[78:81]
	v_mfma_f32_16x16x32_bf16 v[74:77], v[156:159], v[214:217], v[74:77]
	v_mfma_f32_16x16x32_bf16 v[118:121], v[160:163], v[176:179], v[118:121]
	v_mfma_f32_16x16x32_bf16 v[114:117], v[168:171], v[176:179], v[114:117]
	v_mfma_f32_16x16x32_bf16 v[102:105], v[160:163], v[194:197], v[102:105]
	v_mfma_f32_16x16x32_bf16 v[98:101], v[168:171], v[194:197], v[98:101]
	v_mfma_f32_16x16x32_bf16 v[86:89], v[160:163], v[202:205], v[86:89]
	v_mfma_f32_16x16x32_bf16 v[82:85], v[168:171], v[202:205], v[82:85]
	v_mfma_f32_16x16x32_bf16 v[70:73], v[160:163], v[210:213], v[70:73]
	v_mfma_f32_16x16x32_bf16 v[66:69], v[168:171], v[210:213], v[66:69]
	v_mfma_f32_16x16x32_bf16 v[118:121], v[164:167], v[190:193], v[118:121]
	v_mfma_f32_16x16x32_bf16 v[114:117], v[172:175], v[190:193], v[114:117]
	v_mfma_f32_16x16x32_bf16 v[102:105], v[164:167], v[198:201], v[102:105]
	v_mfma_f32_16x16x32_bf16 v[98:101], v[172:175], v[198:201], v[98:101]
	v_mfma_f32_16x16x32_bf16 v[86:89], v[164:167], v[206:209], v[86:89]
	v_mfma_f32_16x16x32_bf16 v[82:85], v[172:175], v[206:209], v[82:85]
	v_mfma_f32_16x16x32_bf16 v[70:73], v[164:167], v[214:217], v[70:73]
	v_mfma_f32_16x16x32_bf16 v[66:69], v[172:175], v[214:217], v[66:69]
	s_setprio 0
	s_barrier
	s_add_i32 s30, s61, s21
	v_lshl_add_u64 v[218:219], v[218:219], 0, s[16:17]
	s_mov_b32 m0, s30
	ds_read_b128 v[176:179], v151 offset:49152
	ds_read_b128 v[190:193], v151 offset:50176
	ds_read_b128 v[194:197], v151 offset:51200
	ds_read_b128 v[198:201], v151 offset:52224
	ds_read_b128 v[202:205], v151 offset:53248
	ds_read_b128 v[206:209], v151 offset:54272
	ds_read_b128 v[210:213], v151 offset:55296
	ds_read_b128 v[214:217], v151 offset:56320
	global_load_lds_dwordx4 v[218:219], off
	s_add_i32 m0, s30, 0x2000
	s_add_u32 s30, s40, 0x60080
	v_lshl_add_u64 v[218:219], v[220:221], 0, s[16:17]
	s_addc_u32 s31, s41, 0
	s_add_i32 s40, s62, s21
	global_load_lds_dwordx4 v[218:219], off
	v_lshl_add_u64 v[218:219], s[30:31], 0, v[180:181]
	s_mov_b32 m0, s40
	s_nop 0
	global_load_lds_dwordx4 v[218:219], off
	v_lshl_add_u64 v[218:219], s[30:31], 0, v[134:135]
	s_add_i32 m0, s40, 0x2000
	s_nop 0
	global_load_lds_dwordx4 v[218:219], off
	v_lshl_add_u64 v[218:219], v[222:223], 0, s[16:17]
	s_mov_b32 m0, s49
	s_nop 0
	global_load_lds_dwordx4 v[218:219], off
	v_lshl_add_u64 v[218:219], v[238:239], 0, s[16:17]
	s_mov_b32 m0, s50
	s_nop 0
	global_load_lds_dwordx4 v[218:219], off
	s_waitcnt vmcnt(8)
	s_waitcnt lgkmcnt(0)
	s_barrier
	s_setprio 1
	s_waitcnt lgkmcnt(0)
	v_mfma_f32_16x16x32_bf16 v[62:65], v[140:143], v[176:179], v[62:65]
	v_mfma_f32_16x16x32_bf16 v[58:61], v[152:155], v[176:179], v[58:61]
	v_mfma_f32_16x16x32_bf16 v[46:49], v[140:143], v[194:197], v[46:49]
	v_mfma_f32_16x16x32_bf16 v[42:45], v[152:155], v[194:197], v[42:45]
	v_mfma_f32_16x16x32_bf16 v[30:33], v[140:143], v[202:205], v[30:33]
	v_mfma_f32_16x16x32_bf16 v[26:29], v[152:155], v[202:205], v[26:29]
	v_mfma_f32_16x16x32_bf16 v[14:17], v[140:143], v[210:213], v[14:17]
	v_mfma_f32_16x16x32_bf16 v[10:13], v[152:155], v[210:213], v[10:13]
	v_mfma_f32_16x16x32_bf16 v[62:65], v[144:147], v[190:193], v[62:65]
	v_mfma_f32_16x16x32_bf16 v[58:61], v[156:159], v[190:193], v[58:61]
	v_mfma_f32_16x16x32_bf16 v[46:49], v[144:147], v[198:201], v[46:49]
	v_mfma_f32_16x16x32_bf16 v[42:45], v[156:159], v[198:201], v[42:45]
	v_mfma_f32_16x16x32_bf16 v[30:33], v[144:147], v[206:209], v[30:33]
	v_mfma_f32_16x16x32_bf16 v[26:29], v[156:159], v[206:209], v[26:29]
	v_mfma_f32_16x16x32_bf16 v[14:17], v[144:147], v[214:217], v[14:17]
	v_mfma_f32_16x16x32_bf16 v[10:13], v[156:159], v[214:217], v[10:13]
	v_mfma_f32_16x16x32_bf16 v[54:57], v[160:163], v[176:179], v[54:57]
	v_mfma_f32_16x16x32_bf16 v[50:53], v[168:171], v[176:179], v[50:53]
	v_mfma_f32_16x16x32_bf16 v[38:41], v[160:163], v[194:197], v[38:41]
	v_mfma_f32_16x16x32_bf16 v[34:37], v[168:171], v[194:197], v[34:37]
	v_mfma_f32_16x16x32_bf16 v[22:25], v[160:163], v[202:205], v[22:25]
	v_mfma_f32_16x16x32_bf16 v[18:21], v[168:171], v[202:205], v[18:21]
	v_mfma_f32_16x16x32_bf16 v[6:9], v[160:163], v[210:213], v[6:9]
	v_mfma_f32_16x16x32_bf16 v[2:5], v[168:171], v[210:213], v[2:5]
	v_mfma_f32_16x16x32_bf16 v[54:57], v[164:167], v[190:193], v[54:57]
	v_mfma_f32_16x16x32_bf16 v[50:53], v[172:175], v[190:193], v[50:53]
	v_mfma_f32_16x16x32_bf16 v[38:41], v[164:167], v[198:201], v[38:41]
	v_mfma_f32_16x16x32_bf16 v[34:37], v[172:175], v[198:201], v[34:37]
	v_mfma_f32_16x16x32_bf16 v[22:25], v[164:167], v[206:209], v[22:25]
	v_mfma_f32_16x16x32_bf16 v[18:21], v[172:175], v[206:209], v[18:21]
	v_mfma_f32_16x16x32_bf16 v[6:9], v[164:167], v[214:217], v[6:9]
	v_mfma_f32_16x16x32_bf16 v[2:5], v[172:175], v[214:217], v[2:5]
	s_setprio 0
	s_barrier
	s_add_i32 s60, s60, 2
	s_add_u32 s58, s58, 0x100
	s_addc_u32 s59, s59, 0
	s_cmp_gt_u32 s60, 21
	s_mov_b64 s[30:31], s[34:35]
	s_cbranch_scc0 .LBB0_937
	s_and_b64 vcc, exec, s[24:25]
	s_cbranch_vccnz .LBB0_940
	s_barrier
.LBB0_940:
	s_lshl_b32 s30, s56, 8
	v_mov_b32_e32 v140, v148
	v_mov_b32_e32 v141, v149
	s_add_i32 s30, s30, s12
	v_mov_b64_e32 v[144:145], s[10:11]
	v_add_u32_e32 v146, s30, v140
	s_lshl_b32 s30, s57, 8
	s_or_b32 s30, s30, s48
	v_lshl_add_u32 v142, v141, 3, s30
	v_ashrrev_i32_e32 v143, 31, v142
	v_lshl_add_u64 v[140:141], v[142:143], 2, s[18:19]
	global_load_dwordx4 v[152:155], v[140:141], off offset:16
	global_load_dwordx4 v[156:159], v[140:141], off
	v_mad_i64_i32 v[160:161], s[30:31], v146, s80, v[144:145]
	v_lshlrev_b64 v[142:143], 1, v[142:143]
	v_lshl_add_u64 v[164:165], v[160:161], 0, v[142:143]
	global_load_dwordx4 v[160:163], v[164:165], off
	v_ashrrev_i32_e32 v147, 31, v146
	v_lshlrev_b64 v[166:167], 12, v[146:147]
	v_lshl_add_u64 v[166:167], s[22:23], 0, v[166:167]
	v_lshl_add_u64 v[166:167], v[166:167], 0, v[142:143]
	s_and_b64 vcc, exec, s[38:39]
	s_waitcnt vmcnt(0)
	v_pk_add_f32 v[124:125], v[124:125], v[154:155]
	v_pk_add_f32 v[128:129], v[128:129], v[158:159]
	v_pk_add_f32 v[126:127], v[126:127], v[156:157]
	v_pk_add_f32 v[122:123], v[122:123], v[152:153]
	v_mul_f32_e32 v125, 0xbfb8aa3b, v125
	v_mul_f32_e32 v126, 0xbfb8aa3b, v126
	v_mul_f32_e32 v127, 0xbfb8aa3b, v127
	v_mul_f32_e32 v128, 0xbfb8aa3b, v128
	v_mul_f32_e32 v129, 0xbfb8aa3b, v129
	v_mul_f32_e32 v122, 0xbfb8aa3b, v122
	v_mul_f32_e32 v123, 0xbfb8aa3b, v123
	v_mul_f32_e32 v124, 0xbfb8aa3b, v124
	v_exp_f32_e32 v125, v125
	v_exp_f32_e32 v126, v126
	v_exp_f32_e32 v127, v127
	v_exp_f32_e32 v128, v128
	v_exp_f32_e32 v129, v129
	v_exp_f32_e32 v122, v122
	v_exp_f32_e32 v123, v123
	v_exp_f32_e32 v124, v124
	v_add_f32_e32 v125, 1.0, v125
	v_add_f32_e32 v126, 1.0, v126
	v_add_f32_e32 v127, 1.0, v127
	v_add_f32_e32 v128, 1.0, v128
	v_add_f32_e32 v129, 1.0, v129
	v_add_f32_e32 v122, 1.0, v122
	v_add_f32_e32 v123, 1.0, v123
	v_add_f32_e32 v124, 1.0, v124
	v_rcp_f32_e32 v125, v125
	v_rcp_f32_e32 v126, v126
	v_rcp_f32_e32 v127, v127
	v_rcp_f32_e32 v128, v128
	v_rcp_f32_e32 v129, v129
	v_rcp_f32_e32 v122, v122
	v_rcp_f32_e32 v123, v123
	v_rcp_f32_e32 v124, v124
	v_and_b32_e32 v158, 0xffff0000, v163
	v_lshlrev_b32_e32 v147, 16, v160
	v_and_b32_e32 v152, 0xffff0000, v160
	v_lshlrev_b32_e32 v153, 16, v161
	v_and_b32_e32 v154, 0xffff0000, v161
	v_lshlrev_b32_e32 v155, 16, v162
	v_and_b32_e32 v156, 0xffff0000, v162
	v_lshlrev_b32_e32 v157, 16, v163
	v_mul_f32_e32 v125, v125, v158
	v_mul_f32_e32 v126, v126, v147
	v_mul_f32_e32 v127, v127, v152
	v_mul_f32_e32 v128, v128, v153
	v_mul_f32_e32 v129, v129, v154
	v_mul_f32_e32 v147, v122, v155
	v_mul_f32_e32 v152, v123, v156
	v_mul_f32_e32 v153, v124, v157
	v_cvt_pk_bf16_f32 v122, v126, v127
	v_cvt_pk_bf16_f32 v123, v128, v129
	v_cvt_pk_bf16_f32 v124, v147, v152
	v_cvt_pk_bf16_f32 v125, v153, v125
	global_store_dwordx4 v[166:167], v[122:125], off
	global_load_dwordx4 v[122:125], v[140:141], off offset:512
	global_load_dwordx4 v[126:129], v[140:141], off offset:528
	global_load_dwordx4 v[152:155], v[164:165], off offset:256
	v_add_u32_e32 v156, 16, v146
	v_ashrrev_i32_e32 v157, 31, v156
	s_waitcnt vmcnt(2)
	v_pk_add_f32 v[120:121], v[120:121], v[124:125]
	s_waitcnt vmcnt(1)
	v_pk_add_f32 v[116:117], v[116:117], v[128:129]
	v_pk_add_f32 v[118:119], v[118:119], v[122:123]
	v_pk_add_f32 v[114:115], v[114:115], v[126:127]
	v_mul_f32_e32 v117, 0xbfb8aa3b, v117
	v_mul_f32_e32 v118, 0xbfb8aa3b, v118
	v_mul_f32_e32 v119, 0xbfb8aa3b, v119
	v_mul_f32_e32 v120, 0xbfb8aa3b, v120
	v_mul_f32_e32 v121, 0xbfb8aa3b, v121
	v_mul_f32_e32 v114, 0xbfb8aa3b, v114
	v_mul_f32_e32 v115, 0xbfb8aa3b, v115
	v_mul_f32_e32 v116, 0xbfb8aa3b, v116
	v_exp_f32_e32 v117, v117
	v_exp_f32_e32 v118, v118
	v_exp_f32_e32 v119, v119
	v_exp_f32_e32 v120, v120
	v_exp_f32_e32 v121, v121
	v_exp_f32_e32 v114, v114
	v_exp_f32_e32 v115, v115
	v_exp_f32_e32 v116, v116
	v_add_f32_e32 v117, 1.0, v117
	v_add_f32_e32 v118, 1.0, v118
	v_add_f32_e32 v119, 1.0, v119
	v_add_f32_e32 v120, 1.0, v120
	v_add_f32_e32 v121, 1.0, v121
	v_add_f32_e32 v114, 1.0, v114
	v_add_f32_e32 v115, 1.0, v115
	v_add_f32_e32 v116, 1.0, v116
	v_rcp_f32_e32 v117, v117
	v_rcp_f32_e32 v118, v118
	v_rcp_f32_e32 v119, v119
	v_rcp_f32_e32 v120, v120
	v_rcp_f32_e32 v121, v121
	v_rcp_f32_e32 v114, v114
	v_rcp_f32_e32 v115, v115
	v_rcp_f32_e32 v116, v116
	s_waitcnt vmcnt(0)
	v_and_b32_e32 v129, 0xffff0000, v155
	v_lshlrev_b32_e32 v122, 16, v152
	v_and_b32_e32 v123, 0xffff0000, v152
	v_lshlrev_b32_e32 v124, 16, v153
	v_and_b32_e32 v125, 0xffff0000, v153
	v_lshlrev_b32_e32 v126, 16, v154
	v_and_b32_e32 v127, 0xffff0000, v154
	v_lshlrev_b32_e32 v128, 16, v155
	v_mul_f32_e32 v117, v117, v129
	v_mul_f32_e32 v118, v118, v122
	v_mul_f32_e32 v119, v119, v123
	v_mul_f32_e32 v120, v120, v124
	v_mul_f32_e32 v121, v121, v125
	v_mul_f32_e32 v122, v114, v126
	v_mul_f32_e32 v123, v115, v127
	v_mul_f32_e32 v124, v116, v128
	v_cvt_pk_bf16_f32 v114, v118, v119
	v_cvt_pk_bf16_f32 v115, v120, v121
	v_cvt_pk_bf16_f32 v116, v122, v123
	v_cvt_pk_bf16_f32 v117, v124, v117
	global_store_dwordx4 v[166:167], v[114:117], off offset:256
	global_load_dwordx4 v[114:117], v[140:141], off offset:16
	global_load_dwordx4 v[118:121], v[140:141], off
	v_mad_i64_i32 v[122:123], s[30:31], v156, s80, v[144:145]
	v_lshl_add_u64 v[126:127], v[122:123], 0, v[142:143]
	global_load_dwordx4 v[122:125], v[126:127], off
	v_lshlrev_b64 v[128:129], 12, v[156:157]
	v_lshl_add_u64 v[128:129], s[22:23], 0, v[128:129]
	v_lshl_add_u64 v[128:129], v[128:129], 0, v[142:143]
	s_waitcnt vmcnt(2)
	v_pk_add_f32 v[108:109], v[108:109], v[116:117]
	s_waitcnt vmcnt(1)
	v_pk_add_f32 v[112:113], v[112:113], v[120:121]
	v_pk_add_f32 v[110:111], v[110:111], v[118:119]
	v_pk_add_f32 v[106:107], v[106:107], v[114:115]
	v_mul_f32_e32 v109, 0xbfb8aa3b, v109
	v_mul_f32_e32 v110, 0xbfb8aa3b, v110
	v_mul_f32_e32 v111, 0xbfb8aa3b, v111
	v_mul_f32_e32 v112, 0xbfb8aa3b, v112
	v_mul_f32_e32 v113, 0xbfb8aa3b, v113
	v_mul_f32_e32 v106, 0xbfb8aa3b, v106
	v_mul_f32_e32 v107, 0xbfb8aa3b, v107
	v_mul_f32_e32 v108, 0xbfb8aa3b, v108
	v_exp_f32_e32 v109, v109
	v_exp_f32_e32 v110, v110
	v_exp_f32_e32 v111, v111
	v_exp_f32_e32 v112, v112
	v_exp_f32_e32 v113, v113
	v_exp_f32_e32 v106, v106
	v_exp_f32_e32 v107, v107
	v_exp_f32_e32 v108, v108
	v_add_f32_e32 v109, 1.0, v109
	v_add_f32_e32 v110, 1.0, v110
	v_add_f32_e32 v111, 1.0, v111
	v_add_f32_e32 v112, 1.0, v112
	v_add_f32_e32 v113, 1.0, v113
	v_add_f32_e32 v106, 1.0, v106
	v_add_f32_e32 v107, 1.0, v107
	v_add_f32_e32 v108, 1.0, v108
	v_rcp_f32_e32 v109, v109
	v_rcp_f32_e32 v110, v110
	v_rcp_f32_e32 v111, v111
	v_rcp_f32_e32 v112, v112
	v_rcp_f32_e32 v113, v113
	v_rcp_f32_e32 v106, v106
	v_rcp_f32_e32 v107, v107
	v_rcp_f32_e32 v108, v108
	s_waitcnt vmcnt(0)
	v_and_b32_e32 v121, 0xffff0000, v125
	v_lshlrev_b32_e32 v114, 16, v122
	v_and_b32_e32 v115, 0xffff0000, v122
	v_lshlrev_b32_e32 v116, 16, v123
	v_and_b32_e32 v117, 0xffff0000, v123
	v_lshlrev_b32_e32 v118, 16, v124
	v_and_b32_e32 v119, 0xffff0000, v124
	v_lshlrev_b32_e32 v120, 16, v125
	v_mul_f32_e32 v109, v109, v121
	v_mul_f32_e32 v110, v110, v114
	v_mul_f32_e32 v111, v111, v115
	v_mul_f32_e32 v112, v112, v116
	v_mul_f32_e32 v113, v113, v117
	v_mul_f32_e32 v114, v106, v118
	v_mul_f32_e32 v115, v107, v119
	v_mul_f32_e32 v116, v108, v120
	v_cvt_pk_bf16_f32 v106, v110, v111
	v_cvt_pk_bf16_f32 v107, v112, v113
	v_cvt_pk_bf16_f32 v108, v114, v115
	v_cvt_pk_bf16_f32 v109, v116, v109
	global_store_dwordx4 v[128:129], v[106:109], off
	global_load_dwordx4 v[106:109], v[140:141], off offset:512
	global_load_dwordx4 v[110:113], v[140:141], off offset:528
	global_load_dwordx4 v[114:117], v[126:127], off offset:256
	v_add_u32_e32 v118, 32, v146
	v_ashrrev_i32_e32 v119, 31, v118
	s_waitcnt vmcnt(2)
	v_pk_add_f32 v[104:105], v[104:105], v[108:109]
	s_waitcnt vmcnt(1)
	v_pk_add_f32 v[100:101], v[100:101], v[112:113]
	v_pk_add_f32 v[102:103], v[102:103], v[106:107]
	v_pk_add_f32 v[98:99], v[98:99], v[110:111]
	v_mul_f32_e32 v101, 0xbfb8aa3b, v101
	v_mul_f32_e32 v102, 0xbfb8aa3b, v102
	v_mul_f32_e32 v103, 0xbfb8aa3b, v103
	v_mul_f32_e32 v104, 0xbfb8aa3b, v104
	v_mul_f32_e32 v105, 0xbfb8aa3b, v105
	v_mul_f32_e32 v98, 0xbfb8aa3b, v98
	v_mul_f32_e32 v99, 0xbfb8aa3b, v99
	v_mul_f32_e32 v100, 0xbfb8aa3b, v100
	v_exp_f32_e32 v101, v101
	v_exp_f32_e32 v102, v102
	v_exp_f32_e32 v103, v103
	v_exp_f32_e32 v104, v104
	v_exp_f32_e32 v105, v105
	v_exp_f32_e32 v98, v98
	v_exp_f32_e32 v99, v99
	v_exp_f32_e32 v100, v100
	v_add_f32_e32 v101, 1.0, v101
	v_add_f32_e32 v102, 1.0, v102
	v_add_f32_e32 v103, 1.0, v103
	v_add_f32_e32 v104, 1.0, v104
	v_add_f32_e32 v105, 1.0, v105
	v_add_f32_e32 v98, 1.0, v98
	v_add_f32_e32 v99, 1.0, v99
	v_add_f32_e32 v100, 1.0, v100
	v_rcp_f32_e32 v101, v101
	v_rcp_f32_e32 v102, v102
	v_rcp_f32_e32 v103, v103
	v_rcp_f32_e32 v104, v104
	v_rcp_f32_e32 v105, v105
	v_rcp_f32_e32 v98, v98
	v_rcp_f32_e32 v99, v99
	v_rcp_f32_e32 v100, v100
	s_waitcnt vmcnt(0)
	v_and_b32_e32 v113, 0xffff0000, v117
	v_lshlrev_b32_e32 v106, 16, v114
	v_and_b32_e32 v107, 0xffff0000, v114
	v_lshlrev_b32_e32 v108, 16, v115
	v_and_b32_e32 v109, 0xffff0000, v115
	v_lshlrev_b32_e32 v110, 16, v116
	v_and_b32_e32 v111, 0xffff0000, v116
	v_lshlrev_b32_e32 v112, 16, v117
	v_mul_f32_e32 v101, v101, v113
	v_mul_f32_e32 v102, v102, v106
	v_mul_f32_e32 v103, v103, v107
	v_mul_f32_e32 v104, v104, v108
	v_mul_f32_e32 v105, v105, v109
	v_mul_f32_e32 v106, v98, v110
	v_mul_f32_e32 v107, v99, v111
	v_mul_f32_e32 v108, v100, v112
	v_cvt_pk_bf16_f32 v98, v102, v103
	v_cvt_pk_bf16_f32 v99, v104, v105
	v_cvt_pk_bf16_f32 v100, v106, v107
	v_cvt_pk_bf16_f32 v101, v108, v101
	global_store_dwordx4 v[128:129], v[98:101], off offset:256
	global_load_dwordx4 v[98:101], v[140:141], off offset:16
	global_load_dwordx4 v[102:105], v[140:141], off
	v_mad_i64_i32 v[106:107], s[30:31], v118, s80, v[144:145]
	v_lshl_add_u64 v[110:111], v[106:107], 0, v[142:143]
	global_load_dwordx4 v[106:109], v[110:111], off
	v_lshlrev_b64 v[112:113], 12, v[118:119]
	v_lshl_add_u64 v[112:113], s[22:23], 0, v[112:113]
	v_lshl_add_u64 v[112:113], v[112:113], 0, v[142:143]
	s_waitcnt vmcnt(2)
	v_pk_add_f32 v[92:93], v[92:93], v[100:101]
	s_waitcnt vmcnt(1)
	v_pk_add_f32 v[96:97], v[96:97], v[104:105]
	v_pk_add_f32 v[94:95], v[94:95], v[102:103]
	v_pk_add_f32 v[90:91], v[90:91], v[98:99]
	v_mul_f32_e32 v93, 0xbfb8aa3b, v93
	v_mul_f32_e32 v94, 0xbfb8aa3b, v94
	v_mul_f32_e32 v95, 0xbfb8aa3b, v95
	v_mul_f32_e32 v96, 0xbfb8aa3b, v96
	v_mul_f32_e32 v97, 0xbfb8aa3b, v97
	v_mul_f32_e32 v90, 0xbfb8aa3b, v90
	v_mul_f32_e32 v91, 0xbfb8aa3b, v91
	v_mul_f32_e32 v92, 0xbfb8aa3b, v92
	v_exp_f32_e32 v93, v93
	v_exp_f32_e32 v94, v94
	v_exp_f32_e32 v95, v95
	v_exp_f32_e32 v96, v96
	v_exp_f32_e32 v97, v97
	v_exp_f32_e32 v90, v90
	v_exp_f32_e32 v91, v91
	v_exp_f32_e32 v92, v92
	v_add_f32_e32 v93, 1.0, v93
	v_add_f32_e32 v94, 1.0, v94
	v_add_f32_e32 v95, 1.0, v95
	v_add_f32_e32 v96, 1.0, v96
	v_add_f32_e32 v97, 1.0, v97
	v_add_f32_e32 v90, 1.0, v90
	v_add_f32_e32 v91, 1.0, v91
	v_add_f32_e32 v92, 1.0, v92
	v_rcp_f32_e32 v93, v93
	v_rcp_f32_e32 v94, v94
	v_rcp_f32_e32 v95, v95
	v_rcp_f32_e32 v96, v96
	v_rcp_f32_e32 v97, v97
	v_rcp_f32_e32 v90, v90
	v_rcp_f32_e32 v91, v91
	v_rcp_f32_e32 v92, v92
	s_waitcnt vmcnt(0)
	v_and_b32_e32 v105, 0xffff0000, v109
	v_lshlrev_b32_e32 v98, 16, v106
	v_and_b32_e32 v99, 0xffff0000, v106
	v_lshlrev_b32_e32 v100, 16, v107
	v_and_b32_e32 v101, 0xffff0000, v107
	v_lshlrev_b32_e32 v102, 16, v108
	v_and_b32_e32 v103, 0xffff0000, v108
	v_lshlrev_b32_e32 v104, 16, v109
	v_mul_f32_e32 v93, v93, v105
	v_mul_f32_e32 v94, v94, v98
	v_mul_f32_e32 v95, v95, v99
	v_mul_f32_e32 v96, v96, v100
	v_mul_f32_e32 v97, v97, v101
	v_mul_f32_e32 v98, v90, v102
	v_mul_f32_e32 v99, v91, v103
	v_mul_f32_e32 v100, v92, v104
	v_cvt_pk_bf16_f32 v90, v94, v95
	v_cvt_pk_bf16_f32 v91, v96, v97
	v_cvt_pk_bf16_f32 v92, v98, v99
	v_cvt_pk_bf16_f32 v93, v100, v93
	global_store_dwordx4 v[112:113], v[90:93], off
	global_load_dwordx4 v[90:93], v[140:141], off offset:512
	global_load_dwordx4 v[94:97], v[140:141], off offset:528
	global_load_dwordx4 v[98:101], v[110:111], off offset:256
	v_add_u32_e32 v102, 48, v146
	v_ashrrev_i32_e32 v103, 31, v102
	s_waitcnt vmcnt(2)
	v_pk_add_f32 v[88:89], v[88:89], v[92:93]
	s_waitcnt vmcnt(1)
	v_pk_add_f32 v[84:85], v[84:85], v[96:97]
	v_pk_add_f32 v[86:87], v[86:87], v[90:91]
	v_pk_add_f32 v[82:83], v[82:83], v[94:95]
	v_mul_f32_e32 v85, 0xbfb8aa3b, v85
	v_mul_f32_e32 v86, 0xbfb8aa3b, v86
	v_mul_f32_e32 v87, 0xbfb8aa3b, v87
	v_mul_f32_e32 v88, 0xbfb8aa3b, v88
	v_mul_f32_e32 v89, 0xbfb8aa3b, v89
	v_mul_f32_e32 v82, 0xbfb8aa3b, v82
	v_mul_f32_e32 v83, 0xbfb8aa3b, v83
	v_mul_f32_e32 v84, 0xbfb8aa3b, v84
	v_exp_f32_e32 v85, v85
	v_exp_f32_e32 v86, v86
	v_exp_f32_e32 v87, v87
	v_exp_f32_e32 v88, v88
	v_exp_f32_e32 v89, v89
	v_exp_f32_e32 v82, v82
	v_exp_f32_e32 v83, v83
	v_exp_f32_e32 v84, v84
	v_add_f32_e32 v85, 1.0, v85
	v_add_f32_e32 v86, 1.0, v86
	v_add_f32_e32 v87, 1.0, v87
	v_add_f32_e32 v88, 1.0, v88
	v_add_f32_e32 v89, 1.0, v89
	v_add_f32_e32 v82, 1.0, v82
	v_add_f32_e32 v83, 1.0, v83
	v_add_f32_e32 v84, 1.0, v84
	v_rcp_f32_e32 v85, v85
	v_rcp_f32_e32 v86, v86
	v_rcp_f32_e32 v87, v87
	v_rcp_f32_e32 v88, v88
	v_rcp_f32_e32 v89, v89
	v_rcp_f32_e32 v82, v82
	v_rcp_f32_e32 v83, v83
	v_rcp_f32_e32 v84, v84
	s_waitcnt vmcnt(0)
	v_and_b32_e32 v97, 0xffff0000, v101
	v_lshlrev_b32_e32 v90, 16, v98
	v_and_b32_e32 v91, 0xffff0000, v98
	v_lshlrev_b32_e32 v92, 16, v99
	v_and_b32_e32 v93, 0xffff0000, v99
	v_lshlrev_b32_e32 v94, 16, v100
	v_and_b32_e32 v95, 0xffff0000, v100
	v_lshlrev_b32_e32 v96, 16, v101
	v_mul_f32_e32 v85, v85, v97
	v_mul_f32_e32 v86, v86, v90
	v_mul_f32_e32 v87, v87, v91
	v_mul_f32_e32 v88, v88, v92
	v_mul_f32_e32 v89, v89, v93
	v_mul_f32_e32 v90, v82, v94
	v_mul_f32_e32 v91, v83, v95
	v_mul_f32_e32 v92, v84, v96
	v_cvt_pk_bf16_f32 v82, v86, v87
	v_cvt_pk_bf16_f32 v83, v88, v89
	v_cvt_pk_bf16_f32 v84, v90, v91
	v_cvt_pk_bf16_f32 v85, v92, v85
	global_store_dwordx4 v[112:113], v[82:85], off offset:256
	global_load_dwordx4 v[82:85], v[140:141], off offset:16
	global_load_dwordx4 v[86:89], v[140:141], off
	v_mad_i64_i32 v[90:91], s[30:31], v102, s80, v[144:145]
	v_lshl_add_u64 v[94:95], v[90:91], 0, v[142:143]
	global_load_dwordx4 v[90:93], v[94:95], off
	v_lshlrev_b64 v[96:97], 12, v[102:103]
	v_lshl_add_u64 v[96:97], s[22:23], 0, v[96:97]
	v_lshl_add_u64 v[96:97], v[96:97], 0, v[142:143]
	s_waitcnt vmcnt(2)
	v_pk_add_f32 v[76:77], v[76:77], v[84:85]
	s_waitcnt vmcnt(1)
	v_pk_add_f32 v[80:81], v[80:81], v[88:89]
	v_pk_add_f32 v[78:79], v[78:79], v[86:87]
	v_pk_add_f32 v[74:75], v[74:75], v[82:83]
	v_mul_f32_e32 v77, 0xbfb8aa3b, v77
	v_mul_f32_e32 v78, 0xbfb8aa3b, v78
	v_mul_f32_e32 v79, 0xbfb8aa3b, v79
	v_mul_f32_e32 v80, 0xbfb8aa3b, v80
	v_mul_f32_e32 v81, 0xbfb8aa3b, v81
	v_mul_f32_e32 v74, 0xbfb8aa3b, v74
	v_mul_f32_e32 v75, 0xbfb8aa3b, v75
	v_mul_f32_e32 v76, 0xbfb8aa3b, v76
	v_exp_f32_e32 v77, v77
	v_exp_f32_e32 v78, v78
	v_exp_f32_e32 v79, v79
	v_exp_f32_e32 v80, v80
	v_exp_f32_e32 v81, v81
	v_exp_f32_e32 v74, v74
	v_exp_f32_e32 v75, v75
	v_exp_f32_e32 v76, v76
	v_add_f32_e32 v77, 1.0, v77
	v_add_f32_e32 v78, 1.0, v78
	v_add_f32_e32 v79, 1.0, v79
	v_add_f32_e32 v80, 1.0, v80
	v_add_f32_e32 v81, 1.0, v81
	v_add_f32_e32 v74, 1.0, v74
	v_add_f32_e32 v75, 1.0, v75
	v_add_f32_e32 v76, 1.0, v76
	v_rcp_f32_e32 v77, v77
	v_rcp_f32_e32 v78, v78
	v_rcp_f32_e32 v79, v79
	v_rcp_f32_e32 v80, v80
	v_rcp_f32_e32 v81, v81
	v_rcp_f32_e32 v74, v74
	v_rcp_f32_e32 v75, v75
	v_rcp_f32_e32 v76, v76
	s_waitcnt vmcnt(0)
	v_and_b32_e32 v89, 0xffff0000, v93
	v_lshlrev_b32_e32 v82, 16, v90
	v_and_b32_e32 v83, 0xffff0000, v90
	v_lshlrev_b32_e32 v84, 16, v91
	v_and_b32_e32 v85, 0xffff0000, v91
	v_lshlrev_b32_e32 v86, 16, v92
	v_and_b32_e32 v87, 0xffff0000, v92
	v_lshlrev_b32_e32 v88, 16, v93
	v_mul_f32_e32 v77, v77, v89
	v_mul_f32_e32 v78, v78, v82
	v_mul_f32_e32 v79, v79, v83
	v_mul_f32_e32 v80, v80, v84
	v_mul_f32_e32 v81, v81, v85
	v_mul_f32_e32 v82, v74, v86
	v_mul_f32_e32 v83, v75, v87
	v_mul_f32_e32 v84, v76, v88
	v_cvt_pk_bf16_f32 v74, v78, v79
	v_cvt_pk_bf16_f32 v75, v80, v81
	v_cvt_pk_bf16_f32 v76, v82, v83
	v_cvt_pk_bf16_f32 v77, v84, v77
	global_store_dwordx4 v[96:97], v[74:77], off
	global_load_dwordx4 v[74:77], v[140:141], off offset:512
	global_load_dwordx4 v[78:81], v[140:141], off offset:528
	global_load_dwordx4 v[82:85], v[94:95], off offset:256
	v_add_u32_e32 v86, 0x80, v146
	v_ashrrev_i32_e32 v87, 31, v86
	s_waitcnt vmcnt(2)
	v_pk_add_f32 v[72:73], v[72:73], v[76:77]
	s_waitcnt vmcnt(1)
	v_pk_add_f32 v[68:69], v[68:69], v[80:81]
	v_pk_add_f32 v[70:71], v[70:71], v[74:75]
	v_pk_add_f32 v[66:67], v[66:67], v[78:79]
	v_mul_f32_e32 v69, 0xbfb8aa3b, v69
	v_mul_f32_e32 v70, 0xbfb8aa3b, v70
	v_mul_f32_e32 v71, 0xbfb8aa3b, v71
	v_mul_f32_e32 v72, 0xbfb8aa3b, v72
	v_mul_f32_e32 v73, 0xbfb8aa3b, v73
	v_mul_f32_e32 v66, 0xbfb8aa3b, v66
	v_mul_f32_e32 v67, 0xbfb8aa3b, v67
	v_mul_f32_e32 v68, 0xbfb8aa3b, v68
	v_exp_f32_e32 v69, v69
	v_exp_f32_e32 v70, v70
	v_exp_f32_e32 v71, v71
	v_exp_f32_e32 v72, v72
	v_exp_f32_e32 v73, v73
	v_exp_f32_e32 v66, v66
	v_exp_f32_e32 v67, v67
	v_exp_f32_e32 v68, v68
	v_add_f32_e32 v69, 1.0, v69
	v_add_f32_e32 v70, 1.0, v70
	v_add_f32_e32 v71, 1.0, v71
	v_add_f32_e32 v72, 1.0, v72
	v_add_f32_e32 v73, 1.0, v73
	v_add_f32_e32 v66, 1.0, v66
	v_add_f32_e32 v67, 1.0, v67
	v_add_f32_e32 v68, 1.0, v68
	v_rcp_f32_e32 v69, v69
	v_rcp_f32_e32 v70, v70
	v_rcp_f32_e32 v71, v71
	v_rcp_f32_e32 v72, v72
	v_rcp_f32_e32 v73, v73
	v_rcp_f32_e32 v66, v66
	v_rcp_f32_e32 v67, v67
	v_rcp_f32_e32 v68, v68
	s_waitcnt vmcnt(0)
	v_and_b32_e32 v81, 0xffff0000, v85
	v_lshlrev_b32_e32 v74, 16, v82
	v_and_b32_e32 v75, 0xffff0000, v82
	v_lshlrev_b32_e32 v76, 16, v83
	v_and_b32_e32 v77, 0xffff0000, v83
	v_lshlrev_b32_e32 v78, 16, v84
	v_and_b32_e32 v79, 0xffff0000, v84
	v_lshlrev_b32_e32 v80, 16, v85
	v_mul_f32_e32 v69, v69, v81
	v_mul_f32_e32 v70, v70, v74
	v_mul_f32_e32 v71, v71, v75
	v_mul_f32_e32 v72, v72, v76
	v_mul_f32_e32 v73, v73, v77
	v_mul_f32_e32 v74, v66, v78
	v_mul_f32_e32 v75, v67, v79
	v_mul_f32_e32 v76, v68, v80
	v_cvt_pk_bf16_f32 v66, v70, v71
	v_cvt_pk_bf16_f32 v67, v72, v73
	v_cvt_pk_bf16_f32 v68, v74, v75
	v_cvt_pk_bf16_f32 v69, v76, v69
	global_store_dwordx4 v[96:97], v[66:69], off offset:256
	global_load_dwordx4 v[66:69], v[140:141], off offset:16
	global_load_dwordx4 v[70:73], v[140:141], off
	v_mad_i64_i32 v[74:75], s[30:31], v86, s80, v[144:145]
	v_lshl_add_u64 v[78:79], v[74:75], 0, v[142:143]
	global_load_dwordx4 v[74:77], v[78:79], off
	v_lshlrev_b64 v[80:81], 12, v[86:87]
	v_lshl_add_u64 v[80:81], s[22:23], 0, v[80:81]
	v_lshl_add_u64 v[80:81], v[80:81], 0, v[142:143]
	s_waitcnt vmcnt(2)
	v_pk_add_f32 v[60:61], v[60:61], v[68:69]
	s_waitcnt vmcnt(1)
	v_pk_add_f32 v[64:65], v[64:65], v[72:73]
	v_pk_add_f32 v[62:63], v[62:63], v[70:71]
	v_pk_add_f32 v[58:59], v[58:59], v[66:67]
	v_mul_f32_e32 v61, 0xbfb8aa3b, v61
	v_mul_f32_e32 v62, 0xbfb8aa3b, v62
	v_mul_f32_e32 v63, 0xbfb8aa3b, v63
	v_mul_f32_e32 v64, 0xbfb8aa3b, v64
	v_mul_f32_e32 v65, 0xbfb8aa3b, v65
	v_mul_f32_e32 v58, 0xbfb8aa3b, v58
	v_mul_f32_e32 v59, 0xbfb8aa3b, v59
	v_mul_f32_e32 v60, 0xbfb8aa3b, v60
	v_exp_f32_e32 v61, v61
	v_exp_f32_e32 v62, v62
	v_exp_f32_e32 v63, v63
	v_exp_f32_e32 v64, v64
	v_exp_f32_e32 v65, v65
	v_exp_f32_e32 v58, v58
	v_exp_f32_e32 v59, v59
	v_exp_f32_e32 v60, v60
	v_add_f32_e32 v61, 1.0, v61
	v_add_f32_e32 v62, 1.0, v62
	v_add_f32_e32 v63, 1.0, v63
	v_add_f32_e32 v64, 1.0, v64
	v_add_f32_e32 v65, 1.0, v65
	v_add_f32_e32 v58, 1.0, v58
	v_add_f32_e32 v59, 1.0, v59
	v_add_f32_e32 v60, 1.0, v60
	v_rcp_f32_e32 v61, v61
	v_rcp_f32_e32 v62, v62
	v_rcp_f32_e32 v63, v63
	v_rcp_f32_e32 v64, v64
	v_rcp_f32_e32 v65, v65
	v_rcp_f32_e32 v58, v58
	v_rcp_f32_e32 v59, v59
	v_rcp_f32_e32 v60, v60
	s_waitcnt vmcnt(0)
	v_and_b32_e32 v73, 0xffff0000, v77
	v_lshlrev_b32_e32 v66, 16, v74
	v_and_b32_e32 v67, 0xffff0000, v74
	v_lshlrev_b32_e32 v68, 16, v75
	v_and_b32_e32 v69, 0xffff0000, v75
	v_lshlrev_b32_e32 v70, 16, v76
	v_and_b32_e32 v71, 0xffff0000, v76
	v_lshlrev_b32_e32 v72, 16, v77
	v_mul_f32_e32 v61, v61, v73
	v_mul_f32_e32 v62, v62, v66
	v_mul_f32_e32 v63, v63, v67
	v_mul_f32_e32 v64, v64, v68
	v_mul_f32_e32 v65, v65, v69
	v_mul_f32_e32 v66, v58, v70
	v_mul_f32_e32 v67, v59, v71
	v_mul_f32_e32 v68, v60, v72
	v_cvt_pk_bf16_f32 v58, v62, v63
	v_cvt_pk_bf16_f32 v59, v64, v65
	v_cvt_pk_bf16_f32 v60, v66, v67
	v_cvt_pk_bf16_f32 v61, v68, v61
	global_store_dwordx4 v[80:81], v[58:61], off
	global_load_dwordx4 v[58:61], v[140:141], off offset:512
	global_load_dwordx4 v[62:65], v[140:141], off offset:528
	global_load_dwordx4 v[66:69], v[78:79], off offset:256
	v_add_u32_e32 v70, 0x90, v146
	v_ashrrev_i32_e32 v71, 31, v70
	s_waitcnt vmcnt(2)
	v_pk_add_f32 v[56:57], v[56:57], v[60:61]
	s_waitcnt vmcnt(1)
	v_pk_add_f32 v[52:53], v[52:53], v[64:65]
	v_pk_add_f32 v[54:55], v[54:55], v[58:59]
	v_pk_add_f32 v[50:51], v[50:51], v[62:63]
	v_mul_f32_e32 v53, 0xbfb8aa3b, v53
	v_mul_f32_e32 v54, 0xbfb8aa3b, v54
	v_mul_f32_e32 v55, 0xbfb8aa3b, v55
	v_mul_f32_e32 v56, 0xbfb8aa3b, v56
	v_mul_f32_e32 v57, 0xbfb8aa3b, v57
	v_mul_f32_e32 v50, 0xbfb8aa3b, v50
	v_mul_f32_e32 v51, 0xbfb8aa3b, v51
	v_mul_f32_e32 v52, 0xbfb8aa3b, v52
	v_exp_f32_e32 v53, v53
	v_exp_f32_e32 v54, v54
	v_exp_f32_e32 v55, v55
	v_exp_f32_e32 v56, v56
	v_exp_f32_e32 v57, v57
	v_exp_f32_e32 v50, v50
	v_exp_f32_e32 v51, v51
	v_exp_f32_e32 v52, v52
	v_add_f32_e32 v53, 1.0, v53
	v_add_f32_e32 v54, 1.0, v54
	v_add_f32_e32 v55, 1.0, v55
	v_add_f32_e32 v56, 1.0, v56
	v_add_f32_e32 v57, 1.0, v57
	v_add_f32_e32 v50, 1.0, v50
	v_add_f32_e32 v51, 1.0, v51
	v_add_f32_e32 v52, 1.0, v52
	v_rcp_f32_e32 v53, v53
	v_rcp_f32_e32 v54, v54
	v_rcp_f32_e32 v55, v55
	v_rcp_f32_e32 v56, v56
	v_rcp_f32_e32 v57, v57
	v_rcp_f32_e32 v50, v50
	v_rcp_f32_e32 v51, v51
	v_rcp_f32_e32 v52, v52
	s_waitcnt vmcnt(0)
	v_and_b32_e32 v65, 0xffff0000, v69
	v_lshlrev_b32_e32 v58, 16, v66
	v_and_b32_e32 v59, 0xffff0000, v66
	v_lshlrev_b32_e32 v60, 16, v67
	v_and_b32_e32 v61, 0xffff0000, v67
	v_lshlrev_b32_e32 v62, 16, v68
	v_and_b32_e32 v63, 0xffff0000, v68
	v_lshlrev_b32_e32 v64, 16, v69
	v_mul_f32_e32 v53, v53, v65
	v_mul_f32_e32 v54, v54, v58
	v_mul_f32_e32 v55, v55, v59
	v_mul_f32_e32 v56, v56, v60
	v_mul_f32_e32 v57, v57, v61
	v_mul_f32_e32 v58, v50, v62
	v_mul_f32_e32 v59, v51, v63
	v_mul_f32_e32 v60, v52, v64
	v_cvt_pk_bf16_f32 v50, v54, v55
	v_cvt_pk_bf16_f32 v51, v56, v57
	v_cvt_pk_bf16_f32 v52, v58, v59
	v_cvt_pk_bf16_f32 v53, v60, v53
	global_store_dwordx4 v[80:81], v[50:53], off offset:256
	global_load_dwordx4 v[50:53], v[140:141], off offset:16
	global_load_dwordx4 v[54:57], v[140:141], off
	v_mad_i64_i32 v[58:59], s[30:31], v70, s80, v[144:145]
	v_lshl_add_u64 v[62:63], v[58:59], 0, v[142:143]
	global_load_dwordx4 v[58:61], v[62:63], off
	v_lshlrev_b64 v[64:65], 12, v[70:71]
	v_lshl_add_u64 v[64:65], s[22:23], 0, v[64:65]
	v_lshl_add_u64 v[64:65], v[64:65], 0, v[142:143]
	s_waitcnt vmcnt(2)
	v_pk_add_f32 v[44:45], v[44:45], v[52:53]
	s_waitcnt vmcnt(1)
	v_pk_add_f32 v[48:49], v[48:49], v[56:57]
	v_pk_add_f32 v[46:47], v[46:47], v[54:55]
	v_pk_add_f32 v[42:43], v[42:43], v[50:51]
	v_mul_f32_e32 v45, 0xbfb8aa3b, v45
	v_mul_f32_e32 v46, 0xbfb8aa3b, v46
	v_mul_f32_e32 v47, 0xbfb8aa3b, v47
	v_mul_f32_e32 v48, 0xbfb8aa3b, v48
	v_mul_f32_e32 v49, 0xbfb8aa3b, v49
	v_mul_f32_e32 v42, 0xbfb8aa3b, v42
	v_mul_f32_e32 v43, 0xbfb8aa3b, v43
	v_mul_f32_e32 v44, 0xbfb8aa3b, v44
	v_exp_f32_e32 v45, v45
	v_exp_f32_e32 v46, v46
	v_exp_f32_e32 v47, v47
	v_exp_f32_e32 v48, v48
	v_exp_f32_e32 v49, v49
	v_exp_f32_e32 v42, v42
	v_exp_f32_e32 v43, v43
	v_exp_f32_e32 v44, v44
	v_add_f32_e32 v45, 1.0, v45
	v_add_f32_e32 v46, 1.0, v46
	v_add_f32_e32 v47, 1.0, v47
	v_add_f32_e32 v48, 1.0, v48
	v_add_f32_e32 v49, 1.0, v49
	v_add_f32_e32 v42, 1.0, v42
	v_add_f32_e32 v43, 1.0, v43
	v_add_f32_e32 v44, 1.0, v44
	v_rcp_f32_e32 v45, v45
	v_rcp_f32_e32 v46, v46
	v_rcp_f32_e32 v47, v47
	v_rcp_f32_e32 v48, v48
	v_rcp_f32_e32 v49, v49
	v_rcp_f32_e32 v42, v42
	v_rcp_f32_e32 v43, v43
	v_rcp_f32_e32 v44, v44
	s_waitcnt vmcnt(0)
	v_and_b32_e32 v57, 0xffff0000, v61
	v_lshlrev_b32_e32 v50, 16, v58
	v_and_b32_e32 v51, 0xffff0000, v58
	v_lshlrev_b32_e32 v52, 16, v59
	v_and_b32_e32 v53, 0xffff0000, v59
	v_lshlrev_b32_e32 v54, 16, v60
	v_and_b32_e32 v55, 0xffff0000, v60
	v_lshlrev_b32_e32 v56, 16, v61
	v_mul_f32_e32 v45, v45, v57
	v_mul_f32_e32 v46, v46, v50
	v_mul_f32_e32 v47, v47, v51
	v_mul_f32_e32 v48, v48, v52
	v_mul_f32_e32 v49, v49, v53
	v_mul_f32_e32 v50, v42, v54
	v_mul_f32_e32 v51, v43, v55
	v_mul_f32_e32 v52, v44, v56
	v_cvt_pk_bf16_f32 v42, v46, v47
	v_cvt_pk_bf16_f32 v43, v48, v49
	v_cvt_pk_bf16_f32 v44, v50, v51
	v_cvt_pk_bf16_f32 v45, v52, v45
	global_store_dwordx4 v[64:65], v[42:45], off
	global_load_dwordx4 v[42:45], v[140:141], off offset:512
	global_load_dwordx4 v[46:49], v[140:141], off offset:528
	global_load_dwordx4 v[50:53], v[62:63], off offset:256
	v_add_u32_e32 v54, 0xa0, v146
	v_ashrrev_i32_e32 v55, 31, v54
	s_waitcnt vmcnt(2)
	v_pk_add_f32 v[40:41], v[40:41], v[44:45]
	s_waitcnt vmcnt(1)
	v_pk_add_f32 v[36:37], v[36:37], v[48:49]
	v_pk_add_f32 v[38:39], v[38:39], v[42:43]
	v_pk_add_f32 v[34:35], v[34:35], v[46:47]
	v_mul_f32_e32 v37, 0xbfb8aa3b, v37
	v_mul_f32_e32 v38, 0xbfb8aa3b, v38
	v_mul_f32_e32 v39, 0xbfb8aa3b, v39
	v_mul_f32_e32 v40, 0xbfb8aa3b, v40
	v_mul_f32_e32 v41, 0xbfb8aa3b, v41
	v_mul_f32_e32 v34, 0xbfb8aa3b, v34
	v_mul_f32_e32 v35, 0xbfb8aa3b, v35
	v_mul_f32_e32 v36, 0xbfb8aa3b, v36
	v_exp_f32_e32 v37, v37
	v_exp_f32_e32 v38, v38
	v_exp_f32_e32 v39, v39
	v_exp_f32_e32 v40, v40
	v_exp_f32_e32 v41, v41
	v_exp_f32_e32 v34, v34
	v_exp_f32_e32 v35, v35
	v_exp_f32_e32 v36, v36
	v_add_f32_e32 v37, 1.0, v37
	v_add_f32_e32 v38, 1.0, v38
	v_add_f32_e32 v39, 1.0, v39
	v_add_f32_e32 v40, 1.0, v40
	v_add_f32_e32 v41, 1.0, v41
	v_add_f32_e32 v34, 1.0, v34
	v_add_f32_e32 v35, 1.0, v35
	v_add_f32_e32 v36, 1.0, v36
	v_rcp_f32_e32 v37, v37
	v_rcp_f32_e32 v38, v38
	v_rcp_f32_e32 v39, v39
	v_rcp_f32_e32 v40, v40
	v_rcp_f32_e32 v41, v41
	v_rcp_f32_e32 v34, v34
	v_rcp_f32_e32 v35, v35
	v_rcp_f32_e32 v36, v36
	s_waitcnt vmcnt(0)
	v_and_b32_e32 v49, 0xffff0000, v53
	v_lshlrev_b32_e32 v42, 16, v50
	v_and_b32_e32 v43, 0xffff0000, v50
	v_lshlrev_b32_e32 v44, 16, v51
	v_and_b32_e32 v45, 0xffff0000, v51
	v_lshlrev_b32_e32 v46, 16, v52
	v_and_b32_e32 v47, 0xffff0000, v52
	v_lshlrev_b32_e32 v48, 16, v53
	v_mul_f32_e32 v37, v37, v49
	v_mul_f32_e32 v38, v38, v42
	v_mul_f32_e32 v39, v39, v43
	v_mul_f32_e32 v40, v40, v44
	v_mul_f32_e32 v41, v41, v45
	v_mul_f32_e32 v42, v34, v46
	v_mul_f32_e32 v43, v35, v47
	v_mul_f32_e32 v44, v36, v48
	v_cvt_pk_bf16_f32 v34, v38, v39
	v_cvt_pk_bf16_f32 v35, v40, v41
	v_cvt_pk_bf16_f32 v36, v42, v43
	v_cvt_pk_bf16_f32 v37, v44, v37
	global_store_dwordx4 v[64:65], v[34:37], off offset:256
	global_load_dwordx4 v[34:37], v[140:141], off offset:16
	global_load_dwordx4 v[38:41], v[140:141], off
	v_mad_i64_i32 v[42:43], s[30:31], v54, s80, v[144:145]
	v_lshl_add_u64 v[46:47], v[42:43], 0, v[142:143]
	global_load_dwordx4 v[42:45], v[46:47], off
	v_lshlrev_b64 v[48:49], 12, v[54:55]
	v_lshl_add_u64 v[48:49], s[22:23], 0, v[48:49]
	v_lshl_add_u64 v[48:49], v[48:49], 0, v[142:143]
	s_waitcnt vmcnt(2)
	v_pk_add_f32 v[28:29], v[28:29], v[36:37]
	s_waitcnt vmcnt(1)
	v_pk_add_f32 v[32:33], v[32:33], v[40:41]
	v_pk_add_f32 v[30:31], v[30:31], v[38:39]
	v_pk_add_f32 v[26:27], v[26:27], v[34:35]
	v_mul_f32_e32 v29, 0xbfb8aa3b, v29
	v_mul_f32_e32 v30, 0xbfb8aa3b, v30
	v_mul_f32_e32 v31, 0xbfb8aa3b, v31
	v_mul_f32_e32 v32, 0xbfb8aa3b, v32
	v_mul_f32_e32 v33, 0xbfb8aa3b, v33
	v_mul_f32_e32 v26, 0xbfb8aa3b, v26
	v_mul_f32_e32 v27, 0xbfb8aa3b, v27
	v_mul_f32_e32 v28, 0xbfb8aa3b, v28
	v_exp_f32_e32 v29, v29
	v_exp_f32_e32 v30, v30
	v_exp_f32_e32 v31, v31
	v_exp_f32_e32 v32, v32
	v_exp_f32_e32 v33, v33
	v_exp_f32_e32 v26, v26
	v_exp_f32_e32 v27, v27
	v_exp_f32_e32 v28, v28
	v_add_f32_e32 v29, 1.0, v29
	v_add_f32_e32 v30, 1.0, v30
	v_add_f32_e32 v31, 1.0, v31
	v_add_f32_e32 v32, 1.0, v32
	v_add_f32_e32 v33, 1.0, v33
	v_add_f32_e32 v26, 1.0, v26
	v_add_f32_e32 v27, 1.0, v27
	v_add_f32_e32 v28, 1.0, v28
	v_rcp_f32_e32 v29, v29
	v_rcp_f32_e32 v30, v30
	v_rcp_f32_e32 v31, v31
	v_rcp_f32_e32 v32, v32
	v_rcp_f32_e32 v33, v33
	v_rcp_f32_e32 v26, v26
	v_rcp_f32_e32 v27, v27
	v_rcp_f32_e32 v28, v28
	s_waitcnt vmcnt(0)
	v_and_b32_e32 v41, 0xffff0000, v45
	v_lshlrev_b32_e32 v34, 16, v42
	v_and_b32_e32 v35, 0xffff0000, v42
	v_lshlrev_b32_e32 v36, 16, v43
	v_and_b32_e32 v37, 0xffff0000, v43
	v_lshlrev_b32_e32 v38, 16, v44
	v_and_b32_e32 v39, 0xffff0000, v44
	v_lshlrev_b32_e32 v40, 16, v45
	v_mul_f32_e32 v29, v29, v41
	v_mul_f32_e32 v30, v30, v34
	v_mul_f32_e32 v31, v31, v35
	v_mul_f32_e32 v32, v32, v36
	v_mul_f32_e32 v33, v33, v37
	v_mul_f32_e32 v34, v26, v38
	v_mul_f32_e32 v35, v27, v39
	v_mul_f32_e32 v36, v28, v40
	v_cvt_pk_bf16_f32 v26, v30, v31
	v_cvt_pk_bf16_f32 v27, v32, v33
	v_cvt_pk_bf16_f32 v28, v34, v35
	v_cvt_pk_bf16_f32 v29, v36, v29
	global_store_dwordx4 v[48:49], v[26:29], off
	global_load_dwordx4 v[26:29], v[140:141], off offset:512
	global_load_dwordx4 v[30:33], v[140:141], off offset:528
	global_load_dwordx4 v[34:37], v[46:47], off offset:256
	v_add_u32_e32 v38, 0xb0, v146
	v_ashrrev_i32_e32 v39, 31, v38
	s_waitcnt vmcnt(2)
	v_pk_add_f32 v[24:25], v[24:25], v[28:29]
	s_waitcnt vmcnt(1)
	v_pk_add_f32 v[20:21], v[20:21], v[32:33]
	v_pk_add_f32 v[22:23], v[22:23], v[26:27]
	v_pk_add_f32 v[18:19], v[18:19], v[30:31]
	v_mul_f32_e32 v21, 0xbfb8aa3b, v21
	v_mul_f32_e32 v22, 0xbfb8aa3b, v22
	v_mul_f32_e32 v23, 0xbfb8aa3b, v23
	v_mul_f32_e32 v24, 0xbfb8aa3b, v24
	v_mul_f32_e32 v25, 0xbfb8aa3b, v25
	v_mul_f32_e32 v18, 0xbfb8aa3b, v18
	v_mul_f32_e32 v19, 0xbfb8aa3b, v19
	v_mul_f32_e32 v20, 0xbfb8aa3b, v20
	v_exp_f32_e32 v21, v21
	v_exp_f32_e32 v22, v22
	v_exp_f32_e32 v23, v23
	v_exp_f32_e32 v24, v24
	v_exp_f32_e32 v25, v25
	v_exp_f32_e32 v18, v18
	v_exp_f32_e32 v19, v19
	v_exp_f32_e32 v20, v20
	v_add_f32_e32 v21, 1.0, v21
	v_add_f32_e32 v22, 1.0, v22
	v_add_f32_e32 v23, 1.0, v23
	v_add_f32_e32 v24, 1.0, v24
	v_add_f32_e32 v25, 1.0, v25
	v_add_f32_e32 v18, 1.0, v18
	v_add_f32_e32 v19, 1.0, v19
	v_add_f32_e32 v20, 1.0, v20
	v_rcp_f32_e32 v21, v21
	v_rcp_f32_e32 v22, v22
	v_rcp_f32_e32 v23, v23
	v_rcp_f32_e32 v24, v24
	v_rcp_f32_e32 v25, v25
	v_rcp_f32_e32 v18, v18
	v_rcp_f32_e32 v19, v19
	v_rcp_f32_e32 v20, v20
	s_waitcnt vmcnt(0)
	v_and_b32_e32 v33, 0xffff0000, v37
	v_lshlrev_b32_e32 v26, 16, v34
	v_and_b32_e32 v27, 0xffff0000, v34
	v_lshlrev_b32_e32 v28, 16, v35
	v_and_b32_e32 v29, 0xffff0000, v35
	v_lshlrev_b32_e32 v30, 16, v36
	v_and_b32_e32 v31, 0xffff0000, v36
	v_lshlrev_b32_e32 v32, 16, v37
	v_mul_f32_e32 v21, v21, v33
	v_mul_f32_e32 v22, v22, v26
	v_mul_f32_e32 v23, v23, v27
	v_mul_f32_e32 v24, v24, v28
	v_mul_f32_e32 v25, v25, v29
	v_mul_f32_e32 v26, v18, v30
	v_mul_f32_e32 v27, v19, v31
	v_mul_f32_e32 v28, v20, v32
	v_cvt_pk_bf16_f32 v18, v22, v23
	v_cvt_pk_bf16_f32 v19, v24, v25
	v_cvt_pk_bf16_f32 v20, v26, v27
	v_cvt_pk_bf16_f32 v21, v28, v21
	global_store_dwordx4 v[48:49], v[18:21], off offset:256
	global_load_dwordx4 v[18:21], v[140:141], off offset:16
	global_load_dwordx4 v[22:25], v[140:141], off
	v_mad_i64_i32 v[26:27], s[30:31], v38, s80, v[144:145]
	v_lshl_add_u64 v[30:31], v[26:27], 0, v[142:143]
	global_load_dwordx4 v[26:29], v[30:31], off
	v_lshlrev_b64 v[32:33], 12, v[38:39]
	v_lshl_add_u64 v[32:33], s[22:23], 0, v[32:33]
	v_lshl_add_u64 v[32:33], v[32:33], 0, v[142:143]
	s_mov_b64 s[30:31], -1
	s_waitcnt vmcnt(2)
	v_pk_add_f32 v[12:13], v[12:13], v[20:21]
	s_waitcnt vmcnt(1)
	v_pk_add_f32 v[16:17], v[16:17], v[24:25]
	v_pk_add_f32 v[14:15], v[14:15], v[22:23]
	v_pk_add_f32 v[10:11], v[10:11], v[18:19]
	v_mul_f32_e32 v13, 0xbfb8aa3b, v13
	v_mul_f32_e32 v14, 0xbfb8aa3b, v14
	v_mul_f32_e32 v15, 0xbfb8aa3b, v15
	v_mul_f32_e32 v16, 0xbfb8aa3b, v16
	v_mul_f32_e32 v17, 0xbfb8aa3b, v17
	v_mul_f32_e32 v10, 0xbfb8aa3b, v10
	v_mul_f32_e32 v11, 0xbfb8aa3b, v11
	v_mul_f32_e32 v12, 0xbfb8aa3b, v12
	v_exp_f32_e32 v13, v13
	v_exp_f32_e32 v14, v14
	v_exp_f32_e32 v15, v15
	v_exp_f32_e32 v16, v16
	v_exp_f32_e32 v17, v17
	v_exp_f32_e32 v10, v10
	v_exp_f32_e32 v11, v11
	v_exp_f32_e32 v12, v12
	v_add_f32_e32 v13, 1.0, v13
	v_add_f32_e32 v14, 1.0, v14
	v_add_f32_e32 v15, 1.0, v15
	v_add_f32_e32 v16, 1.0, v16
	v_add_f32_e32 v17, 1.0, v17
	v_add_f32_e32 v10, 1.0, v10
	v_add_f32_e32 v11, 1.0, v11
	v_add_f32_e32 v12, 1.0, v12
	v_rcp_f32_e32 v13, v13
	v_rcp_f32_e32 v14, v14
	v_rcp_f32_e32 v15, v15
	v_rcp_f32_e32 v16, v16
	v_rcp_f32_e32 v17, v17
	v_rcp_f32_e32 v10, v10
	v_rcp_f32_e32 v11, v11
	v_rcp_f32_e32 v12, v12
	s_waitcnt vmcnt(0)
	v_and_b32_e32 v25, 0xffff0000, v29
	v_lshlrev_b32_e32 v18, 16, v26
	v_and_b32_e32 v19, 0xffff0000, v26
	v_lshlrev_b32_e32 v20, 16, v27
	v_and_b32_e32 v21, 0xffff0000, v27
	v_lshlrev_b32_e32 v22, 16, v28
	v_and_b32_e32 v23, 0xffff0000, v28
	v_lshlrev_b32_e32 v24, 16, v29
	v_mul_f32_e32 v13, v13, v25
	v_mul_f32_e32 v14, v14, v18
	v_mul_f32_e32 v15, v15, v19
	v_mul_f32_e32 v16, v16, v20
	v_mul_f32_e32 v17, v17, v21
	v_mul_f32_e32 v18, v10, v22
	v_mul_f32_e32 v19, v11, v23
	v_mul_f32_e32 v20, v12, v24
	v_cvt_pk_bf16_f32 v10, v14, v15
	v_cvt_pk_bf16_f32 v11, v16, v17
	v_cvt_pk_bf16_f32 v12, v18, v19
	v_cvt_pk_bf16_f32 v13, v20, v13
	global_store_dwordx4 v[32:33], v[10:13], off
	global_load_dwordx4 v[10:13], v[140:141], off offset:512
	global_load_dwordx4 v[14:17], v[140:141], off offset:528
	global_load_dwordx4 v[18:21], v[30:31], off offset:256
	s_waitcnt vmcnt(2)
	v_pk_add_f32 v[8:9], v[8:9], v[12:13]
	s_waitcnt vmcnt(1)
	v_pk_add_f32 v[4:5], v[4:5], v[16:17]
	v_pk_add_f32 v[6:7], v[6:7], v[10:11]
	v_pk_add_f32 v[2:3], v[2:3], v[14:15]
	v_mul_f32_e32 v5, 0xbfb8aa3b, v5
	v_mul_f32_e32 v6, 0xbfb8aa3b, v6
	v_mul_f32_e32 v7, 0xbfb8aa3b, v7
	v_mul_f32_e32 v8, 0xbfb8aa3b, v8
	v_mul_f32_e32 v9, 0xbfb8aa3b, v9
	v_mul_f32_e32 v2, 0xbfb8aa3b, v2
	v_mul_f32_e32 v3, 0xbfb8aa3b, v3
	v_mul_f32_e32 v4, 0xbfb8aa3b, v4
	v_exp_f32_e32 v5, v5
	v_exp_f32_e32 v6, v6
	v_exp_f32_e32 v7, v7
	v_exp_f32_e32 v8, v8
	v_exp_f32_e32 v9, v9
	v_exp_f32_e32 v2, v2
	v_exp_f32_e32 v3, v3
	v_exp_f32_e32 v4, v4
	v_add_f32_e32 v5, 1.0, v5
	v_add_f32_e32 v6, 1.0, v6
	v_add_f32_e32 v7, 1.0, v7
	v_add_f32_e32 v8, 1.0, v8
	v_add_f32_e32 v9, 1.0, v9
	v_add_f32_e32 v2, 1.0, v2
	v_add_f32_e32 v3, 1.0, v3
	v_add_f32_e32 v4, 1.0, v4
	v_rcp_f32_e32 v5, v5
	v_rcp_f32_e32 v6, v6
	v_rcp_f32_e32 v7, v7
	v_rcp_f32_e32 v8, v8
	v_rcp_f32_e32 v9, v9
	v_rcp_f32_e32 v2, v2
	v_rcp_f32_e32 v3, v3
	v_rcp_f32_e32 v4, v4
	s_waitcnt vmcnt(0)
	v_and_b32_e32 v17, 0xffff0000, v21
	v_lshlrev_b32_e32 v10, 16, v18
	v_and_b32_e32 v11, 0xffff0000, v18
	v_lshlrev_b32_e32 v12, 16, v19
	v_and_b32_e32 v13, 0xffff0000, v19
	v_lshlrev_b32_e32 v14, 16, v20
	v_and_b32_e32 v15, 0xffff0000, v20
	v_lshlrev_b32_e32 v16, 16, v21
	v_mul_f32_e32 v5, v5, v17
	v_mul_f32_e32 v6, v6, v10
	v_mul_f32_e32 v7, v7, v11
	v_mul_f32_e32 v8, v8, v12
	v_mul_f32_e32 v9, v9, v13
	v_mul_f32_e32 v10, v2, v14
	v_mul_f32_e32 v11, v3, v15
	v_mul_f32_e32 v12, v4, v16
	v_cvt_pk_bf16_f32 v2, v6, v7
	v_cvt_pk_bf16_f32 v3, v8, v9
	v_cvt_pk_bf16_f32 v4, v10, v11
	v_cvt_pk_bf16_f32 v5, v12, v5
	global_store_dwordx4 v[32:33], v[2:5], off offset:256
	s_cbranch_vccnz .LBB0_925
	s_andn2_b64 vcc, exec, s[14:15]
	s_cbranch_vccz .LBB0_924
	s_barrier
	s_branch .LBB0_924

.LBB0_1005:
	v_readlane_b32 s3, v255, 41
	s_andn2_b64 vcc, exec, s[14:15]
	s_lshl_b32 s12, s3, 6
	s_cbranch_vccnz .LBB0_1222
	v_ashrrev_i32_e32 v3, 31, v10
	v_lshrrev_b32_e32 v3, 26, v3
	v_add_u32_e32 v3, v10, v3
	v_ashrrev_i32_e32 v11, 6, v3
	v_bfe_i32 v3, v10, 27, 1
	v_lshlrev_b32_e32 v2, 4, v10
	v_lshrrev_b32_e32 v3, 22, v3
	v_add_u32_e32 v3, v2, v3
	v_and_b32_e32 v3, 0xfffffc00, v3
	s_load_dwordx2 s[30:31], s[0:1], s69 offset:0x118
	v_sub_u32_e32 v3, v2, v3
	v_lshrrev_b32_e32 v4, 4, v3
	v_bitop3_b32 v3, v4, v3, 32 bitop3:0x6c
	v_ashrrev_i32_e32 v5, 31, v3
	v_lshrrev_b32_e32 v5, 26, v5
	v_readlane_b32 s3, v255, 41
	s_waitcnt lgkmcnt(0)
	s_add_u32 s7, s30, 0x1de00000
	v_add_u32_e32 v5, v3, v5
	s_mul_i32 s11, s3, 0xe00000
	s_addc_u32 s8, s31, 0
	v_lshlrev_b32_e32 v4, 3, v11
	v_ashrrev_i32_e32 v12, 6, v5
	v_and_b32_e32 v5, 0xc0, v5
	s_mul_hi_u32 s9, s3, 0xe00000
	s_add_u32 s11, s30, s11
	v_and_b32_e32 v4, -16, v4
	v_sub_u32_e32 v3, v3, v5
	s_addc_u32 s14, s31, s9
	v_add_u32_e32 v4, v12, v4
	v_ashrrev_i16_sdwa v3, v224, sext(v3) dst_sel:DWORD dst_unused:UNUSED_PAD src0_sel:DWORD src1_sel:BYTE_0
	s_add_u32 s9, s11, 0x100000
	v_lshlrev_b32_e32 v6, 5, v11
	v_bfe_i32 v13, v3, 0, 16
	v_lshlrev_b32_e32 v3, 1, v4
	v_lshrrev_b32_e32 v5, 2, v4
	v_and_b32_e32 v7, 3, v12
	s_mov_b32 s11, 0xfffe0
	v_and_b32_e32 v6, 32, v6
	v_and_b32_e32 v3, 24, v3
	v_and_b32_e32 v5, 4, v5
	v_and_or_b32 v7, v4, s11, v7
	v_or3_b32 v3, v7, v5, v3
	v_add_lshl_u32 v5, v6, v13, 1
	v_add_u32_e32 v2, 0x2000, v2
	v_lshl_add_u32 v180, v3, 12, v5
	v_ashrrev_i32_e32 v3, 31, v2
	v_lshrrev_b32_e32 v3, 22, v3
	v_add_u32_e32 v3, v2, v3
	v_ashrrev_i32_e32 v14, 10, v3
	v_mul_i32_i24_e32 v3, 0x400, v14
	v_sub_u32_e32 v2, v2, v3
	v_lshrrev_b32_e32 v3, 4, v2
	v_bitop3_b32 v2, v3, v2, 32 bitop3:0x6c
	s_waitcnt vmcnt(0)
	v_lshl_add_u32 v132, v4, 12, v5
	v_ashrrev_i32_e32 v4, 31, v2
	v_lshrrev_b32_e32 v4, 26, v4
	v_lshlrev_b32_e32 v3, 3, v14
	v_add_u32_e32 v4, v2, v4
	v_and_b32_e32 v3, -16, v3
	v_ashrrev_i32_e32 v15, 6, v4
	v_add_u32_e32 v3, v15, v3
	v_and_b32_e32 v6, 3, v15
	s_addc_u32 s21, s14, 0
	v_and_b32_e32 v4, 0xc0, v4
	v_and_or_b32 v6, v3, s11, v6
	s_ashr_i32 s42, s34, 6
	s_ashr_i32 s11, s10, 31
	s_ashr_i32 s37, s36, 31
	s_ashr_i32 s35, s34, 8
	v_sub_u32_e32 v2, v2, v4
	s_lshl_b32 s60, s42, 10
	s_lshl_b64 s[14:15], s[10:11], 20
	s_lshl_b64 s[18:19], s[36:37], 20
	v_ashrrev_i16_sdwa v2, v224, sext(v2) dst_sel:DWORD dst_unused:UNUSED_PAD src0_sel:DWORD src1_sel:BYTE_0
	s_add_u32 s40, s9, s18
	v_lshlrev_b32_e32 v5, 5, v14
	v_bfe_i32 v16, v2, 0, 16
	v_lshlrev_b32_e32 v2, 1, v3
	v_lshrrev_b32_e32 v4, 2, v3
	s_addc_u32 s41, s21, s19
	s_add_i32 s61, s60, 0
	v_and_b32_e32 v5, 32, v5
	v_and_b32_e32 v2, 24, v2
	v_and_b32_e32 v4, 4, v4
	s_add_i32 m0, s61, 0x10000
	v_or3_b32 v2, v6, v4, v2
	v_add_lshl_u32 v4, v5, v16, 1
	global_load_lds_dwordx4 v180, s[40:41]
	s_add_i32 m0, s61, 0x12000
	v_lshl_add_u32 v136, v2, 12, v4
	s_add_u32 s18, s40, 0x80000
	global_load_lds_dwordx4 v136, s[40:41]
	s_addc_u32 s19, s41, 0
	s_add_i32 m0, s61, 0x14000
	v_lshl_add_u32 v134, v3, 12, v4
	global_load_lds_dwordx4 v180, s[18:19]
	s_add_i32 m0, s61, 0x16000
	s_add_u32 s38, s7, s14
	s_addc_u32 s39, s8, s15
	s_add_i32 s62, s61, 0x2000
	global_load_lds_dwordx4 v136, s[18:19]
	s_mov_b32 m0, s61
	s_add_u32 s14, s38, 0x80000
	global_load_lds_dwordx4 v132, s[38:39]
	s_mov_b32 m0, s62
	s_addc_u32 s15, s39, 0
	s_add_i32 s63, s61, 0x4000
	global_load_lds_dwordx4 v134, s[38:39]
	s_mov_b32 m0, s63
	s_add_i32 s64, s61, 0x6000
	global_load_lds_dwordx4 v132, s[14:15]
	s_mov_b32 m0, s64
	v_mov_b32_e32 v137, v181
	global_load_lds_dwordx4 v134, s[14:15]
	v_mov_b32_e32 v133, v181
	v_mov_b32_e32 v135, v181
	s_cmp_eq_u32 s35, 1
	v_lshl_add_u64 v[8:9], s[40:41], 0, v[180:181]
	v_lshl_add_u64 v[6:7], s[40:41], 0, v[136:137]
	v_lshl_add_u64 v[2:3], s[38:39], 0, v[132:133]
	s_cselect_b64 s[14:15], -1, 0
	s_cmp_lg_u32 s35, 1
	v_lshl_add_u64 v[4:5], s[38:39], 0, v[134:135]
	s_cbranch_scc0 .LBB0_1008
	s_barrier

.LBB0_1018:
	s_add_u32 s40, s38, 0xfff80080
	s_addc_u32 s41, s39, -1
	s_add_i32 s51, 0, 0x10000
	s_cmp_eq_u32 s49, 28
	s_cselect_b32 s43, s11, s41
	s_cselect_b32 s42, s37, s40
	s_cselect_b32 s41, s44, s47
	s_cselect_b32 s40, s45, s46
	s_add_i32 s83, 0, 0x14000
	v_add_u32_e32 v154, s51, v159
	v_add_u32_e32 v161, s83, v159
	ds_read_b128 v[142:145], v154
	ds_read_b128 v[146:149], v154 offset:1024
	ds_read_b128 v[150:153], v154 offset:2048
	ds_read_b128 v[154:157], v154 offset:3072
	ds_read_b128 v[162:165], v161
	ds_read_b128 v[166:169], v161 offset:1024
	ds_read_b128 v[170:173], v161 offset:2048
	ds_read_b128 v[174:177], v161 offset:3072
	v_lshl_add_u64 v[178:179], s[38:39], 0, v[138:139]
	s_add_i32 m0, s61, 0xc000
	ds_read_b128 v[190:193], v160
	ds_read_b128 v[194:197], v160 offset:1024
	ds_read_b128 v[198:201], v160 offset:2048
	ds_read_b128 v[202:205], v160 offset:3072
	ds_read_b128 v[206:209], v160 offset:4096
	ds_read_b128 v[210:213], v160 offset:5120
	ds_read_b128 v[214:217], v160 offset:6144
	ds_read_b128 v[218:221], v160 offset:7168
	global_load_lds_dwordx4 v[178:179], off
	v_lshl_add_u64 v[178:179], s[38:39], 0, v[140:141]
	s_add_i32 m0, s61, 0xe000
	s_nop 0
	global_load_lds_dwordx4 v[178:179], off
	s_waitcnt vmcnt(8)
	s_waitcnt lgkmcnt(0)
	s_barrier
	s_setprio 1
	s_waitcnt lgkmcnt(0)
	v_mfma_f32_16x16x32_bf16 v[126:129], v[142:145], v[190:193], v[126:129]
	v_mfma_f32_16x16x32_bf16 v[122:125], v[150:153], v[190:193], v[122:125]
	v_mfma_f32_16x16x32_bf16 v[110:113], v[142:145], v[198:201], v[110:113]
	v_mfma_f32_16x16x32_bf16 v[106:109], v[150:153], v[198:201], v[106:109]
	v_mfma_f32_16x16x32_bf16 v[94:97], v[142:145], v[206:209], v[94:97]
	v_mfma_f32_16x16x32_bf16 v[90:93], v[150:153], v[206:209], v[90:93]
	v_mfma_f32_16x16x32_bf16 v[78:81], v[142:145], v[214:217], v[78:81]
	v_mfma_f32_16x16x32_bf16 v[74:77], v[150:153], v[214:217], v[74:77]
	v_mfma_f32_16x16x32_bf16 v[126:129], v[146:149], v[194:197], v[126:129]
	v_mfma_f32_16x16x32_bf16 v[122:125], v[154:157], v[194:197], v[122:125]
	v_mfma_f32_16x16x32_bf16 v[110:113], v[146:149], v[202:205], v[110:113]
	v_mfma_f32_16x16x32_bf16 v[106:109], v[154:157], v[202:205], v[106:109]
	v_mfma_f32_16x16x32_bf16 v[94:97], v[146:149], v[210:213], v[94:97]
	v_mfma_f32_16x16x32_bf16 v[90:93], v[154:157], v[210:213], v[90:93]
	v_mfma_f32_16x16x32_bf16 v[78:81], v[146:149], v[218:221], v[78:81]
	v_mfma_f32_16x16x32_bf16 v[74:77], v[154:157], v[218:221], v[74:77]
	v_mfma_f32_16x16x32_bf16 v[118:121], v[162:165], v[190:193], v[118:121]
	v_mfma_f32_16x16x32_bf16 v[114:117], v[170:173], v[190:193], v[114:117]
	v_mfma_f32_16x16x32_bf16 v[102:105], v[162:165], v[198:201], v[102:105]
	v_mfma_f32_16x16x32_bf16 v[98:101], v[170:173], v[198:201], v[98:101]
	v_mfma_f32_16x16x32_bf16 v[86:89], v[162:165], v[206:209], v[86:89]
	v_mfma_f32_16x16x32_bf16 v[82:85], v[170:173], v[206:209], v[82:85]
	v_mfma_f32_16x16x32_bf16 v[70:73], v[162:165], v[214:217], v[70:73]
	v_mfma_f32_16x16x32_bf16 v[66:69], v[170:173], v[214:217], v[66:69]
	v_mfma_f32_16x16x32_bf16 v[118:121], v[166:169], v[194:197], v[118:121]
	v_mfma_f32_16x16x32_bf16 v[114:117], v[174:177], v[194:197], v[114:117]
	v_mfma_f32_16x16x32_bf16 v[102:105], v[166:169], v[202:205], v[102:105]
	v_mfma_f32_16x16x32_bf16 v[98:101], v[174:177], v[202:205], v[98:101]
	v_mfma_f32_16x16x32_bf16 v[86:89], v[166:169], v[210:213], v[86:89]
	v_mfma_f32_16x16x32_bf16 v[82:85], v[174:177], v[210:213], v[82:85]
	v_mfma_f32_16x16x32_bf16 v[70:73], v[166:169], v[218:221], v[70:73]
	v_mfma_f32_16x16x32_bf16 v[66:69], v[174:177], v[218:221], v[66:69]
	s_setprio 0
	s_barrier
	s_add_i32 s51, s51, s60
	v_lshl_add_u64 v[178:179], s[40:41], 0, v[180:181]
	s_mov_b32 m0, s51
	ds_read_b128 v[190:193], v160 offset:16384
	ds_read_b128 v[194:197], v160 offset:17408
	ds_read_b128 v[198:201], v160 offset:18432
	ds_read_b128 v[202:205], v160 offset:19456
	ds_read_b128 v[206:209], v160 offset:20480
	ds_read_b128 v[210:213], v160 offset:21504
	ds_read_b128 v[214:217], v160 offset:22528
	ds_read_b128 v[218:221], v160 offset:23552
	global_load_lds_dwordx4 v[178:179], off
	s_add_i32 m0, s51, 0x2000
	s_add_u32 vcc_lo, s40, 0x80000
	v_lshl_add_u64 v[222:223], s[40:41], 0, v[136:137]
	s_addc_u32 vcc_hi, s41, 0
	s_add_i32 s51, s83, s60
	global_load_lds_dwordx4 v[222:223], off
	v_lshl_add_u64 v[238:239], vcc, 0, v[180:181]
	s_mov_b32 m0, s51
	v_lshl_add_u64 v[240:241], s[42:43], 0, v[134:135]
	global_load_lds_dwordx4 v[238:239], off
	v_lshl_add_u64 v[238:239], vcc, 0, v[136:137]
	s_add_i32 m0, s51, 0x2000
	s_nop 0
	global_load_lds_dwordx4 v[238:239], off
	v_lshl_add_u64 v[238:239], s[42:43], 0, v[132:133]
	s_mov_b32 m0, s61
	s_nop 0
	global_load_lds_dwordx4 v[238:239], off
	s_mov_b32 m0, s62
	s_nop 0
	global_load_lds_dwordx4 v[240:241], off
	s_waitcnt vmcnt(8)
	s_waitcnt lgkmcnt(0)
	s_barrier
	s_setprio 1
	s_waitcnt lgkmcnt(0)
	v_mfma_f32_16x16x32_bf16 v[62:65], v[142:145], v[190:193], v[62:65]
	v_mfma_f32_16x16x32_bf16 v[58:61], v[150:153], v[190:193], v[58:61]
	v_mfma_f32_16x16x32_bf16 v[46:49], v[142:145], v[198:201], v[46:49]
	v_mfma_f32_16x16x32_bf16 v[42:45], v[150:153], v[198:201], v[42:45]
	v_mfma_f32_16x16x32_bf16 v[30:33], v[142:145], v[206:209], v[30:33]
	v_mfma_f32_16x16x32_bf16 v[26:29], v[150:153], v[206:209], v[26:29]
	v_mfma_f32_16x16x32_bf16 v[14:17], v[142:145], v[214:217], v[14:17]
	v_mfma_f32_16x16x32_bf16 v[10:13], v[150:153], v[214:217], v[10:13]
	v_mfma_f32_16x16x32_bf16 v[62:65], v[146:149], v[194:197], v[62:65]
	v_mfma_f32_16x16x32_bf16 v[58:61], v[154:157], v[194:197], v[58:61]
	v_mfma_f32_16x16x32_bf16 v[46:49], v[146:149], v[202:205], v[46:49]
	v_mfma_f32_16x16x32_bf16 v[42:45], v[154:157], v[202:205], v[42:45]
	v_mfma_f32_16x16x32_bf16 v[30:33], v[146:149], v[210:213], v[30:33]
	v_mfma_f32_16x16x32_bf16 v[26:29], v[154:157], v[210:213], v[26:29]
	v_mfma_f32_16x16x32_bf16 v[14:17], v[146:149], v[218:221], v[14:17]
	v_mfma_f32_16x16x32_bf16 v[10:13], v[154:157], v[218:221], v[10:13]
	v_mfma_f32_16x16x32_bf16 v[54:57], v[162:165], v[190:193], v[54:57]
	v_mfma_f32_16x16x32_bf16 v[50:53], v[170:173], v[190:193], v[50:53]
	v_mfma_f32_16x16x32_bf16 v[38:41], v[162:165], v[198:201], v[38:41]
	v_mfma_f32_16x16x32_bf16 v[34:37], v[170:173], v[198:201], v[34:37]
	v_mfma_f32_16x16x32_bf16 v[22:25], v[162:165], v[206:209], v[22:25]
	v_mfma_f32_16x16x32_bf16 v[18:21], v[170:173], v[206:209], v[18:21]
	v_mfma_f32_16x16x32_bf16 v[6:9], v[162:165], v[214:217], v[6:9]
	v_mfma_f32_16x16x32_bf16 v[2:5], v[170:173], v[214:217], v[2:5]
	v_mfma_f32_16x16x32_bf16 v[54:57], v[166:169], v[194:197], v[54:57]
	v_mfma_f32_16x16x32_bf16 v[50:53], v[174:177], v[194:197], v[50:53]
	v_mfma_f32_16x16x32_bf16 v[38:41], v[166:169], v[202:205], v[38:41]
	v_mfma_f32_16x16x32_bf16 v[34:37], v[174:177], v[202:205], v[34:37]
	v_mfma_f32_16x16x32_bf16 v[22:25], v[166:169], v[210:213], v[22:25]
	v_mfma_f32_16x16x32_bf16 v[18:21], v[174:177], v[210:213], v[18:21]
	v_mfma_f32_16x16x32_bf16 v[6:9], v[166:169], v[218:221], v[6:9]
	v_mfma_f32_16x16x32_bf16 v[2:5], v[174:177], v[218:221], v[2:5]
	s_setprio 0
	s_barrier
	s_add_i32 s51, 0, 0x18000
	s_add_i32 s83, 0, 0x1c000
	v_add_u32_e32 v154, s51, v159
	v_add_u32_e32 v161, s83, v159
	ds_read_b128 v[142:145], v154
	ds_read_b128 v[146:149], v154 offset:1024
	ds_read_b128 v[150:153], v154 offset:2048
	ds_read_b128 v[154:157], v154 offset:3072
	ds_read_b128 v[162:165], v161
	ds_read_b128 v[166:169], v161 offset:1024
	ds_read_b128 v[170:173], v161 offset:2048
	ds_read_b128 v[174:177], v161 offset:3072
	s_add_u32 s42, s42, 0x80000
	s_addc_u32 s43, s43, 0
	s_mov_b32 m0, s63
	v_lshl_add_u64 v[242:243], s[42:43], 0, v[132:133]
	ds_read_b128 v[190:193], v160 offset:32768
	ds_read_b128 v[194:197], v160 offset:33792
	ds_read_b128 v[198:201], v160 offset:34816
	ds_read_b128 v[202:205], v160 offset:35840
	ds_read_b128 v[206:209], v160 offset:36864
	ds_read_b128 v[210:213], v160 offset:37888
	ds_read_b128 v[214:217], v160 offset:38912
	ds_read_b128 v[218:221], v160 offset:39936
	global_load_lds_dwordx4 v[242:243], off
	v_lshl_add_u64 v[242:243], s[42:43], 0, v[134:135]
	s_mov_b32 m0, s64
	s_nop 0
	global_load_lds_dwordx4 v[242:243], off
	s_waitcnt vmcnt(8)
	s_waitcnt lgkmcnt(0)
	s_barrier
	s_setprio 1
	s_waitcnt lgkmcnt(0)
	v_mfma_f32_16x16x32_bf16 v[126:129], v[142:145], v[190:193], v[126:129]
	v_mfma_f32_16x16x32_bf16 v[122:125], v[150:153], v[190:193], v[122:125]
	v_mfma_f32_16x16x32_bf16 v[110:113], v[142:145], v[198:201], v[110:113]
	v_mfma_f32_16x16x32_bf16 v[106:109], v[150:153], v[198:201], v[106:109]
	v_mfma_f32_16x16x32_bf16 v[94:97], v[142:145], v[206:209], v[94:97]
	v_mfma_f32_16x16x32_bf16 v[90:93], v[150:153], v[206:209], v[90:93]
	v_mfma_f32_16x16x32_bf16 v[78:81], v[142:145], v[214:217], v[78:81]
	v_mfma_f32_16x16x32_bf16 v[74:77], v[150:153], v[214:217], v[74:77]
	v_mfma_f32_16x16x32_bf16 v[126:129], v[146:149], v[194:197], v[126:129]
	v_mfma_f32_16x16x32_bf16 v[122:125], v[154:157], v[194:197], v[122:125]
	v_mfma_f32_16x16x32_bf16 v[110:113], v[146:149], v[202:205], v[110:113]
	v_mfma_f32_16x16x32_bf16 v[106:109], v[154:157], v[202:205], v[106:109]
	v_mfma_f32_16x16x32_bf16 v[94:97], v[146:149], v[210:213], v[94:97]
	v_mfma_f32_16x16x32_bf16 v[90:93], v[154:157], v[210:213], v[90:93]
	v_mfma_f32_16x16x32_bf16 v[78:81], v[146:149], v[218:221], v[78:81]
	v_mfma_f32_16x16x32_bf16 v[74:77], v[154:157], v[218:221], v[74:77]
	v_mfma_f32_16x16x32_bf16 v[118:121], v[162:165], v[190:193], v[118:121]
	v_mfma_f32_16x16x32_bf16 v[114:117], v[170:173], v[190:193], v[114:117]
	v_mfma_f32_16x16x32_bf16 v[102:105], v[162:165], v[198:201], v[102:105]
	v_mfma_f32_16x16x32_bf16 v[98:101], v[170:173], v[198:201], v[98:101]
	v_mfma_f32_16x16x32_bf16 v[86:89], v[162:165], v[206:209], v[86:89]
	v_mfma_f32_16x16x32_bf16 v[82:85], v[170:173], v[206:209], v[82:85]
	v_mfma_f32_16x16x32_bf16 v[70:73], v[162:165], v[214:217], v[70:73]
	v_mfma_f32_16x16x32_bf16 v[66:69], v[170:173], v[214:217], v[66:69]
	v_mfma_f32_16x16x32_bf16 v[118:121], v[166:169], v[194:197], v[118:121]
	v_mfma_f32_16x16x32_bf16 v[114:117], v[174:177], v[194:197], v[114:117]
	v_mfma_f32_16x16x32_bf16 v[102:105], v[166:169], v[202:205], v[102:105]
	v_mfma_f32_16x16x32_bf16 v[98:101], v[174:177], v[202:205], v[98:101]
	v_mfma_f32_16x16x32_bf16 v[86:89], v[166:169], v[210:213], v[86:89]
	v_mfma_f32_16x16x32_bf16 v[82:85], v[174:177], v[210:213], v[82:85]
	v_mfma_f32_16x16x32_bf16 v[70:73], v[166:169], v[218:221], v[70:73]
	v_mfma_f32_16x16x32_bf16 v[66:69], v[174:177], v[218:221], v[66:69]
	s_setprio 0
	s_barrier
	s_add_i32 s42, s51, s60
	v_lshl_add_u64 v[178:179], v[178:179], 0, s[16:17]
	s_mov_b32 m0, s42
	ds_read_b128 v[190:193], v160 offset:49152
	ds_read_b128 v[194:197], v160 offset:50176
	ds_read_b128 v[198:201], v160 offset:51200
	ds_read_b128 v[202:205], v160 offset:52224
	ds_read_b128 v[206:209], v160 offset:53248
	ds_read_b128 v[210:213], v160 offset:54272
	ds_read_b128 v[214:217], v160 offset:55296
	ds_read_b128 v[218:221], v160 offset:56320
	global_load_lds_dwordx4 v[178:179], off
	s_add_i32 m0, s42, 0x2000
	s_add_u32 s40, s40, 0x80080
	v_lshl_add_u64 v[178:179], v[222:223], 0, s[16:17]
	s_addc_u32 s41, s41, 0
	s_add_i32 s42, s83, s60
	global_load_lds_dwordx4 v[178:179], off
	v_lshl_add_u64 v[178:179], s[40:41], 0, v[180:181]
	s_mov_b32 m0, s42
	s_nop 0
	global_load_lds_dwordx4 v[178:179], off
	v_lshl_add_u64 v[178:179], s[40:41], 0, v[136:137]
	s_add_i32 m0, s42, 0x2000
	s_nop 0
	global_load_lds_dwordx4 v[178:179], off
	v_lshl_add_u64 v[178:179], v[238:239], 0, s[16:17]
	s_mov_b32 m0, s74
	s_nop 0
	global_load_lds_dwordx4 v[178:179], off
	v_lshl_add_u64 v[178:179], v[240:241], 0, s[16:17]
	s_mov_b32 m0, s75
	s_nop 0
	global_load_lds_dwordx4 v[178:179], off
	s_waitcnt vmcnt(8)
	s_waitcnt lgkmcnt(0)
	s_barrier
	s_setprio 1
	s_waitcnt lgkmcnt(0)
	v_mfma_f32_16x16x32_bf16 v[62:65], v[142:145], v[190:193], v[62:65]
	v_mfma_f32_16x16x32_bf16 v[58:61], v[150:153], v[190:193], v[58:61]
	v_mfma_f32_16x16x32_bf16 v[46:49], v[142:145], v[198:201], v[46:49]
	v_mfma_f32_16x16x32_bf16 v[42:45], v[150:153], v[198:201], v[42:45]
	v_mfma_f32_16x16x32_bf16 v[30:33], v[142:145], v[206:209], v[30:33]
	v_mfma_f32_16x16x32_bf16 v[26:29], v[150:153], v[206:209], v[26:29]
	v_mfma_f32_16x16x32_bf16 v[14:17], v[142:145], v[214:217], v[14:17]
	v_mfma_f32_16x16x32_bf16 v[10:13], v[150:153], v[214:217], v[10:13]
	v_mfma_f32_16x16x32_bf16 v[62:65], v[146:149], v[194:197], v[62:65]
	v_mfma_f32_16x16x32_bf16 v[58:61], v[154:157], v[194:197], v[58:61]
	v_mfma_f32_16x16x32_bf16 v[46:49], v[146:149], v[202:205], v[46:49]
	v_mfma_f32_16x16x32_bf16 v[42:45], v[154:157], v[202:205], v[42:45]
	v_mfma_f32_16x16x32_bf16 v[30:33], v[146:149], v[210:213], v[30:33]
	v_mfma_f32_16x16x32_bf16 v[26:29], v[154:157], v[210:213], v[26:29]
	v_mfma_f32_16x16x32_bf16 v[14:17], v[146:149], v[218:221], v[14:17]
	v_mfma_f32_16x16x32_bf16 v[10:13], v[154:157], v[218:221], v[10:13]
	v_mfma_f32_16x16x32_bf16 v[54:57], v[162:165], v[190:193], v[54:57]
	v_mfma_f32_16x16x32_bf16 v[50:53], v[170:173], v[190:193], v[50:53]
	v_mfma_f32_16x16x32_bf16 v[38:41], v[162:165], v[198:201], v[38:41]
	v_mfma_f32_16x16x32_bf16 v[34:37], v[170:173], v[198:201], v[34:37]
	v_mfma_f32_16x16x32_bf16 v[22:25], v[162:165], v[206:209], v[22:25]
	v_mfma_f32_16x16x32_bf16 v[18:21], v[170:173], v[206:209], v[18:21]
	v_mfma_f32_16x16x32_bf16 v[6:9], v[162:165], v[214:217], v[6:9]
	v_mfma_f32_16x16x32_bf16 v[2:5], v[170:173], v[214:217], v[2:5]
	v_mfma_f32_16x16x32_bf16 v[54:57], v[166:169], v[194:197], v[54:57]
	v_mfma_f32_16x16x32_bf16 v[50:53], v[174:177], v[194:197], v[50:53]
	v_mfma_f32_16x16x32_bf16 v[38:41], v[166:169], v[202:205], v[38:41]
	v_mfma_f32_16x16x32_bf16 v[34:37], v[174:177], v[202:205], v[34:37]
	v_mfma_f32_16x16x32_bf16 v[22:25], v[166:169], v[210:213], v[22:25]
	v_mfma_f32_16x16x32_bf16 v[18:21], v[174:177], v[210:213], v[18:21]
	v_mfma_f32_16x16x32_bf16 v[6:9], v[166:169], v[218:221], v[6:9]
	v_mfma_f32_16x16x32_bf16 v[2:5], v[174:177], v[218:221], v[2:5]
	s_setprio 0
	s_barrier
	s_add_i32 s49, s49, 2
	s_add_u32 s38, s38, 0x100
	s_addc_u32 s39, s39, 0
	s_add_u32 s46, s46, 0x100
	s_addc_u32 s47, s47, 0
	s_cmp_gt_u32 s49, 29
	s_cbranch_scc0 .LBB0_1018
	s_and_b64 vcc, exec, s[34:35]
	s_cbranch_vccnz .LBB0_1021
	s_barrier

.LBB0_1218:
	s_andn2_b64 vcc, exec, s[54:55]
	s_mov_b64 s[10:11], -1
	s_cbranch_vccnz .LBB0_1010
	s_andn2_b64 vcc, exec, s[14:15]
	s_cbranch_vccz .LBB0_1009
	s_barrier
	s_branch .LBB0_1009

.LBB0_1222:
	s_add_u32 s8, s0, s69
	s_addc_u32 s9, s1, 0
	s_load_dwordx2 s[28:29], s[8:9], 0x118
	v_readlane_b32 s2, v255, 43
	s_cmp_lg_u32 s2, 0
	s_mov_b32 s66, 0x3f22f983
	s_cbranch_scc1 .LBB0_1327
	s_add_i32 s6, s6, s33
	v_readlane_b32 s7, v255, 17
	s_sub_i32 s7, s6, s7
	s_ashr_i32 s8, s7, 31
	s_abs_i32 s7, s7
	v_readlane_b32 s9, v255, 20
	s_mul_hi_u32 s9, s7, s9
	v_readlane_b32 s10, v255, 21
	s_mul_i32 s9, s9, s10
	s_sub_i32 s7, s7, s9
	s_sub_i32 s9, s7, s10
	s_cmp_ge_u32 s7, s10
	s_cselect_b32 s7, s9, s7
	s_sub_i32 s9, s7, s10
	s_cmp_ge_u32 s7, s10
	s_cselect_b32 s7, s9, s7
	s_xor_b32 s7, s7, s8
	v_mov_b32_e32 v16, v0
	s_sub_i32 s7, s7, s8
	s_cmp_gt_i32 s7, 15
	v_readfirstlane_b32 s30, v16
	s_cbranch_scc1 .LBB0_1237
	v_lshlrev_b32_e32 v2, 4, v16
	s_waitcnt lgkmcnt(0)
	v_add_u32_e32 v3, 0x2000, v2
	v_ashrrev_i32_e32 v4, 31, v3
	v_lshrrev_b32_e32 v4, 22, v4
	v_add_u32_e32 v4, v3, v4
	v_ashrrev_i32_e32 v10, 10, v4
	v_mul_i32_i24_e32 v5, 0x400, v10
	v_sub_u32_e32 v3, v3, v5
	v_lshrrev_b32_e32 v5, 4, v3
	v_bitop3_b32 v3, v5, v3, 32 bitop3:0x6c
	v_ashrrev_i32_e32 v5, 31, v3
	v_lshrrev_b32_e32 v5, 26, v5
	v_add_u32_e32 v5, v3, v5
	v_ashrrev_i32_e32 v11, 6, v5
	v_and_b32_e32 v5, 0xc0, v5
	v_sub_u32_e32 v3, v3, v5
	v_lshlrev_b32_e32 v4, 5, v10
	v_ashrrev_i16_sdwa v3, v224, sext(v3) dst_sel:DWORD dst_unused:UNUSED_PAD src0_sel:DWORD src1_sel:BYTE_0
	v_and_b32_e32 v4, 32, v4
	v_bfe_i32 v12, v3, 0, 16
	v_add_u32_e32 v3, v4, v12
	v_lshlrev_b32_e32 v4, 3, v10
	v_and_b32_e32 v4, 0xffff0, v4
	v_add_lshl_u32 v4, v11, v4, 12
	s_waitcnt vmcnt(0)
	v_lshl_add_u32 v132, v3, 1, v4
	v_bfe_i32 v4, v16, 27, 1
	v_lshrrev_b32_e32 v4, 22, v4
	v_add_u32_e32 v4, v2, v4
	v_and_b32_e32 v4, 0xfffffc00, v4
	v_sub_u32_e32 v2, v2, v4
	v_lshrrev_b32_e32 v4, 4, v2
	v_bitop3_b32 v2, v4, v2, 32 bitop3:0x6c
	s_add_u32 s8, s28, 0x1ff00000
	v_ashrrev_i32_e32 v4, 31, v2
	s_addc_u32 s9, s29, 0
	v_ashrrev_i32_e32 v3, 31, v16
	v_lshrrev_b32_e32 v4, 26, v4
	s_add_u32 s21, s28, 0x15800000
	v_lshrrev_b32_e32 v3, 26, v3
	v_add_u32_e32 v4, v2, v4
	s_addc_u32 s42, s29, 0
	v_add_u32_e32 v3, v16, v3
	v_ashrrev_i32_e32 v14, 6, v4
	v_and_b32_e32 v4, 0xc0, v4
	s_add_u32 s18, s0, s69
	v_ashrrev_i32_e32 v13, 6, v3
	v_sub_u32_e32 v2, v2, v4
	s_addc_u32 s19, s1, 0
	s_ashr_i32 s10, s7, 2
	v_lshlrev_b32_e32 v3, 5, v13
	v_ashrrev_i16_sdwa v2, v224, sext(v2) dst_sel:DWORD dst_unused:UNUSED_PAD src0_sel:DWORD src1_sel:BYTE_0
	s_ashr_i32 s31, s30, 6
	s_and_b32 s44, s7, 3
	v_and_b32_e32 v3, 32, v3
	v_bfe_i32 v15, v2, 0, 16
	s_ashr_i32 s11, s10, 31
	s_ashr_i32 s34, s30, 8
	s_lshl_b32 s43, s31, 10
	v_add_u32_e32 v2, v3, v15
	v_lshlrev_b32_e32 v3, 3, v13
	s_lshl_b32 s24, s44, 20
	s_lshl_b64 s[14:15], s[10:11], 20
	v_and_b32_e32 v3, 0xffff0, v3
	s_add_u32 s14, s21, s14
	v_add_lshl_u32 v3, v14, v3, 12
	s_addc_u32 s15, s42, s15
	s_add_i32 s11, s43, 0
	v_lshl_add_u32 v134, v2, 1, v3
	s_add_i32 m0, s11, 0x10000
	s_load_dwordx2 s[18:19], s[18:19], 0x110
	global_load_lds_dwordx4 v134, s[14:15]
	s_add_i32 m0, s11, 0x12000
	s_add_u32 s22, s14, 0x80000
	global_load_lds_dwordx4 v132, s[14:15]
	s_addc_u32 s23, s15, 0
	s_add_i32 m0, s11, 0x14000
	v_mov_b32_e32 v135, v181
	global_load_lds_dwordx4 v134, s[22:23]
	s_add_i32 m0, s11, 0x16000
	v_mov_b32_e32 v133, v181
	global_load_lds_dwordx4 v132, s[22:23]
	s_add_u32 s22, s8, s24
	s_addc_u32 s23, s9, 0
	s_add_i32 s45, s11, 0x2000
	s_mov_b32 m0, s11
	s_add_u32 s24, s22, 0x80000
	global_load_lds_dwordx4 v134, s[22:23]
	s_mov_b32 m0, s45
	s_addc_u32 s25, s23, 0
	s_add_i32 s46, s11, 0x4000
	global_load_lds_dwordx4 v132, s[22:23]
	s_mov_b32 m0, s46
	s_add_i32 s47, s11, 0x6000
	global_load_lds_dwordx4 v134, s[24:25]
	s_mov_b32 m0, s47
	s_cmp_eq_u32 s34, 1
	global_load_lds_dwordx4 v132, s[24:25]
	v_lshl_add_u64 v[8:9], s[14:15], 0, v[134:135]
	v_lshl_add_u64 v[6:7], s[14:15], 0, v[132:133]
	v_lshl_add_u64 v[2:3], s[22:23], 0, v[134:135]
	s_cselect_b64 s[24:25], -1, 0
	s_cmp_lg_u32 s34, 1
	v_lshl_add_u64 v[4:5], s[22:23], 0, v[132:133]
	s_cbranch_scc0 .LBB0_1226
	s_barrier

.LBB0_1230:
	s_add_u32 s38, s36, 0xfff80080
	s_addc_u32 s39, s37, -1
	s_add_i32 s64, 0, 0x10000
	s_cmp_eq_u32 s63, 28
	s_cselect_b32 s41, s57, s39
	s_cselect_b32 s40, s58, s38
	v_add_u32_e32 v155, s64, v153
	s_cselect_b32 s39, s59, s62
	s_cselect_b32 s38, s60, s61
	s_add_i32 s74, 0, 0x14000
	ds_read_b128 v[140:143], v155
	ds_read_b128 v[144:147], v155 offset:1024
	ds_read_b128 v[148:151], v155 offset:2048
	ds_read_b128 v[156:159], v155 offset:3072
	v_add_u32_e32 v155, s74, v153
	ds_read_b128 v[160:163], v155
	ds_read_b128 v[164:167], v155 offset:1024
	ds_read_b128 v[168:171], v155 offset:2048
	ds_read_b128 v[172:175], v155 offset:3072
	v_lshl_add_u64 v[218:219], s[36:37], 0, v[136:137]
	s_add_i32 m0, s11, 0xc000
	ds_read_b128 v[176:179], v154
	ds_read_b128 v[190:193], v154 offset:1024
	ds_read_b128 v[194:197], v154 offset:2048
	ds_read_b128 v[198:201], v154 offset:3072
	ds_read_b128 v[202:205], v154 offset:4096
	ds_read_b128 v[206:209], v154 offset:5120
	ds_read_b128 v[210:213], v154 offset:6144
	ds_read_b128 v[214:217], v154 offset:7168
	global_load_lds_dwordx4 v[218:219], off
	v_lshl_add_u64 v[218:219], s[36:37], 0, v[138:139]
	s_add_i32 m0, s11, 0xe000
	s_nop 0
	global_load_lds_dwordx4 v[218:219], off
	s_waitcnt vmcnt(8)
	s_waitcnt lgkmcnt(0)
	s_barrier
	s_setprio 1
	s_waitcnt lgkmcnt(0)
	v_mfma_f32_16x16x32_bf16 v[126:129], v[140:143], v[176:179], v[126:129]
	v_mfma_f32_16x16x32_bf16 v[122:125], v[148:151], v[176:179], v[122:125]
	v_mfma_f32_16x16x32_bf16 v[110:113], v[140:143], v[194:197], v[110:113]
	v_mfma_f32_16x16x32_bf16 v[106:109], v[148:151], v[194:197], v[106:109]
	v_mfma_f32_16x16x32_bf16 v[94:97], v[140:143], v[202:205], v[94:97]
	v_mfma_f32_16x16x32_bf16 v[90:93], v[148:151], v[202:205], v[90:93]
	v_mfma_f32_16x16x32_bf16 v[78:81], v[140:143], v[210:213], v[78:81]
	v_mfma_f32_16x16x32_bf16 v[74:77], v[148:151], v[210:213], v[74:77]
	v_mfma_f32_16x16x32_bf16 v[126:129], v[144:147], v[190:193], v[126:129]
	v_mfma_f32_16x16x32_bf16 v[122:125], v[156:159], v[190:193], v[122:125]
	v_mfma_f32_16x16x32_bf16 v[110:113], v[144:147], v[198:201], v[110:113]
	v_mfma_f32_16x16x32_bf16 v[106:109], v[156:159], v[198:201], v[106:109]
	v_mfma_f32_16x16x32_bf16 v[94:97], v[144:147], v[206:209], v[94:97]
	v_mfma_f32_16x16x32_bf16 v[90:93], v[156:159], v[206:209], v[90:93]
	v_mfma_f32_16x16x32_bf16 v[78:81], v[144:147], v[214:217], v[78:81]
	v_mfma_f32_16x16x32_bf16 v[74:77], v[156:159], v[214:217], v[74:77]
	v_mfma_f32_16x16x32_bf16 v[118:121], v[160:163], v[176:179], v[118:121]
	v_mfma_f32_16x16x32_bf16 v[114:117], v[168:171], v[176:179], v[114:117]
	v_mfma_f32_16x16x32_bf16 v[102:105], v[160:163], v[194:197], v[102:105]
	v_mfma_f32_16x16x32_bf16 v[98:101], v[168:171], v[194:197], v[98:101]
	v_mfma_f32_16x16x32_bf16 v[86:89], v[160:163], v[202:205], v[86:89]
	v_mfma_f32_16x16x32_bf16 v[82:85], v[168:171], v[202:205], v[82:85]
	v_mfma_f32_16x16x32_bf16 v[70:73], v[160:163], v[210:213], v[70:73]
	v_mfma_f32_16x16x32_bf16 v[66:69], v[168:171], v[210:213], v[66:69]
	v_mfma_f32_16x16x32_bf16 v[118:121], v[164:167], v[190:193], v[118:121]
	v_mfma_f32_16x16x32_bf16 v[114:117], v[172:175], v[190:193], v[114:117]
	v_mfma_f32_16x16x32_bf16 v[102:105], v[164:167], v[198:201], v[102:105]
	v_mfma_f32_16x16x32_bf16 v[98:101], v[172:175], v[198:201], v[98:101]
	v_mfma_f32_16x16x32_bf16 v[86:89], v[164:167], v[206:209], v[86:89]
	v_mfma_f32_16x16x32_bf16 v[82:85], v[172:175], v[206:209], v[82:85]
	v_mfma_f32_16x16x32_bf16 v[70:73], v[164:167], v[214:217], v[70:73]
	v_mfma_f32_16x16x32_bf16 v[66:69], v[172:175], v[214:217], v[66:69]
	s_setprio 0
	s_barrier
	s_add_i32 s64, s64, s43
	v_lshl_add_u64 v[218:219], s[38:39], 0, v[134:135]
	s_mov_b32 m0, s64
	ds_read_b128 v[176:179], v154 offset:16384
	ds_read_b128 v[190:193], v154 offset:17408
	ds_read_b128 v[194:197], v154 offset:18432
	ds_read_b128 v[198:201], v154 offset:19456
	ds_read_b128 v[202:205], v154 offset:20480
	ds_read_b128 v[206:209], v154 offset:21504
	ds_read_b128 v[210:213], v154 offset:22528
	ds_read_b128 v[214:217], v154 offset:23552
	global_load_lds_dwordx4 v[218:219], off
	s_add_i32 m0, s64, 0x2000
	s_add_u32 s70, s38, 0x80000
	v_lshl_add_u64 v[220:221], s[38:39], 0, v[132:133]
	s_addc_u32 s71, s39, 0
	s_add_i32 s64, s74, s43
	global_load_lds_dwordx4 v[220:221], off
	v_lshl_add_u64 v[222:223], s[70:71], 0, v[134:135]
	s_mov_b32 m0, s64
	v_lshl_add_u64 v[238:239], s[40:41], 0, v[132:133]
	global_load_lds_dwordx4 v[222:223], off
	v_lshl_add_u64 v[222:223], s[70:71], 0, v[132:133]
	s_add_i32 m0, s64, 0x2000
	s_nop 0
	global_load_lds_dwordx4 v[222:223], off
	v_lshl_add_u64 v[222:223], s[40:41], 0, v[134:135]
	s_mov_b32 m0, s11
	s_nop 0
	global_load_lds_dwordx4 v[222:223], off
	s_mov_b32 m0, s45
	s_nop 0
	global_load_lds_dwordx4 v[238:239], off
	s_waitcnt vmcnt(8)
	s_waitcnt lgkmcnt(0)
	s_barrier
	s_setprio 1
	s_waitcnt lgkmcnt(0)
	v_mfma_f32_16x16x32_bf16 v[62:65], v[140:143], v[176:179], v[62:65]
	v_mfma_f32_16x16x32_bf16 v[58:61], v[148:151], v[176:179], v[58:61]
	v_mfma_f32_16x16x32_bf16 v[46:49], v[140:143], v[194:197], v[46:49]
	v_mfma_f32_16x16x32_bf16 v[42:45], v[148:151], v[194:197], v[42:45]
	v_mfma_f32_16x16x32_bf16 v[30:33], v[140:143], v[202:205], v[30:33]
	v_mfma_f32_16x16x32_bf16 v[26:29], v[148:151], v[202:205], v[26:29]
	v_mfma_f32_16x16x32_bf16 v[14:17], v[140:143], v[210:213], v[14:17]
	v_mfma_f32_16x16x32_bf16 v[10:13], v[148:151], v[210:213], v[10:13]
	v_mfma_f32_16x16x32_bf16 v[62:65], v[144:147], v[190:193], v[62:65]
	v_mfma_f32_16x16x32_bf16 v[58:61], v[156:159], v[190:193], v[58:61]
	v_mfma_f32_16x16x32_bf16 v[46:49], v[144:147], v[198:201], v[46:49]
	v_mfma_f32_16x16x32_bf16 v[42:45], v[156:159], v[198:201], v[42:45]
	v_mfma_f32_16x16x32_bf16 v[30:33], v[144:147], v[206:209], v[30:33]
	v_mfma_f32_16x16x32_bf16 v[26:29], v[156:159], v[206:209], v[26:29]
	v_mfma_f32_16x16x32_bf16 v[14:17], v[144:147], v[214:217], v[14:17]
	v_mfma_f32_16x16x32_bf16 v[10:13], v[156:159], v[214:217], v[10:13]
	v_mfma_f32_16x16x32_bf16 v[54:57], v[160:163], v[176:179], v[54:57]
	v_mfma_f32_16x16x32_bf16 v[50:53], v[168:171], v[176:179], v[50:53]
	v_mfma_f32_16x16x32_bf16 v[38:41], v[160:163], v[194:197], v[38:41]
	v_mfma_f32_16x16x32_bf16 v[34:37], v[168:171], v[194:197], v[34:37]
	v_mfma_f32_16x16x32_bf16 v[22:25], v[160:163], v[202:205], v[22:25]
	v_mfma_f32_16x16x32_bf16 v[18:21], v[168:171], v[202:205], v[18:21]
	v_mfma_f32_16x16x32_bf16 v[6:9], v[160:163], v[210:213], v[6:9]
	v_mfma_f32_16x16x32_bf16 v[2:5], v[168:171], v[210:213], v[2:5]
	v_mfma_f32_16x16x32_bf16 v[54:57], v[164:167], v[190:193], v[54:57]
	v_mfma_f32_16x16x32_bf16 v[50:53], v[172:175], v[190:193], v[50:53]
	v_mfma_f32_16x16x32_bf16 v[38:41], v[164:167], v[198:201], v[38:41]
	v_mfma_f32_16x16x32_bf16 v[34:37], v[172:175], v[198:201], v[34:37]
	v_mfma_f32_16x16x32_bf16 v[22:25], v[164:167], v[206:209], v[22:25]
	v_mfma_f32_16x16x32_bf16 v[18:21], v[172:175], v[206:209], v[18:21]
	v_mfma_f32_16x16x32_bf16 v[6:9], v[164:167], v[214:217], v[6:9]
	v_mfma_f32_16x16x32_bf16 v[2:5], v[172:175], v[214:217], v[2:5]
	s_setprio 0
	s_barrier
	s_add_i32 s64, 0, 0x18000
	v_add_u32_e32 v155, s64, v153
	s_add_i32 s70, 0, 0x1c000
	ds_read_b128 v[140:143], v155
	ds_read_b128 v[144:147], v155 offset:1024
	ds_read_b128 v[148:151], v155 offset:2048
	ds_read_b128 v[156:159], v155 offset:3072
	v_add_u32_e32 v155, s70, v153
	ds_read_b128 v[160:163], v155
	ds_read_b128 v[164:167], v155 offset:1024
	ds_read_b128 v[168:171], v155 offset:2048
	ds_read_b128 v[172:175], v155 offset:3072
	s_add_u32 s40, s40, 0x80000
	s_addc_u32 s41, s41, 0
	s_mov_b32 m0, s46
	v_lshl_add_u64 v[240:241], s[40:41], 0, v[134:135]
	ds_read_b128 v[176:179], v154 offset:32768
	ds_read_b128 v[190:193], v154 offset:33792
	ds_read_b128 v[194:197], v154 offset:34816
	ds_read_b128 v[198:201], v154 offset:35840
	ds_read_b128 v[202:205], v154 offset:36864
	ds_read_b128 v[206:209], v154 offset:37888
	ds_read_b128 v[210:213], v154 offset:38912
	ds_read_b128 v[214:217], v154 offset:39936
	global_load_lds_dwordx4 v[240:241], off
	v_lshl_add_u64 v[240:241], s[40:41], 0, v[132:133]
	s_mov_b32 m0, s47
	s_nop 0
	global_load_lds_dwordx4 v[240:241], off
	s_waitcnt vmcnt(8)
	s_waitcnt lgkmcnt(0)
	s_barrier
	s_setprio 1
	s_waitcnt lgkmcnt(0)
	v_mfma_f32_16x16x32_bf16 v[126:129], v[140:143], v[176:179], v[126:129]
	v_mfma_f32_16x16x32_bf16 v[122:125], v[148:151], v[176:179], v[122:125]
	v_mfma_f32_16x16x32_bf16 v[110:113], v[140:143], v[194:197], v[110:113]
	v_mfma_f32_16x16x32_bf16 v[106:109], v[148:151], v[194:197], v[106:109]
	v_mfma_f32_16x16x32_bf16 v[94:97], v[140:143], v[202:205], v[94:97]
	v_mfma_f32_16x16x32_bf16 v[90:93], v[148:151], v[202:205], v[90:93]
	v_mfma_f32_16x16x32_bf16 v[78:81], v[140:143], v[210:213], v[78:81]
	v_mfma_f32_16x16x32_bf16 v[74:77], v[148:151], v[210:213], v[74:77]
	v_mfma_f32_16x16x32_bf16 v[126:129], v[144:147], v[190:193], v[126:129]
	v_mfma_f32_16x16x32_bf16 v[122:125], v[156:159], v[190:193], v[122:125]
	v_mfma_f32_16x16x32_bf16 v[110:113], v[144:147], v[198:201], v[110:113]
	v_mfma_f32_16x16x32_bf16 v[106:109], v[156:159], v[198:201], v[106:109]
	v_mfma_f32_16x16x32_bf16 v[94:97], v[144:147], v[206:209], v[94:97]
	v_mfma_f32_16x16x32_bf16 v[90:93], v[156:159], v[206:209], v[90:93]
	v_mfma_f32_16x16x32_bf16 v[78:81], v[144:147], v[214:217], v[78:81]
	v_mfma_f32_16x16x32_bf16 v[74:77], v[156:159], v[214:217], v[74:77]
	v_mfma_f32_16x16x32_bf16 v[118:121], v[160:163], v[176:179], v[118:121]
	v_mfma_f32_16x16x32_bf16 v[114:117], v[168:171], v[176:179], v[114:117]
	v_mfma_f32_16x16x32_bf16 v[102:105], v[160:163], v[194:197], v[102:105]
	v_mfma_f32_16x16x32_bf16 v[98:101], v[168:171], v[194:197], v[98:101]
	v_mfma_f32_16x16x32_bf16 v[86:89], v[160:163], v[202:205], v[86:89]
	v_mfma_f32_16x16x32_bf16 v[82:85], v[168:171], v[202:205], v[82:85]
	v_mfma_f32_16x16x32_bf16 v[70:73], v[160:163], v[210:213], v[70:73]
	v_mfma_f32_16x16x32_bf16 v[66:69], v[168:171], v[210:213], v[66:69]
	v_mfma_f32_16x16x32_bf16 v[118:121], v[164:167], v[190:193], v[118:121]
	v_mfma_f32_16x16x32_bf16 v[114:117], v[172:175], v[190:193], v[114:117]
	v_mfma_f32_16x16x32_bf16 v[102:105], v[164:167], v[198:201], v[102:105]
	v_mfma_f32_16x16x32_bf16 v[98:101], v[172:175], v[198:201], v[98:101]
	v_mfma_f32_16x16x32_bf16 v[86:89], v[164:167], v[206:209], v[86:89]
	v_mfma_f32_16x16x32_bf16 v[82:85], v[172:175], v[206:209], v[82:85]
	v_mfma_f32_16x16x32_bf16 v[70:73], v[164:167], v[214:217], v[70:73]
	v_mfma_f32_16x16x32_bf16 v[66:69], v[172:175], v[214:217], v[66:69]
	s_setprio 0
	s_barrier
	s_add_i32 s40, s64, s43
	v_lshl_add_u64 v[218:219], v[218:219], 0, s[16:17]
	s_mov_b32 m0, s40
	ds_read_b128 v[176:179], v154 offset:49152
	ds_read_b128 v[190:193], v154 offset:50176
	ds_read_b128 v[194:197], v154 offset:51200
	ds_read_b128 v[198:201], v154 offset:52224
	ds_read_b128 v[202:205], v154 offset:53248
	ds_read_b128 v[206:209], v154 offset:54272
	ds_read_b128 v[210:213], v154 offset:55296
	ds_read_b128 v[214:217], v154 offset:56320
	global_load_lds_dwordx4 v[218:219], off
	s_add_i32 m0, s40, 0x2000
	s_add_u32 s38, s38, 0x80080
	v_lshl_add_u64 v[218:219], v[220:221], 0, s[16:17]
	s_addc_u32 s39, s39, 0
	s_add_i32 s40, s70, s43
	global_load_lds_dwordx4 v[218:219], off
	v_lshl_add_u64 v[218:219], s[38:39], 0, v[134:135]
	s_mov_b32 m0, s40
	s_nop 0
	global_load_lds_dwordx4 v[218:219], off
	v_lshl_add_u64 v[218:219], s[38:39], 0, v[132:133]
	s_add_i32 m0, s40, 0x2000
	s_nop 0
	global_load_lds_dwordx4 v[218:219], off
	v_lshl_add_u64 v[218:219], v[222:223], 0, s[16:17]
	s_mov_b32 m0, s50
	s_nop 0
	global_load_lds_dwordx4 v[218:219], off
	v_lshl_add_u64 v[218:219], v[238:239], 0, s[16:17]
	s_mov_b32 m0, s51
	s_nop 0
	global_load_lds_dwordx4 v[218:219], off
	s_waitcnt vmcnt(8)
	s_waitcnt lgkmcnt(0)
	s_barrier
	s_setprio 1
	s_waitcnt lgkmcnt(0)
	v_mfma_f32_16x16x32_bf16 v[62:65], v[140:143], v[176:179], v[62:65]
	v_mfma_f32_16x16x32_bf16 v[58:61], v[148:151], v[176:179], v[58:61]
	v_mfma_f32_16x16x32_bf16 v[46:49], v[140:143], v[194:197], v[46:49]
	v_mfma_f32_16x16x32_bf16 v[42:45], v[148:151], v[194:197], v[42:45]
	v_mfma_f32_16x16x32_bf16 v[30:33], v[140:143], v[202:205], v[30:33]
	v_mfma_f32_16x16x32_bf16 v[26:29], v[148:151], v[202:205], v[26:29]
	v_mfma_f32_16x16x32_bf16 v[14:17], v[140:143], v[210:213], v[14:17]
	v_mfma_f32_16x16x32_bf16 v[10:13], v[148:151], v[210:213], v[10:13]
	v_mfma_f32_16x16x32_bf16 v[62:65], v[144:147], v[190:193], v[62:65]
	v_mfma_f32_16x16x32_bf16 v[58:61], v[156:159], v[190:193], v[58:61]
	v_mfma_f32_16x16x32_bf16 v[46:49], v[144:147], v[198:201], v[46:49]
	v_mfma_f32_16x16x32_bf16 v[42:45], v[156:159], v[198:201], v[42:45]
	v_mfma_f32_16x16x32_bf16 v[30:33], v[144:147], v[206:209], v[30:33]
	v_mfma_f32_16x16x32_bf16 v[26:29], v[156:159], v[206:209], v[26:29]
	v_mfma_f32_16x16x32_bf16 v[14:17], v[144:147], v[214:217], v[14:17]
	v_mfma_f32_16x16x32_bf16 v[10:13], v[156:159], v[214:217], v[10:13]
	v_mfma_f32_16x16x32_bf16 v[54:57], v[160:163], v[176:179], v[54:57]
	v_mfma_f32_16x16x32_bf16 v[50:53], v[168:171], v[176:179], v[50:53]
	v_mfma_f32_16x16x32_bf16 v[38:41], v[160:163], v[194:197], v[38:41]
	v_mfma_f32_16x16x32_bf16 v[34:37], v[168:171], v[194:197], v[34:37]
	v_mfma_f32_16x16x32_bf16 v[22:25], v[160:163], v[202:205], v[22:25]
	v_mfma_f32_16x16x32_bf16 v[18:21], v[168:171], v[202:205], v[18:21]
	v_mfma_f32_16x16x32_bf16 v[6:9], v[160:163], v[210:213], v[6:9]
	v_mfma_f32_16x16x32_bf16 v[2:5], v[168:171], v[210:213], v[2:5]
	v_mfma_f32_16x16x32_bf16 v[54:57], v[164:167], v[190:193], v[54:57]
	v_mfma_f32_16x16x32_bf16 v[50:53], v[172:175], v[190:193], v[50:53]
	v_mfma_f32_16x16x32_bf16 v[38:41], v[164:167], v[198:201], v[38:41]
	v_mfma_f32_16x16x32_bf16 v[34:37], v[172:175], v[198:201], v[34:37]
	v_mfma_f32_16x16x32_bf16 v[22:25], v[164:167], v[206:209], v[22:25]
	v_mfma_f32_16x16x32_bf16 v[18:21], v[172:175], v[206:209], v[18:21]
	v_mfma_f32_16x16x32_bf16 v[6:9], v[164:167], v[214:217], v[6:9]
	v_mfma_f32_16x16x32_bf16 v[2:5], v[172:175], v[214:217], v[2:5]
	s_setprio 0
	s_barrier
	s_add_i32 s63, s63, 2
	s_add_u32 s36, s36, 0x100
	s_addc_u32 s37, s37, 0
	s_add_u32 s61, s61, 0x100
	s_addc_u32 s62, s62, 0
	s_cmp_gt_u32 s63, 29
	s_cbranch_scc0 .LBB0_1230
	s_and_b64 vcc, exec, s[30:31]
	s_cbranch_vccnz .LBB0_1233
	s_barrier
.LBB0_1233:
	v_mov_b32_e32 v140, v131
	v_mov_b32_e32 v141, v152
	s_lshl_b32 s36, s56, 8
	s_lshl_b32 s37, s55, 8
	s_add_i32 s36, s36, s48
	v_add_u32_e32 v140, s36, v140
	s_or_b32 s36, s37, s49
	v_lshl_add_u32 v149, v141, 2, s36
	v_ashrrev_i32_e32 v141, 31, v140
	v_lshl_add_u64 v[142:143], v[140:141], 3, s[26:27]
	global_load_dwordx2 v[144:145], v[142:143], off
	v_and_b32_e32 v155, 0x3fc, v149
	s_movk_i32 s36, 0x200
	v_and_b32_e32 v156, 0x1fc, v149
	v_add_u32_e32 v158, 16, v149
	v_and_b32_e32 v159, 0x3fc, v158
	v_add_u32_e32 v162, 0x80, v149
	v_and_b32_e32 v163, 0x3fc, v162
	v_readlane_b32 s64, v255, 40
	s_mov_b32 s68, 0xff61b1e6
	s_mov_b32 s74, 0x24600000
	s_waitcnt vmcnt(0)
	v_ffbh_u32_e32 v141, v145
	v_min_u32_e32 v141, 32, v141
	v_lshlrev_b64 v[144:145], v141, v[144:145]
	v_min_u32_e32 v144, 1, v144
	v_or_b32_e32 v144, v145, v144
	v_cvt_f32_u32_e32 v144, v144
	v_sub_u32_e32 v141, 32, v141
	v_ldexp_f32 v141, v144, v141
	v_mul_f32_e32 v141, 0x30800000, v141
	v_fmamk_f32 v141, v141, 0x3a000000, v1
	v_cmp_gt_f32_e32 vcc, s65, v141
	v_mul_f32_e32 v144, 0x4b800000, v141
	s_nop 0
	v_cndmask_b32_e32 v141, v141, v144, vcc
	v_rsq_f32_e32 v141, v141
	s_nop 0
	v_mul_f32_e32 v144, 0x45800000, v141
	v_cndmask_b32_e32 v148, v141, v144, vcc
	v_and_b32_e32 v141, 0xfffffc00, v149
	v_pk_mul_f32 v[146:147], v[128:129], v[148:149] op_sel_hi:[1,0]
	v_cmp_gt_u32_e32 vcc, s36, v155
	v_add_u32_e32 v128, v141, v140
	v_ashrrev_i32_e32 v129, 31, v128
	v_cndmask_b32_e32 v180, v230, v231, vcc
	v_pk_mul_f32 v[144:145], v[126:127], v[148:149] op_sel_hi:[1,0]
	v_lshl_add_u64 v[126:127], s[18:19], 0, v[180:181]
	v_lshlrev_b64 v[128:129], 11, v[128:129]
	v_lshl_add_u64 v[150:151], v[126:127], 0, v[128:129]
	v_lshlrev_b32_e32 v180, 2, v156
	v_lshl_add_u64 v[150:151], v[150:151], 0, v[180:181]
	global_store_dwordx4 v[150:151], v[144:147], off
	v_cmp_gt_u32_e32 vcc, s36, v159
	v_pk_mul_f32 v[160:161], v[120:121], v[148:149] op_sel_hi:[1,0]
	v_cvt_pk_bf16_f32 v144, v144, v145
	v_cvt_pk_bf16_f32 v145, v146, v147
	v_lshl_add_u64 v[146:147], s[28:29], 0, v[128:129]
	v_lshlrev_b32_e32 v128, 1, v155
	v_mov_b32_e32 v129, v181
	v_lshl_add_u64 v[146:147], v[146:147], 0, v[128:129]
	v_and_b32_e32 v155, 0xfffffc00, v158
	global_store_dwordx2 v[146:147], v[144:145], off
	v_pk_mul_f32 v[146:147], v[124:125], v[148:149] op_sel_hi:[1,0]
	v_add_u32_e32 v124, v155, v140
	v_pk_mul_f32 v[144:145], v[122:123], v[148:149] op_sel_hi:[1,0]
	v_cndmask_b32_e32 v122, v230, v231, vcc
	v_mov_b32_e32 v123, v181
	v_ashrrev_i32_e32 v125, 31, v124
	v_lshl_add_u64 v[122:123], s[18:19], 0, v[122:123]
	v_lshlrev_b64 v[150:151], 11, v[124:125]
	v_and_b32_e32 v124, 0x1fc, v158
	v_lshl_add_u64 v[156:157], v[122:123], 0, v[150:151]
	v_lshlrev_b32_e32 v124, 2, v124
	v_mov_b32_e32 v125, v181
	v_lshl_add_u64 v[156:157], v[156:157], 0, v[124:125]
	global_store_dwordx4 v[156:157], v[144:147], off
	v_cvt_pk_bf16_f32 v156, v144, v145
	v_cvt_pk_bf16_f32 v157, v146, v147
	v_cmp_gt_u32_e32 vcc, s36, v163
	v_pk_mul_f32 v[116:117], v[116:117], v[148:149] op_sel_hi:[1,0]
	v_lshl_add_u64 v[146:147], s[28:29], 0, v[150:151]
	v_lshlrev_b32_e32 v144, 1, v159
	v_mov_b32_e32 v145, v181
	v_lshl_add_u64 v[146:147], v[146:147], 0, v[144:145]
	global_store_dwordx2 v[146:147], v[156:157], off
	v_and_b32_e32 v156, 0xfffffc00, v162
	v_add_u32_e32 v120, v156, v140
	v_pk_mul_f32 v[158:159], v[118:119], v[148:149] op_sel_hi:[1,0]
	v_cndmask_b32_e32 v118, v230, v231, vcc
	v_mov_b32_e32 v119, v181
	v_ashrrev_i32_e32 v121, 31, v120
	v_lshl_add_u64 v[118:119], s[18:19], 0, v[118:119]
	v_lshlrev_b64 v[146:147], 11, v[120:121]
	v_and_b32_e32 v120, 0x1fc, v162
	v_lshl_add_u64 v[150:151], v[118:119], 0, v[146:147]
	v_lshlrev_b32_e32 v120, 2, v120
	v_mov_b32_e32 v121, v181
	v_lshl_add_u64 v[150:151], v[150:151], 0, v[120:121]
	global_store_dwordx4 v[150:151], v[158:161], off
	v_cvt_pk_bf16_f32 v150, v158, v159
	v_add_u32_e32 v162, 0x90, v149
	v_and_b32_e32 v157, 0xfffffc00, v162
	v_lshl_add_u64 v[158:159], s[28:29], 0, v[146:147]
	v_lshlrev_b32_e32 v146, 1, v163
	v_mov_b32_e32 v147, v181
	v_lshl_add_u64 v[158:159], v[158:159], 0, v[146:147]
	v_and_b32_e32 v163, 0x3fc, v162
	v_cvt_pk_bf16_f32 v151, v160, v161
	global_store_dwordx2 v[158:159], v[150:151], off
	v_cmp_gt_u32_e32 vcc, s36, v163
	v_add_u32_e32 v150, v157, v140
	v_pk_mul_f32 v[114:115], v[114:115], v[148:149] op_sel_hi:[1,0]
	v_cndmask_b32_e32 v148, v230, v231, vcc
	v_mov_b32_e32 v149, v181
	v_ashrrev_i32_e32 v151, 31, v150
	v_lshl_add_u64 v[148:149], s[18:19], 0, v[148:149]
	v_lshlrev_b64 v[158:159], 11, v[150:151]
	v_and_b32_e32 v150, 0x1fc, v162
	v_lshl_add_u64 v[160:161], v[148:149], 0, v[158:159]
	v_lshlrev_b32_e32 v150, 2, v150
	v_mov_b32_e32 v151, v181
	v_lshl_add_u64 v[160:161], v[160:161], 0, v[150:151]
	global_store_dwordx4 v[160:161], v[114:117], off
	v_cvt_pk_bf16_f32 v160, v114, v115
	v_cvt_pk_bf16_f32 v161, v116, v117
	v_add_u32_e32 v162, 16, v140
	s_mov_b64 s[36:37], -1
	v_lshl_add_u64 v[116:117], s[28:29], 0, v[158:159]
	v_lshlrev_b32_e32 v114, 1, v163
	v_mov_b32_e32 v115, v181
	v_lshl_add_u64 v[116:117], v[116:117], 0, v[114:115]
	global_store_dwordx2 v[116:117], v[160:161], off
	global_load_dwordx2 v[116:117], v[142:143], off offset:128
	s_waitcnt vmcnt(0)
	v_ffbh_u32_e32 v158, v117
	v_min_u32_e32 v158, 32, v158
	v_lshlrev_b64 v[116:117], v158, v[116:117]
	v_min_u32_e32 v116, 1, v116
	v_or_b32_e32 v116, v117, v116
	v_cvt_f32_u32_e32 v116, v116
	v_sub_u32_e32 v117, 32, v158
	v_add_u32_e32 v158, v141, v162
	v_ashrrev_i32_e32 v159, 31, v158
	v_ldexp_f32 v116, v116, v117
	v_mul_f32_e32 v116, 0x30800000, v116
	v_fmamk_f32 v116, v116, 0x3a000000, v1
	v_cmp_gt_f32_e32 vcc, s65, v116
	v_mul_f32_e32 v117, 0x4b800000, v116
	v_lshlrev_b64 v[158:159], 11, v[158:159]
	v_cndmask_b32_e32 v116, v116, v117, vcc
	v_rsq_f32_e32 v116, v116
	v_lshl_add_u64 v[160:161], v[126:127], 0, v[158:159]
	v_lshl_add_u64 v[160:161], v[160:161], 0, v[180:181]
	v_mul_f32_e32 v117, 0x45800000, v116
	v_cndmask_b32_e32 v116, v116, v117, vcc
	v_pk_mul_f32 v[112:113], v[112:113], v[116:117] op_sel_hi:[1,0]
	v_pk_mul_f32 v[110:111], v[110:111], v[116:117] op_sel_hi:[1,0]
	global_store_dwordx4 v[160:161], v[110:113], off
	v_pk_mul_f32 v[108:109], v[108:109], v[116:117] op_sel_hi:[1,0]
	v_pk_mul_f32 v[106:107], v[106:107], v[116:117] op_sel_hi:[1,0]
	v_cvt_pk_bf16_f32 v110, v110, v111
	v_cvt_pk_bf16_f32 v111, v112, v113
	v_lshl_add_u64 v[112:113], s[28:29], 0, v[158:159]
	v_lshl_add_u64 v[112:113], v[112:113], 0, v[128:129]
	global_store_dwordx2 v[112:113], v[110:111], off
	v_add_u32_e32 v110, v155, v162
	v_ashrrev_i32_e32 v111, 31, v110
	v_lshlrev_b64 v[110:111], 11, v[110:111]
	v_lshl_add_u64 v[112:113], v[122:123], 0, v[110:111]
	v_lshl_add_u64 v[112:113], v[112:113], 0, v[124:125]
	global_store_dwordx4 v[112:113], v[106:109], off
	v_pk_mul_f32 v[104:105], v[104:105], v[116:117] op_sel_hi:[1,0]
	v_pk_mul_f32 v[102:103], v[102:103], v[116:117] op_sel_hi:[1,0]
	v_cvt_pk_bf16_f32 v106, v106, v107
	v_cvt_pk_bf16_f32 v107, v108, v109
	v_lshl_add_u64 v[108:109], s[28:29], 0, v[110:111]
	v_lshl_add_u64 v[108:109], v[108:109], 0, v[144:145]
	global_store_dwordx2 v[108:109], v[106:107], off
	v_add_u32_e32 v106, v156, v162
	v_ashrrev_i32_e32 v107, 31, v106
	v_lshlrev_b64 v[106:107], 11, v[106:107]
	v_lshl_add_u64 v[108:109], v[118:119], 0, v[106:107]
	v_lshl_add_u64 v[108:109], v[108:109], 0, v[120:121]
	global_store_dwordx4 v[108:109], v[102:105], off
	v_pk_mul_f32 v[100:101], v[100:101], v[116:117] op_sel_hi:[1,0]
	v_pk_mul_f32 v[98:99], v[98:99], v[116:117] op_sel_hi:[1,0]
	v_cvt_pk_bf16_f32 v102, v102, v103
	v_cvt_pk_bf16_f32 v103, v104, v105
	v_lshl_add_u64 v[104:105], s[28:29], 0, v[106:107]
	v_lshl_add_u64 v[104:105], v[104:105], 0, v[146:147]
	global_store_dwordx2 v[104:105], v[102:103], off
	v_add_u32_e32 v102, v157, v162
	v_ashrrev_i32_e32 v103, 31, v102
	v_lshlrev_b64 v[102:103], 11, v[102:103]
	v_lshl_add_u64 v[104:105], v[148:149], 0, v[102:103]
	v_lshl_add_u64 v[104:105], v[104:105], 0, v[150:151]
	global_store_dwordx4 v[104:105], v[98:101], off
	v_add_u32_e32 v104, 32, v140
	s_nop 0
	v_cvt_pk_bf16_f32 v98, v98, v99
	v_cvt_pk_bf16_f32 v99, v100, v101
	v_lshl_add_u64 v[100:101], s[28:29], 0, v[102:103]
	v_lshl_add_u64 v[100:101], v[100:101], 0, v[114:115]
	global_store_dwordx2 v[100:101], v[98:99], off
	global_load_dwordx2 v[98:99], v[142:143], off offset:256
	s_waitcnt vmcnt(0)
	v_ffbh_u32_e32 v100, v99
	v_min_u32_e32 v100, 32, v100
	v_lshlrev_b64 v[98:99], v100, v[98:99]
	v_min_u32_e32 v98, 1, v98
	v_or_b32_e32 v98, v99, v98
	v_cvt_f32_u32_e32 v98, v98
	v_sub_u32_e32 v99, 32, v100
	v_add_u32_e32 v100, v141, v104
	v_ashrrev_i32_e32 v101, 31, v100
	v_ldexp_f32 v98, v98, v99
	v_mul_f32_e32 v98, 0x30800000, v98
	v_fmamk_f32 v98, v98, 0x3a000000, v1
	v_cmp_gt_f32_e32 vcc, s65, v98
	v_mul_f32_e32 v99, 0x4b800000, v98
	v_lshlrev_b64 v[100:101], 11, v[100:101]
	v_cndmask_b32_e32 v98, v98, v99, vcc
	v_rsq_f32_e32 v98, v98
	v_lshl_add_u64 v[102:103], v[126:127], 0, v[100:101]
	v_lshl_add_u64 v[102:103], v[102:103], 0, v[180:181]
	v_mul_f32_e32 v99, 0x45800000, v98
	v_cndmask_b32_e32 v98, v98, v99, vcc
	v_pk_mul_f32 v[96:97], v[96:97], v[98:99] op_sel_hi:[1,0]
	v_pk_mul_f32 v[94:95], v[94:95], v[98:99] op_sel_hi:[1,0]
	global_store_dwordx4 v[102:103], v[94:97], off
	v_pk_mul_f32 v[92:93], v[92:93], v[98:99] op_sel_hi:[1,0]
	v_pk_mul_f32 v[90:91], v[90:91], v[98:99] op_sel_hi:[1,0]
	v_cvt_pk_bf16_f32 v94, v94, v95
	v_cvt_pk_bf16_f32 v95, v96, v97
	v_lshl_add_u64 v[96:97], s[28:29], 0, v[100:101]
	v_lshl_add_u64 v[96:97], v[96:97], 0, v[128:129]
	global_store_dwordx2 v[96:97], v[94:95], off
	v_add_u32_e32 v94, v155, v104
	v_ashrrev_i32_e32 v95, 31, v94
	v_lshlrev_b64 v[94:95], 11, v[94:95]
	v_lshl_add_u64 v[96:97], v[122:123], 0, v[94:95]
	v_lshl_add_u64 v[96:97], v[96:97], 0, v[124:125]
	global_store_dwordx4 v[96:97], v[90:93], off
	v_pk_mul_f32 v[88:89], v[88:89], v[98:99] op_sel_hi:[1,0]
	v_pk_mul_f32 v[86:87], v[86:87], v[98:99] op_sel_hi:[1,0]
	v_cvt_pk_bf16_f32 v90, v90, v91
	v_cvt_pk_bf16_f32 v91, v92, v93
	v_lshl_add_u64 v[92:93], s[28:29], 0, v[94:95]
	v_lshl_add_u64 v[92:93], v[92:93], 0, v[144:145]
	global_store_dwordx2 v[92:93], v[90:91], off
	v_add_u32_e32 v90, v156, v104
	v_ashrrev_i32_e32 v91, 31, v90
	v_lshlrev_b64 v[90:91], 11, v[90:91]
	v_lshl_add_u64 v[92:93], v[118:119], 0, v[90:91]
	v_lshl_add_u64 v[92:93], v[92:93], 0, v[120:121]
	global_store_dwordx4 v[92:93], v[86:89], off
	v_pk_mul_f32 v[84:85], v[84:85], v[98:99] op_sel_hi:[1,0]
	v_pk_mul_f32 v[82:83], v[82:83], v[98:99] op_sel_hi:[1,0]
	v_cvt_pk_bf16_f32 v86, v86, v87
	v_cvt_pk_bf16_f32 v87, v88, v89
	v_lshl_add_u64 v[88:89], s[28:29], 0, v[90:91]
	v_lshl_add_u64 v[88:89], v[88:89], 0, v[146:147]
	global_store_dwordx2 v[88:89], v[86:87], off
	v_add_u32_e32 v86, v157, v104
	v_ashrrev_i32_e32 v87, 31, v86
	v_lshlrev_b64 v[86:87], 11, v[86:87]
	v_lshl_add_u64 v[88:89], v[148:149], 0, v[86:87]
	v_lshl_add_u64 v[88:89], v[88:89], 0, v[150:151]
	global_store_dwordx4 v[88:89], v[82:85], off
	v_add_u32_e32 v88, 48, v140
	s_nop 0
	v_cvt_pk_bf16_f32 v82, v82, v83
	v_cvt_pk_bf16_f32 v83, v84, v85
	v_lshl_add_u64 v[84:85], s[28:29], 0, v[86:87]
	v_lshl_add_u64 v[84:85], v[84:85], 0, v[114:115]
	global_store_dwordx2 v[84:85], v[82:83], off
	global_load_dwordx2 v[82:83], v[142:143], off offset:384
	s_waitcnt vmcnt(0)
	v_ffbh_u32_e32 v84, v83
	v_min_u32_e32 v84, 32, v84
	v_lshlrev_b64 v[82:83], v84, v[82:83]
	v_min_u32_e32 v82, 1, v82
	v_or_b32_e32 v82, v83, v82
	v_cvt_f32_u32_e32 v82, v82
	v_sub_u32_e32 v83, 32, v84
	v_add_u32_e32 v84, v141, v88
	v_ashrrev_i32_e32 v85, 31, v84
	v_ldexp_f32 v82, v82, v83
	v_mul_f32_e32 v82, 0x30800000, v82
	v_fmamk_f32 v82, v82, 0x3a000000, v1
	v_cmp_gt_f32_e32 vcc, s65, v82
	v_mul_f32_e32 v83, 0x4b800000, v82
	v_lshlrev_b64 v[84:85], 11, v[84:85]
	v_cndmask_b32_e32 v82, v82, v83, vcc
	v_rsq_f32_e32 v82, v82
	v_lshl_add_u64 v[86:87], v[126:127], 0, v[84:85]
	v_lshl_add_u64 v[86:87], v[86:87], 0, v[180:181]
	v_mul_f32_e32 v83, 0x45800000, v82
	v_cndmask_b32_e32 v82, v82, v83, vcc
	v_pk_mul_f32 v[80:81], v[80:81], v[82:83] op_sel_hi:[1,0]
	v_pk_mul_f32 v[78:79], v[78:79], v[82:83] op_sel_hi:[1,0]
	global_store_dwordx4 v[86:87], v[78:81], off
	v_pk_mul_f32 v[76:77], v[76:77], v[82:83] op_sel_hi:[1,0]
	v_pk_mul_f32 v[74:75], v[74:75], v[82:83] op_sel_hi:[1,0]
	v_cvt_pk_bf16_f32 v78, v78, v79
	v_cvt_pk_bf16_f32 v79, v80, v81
	v_lshl_add_u64 v[80:81], s[28:29], 0, v[84:85]
	v_lshl_add_u64 v[80:81], v[80:81], 0, v[128:129]
	global_store_dwordx2 v[80:81], v[78:79], off
	v_add_u32_e32 v78, v155, v88
	v_ashrrev_i32_e32 v79, 31, v78
	v_lshlrev_b64 v[78:79], 11, v[78:79]
	v_lshl_add_u64 v[80:81], v[122:123], 0, v[78:79]
	v_lshl_add_u64 v[80:81], v[80:81], 0, v[124:125]
	global_store_dwordx4 v[80:81], v[74:77], off
	v_pk_mul_f32 v[72:73], v[72:73], v[82:83] op_sel_hi:[1,0]
	v_pk_mul_f32 v[70:71], v[70:71], v[82:83] op_sel_hi:[1,0]
	v_cvt_pk_bf16_f32 v74, v74, v75
	v_cvt_pk_bf16_f32 v75, v76, v77
	v_lshl_add_u64 v[76:77], s[28:29], 0, v[78:79]
	v_lshl_add_u64 v[76:77], v[76:77], 0, v[144:145]
	global_store_dwordx2 v[76:77], v[74:75], off
	v_add_u32_e32 v74, v156, v88
	v_ashrrev_i32_e32 v75, 31, v74
	v_lshlrev_b64 v[74:75], 11, v[74:75]
	v_lshl_add_u64 v[76:77], v[118:119], 0, v[74:75]
	v_lshl_add_u64 v[76:77], v[76:77], 0, v[120:121]
	global_store_dwordx4 v[76:77], v[70:73], off
	v_pk_mul_f32 v[68:69], v[68:69], v[82:83] op_sel_hi:[1,0]
	v_pk_mul_f32 v[66:67], v[66:67], v[82:83] op_sel_hi:[1,0]
	v_cvt_pk_bf16_f32 v70, v70, v71
	v_cvt_pk_bf16_f32 v71, v72, v73
	v_lshl_add_u64 v[72:73], s[28:29], 0, v[74:75]
	v_lshl_add_u64 v[72:73], v[72:73], 0, v[146:147]
	global_store_dwordx2 v[72:73], v[70:71], off
	v_add_u32_e32 v70, v157, v88
	v_ashrrev_i32_e32 v71, 31, v70
	v_lshlrev_b64 v[70:71], 11, v[70:71]
	v_lshl_add_u64 v[72:73], v[148:149], 0, v[70:71]
	v_lshl_add_u64 v[72:73], v[72:73], 0, v[150:151]
	global_store_dwordx4 v[72:73], v[66:69], off
	v_add_u32_e32 v72, 0x80, v140
	s_nop 0
	v_cvt_pk_bf16_f32 v66, v66, v67
	v_cvt_pk_bf16_f32 v67, v68, v69
	v_lshl_add_u64 v[68:69], s[28:29], 0, v[70:71]
	v_lshl_add_u64 v[68:69], v[68:69], 0, v[114:115]
	global_store_dwordx2 v[68:69], v[66:67], off
	global_load_dwordx2 v[66:67], v[142:143], off offset:1024
	s_waitcnt vmcnt(0)
	v_ffbh_u32_e32 v68, v67
	v_min_u32_e32 v68, 32, v68
	v_lshlrev_b64 v[66:67], v68, v[66:67]
	v_min_u32_e32 v66, 1, v66
	v_or_b32_e32 v66, v67, v66
	v_cvt_f32_u32_e32 v66, v66
	v_sub_u32_e32 v67, 32, v68
	v_add_u32_e32 v68, v141, v72
	v_ashrrev_i32_e32 v69, 31, v68
	v_ldexp_f32 v66, v66, v67
	v_mul_f32_e32 v66, 0x30800000, v66
	v_fmamk_f32 v66, v66, 0x3a000000, v1
	v_cmp_gt_f32_e32 vcc, s65, v66
	v_mul_f32_e32 v67, 0x4b800000, v66
	v_lshlrev_b64 v[68:69], 11, v[68:69]
	v_cndmask_b32_e32 v66, v66, v67, vcc
	v_rsq_f32_e32 v66, v66
	v_lshl_add_u64 v[70:71], v[126:127], 0, v[68:69]
	v_lshl_add_u64 v[70:71], v[70:71], 0, v[180:181]
	v_mul_f32_e32 v67, 0x45800000, v66
	v_cndmask_b32_e32 v66, v66, v67, vcc
	v_pk_mul_f32 v[64:65], v[64:65], v[66:67] op_sel_hi:[1,0]
	v_pk_mul_f32 v[62:63], v[62:63], v[66:67] op_sel_hi:[1,0]
	global_store_dwordx4 v[70:71], v[62:65], off
	v_pk_mul_f32 v[60:61], v[60:61], v[66:67] op_sel_hi:[1,0]
	v_pk_mul_f32 v[58:59], v[58:59], v[66:67] op_sel_hi:[1,0]
	v_cvt_pk_bf16_f32 v62, v62, v63
	v_cvt_pk_bf16_f32 v63, v64, v65
	v_lshl_add_u64 v[64:65], s[28:29], 0, v[68:69]
	v_lshl_add_u64 v[64:65], v[64:65], 0, v[128:129]
	global_store_dwordx2 v[64:65], v[62:63], off
	v_add_u32_e32 v62, v155, v72
	v_ashrrev_i32_e32 v63, 31, v62
	v_lshlrev_b64 v[62:63], 11, v[62:63]
	v_lshl_add_u64 v[64:65], v[122:123], 0, v[62:63]
	v_lshl_add_u64 v[64:65], v[64:65], 0, v[124:125]
	global_store_dwordx4 v[64:65], v[58:61], off
	v_pk_mul_f32 v[56:57], v[56:57], v[66:67] op_sel_hi:[1,0]
	v_pk_mul_f32 v[54:55], v[54:55], v[66:67] op_sel_hi:[1,0]
	v_cvt_pk_bf16_f32 v58, v58, v59
	v_cvt_pk_bf16_f32 v59, v60, v61
	v_lshl_add_u64 v[60:61], s[28:29], 0, v[62:63]
	v_lshl_add_u64 v[60:61], v[60:61], 0, v[144:145]
	global_store_dwordx2 v[60:61], v[58:59], off
	v_add_u32_e32 v58, v156, v72
	v_ashrrev_i32_e32 v59, 31, v58
	v_lshlrev_b64 v[58:59], 11, v[58:59]
	v_lshl_add_u64 v[60:61], v[118:119], 0, v[58:59]
	v_lshl_add_u64 v[60:61], v[60:61], 0, v[120:121]
	global_store_dwordx4 v[60:61], v[54:57], off
	v_pk_mul_f32 v[52:53], v[52:53], v[66:67] op_sel_hi:[1,0]
	v_pk_mul_f32 v[50:51], v[50:51], v[66:67] op_sel_hi:[1,0]
	v_cvt_pk_bf16_f32 v54, v54, v55
	v_cvt_pk_bf16_f32 v55, v56, v57
	v_lshl_add_u64 v[56:57], s[28:29], 0, v[58:59]
	v_lshl_add_u64 v[56:57], v[56:57], 0, v[146:147]
	global_store_dwordx2 v[56:57], v[54:55], off
	v_add_u32_e32 v54, v157, v72
	v_ashrrev_i32_e32 v55, 31, v54
	v_lshlrev_b64 v[54:55], 11, v[54:55]
	v_lshl_add_u64 v[56:57], v[148:149], 0, v[54:55]
	v_lshl_add_u64 v[56:57], v[56:57], 0, v[150:151]
	global_store_dwordx4 v[56:57], v[50:53], off
	v_add_u32_e32 v56, 0x90, v140
	s_nop 0
	v_cvt_pk_bf16_f32 v50, v50, v51
	v_cvt_pk_bf16_f32 v51, v52, v53
	v_lshl_add_u64 v[52:53], s[28:29], 0, v[54:55]
	v_lshl_add_u64 v[52:53], v[52:53], 0, v[114:115]
	global_store_dwordx2 v[52:53], v[50:51], off
	global_load_dwordx2 v[50:51], v[142:143], off offset:1152
	s_waitcnt vmcnt(0)
	v_ffbh_u32_e32 v52, v51
	v_min_u32_e32 v52, 32, v52
	v_lshlrev_b64 v[50:51], v52, v[50:51]
	v_min_u32_e32 v50, 1, v50
	v_or_b32_e32 v50, v51, v50
	v_cvt_f32_u32_e32 v50, v50
	v_sub_u32_e32 v51, 32, v52
	v_add_u32_e32 v52, v141, v56
	v_ashrrev_i32_e32 v53, 31, v52
	v_ldexp_f32 v50, v50, v51
	v_mul_f32_e32 v50, 0x30800000, v50
	v_fmamk_f32 v50, v50, 0x3a000000, v1
	v_cmp_gt_f32_e32 vcc, s65, v50
	v_mul_f32_e32 v51, 0x4b800000, v50
	v_lshlrev_b64 v[52:53], 11, v[52:53]
	v_cndmask_b32_e32 v50, v50, v51, vcc
	v_rsq_f32_e32 v50, v50
	v_lshl_add_u64 v[54:55], v[126:127], 0, v[52:53]
	v_lshl_add_u64 v[54:55], v[54:55], 0, v[180:181]
	v_mul_f32_e32 v51, 0x45800000, v50
	v_cndmask_b32_e32 v50, v50, v51, vcc
	v_pk_mul_f32 v[48:49], v[48:49], v[50:51] op_sel_hi:[1,0]
	v_pk_mul_f32 v[46:47], v[46:47], v[50:51] op_sel_hi:[1,0]
	global_store_dwordx4 v[54:55], v[46:49], off
	v_pk_mul_f32 v[44:45], v[44:45], v[50:51] op_sel_hi:[1,0]
	v_pk_mul_f32 v[42:43], v[42:43], v[50:51] op_sel_hi:[1,0]
	v_cvt_pk_bf16_f32 v46, v46, v47
	v_cvt_pk_bf16_f32 v47, v48, v49
	v_lshl_add_u64 v[48:49], s[28:29], 0, v[52:53]
	v_lshl_add_u64 v[48:49], v[48:49], 0, v[128:129]
	global_store_dwordx2 v[48:49], v[46:47], off
	v_add_u32_e32 v46, v155, v56
	v_ashrrev_i32_e32 v47, 31, v46
	v_lshlrev_b64 v[46:47], 11, v[46:47]
	v_lshl_add_u64 v[48:49], v[122:123], 0, v[46:47]
	v_lshl_add_u64 v[48:49], v[48:49], 0, v[124:125]
	global_store_dwordx4 v[48:49], v[42:45], off
	v_pk_mul_f32 v[40:41], v[40:41], v[50:51] op_sel_hi:[1,0]
	v_pk_mul_f32 v[38:39], v[38:39], v[50:51] op_sel_hi:[1,0]
	v_cvt_pk_bf16_f32 v42, v42, v43
	v_cvt_pk_bf16_f32 v43, v44, v45
	v_lshl_add_u64 v[44:45], s[28:29], 0, v[46:47]
	v_lshl_add_u64 v[44:45], v[44:45], 0, v[144:145]
	global_store_dwordx2 v[44:45], v[42:43], off
	v_add_u32_e32 v42, v156, v56
	v_ashrrev_i32_e32 v43, 31, v42
	v_lshlrev_b64 v[42:43], 11, v[42:43]
	v_lshl_add_u64 v[44:45], v[118:119], 0, v[42:43]
	v_lshl_add_u64 v[44:45], v[44:45], 0, v[120:121]
	global_store_dwordx4 v[44:45], v[38:41], off
	v_pk_mul_f32 v[36:37], v[36:37], v[50:51] op_sel_hi:[1,0]
	v_pk_mul_f32 v[34:35], v[34:35], v[50:51] op_sel_hi:[1,0]
	v_cvt_pk_bf16_f32 v38, v38, v39
	v_cvt_pk_bf16_f32 v39, v40, v41
	v_lshl_add_u64 v[40:41], s[28:29], 0, v[42:43]
	v_lshl_add_u64 v[40:41], v[40:41], 0, v[146:147]
	global_store_dwordx2 v[40:41], v[38:39], off
	v_add_u32_e32 v38, v157, v56
	v_ashrrev_i32_e32 v39, 31, v38
	v_lshlrev_b64 v[38:39], 11, v[38:39]
	v_lshl_add_u64 v[40:41], v[148:149], 0, v[38:39]
	v_lshl_add_u64 v[40:41], v[40:41], 0, v[150:151]
	global_store_dwordx4 v[40:41], v[34:37], off
	v_add_u32_e32 v40, 0xa0, v140
	s_nop 0
	v_cvt_pk_bf16_f32 v34, v34, v35
	v_cvt_pk_bf16_f32 v35, v36, v37
	v_lshl_add_u64 v[36:37], s[28:29], 0, v[38:39]
	v_lshl_add_u64 v[36:37], v[36:37], 0, v[114:115]
	global_store_dwordx2 v[36:37], v[34:35], off
	global_load_dwordx2 v[34:35], v[142:143], off offset:1280
	s_waitcnt vmcnt(0)
	v_ffbh_u32_e32 v36, v35
	v_min_u32_e32 v36, 32, v36
	v_lshlrev_b64 v[34:35], v36, v[34:35]
	v_min_u32_e32 v34, 1, v34
	v_or_b32_e32 v34, v35, v34
	v_cvt_f32_u32_e32 v34, v34
	v_sub_u32_e32 v35, 32, v36
	v_add_u32_e32 v36, v141, v40
	v_ashrrev_i32_e32 v37, 31, v36
	v_ldexp_f32 v34, v34, v35
	v_mul_f32_e32 v34, 0x30800000, v34
	v_fmamk_f32 v34, v34, 0x3a000000, v1
	v_cmp_gt_f32_e32 vcc, s65, v34
	v_mul_f32_e32 v35, 0x4b800000, v34
	v_lshlrev_b64 v[36:37], 11, v[36:37]
	v_cndmask_b32_e32 v34, v34, v35, vcc
	v_rsq_f32_e32 v34, v34
	v_lshl_add_u64 v[38:39], v[126:127], 0, v[36:37]
	v_lshl_add_u64 v[38:39], v[38:39], 0, v[180:181]
	v_mul_f32_e32 v35, 0x45800000, v34
	v_cndmask_b32_e32 v34, v34, v35, vcc
	v_pk_mul_f32 v[32:33], v[32:33], v[34:35] op_sel_hi:[1,0]
	v_pk_mul_f32 v[30:31], v[30:31], v[34:35] op_sel_hi:[1,0]
	global_store_dwordx4 v[38:39], v[30:33], off
	v_pk_mul_f32 v[28:29], v[28:29], v[34:35] op_sel_hi:[1,0]
	v_pk_mul_f32 v[26:27], v[26:27], v[34:35] op_sel_hi:[1,0]
	v_cvt_pk_bf16_f32 v30, v30, v31
	v_cvt_pk_bf16_f32 v31, v32, v33
	v_lshl_add_u64 v[32:33], s[28:29], 0, v[36:37]
	v_lshl_add_u64 v[32:33], v[32:33], 0, v[128:129]
	global_store_dwordx2 v[32:33], v[30:31], off
	v_add_u32_e32 v30, v155, v40
	v_ashrrev_i32_e32 v31, 31, v30
	v_lshlrev_b64 v[30:31], 11, v[30:31]
	v_lshl_add_u64 v[32:33], v[122:123], 0, v[30:31]
	v_lshl_add_u64 v[32:33], v[32:33], 0, v[124:125]
	global_store_dwordx4 v[32:33], v[26:29], off
	v_pk_mul_f32 v[24:25], v[24:25], v[34:35] op_sel_hi:[1,0]
	v_pk_mul_f32 v[22:23], v[22:23], v[34:35] op_sel_hi:[1,0]
	v_cvt_pk_bf16_f32 v26, v26, v27
	v_cvt_pk_bf16_f32 v27, v28, v29
	v_lshl_add_u64 v[28:29], s[28:29], 0, v[30:31]
	v_lshl_add_u64 v[28:29], v[28:29], 0, v[144:145]
	global_store_dwordx2 v[28:29], v[26:27], off
	v_add_u32_e32 v26, v156, v40
	v_ashrrev_i32_e32 v27, 31, v26
	v_lshlrev_b64 v[26:27], 11, v[26:27]
	v_lshl_add_u64 v[28:29], v[118:119], 0, v[26:27]
	v_lshl_add_u64 v[28:29], v[28:29], 0, v[120:121]
	global_store_dwordx4 v[28:29], v[22:25], off
	v_pk_mul_f32 v[20:21], v[20:21], v[34:35] op_sel_hi:[1,0]
	v_pk_mul_f32 v[18:19], v[18:19], v[34:35] op_sel_hi:[1,0]
	v_cvt_pk_bf16_f32 v22, v22, v23
	v_cvt_pk_bf16_f32 v23, v24, v25
	v_lshl_add_u64 v[24:25], s[28:29], 0, v[26:27]
	v_lshl_add_u64 v[24:25], v[24:25], 0, v[146:147]
	global_store_dwordx2 v[24:25], v[22:23], off
	v_add_u32_e32 v22, v157, v40
	v_ashrrev_i32_e32 v23, 31, v22
	v_lshlrev_b64 v[22:23], 11, v[22:23]
	v_lshl_add_u64 v[24:25], v[148:149], 0, v[22:23]
	v_lshl_add_u64 v[24:25], v[24:25], 0, v[150:151]
	global_store_dwordx4 v[24:25], v[18:21], off
	v_add_u32_e32 v24, 0xb0, v140
	s_nop 0
	v_cvt_pk_bf16_f32 v18, v18, v19
	v_cvt_pk_bf16_f32 v19, v20, v21
	v_lshl_add_u64 v[20:21], s[28:29], 0, v[22:23]
	v_lshl_add_u64 v[20:21], v[20:21], 0, v[114:115]
	global_store_dwordx2 v[20:21], v[18:19], off
	global_load_dwordx2 v[18:19], v[142:143], off offset:1408
	s_waitcnt vmcnt(0)
	v_ffbh_u32_e32 v20, v19
	v_min_u32_e32 v20, 32, v20
	v_lshlrev_b64 v[18:19], v20, v[18:19]
	v_min_u32_e32 v18, 1, v18
	v_or_b32_e32 v18, v19, v18
	v_cvt_f32_u32_e32 v18, v18
	v_sub_u32_e32 v19, 32, v20
	v_add_u32_e32 v20, v141, v24
	v_ashrrev_i32_e32 v21, 31, v20
	v_ldexp_f32 v18, v18, v19
	v_mul_f32_e32 v18, 0x30800000, v18
	v_fmamk_f32 v18, v18, 0x3a000000, v1
	v_cmp_gt_f32_e32 vcc, s65, v18
	v_mul_f32_e32 v19, 0x4b800000, v18
	v_lshlrev_b64 v[20:21], 11, v[20:21]
	v_cndmask_b32_e32 v18, v18, v19, vcc
	v_rsq_f32_e32 v18, v18
	v_lshl_add_u64 v[22:23], v[126:127], 0, v[20:21]
	v_lshl_add_u64 v[22:23], v[22:23], 0, v[180:181]
	v_mul_f32_e32 v19, 0x45800000, v18
	v_cndmask_b32_e32 v18, v18, v19, vcc
	v_pk_mul_f32 v[16:17], v[16:17], v[18:19] op_sel_hi:[1,0]
	v_pk_mul_f32 v[14:15], v[14:15], v[18:19] op_sel_hi:[1,0]
	global_store_dwordx4 v[22:23], v[14:17], off
	v_pk_mul_f32 v[12:13], v[12:13], v[18:19] op_sel_hi:[1,0]
	v_pk_mul_f32 v[10:11], v[10:11], v[18:19] op_sel_hi:[1,0]
	v_cvt_pk_bf16_f32 v14, v14, v15
	v_cvt_pk_bf16_f32 v15, v16, v17
	v_lshl_add_u64 v[16:17], s[28:29], 0, v[20:21]
	v_lshl_add_u64 v[16:17], v[16:17], 0, v[128:129]
	global_store_dwordx2 v[16:17], v[14:15], off
	v_add_u32_e32 v14, v155, v24
	v_ashrrev_i32_e32 v15, 31, v14
	v_lshlrev_b64 v[14:15], 11, v[14:15]
	v_lshl_add_u64 v[16:17], v[122:123], 0, v[14:15]
	v_lshl_add_u64 v[16:17], v[16:17], 0, v[124:125]
	global_store_dwordx4 v[16:17], v[10:13], off
	v_pk_mul_f32 v[8:9], v[8:9], v[18:19] op_sel_hi:[1,0]
	v_pk_mul_f32 v[6:7], v[6:7], v[18:19] op_sel_hi:[1,0]
	v_cvt_pk_bf16_f32 v10, v10, v11
	v_cvt_pk_bf16_f32 v11, v12, v13
	v_lshl_add_u64 v[12:13], s[28:29], 0, v[14:15]
	v_lshl_add_u64 v[12:13], v[12:13], 0, v[144:145]
	global_store_dwordx2 v[12:13], v[10:11], off
	v_add_u32_e32 v10, v156, v24
	v_ashrrev_i32_e32 v11, 31, v10
	v_lshlrev_b64 v[10:11], 11, v[10:11]
	v_lshl_add_u64 v[12:13], v[118:119], 0, v[10:11]
	v_lshl_add_u64 v[12:13], v[12:13], 0, v[120:121]
	global_store_dwordx4 v[12:13], v[6:9], off
	v_pk_mul_f32 v[4:5], v[4:5], v[18:19] op_sel_hi:[1,0]
	v_pk_mul_f32 v[2:3], v[2:3], v[18:19] op_sel_hi:[1,0]
	v_cvt_pk_bf16_f32 v6, v6, v7
	v_cvt_pk_bf16_f32 v7, v8, v9
	v_lshl_add_u64 v[8:9], s[28:29], 0, v[10:11]
	v_lshl_add_u64 v[8:9], v[8:9], 0, v[146:147]
	global_store_dwordx2 v[8:9], v[6:7], off
	v_add_u32_e32 v6, v157, v24
	v_ashrrev_i32_e32 v7, 31, v6
	v_lshlrev_b64 v[6:7], 11, v[6:7]
	v_lshl_add_u64 v[8:9], v[148:149], 0, v[6:7]
	v_lshl_add_u64 v[8:9], v[8:9], 0, v[150:151]
	global_store_dwordx4 v[8:9], v[2:5], off
	s_andn2_b64 vcc, exec, s[34:35]
	s_nop 0
	v_cvt_pk_bf16_f32 v2, v2, v3
	v_cvt_pk_bf16_f32 v3, v4, v5
	v_lshl_add_u64 v[4:5], s[28:29], 0, v[6:7]
	v_lshl_add_u64 v[4:5], v[4:5], 0, v[114:115]
	global_store_dwordx2 v[4:5], v[2:3], off
	s_cbranch_vccnz .LBB0_1228
	s_andn2_b64 vcc, exec, s[24:25]
	s_cbranch_vccz .LBB0_1227
	s_barrier
	s_branch .LBB0_1227

.LBB0_1571:
	v_ashrrev_i32_e32 v4, 31, v2
	v_lshrrev_b32_e32 v4, 26, v4
	v_add_u32_e32 v4, v2, v4
	v_ashrrev_i32_e32 v146, 6, v4
	v_bfe_i32 v4, v2, 27, 1
	v_lshlrev_b32_e32 v3, 4, v2
	v_lshrrev_b32_e32 v4, 22, v4
	v_add_u32_e32 v4, v3, v4
	v_and_b32_e32 v4, 0xfffffc00, v4
	v_sub_u32_e32 v4, v3, v4
	v_lshrrev_b32_e32 v5, 4, v4
	v_bitop3_b32 v4, v5, v4, 32 bitop3:0x6c
	v_ashrrev_i32_e32 v6, 31, v4
	v_lshrrev_b32_e32 v6, 26, v6
	v_add_u32_e32 v6, v4, v6
	v_lshlrev_b32_e32 v5, 3, v146
	v_ashrrev_i32_e32 v147, 6, v6
	v_and_b32_e32 v6, 0xc0, v6
	v_and_b32_e32 v5, -16, v5
	v_sub_u32_e32 v4, v4, v6
	v_add_u32_e32 v5, v147, v5
	v_ashrrev_i16_sdwa v4, v224, sext(v4) dst_sel:DWORD dst_unused:UNUSED_PAD src0_sel:DWORD src1_sel:BYTE_0
	v_lshlrev_b32_e32 v7, 5, v146
	v_bfe_i32 v153, v4, 0, 16
	v_lshlrev_b32_e32 v4, 1, v5
	v_lshrrev_b32_e32 v6, 2, v5
	v_and_b32_e32 v8, 3, v147
	s_mov_b32 s8, 0xfffe0
	v_and_b32_e32 v7, 32, v7
	v_and_b32_e32 v4, 24, v4
	v_and_b32_e32 v6, 4, v6
	v_and_or_b32 v8, v5, s8, v8
	v_or3_b32 v4, v8, v6, v4
	v_add_lshl_u32 v6, v7, v153, 1
	v_add_u32_e32 v3, 0x2000, v3
	s_waitcnt vmcnt(0)
	v_lshl_add_u32 v134, v4, 12, v6
	v_ashrrev_i32_e32 v4, 31, v3
	v_lshrrev_b32_e32 v4, 22, v4
	v_add_u32_e32 v4, v3, v4
	v_ashrrev_i32_e32 v154, 10, v4
	v_mul_i32_i24_e32 v4, 0x400, v154
	v_sub_u32_e32 v3, v3, v4
	v_lshrrev_b32_e32 v4, 4, v3
	v_bitop3_b32 v3, v4, v3, 32 bitop3:0x6c
	v_lshl_add_u32 v132, v5, 12, v6
	v_ashrrev_i32_e32 v5, 31, v3
	v_lshrrev_b32_e32 v5, 26, v5
	v_lshlrev_b32_e32 v4, 3, v154
	v_add_u32_e32 v5, v3, v5
	v_and_b32_e32 v4, -16, v4
	v_ashrrev_i32_e32 v155, 6, v5
	v_add_u32_e32 v4, v155, v4
	v_and_b32_e32 v7, 3, v155
	s_ashr_i32 s12, s30, 6
	s_ashr_i32 s28, s30, 8
	v_and_b32_e32 v5, 0xc0, v5
	v_and_or_b32 v7, v4, s8, v7
	s_lshl_b32 s8, s12, 10
	s_lshl_b32 s12, s12, 5
	v_sub_u32_e32 v3, v3, v5
	s_lshl_b32 s9, s28, 6
	s_and_b32 s21, s12, 0x60
	v_ashrrev_i16_sdwa v3, v224, sext(v3) dst_sel:DWORD dst_unused:UNUSED_PAD src0_sel:DWORD src1_sel:BYTE_0
	s_add_u32 s54, s26, 0x24600000
	v_lshlrev_b32_e32 v6, 5, v154
	v_bfe_i32 v156, v3, 0, 16
	v_lshlrev_b32_e32 v3, 1, v4
	v_lshrrev_b32_e32 v5, 2, v4
	s_addc_u32 s55, s27, 0
	s_lshl_b32 s12, s44, 8
	v_and_b32_e32 v6, 32, v6
	v_and_b32_e32 v3, 24, v3
	v_and_b32_e32 v5, 4, v5
	v_and_b32_e32 v150, 15, v2
	s_add_i32 s12, s12, s9
	v_bfe_u32 v131, v2, 4, 2
	v_or3_b32 v3, v7, v5, v3
	v_add_lshl_u32 v5, v6, v156, 1
	v_or_b32_e32 v2, s12, v150
	v_lshl_add_u32 v138, v3, 12, v5
	v_ashrrev_i32_e32 v3, 31, v2
	v_lshlrev_b64 v[2:3], 12, v[2:3]
	s_lshl_b32 s26, s38, 8
	v_lshl_add_u64 v[2:3], s[14:15], 0, v[2:3]
	s_ashr_i32 s27, s26, 31
	v_lshl_add_u64 v[2:3], s[26:27], 1, v[2:3]
	s_lshl_b32 s12, s21, 1
	v_lshl_add_u64 v[2:3], v[2:3], 0, s[12:13]
	v_lshlrev_b32_e32 v180, 4, v131
	v_lshl_add_u64 v[2:3], v[2:3], 0, v[180:181]
	s_mov_b32 s26, 0x10000
	v_lshl_add_u32 v136, v4, 12, v5
	v_add_co_u32_e32 v4, vcc, s26, v2
	s_mov_b32 s26, 0x20000
	s_nop 0
	v_addc_co_u32_e32 v5, vcc, 0, v3, vcc
	global_load_dwordx4 v[64:67], v[2:3], off
	global_load_dwordx4 v[60:63], v[2:3], off offset:256
	global_load_dwordx4 v[56:59], v[4:5], off
	global_load_dwordx4 v[52:55], v[4:5], off offset:256
	v_add_co_u32_e32 v4, vcc, s26, v2
	s_mov_b32 s26, 0x30000
	s_nop 0
	v_addc_co_u32_e32 v5, vcc, 0, v3, vcc
	global_load_dwordx4 v[48:51], v[4:5], off
	global_load_dwordx4 v[44:47], v[4:5], off offset:256
	v_add_co_u32_e32 v4, vcc, s26, v2
	s_mov_b32 s26, 0x80000
	s_nop 0
	v_addc_co_u32_e32 v5, vcc, 0, v3, vcc
	global_load_dwordx4 v[40:43], v[4:5], off
	global_load_dwordx4 v[36:39], v[4:5], off offset:256
	v_add_co_u32_e32 v4, vcc, s26, v2
	s_mov_b32 s26, 0x90000
	s_nop 0
	v_addc_co_u32_e32 v5, vcc, 0, v3, vcc
	global_load_dwordx4 v[32:35], v[4:5], off
	global_load_dwordx4 v[28:31], v[4:5], off offset:256
	v_add_co_u32_e32 v4, vcc, s26, v2
	s_mov_b32 s26, 0xa0000
	s_nop 0
	v_addc_co_u32_e32 v5, vcc, 0, v3, vcc
	global_load_dwordx4 v[24:27], v[4:5], off
	global_load_dwordx4 v[18:21], v[4:5], off offset:256
	v_add_co_u32_e32 v4, vcc, s26, v2
	s_mov_b32 s26, 0xb0000
	s_nop 0
	v_addc_co_u32_e32 v5, vcc, 0, v3, vcc
	s_ashr_i32 s45, s44, 31
	s_ashr_i32 s39, s38, 31
	v_add_co_u32_e32 v14, vcc, s26, v2
	s_lshl_b64 s[26:27], s[44:45], 20
	s_lshl_b64 s[34:35], s[38:39], 20
	s_add_u32 s46, s18, s34
	s_addc_u32 s47, s19, s35
	s_add_i32 s56, s8, 0
	v_addc_co_u32_e32 v15, vcc, 0, v3, vcc
	s_add_i32 m0, s56, 0x10000
	global_load_dwordx4 v[10:13], v[4:5], off
	global_load_dwordx4 v[6:9], v[4:5], off offset:256
	s_nop 0
	global_load_dwordx4 v[2:5], v[14:15], off
	s_nop 0
	global_load_dwordx4 v[14:17], v[14:15], off offset:256
	v_mov_b32_e32 v135, v181
	global_load_lds_dwordx4 v134, s[46:47]
	s_add_i32 m0, s56, 0x12000
	s_add_u32 s34, s46, 0x80000
	global_load_lds_dwordx4 v138, s[46:47]
	s_addc_u32 s35, s47, 0
	s_add_i32 m0, s56, 0x14000
	v_mov_b32_e32 v139, v181
	global_load_lds_dwordx4 v134, s[34:35]
	s_add_i32 m0, s56, 0x16000
	s_add_u32 s48, s54, s26
	s_addc_u32 s49, s55, s27
	s_add_i32 s57, s56, 0x2000
	global_load_lds_dwordx4 v138, s[34:35]
	s_mov_b32 m0, s56
	s_add_u32 s26, s48, 0x80000
	global_load_lds_dwordx4 v132, s[48:49]
	s_mov_b32 m0, s57
	s_addc_u32 s27, s49, 0
	s_add_i32 s58, s56, 0x4000
	global_load_lds_dwordx4 v136, s[48:49]
	s_mov_b32 m0, s58
	s_add_i32 s59, s56, 0x6000
	global_load_lds_dwordx4 v132, s[26:27]
	s_mov_b32 m0, s59
	v_mov_b32_e32 v133, v181
	global_load_lds_dwordx4 v136, s[26:27]
	v_mov_b32_e32 v137, v181
	s_cmp_eq_u32 s28, 1
	v_lshl_add_u64 v[144:145], s[46:47], 0, v[134:135]
	v_lshl_add_u64 v[142:143], s[46:47], 0, v[138:139]
	v_lshl_add_u64 v[68:69], s[48:49], 0, v[132:133]
	s_cselect_b64 s[26:27], -1, 0
	s_cmp_lg_u32 s28, 1
	v_lshl_add_u64 v[140:141], s[48:49], 0, v[136:137]
	s_cbranch_scc0 .LBB0_1573
	s_barrier

.LBB0_1583:
	s_add_u32 s46, s48, 0xfff80080
	s_addc_u32 s47, s49, -1
	s_add_i32 s68, 0, 0x10000
	s_cmp_eq_u32 s67, 28
	s_cselect_b32 s51, s35, s47
	s_cselect_b32 s50, s39, s46
	s_cselect_b32 s47, s31, s66
	s_cselect_b32 s46, s45, s64
	s_add_i32 s70, 0, 0x14000
	v_add_u32_e32 v162, s68, v152
	v_add_u32_e32 v178, s70, v152
	ds_read_b128 v[144:147], v162
	ds_read_b128 v[154:157], v162 offset:1024
	ds_read_b128 v[158:161], v162 offset:2048
	ds_read_b128 v[162:165], v162 offset:3072
	ds_read_b128 v[166:169], v178
	ds_read_b128 v[170:173], v178 offset:1024
	ds_read_b128 v[174:177], v178 offset:2048
	ds_read_b128 v[190:193], v178 offset:3072
	v_lshl_add_u64 v[178:179], s[48:49], 0, v[140:141]
	s_add_i32 m0, s56, 0xc000
	ds_read_b128 v[194:197], v153
	ds_read_b128 v[198:201], v153 offset:1024
	ds_read_b128 v[202:205], v153 offset:2048
	ds_read_b128 v[206:209], v153 offset:3072
	ds_read_b128 v[210:213], v153 offset:4096
	ds_read_b128 v[214:217], v153 offset:5120
	ds_read_b128 v[218:221], v153 offset:6144
	ds_read_b128 v[238:241], v153 offset:7168
	global_load_lds_dwordx4 v[178:179], off
	v_lshl_add_u64 v[178:179], s[48:49], 0, v[142:143]
	s_add_i32 m0, s56, 0xe000
	s_nop 0
	global_load_lds_dwordx4 v[178:179], off
	s_waitcnt vmcnt(8)
	s_waitcnt lgkmcnt(0)
	s_barrier
	s_setprio 1
	s_waitcnt lgkmcnt(0)
	v_mfma_f32_16x16x32_bf16 v[126:129], v[144:147], v[194:197], v[126:129]
	v_mfma_f32_16x16x32_bf16 v[114:117], v[158:161], v[194:197], v[114:117]
	v_mfma_f32_16x16x32_bf16 v[106:109], v[144:147], v[202:205], v[106:109]
	v_mfma_f32_16x16x32_bf16 v[98:101], v[158:161], v[202:205], v[98:101]
	v_mfma_f32_16x16x32_bf16 v[90:93], v[144:147], v[210:213], v[90:93]
	v_mfma_f32_16x16x32_bf16 v[82:85], v[158:161], v[210:213], v[82:85]
	v_mfma_f32_16x16x32_bf16 v[74:77], v[144:147], v[218:221], v[74:77]
	v_mfma_f32_16x16x32_bf16 v[54:57], v[158:161], v[218:221], v[54:57]
	v_mfma_f32_16x16x32_bf16 v[126:129], v[154:157], v[198:201], v[126:129]
	v_mfma_f32_16x16x32_bf16 v[114:117], v[162:165], v[198:201], v[114:117]
	v_mfma_f32_16x16x32_bf16 v[106:109], v[154:157], v[206:209], v[106:109]
	v_mfma_f32_16x16x32_bf16 v[98:101], v[162:165], v[206:209], v[98:101]
	v_mfma_f32_16x16x32_bf16 v[90:93], v[154:157], v[214:217], v[90:93]
	v_mfma_f32_16x16x32_bf16 v[82:85], v[162:165], v[214:217], v[82:85]
	v_mfma_f32_16x16x32_bf16 v[74:77], v[154:157], v[238:241], v[74:77]
	v_mfma_f32_16x16x32_bf16 v[54:57], v[162:165], v[238:241], v[54:57]
	v_mfma_f32_16x16x32_bf16 v[118:121], v[166:169], v[194:197], v[118:121]
	v_mfma_f32_16x16x32_bf16 v[122:125], v[174:177], v[194:197], v[122:125]
	v_mfma_f32_16x16x32_bf16 v[102:105], v[166:169], v[202:205], v[102:105]
	v_mfma_f32_16x16x32_bf16 v[110:113], v[174:177], v[202:205], v[110:113]
	v_mfma_f32_16x16x32_bf16 v[86:89], v[166:169], v[210:213], v[86:89]
	v_mfma_f32_16x16x32_bf16 v[94:97], v[174:177], v[210:213], v[94:97]
	v_mfma_f32_16x16x32_bf16 v[70:73], v[166:169], v[218:221], v[70:73]
	v_mfma_f32_16x16x32_bf16 v[78:81], v[174:177], v[218:221], v[78:81]
	v_mfma_f32_16x16x32_bf16 v[118:121], v[170:173], v[198:201], v[118:121]
	v_mfma_f32_16x16x32_bf16 v[122:125], v[190:193], v[198:201], v[122:125]
	v_mfma_f32_16x16x32_bf16 v[102:105], v[170:173], v[206:209], v[102:105]
	v_mfma_f32_16x16x32_bf16 v[110:113], v[190:193], v[206:209], v[110:113]
	v_mfma_f32_16x16x32_bf16 v[86:89], v[170:173], v[214:217], v[86:89]
	v_mfma_f32_16x16x32_bf16 v[94:97], v[190:193], v[214:217], v[94:97]
	v_mfma_f32_16x16x32_bf16 v[70:73], v[170:173], v[238:241], v[70:73]
	v_mfma_f32_16x16x32_bf16 v[78:81], v[190:193], v[238:241], v[78:81]
	s_setprio 0
	s_barrier
	s_add_i32 s68, s68, s8
	v_lshl_add_u64 v[178:179], s[46:47], 0, v[134:135]
	s_mov_b32 m0, s68
	ds_read_b128 v[194:197], v153 offset:16384
	ds_read_b128 v[198:201], v153 offset:17408
	ds_read_b128 v[202:205], v153 offset:18432
	ds_read_b128 v[206:209], v153 offset:19456
	ds_read_b128 v[210:213], v153 offset:20480
	ds_read_b128 v[214:217], v153 offset:21504
	ds_read_b128 v[218:221], v153 offset:22528
	ds_read_b128 v[238:241], v153 offset:23552
	global_load_lds_dwordx4 v[178:179], off
	s_add_i32 m0, s68, 0x2000
	s_add_u32 s68, s46, 0x80000
	v_lshl_add_u64 v[222:223], s[46:47], 0, v[138:139]
	s_addc_u32 s69, s47, 0
	s_add_i32 s70, s70, s8
	global_load_lds_dwordx4 v[222:223], off
	v_lshl_add_u64 v[242:243], s[68:69], 0, v[134:135]
	s_mov_b32 m0, s70
	v_lshl_add_u64 v[244:245], s[50:51], 0, v[136:137]
	global_load_lds_dwordx4 v[242:243], off
	v_lshl_add_u64 v[242:243], s[68:69], 0, v[138:139]
	s_add_i32 m0, s70, 0x2000
	s_nop 0
	global_load_lds_dwordx4 v[242:243], off
	v_lshl_add_u64 v[242:243], s[50:51], 0, v[132:133]
	s_mov_b32 m0, s56
	s_nop 0
	global_load_lds_dwordx4 v[242:243], off
	s_mov_b32 m0, s57
	s_nop 0
	global_load_lds_dwordx4 v[244:245], off
	s_waitcnt vmcnt(8)
	s_waitcnt lgkmcnt(0)
	s_barrier
	s_setprio 1
	s_waitcnt lgkmcnt(0)
	v_mfma_f32_16x16x32_bf16 v[50:53], v[144:147], v[194:197], v[50:53]
	v_mfma_f32_16x16x32_bf16 v[38:41], v[158:161], v[194:197], v[38:41]
	v_mfma_f32_16x16x32_bf16 v[22:25], v[144:147], v[202:205], v[22:25]
	v_mfma_f32_16x16x32_bf16 v[42:45], v[158:161], v[202:205], v[42:45]
	v_mfma_f32_16x16x32_bf16 v[30:33], v[144:147], v[210:213], v[30:33]
	v_mfma_f32_16x16x32_bf16 v[18:21], v[158:161], v[210:213], v[18:21]
	v_mfma_f32_16x16x32_bf16 v[10:13], v[144:147], v[218:221], v[10:13]
	v_mfma_f32_16x16x32_bf16 v[2:5], v[158:161], v[218:221], v[2:5]
	v_mfma_f32_16x16x32_bf16 v[50:53], v[154:157], v[198:201], v[50:53]
	v_mfma_f32_16x16x32_bf16 v[38:41], v[162:165], v[198:201], v[38:41]
	v_mfma_f32_16x16x32_bf16 v[22:25], v[154:157], v[206:209], v[22:25]
	v_mfma_f32_16x16x32_bf16 v[42:45], v[162:165], v[206:209], v[42:45]
	v_mfma_f32_16x16x32_bf16 v[30:33], v[154:157], v[214:217], v[30:33]
	v_mfma_f32_16x16x32_bf16 v[18:21], v[162:165], v[214:217], v[18:21]
	v_mfma_f32_16x16x32_bf16 v[10:13], v[154:157], v[238:241], v[10:13]
	v_mfma_f32_16x16x32_bf16 v[2:5], v[162:165], v[238:241], v[2:5]
	v_mfma_f32_16x16x32_bf16 v[46:49], v[166:169], v[194:197], v[46:49]
	v_mfma_f32_16x16x32_bf16 v[58:61], v[174:177], v[194:197], v[58:61]
	v_mfma_f32_16x16x32_bf16 v[62:65], v[166:169], v[202:205], v[62:65]
	v_mfma_f32_16x16x32_bf16 v[66:69], v[174:177], v[202:205], v[66:69]
	v_mfma_f32_16x16x32_bf16 v[26:29], v[166:169], v[210:213], v[26:29]
	v_mfma_f32_16x16x32_bf16 v[34:37], v[174:177], v[210:213], v[34:37]
	v_mfma_f32_16x16x32_bf16 v[6:9], v[166:169], v[218:221], v[6:9]
	v_mfma_f32_16x16x32_bf16 v[14:17], v[174:177], v[218:221], v[14:17]
	v_mfma_f32_16x16x32_bf16 v[46:49], v[170:173], v[198:201], v[46:49]
	v_mfma_f32_16x16x32_bf16 v[58:61], v[190:193], v[198:201], v[58:61]
	v_mfma_f32_16x16x32_bf16 v[62:65], v[170:173], v[206:209], v[62:65]
	v_mfma_f32_16x16x32_bf16 v[66:69], v[190:193], v[206:209], v[66:69]
	v_mfma_f32_16x16x32_bf16 v[26:29], v[170:173], v[214:217], v[26:29]
	v_mfma_f32_16x16x32_bf16 v[34:37], v[190:193], v[214:217], v[34:37]
	v_mfma_f32_16x16x32_bf16 v[6:9], v[170:173], v[238:241], v[6:9]
	v_mfma_f32_16x16x32_bf16 v[14:17], v[190:193], v[238:241], v[14:17]
	s_setprio 0
	s_barrier
	s_add_i32 s68, 0, 0x18000
	s_add_i32 s69, 0, 0x1c000
	v_add_u32_e32 v162, s68, v152
	v_add_u32_e32 v190, s69, v152
	ds_read_b128 v[144:147], v162
	ds_read_b128 v[154:157], v162 offset:1024
	ds_read_b128 v[158:161], v162 offset:2048
	ds_read_b128 v[162:165], v162 offset:3072
	ds_read_b128 v[166:169], v190
	ds_read_b128 v[170:173], v190 offset:1024
	ds_read_b128 v[174:177], v190 offset:2048
	ds_read_b128 v[190:193], v190 offset:3072
	s_add_u32 s50, s50, 0x80000
	s_addc_u32 s51, s51, 0
	s_mov_b32 m0, s58
	v_lshl_add_u64 v[246:247], s[50:51], 0, v[132:133]
	ds_read_b128 v[194:197], v153 offset:32768
	ds_read_b128 v[198:201], v153 offset:33792
	ds_read_b128 v[202:205], v153 offset:34816
	ds_read_b128 v[206:209], v153 offset:35840
	ds_read_b128 v[210:213], v153 offset:36864
	ds_read_b128 v[214:217], v153 offset:37888
	ds_read_b128 v[218:221], v153 offset:38912
	ds_read_b128 v[238:241], v153 offset:39936
	global_load_lds_dwordx4 v[246:247], off
	v_lshl_add_u64 v[246:247], s[50:51], 0, v[136:137]
	s_mov_b32 m0, s59
	s_nop 0
	global_load_lds_dwordx4 v[246:247], off
	s_waitcnt vmcnt(8)
	s_waitcnt lgkmcnt(0)
	s_barrier
	s_setprio 1
	s_waitcnt lgkmcnt(0)
	v_mfma_f32_16x16x32_bf16 v[126:129], v[144:147], v[194:197], v[126:129]
	v_mfma_f32_16x16x32_bf16 v[114:117], v[158:161], v[194:197], v[114:117]
	v_mfma_f32_16x16x32_bf16 v[106:109], v[144:147], v[202:205], v[106:109]
	v_mfma_f32_16x16x32_bf16 v[98:101], v[158:161], v[202:205], v[98:101]
	v_mfma_f32_16x16x32_bf16 v[90:93], v[144:147], v[210:213], v[90:93]
	v_mfma_f32_16x16x32_bf16 v[82:85], v[158:161], v[210:213], v[82:85]
	v_mfma_f32_16x16x32_bf16 v[74:77], v[144:147], v[218:221], v[74:77]
	v_mfma_f32_16x16x32_bf16 v[54:57], v[158:161], v[218:221], v[54:57]
	v_mfma_f32_16x16x32_bf16 v[126:129], v[154:157], v[198:201], v[126:129]
	v_mfma_f32_16x16x32_bf16 v[114:117], v[162:165], v[198:201], v[114:117]
	v_mfma_f32_16x16x32_bf16 v[106:109], v[154:157], v[206:209], v[106:109]
	v_mfma_f32_16x16x32_bf16 v[98:101], v[162:165], v[206:209], v[98:101]
	v_mfma_f32_16x16x32_bf16 v[90:93], v[154:157], v[214:217], v[90:93]
	v_mfma_f32_16x16x32_bf16 v[82:85], v[162:165], v[214:217], v[82:85]
	v_mfma_f32_16x16x32_bf16 v[74:77], v[154:157], v[238:241], v[74:77]
	v_mfma_f32_16x16x32_bf16 v[54:57], v[162:165], v[238:241], v[54:57]
	v_mfma_f32_16x16x32_bf16 v[118:121], v[166:169], v[194:197], v[118:121]
	v_mfma_f32_16x16x32_bf16 v[122:125], v[174:177], v[194:197], v[122:125]
	v_mfma_f32_16x16x32_bf16 v[102:105], v[166:169], v[202:205], v[102:105]
	v_mfma_f32_16x16x32_bf16 v[110:113], v[174:177], v[202:205], v[110:113]
	v_mfma_f32_16x16x32_bf16 v[86:89], v[166:169], v[210:213], v[86:89]
	v_mfma_f32_16x16x32_bf16 v[94:97], v[174:177], v[210:213], v[94:97]
	v_mfma_f32_16x16x32_bf16 v[70:73], v[166:169], v[218:221], v[70:73]
	v_mfma_f32_16x16x32_bf16 v[78:81], v[174:177], v[218:221], v[78:81]
	v_mfma_f32_16x16x32_bf16 v[118:121], v[170:173], v[198:201], v[118:121]
	v_mfma_f32_16x16x32_bf16 v[122:125], v[190:193], v[198:201], v[122:125]
	v_mfma_f32_16x16x32_bf16 v[102:105], v[170:173], v[206:209], v[102:105]
	v_mfma_f32_16x16x32_bf16 v[110:113], v[190:193], v[206:209], v[110:113]
	v_mfma_f32_16x16x32_bf16 v[86:89], v[170:173], v[214:217], v[86:89]
	v_mfma_f32_16x16x32_bf16 v[94:97], v[190:193], v[214:217], v[94:97]
	v_mfma_f32_16x16x32_bf16 v[70:73], v[170:173], v[238:241], v[70:73]
	v_mfma_f32_16x16x32_bf16 v[78:81], v[190:193], v[238:241], v[78:81]
	s_setprio 0
	s_barrier
	s_add_i32 s50, s68, s8
	v_lshl_add_u64 v[178:179], v[178:179], 0, s[16:17]
	s_mov_b32 m0, s50
	ds_read_b128 v[194:197], v153 offset:49152
	ds_read_b128 v[198:201], v153 offset:50176
	ds_read_b128 v[202:205], v153 offset:51200
	ds_read_b128 v[206:209], v153 offset:52224
	ds_read_b128 v[210:213], v153 offset:53248
	ds_read_b128 v[214:217], v153 offset:54272
	ds_read_b128 v[218:221], v153 offset:55296
	ds_read_b128 v[238:241], v153 offset:56320
	global_load_lds_dwordx4 v[178:179], off
	s_add_i32 m0, s50, 0x2000
	s_add_u32 s46, s46, 0x80080
	v_lshl_add_u64 v[178:179], v[222:223], 0, s[16:17]
	s_addc_u32 s47, s47, 0
	s_add_i32 s50, s69, s8
	global_load_lds_dwordx4 v[178:179], off
	v_lshl_add_u64 v[178:179], s[46:47], 0, v[134:135]
	s_mov_b32 m0, s50
	s_nop 0
	global_load_lds_dwordx4 v[178:179], off
	v_lshl_add_u64 v[178:179], s[46:47], 0, v[138:139]
	s_add_i32 m0, s50, 0x2000
	s_nop 0
	global_load_lds_dwordx4 v[178:179], off
	v_lshl_add_u64 v[178:179], v[242:243], 0, s[16:17]
	s_mov_b32 m0, s60
	s_nop 0
	global_load_lds_dwordx4 v[178:179], off
	v_lshl_add_u64 v[178:179], v[244:245], 0, s[16:17]
	s_mov_b32 m0, s61
	s_nop 0
	global_load_lds_dwordx4 v[178:179], off
	s_waitcnt vmcnt(8)
	s_waitcnt lgkmcnt(0)
	s_barrier
	s_setprio 1
	s_waitcnt lgkmcnt(0)
	v_mfma_f32_16x16x32_bf16 v[50:53], v[144:147], v[194:197], v[50:53]
	v_mfma_f32_16x16x32_bf16 v[38:41], v[158:161], v[194:197], v[38:41]
	v_mfma_f32_16x16x32_bf16 v[22:25], v[144:147], v[202:205], v[22:25]
	v_mfma_f32_16x16x32_bf16 v[42:45], v[158:161], v[202:205], v[42:45]
	v_mfma_f32_16x16x32_bf16 v[30:33], v[144:147], v[210:213], v[30:33]
	v_mfma_f32_16x16x32_bf16 v[18:21], v[158:161], v[210:213], v[18:21]
	v_mfma_f32_16x16x32_bf16 v[10:13], v[144:147], v[218:221], v[10:13]
	v_mfma_f32_16x16x32_bf16 v[2:5], v[158:161], v[218:221], v[2:5]
	v_mfma_f32_16x16x32_bf16 v[50:53], v[154:157], v[198:201], v[50:53]
	v_mfma_f32_16x16x32_bf16 v[38:41], v[162:165], v[198:201], v[38:41]
	v_mfma_f32_16x16x32_bf16 v[22:25], v[154:157], v[206:209], v[22:25]
	v_mfma_f32_16x16x32_bf16 v[42:45], v[162:165], v[206:209], v[42:45]
	v_mfma_f32_16x16x32_bf16 v[30:33], v[154:157], v[214:217], v[30:33]
	v_mfma_f32_16x16x32_bf16 v[18:21], v[162:165], v[214:217], v[18:21]
	v_mfma_f32_16x16x32_bf16 v[10:13], v[154:157], v[238:241], v[10:13]
	v_mfma_f32_16x16x32_bf16 v[2:5], v[162:165], v[238:241], v[2:5]
	v_mfma_f32_16x16x32_bf16 v[46:49], v[166:169], v[194:197], v[46:49]
	v_mfma_f32_16x16x32_bf16 v[58:61], v[174:177], v[194:197], v[58:61]
	v_mfma_f32_16x16x32_bf16 v[62:65], v[166:169], v[202:205], v[62:65]
	v_mfma_f32_16x16x32_bf16 v[66:69], v[174:177], v[202:205], v[66:69]
	v_mfma_f32_16x16x32_bf16 v[26:29], v[166:169], v[210:213], v[26:29]
	v_mfma_f32_16x16x32_bf16 v[34:37], v[174:177], v[210:213], v[34:37]
	v_mfma_f32_16x16x32_bf16 v[6:9], v[166:169], v[218:221], v[6:9]
	v_mfma_f32_16x16x32_bf16 v[14:17], v[174:177], v[218:221], v[14:17]
	v_mfma_f32_16x16x32_bf16 v[46:49], v[170:173], v[198:201], v[46:49]
	v_mfma_f32_16x16x32_bf16 v[58:61], v[190:193], v[198:201], v[58:61]
	v_mfma_f32_16x16x32_bf16 v[62:65], v[170:173], v[206:209], v[62:65]
	v_mfma_f32_16x16x32_bf16 v[66:69], v[190:193], v[206:209], v[66:69]
	v_mfma_f32_16x16x32_bf16 v[26:29], v[170:173], v[214:217], v[26:29]
	v_mfma_f32_16x16x32_bf16 v[34:37], v[190:193], v[214:217], v[34:37]
	v_mfma_f32_16x16x32_bf16 v[6:9], v[170:173], v[238:241], v[6:9]
	v_mfma_f32_16x16x32_bf16 v[14:17], v[190:193], v[238:241], v[14:17]
	s_setprio 0
	s_barrier
	s_add_i32 s67, s67, 2
	s_add_u32 s48, s48, 0x100
	s_addc_u32 s49, s49, 0
	s_add_u32 s64, s64, 0x100
	s_addc_u32 s66, s66, 0
	s_cmp_gt_u32 s67, 29
	s_cbranch_scc0 .LBB0_1583
	s_and_b64 vcc, exec, s[28:29]
	s_cbranch_vccnz .LBB0_1586
	s_barrier

.LBB0_1602:
	s_or_b64 exec, exec, s[38:39]
	s_andn2_b64 vcc, exec, s[36:37]
	s_mov_b64 s[36:37], -1
	s_cbranch_vccnz .LBB0_1575
	v_lshl_add_u32 v2, s34, 8, v151
	s_waitcnt lgkmcnt(0)
	v_ashrrev_i32_e32 v3, 31, v2
	v_lshlrev_b64 v[2:3], 12, v[2:3]
	s_lshl_b32 s36, s30, 8
	v_lshl_add_u64 v[2:3], s[14:15], 0, v[2:3]
	s_ashr_i32 s37, s36, 31
	v_lshl_add_u64 v[2:3], s[36:37], 1, v[2:3]
	v_lshl_add_u64 v[2:3], v[2:3], 0, s[12:13]
	v_lshl_add_u64 v[2:3], v[2:3], 0, v[180:181]
	s_mov_b32 s31, 0x10000
	v_add_co_u32_e32 v4, vcc, s31, v2
	s_mov_b32 s31, 0x20000
	s_nop 0
	v_addc_co_u32_e32 v5, vcc, 0, v3, vcc
	global_load_dwordx4 v[62:65], v[2:3], off
	global_load_dwordx4 v[54:57], v[2:3], off offset:256
	global_load_dwordx4 v[58:61], v[4:5], off
	global_load_dwordx4 v[46:49], v[4:5], off offset:256
	v_add_co_u32_e32 v4, vcc, s31, v2
	s_mov_b32 s31, 0x30000
	s_nop 0
	v_addc_co_u32_e32 v5, vcc, 0, v3, vcc
	global_load_dwordx4 v[50:53], v[4:5], off
	global_load_dwordx4 v[38:41], v[4:5], off offset:256
	v_add_co_u32_e32 v4, vcc, s31, v2
	s_mov_b32 s31, 0x80000
	s_nop 0
	v_addc_co_u32_e32 v5, vcc, 0, v3, vcc
	global_load_dwordx4 v[42:45], v[4:5], off
	global_load_dwordx4 v[30:33], v[4:5], off offset:256
	v_add_co_u32_e32 v4, vcc, s31, v2
	s_mov_b32 s31, 0x90000
	s_nop 0
	v_addc_co_u32_e32 v5, vcc, 0, v3, vcc
	global_load_dwordx4 v[34:37], v[4:5], off
	global_load_dwordx4 v[22:25], v[4:5], off offset:256
	v_add_co_u32_e32 v4, vcc, s31, v2
	s_nop 1
	v_addc_co_u32_e32 v5, vcc, 0, v3, vcc
	global_load_dwordx4 v[26:29], v[4:5], off
	global_load_dwordx4 v[18:21], v[4:5], off offset:256
	v_add_co_u32_e32 v4, vcc, 0xa0000, v2
	s_nop 1
	v_addc_co_u32_e32 v5, vcc, 0, v3, vcc
	v_add_co_u32_e32 v14, vcc, 0xb0000, v2
	global_load_dwordx4 v[10:13], v[4:5], off
	global_load_dwordx4 v[6:9], v[4:5], off offset:256
	v_addc_co_u32_e32 v15, vcc, 0, v3, vcc
	global_load_dwordx4 v[2:5], v[14:15], off
	s_nop 0
	global_load_dwordx4 v[14:17], v[14:15], off offset:256
	s_andn2_b64 vcc, exec, s[26:27]
	s_cbranch_vccz .LBB0_1574
	s_barrier
	s_branch .LBB0_1574

.LBB0_1672:
	s_waitcnt lgkmcnt(0)
	v_readlane_b32 s15, v255, 43
	s_lshl_b32 s6, s15, 6
	s_mov_b32 s7, s13
	v_writelane_b32 v255, s6, 53
	s_mul_i32 s12, s15, 0x4200
	s_andn2_b64 vcc, exec, s[2:3]
	v_writelane_b32 v255, s7, 54
	s_cbranch_vccnz .LBB0_1753
	s_waitcnt lgkmcnt(0)
	v_ashrrev_i32_e32 v3, 31, v16
	v_lshrrev_b32_e32 v3, 26, v3
	v_add_u32_e32 v3, v16, v3
	v_ashrrev_i32_e32 v10, 6, v3
	v_bfe_i32 v3, v16, 27, 1
	v_lshlrev_b32_e32 v2, 4, v16
	v_lshrrev_b32_e32 v3, 22, v3
	v_add_u32_e32 v3, v2, v3
	s_load_dwordx4 s[36:39], s[0:1], s8 offset:0x110
	v_and_b32_e32 v3, 0xfffffc00, v3
	v_sub_u32_e32 v3, v2, v3
	v_lshrrev_b32_e32 v4, 4, v3
	v_bitop3_b32 v3, v4, v3, 32 bitop3:0x6c
	v_ashrrev_i32_e32 v5, 31, v3
	s_waitcnt lgkmcnt(0)
	s_add_u32 s29, s38, 0x1de00000
	v_lshrrev_b32_e32 v5, 26, v5
	s_mul_i32 s3, s15, 0x2b00000
	s_addc_u32 s64, s39, 0
	v_add_u32_e32 v5, v3, v5
	s_mul_hi_u32 s2, s15, 0x2b00000
	s_add_u32 s3, s38, s3
	v_lshlrev_b32_e32 v4, 3, v10
	v_ashrrev_i32_e32 v11, 6, v5
	v_and_b32_e32 v5, 0xc0, v5
	s_addc_u32 s2, s39, s2
	v_and_b32_e32 v4, -16, v4
	v_sub_u32_e32 v3, v3, v5
	s_add_u32 s76, s3, 0x5600000
	v_add_u32_e32 v4, v11, v4
	v_ashrrev_i16_sdwa v3, v224, sext(v3) dst_sel:DWORD dst_unused:UNUSED_PAD src0_sel:DWORD src1_sel:BYTE_0
	s_addc_u32 s22, s2, 0
	v_lshlrev_b32_e32 v6, 5, v10
	v_bfe_i32 v12, v3, 0, 16
	v_lshlrev_b32_e32 v3, 1, v4
	v_lshrrev_b32_e32 v5, 2, v4
	v_and_b32_e32 v7, 3, v11
	s_mov_b32 s2, 0xfffe0
	v_and_b32_e32 v6, 32, v6
	v_and_b32_e32 v3, 24, v3
	v_and_b32_e32 v5, 4, v5
	v_and_or_b32 v7, v4, s2, v7
	v_or3_b32 v3, v7, v5, v3
	v_add_lshl_u32 v5, v6, v12, 1
	v_add_u32_e32 v2, 0x2000, v2
	v_lshl_add_u32 v180, v3, 12, v5
	v_ashrrev_i32_e32 v3, 31, v2
	v_lshrrev_b32_e32 v3, 22, v3
	v_add_u32_e32 v3, v2, v3
	v_ashrrev_i32_e32 v13, 10, v3
	v_mul_i32_i24_e32 v3, 0x400, v13
	v_sub_u32_e32 v2, v2, v3
	v_lshrrev_b32_e32 v3, 4, v2
	v_bitop3_b32 v2, v3, v2, 32 bitop3:0x6c
	v_lshl_add_u32 v192, v4, 12, v5
	v_ashrrev_i32_e32 v4, 31, v2
	v_lshrrev_b32_e32 v4, 26, v4
	v_lshlrev_b32_e32 v3, 3, v13
	v_add_u32_e32 v4, v2, v4
	v_and_b32_e32 v3, -16, v3
	v_ashrrev_i32_e32 v14, 6, v4
	v_add_u32_e32 v3, v14, v3
	v_and_b32_e32 v4, 0xc0, v4
	v_and_b32_e32 v6, 3, v14
	s_ashr_i32 s14, s10, 6
	s_ashr_i32 s45, s44, 31
	s_ashr_i32 s27, s26, 31
	v_sub_u32_e32 v2, v2, v4
	v_and_or_b32 v6, v3, s2, v6
	s_ashr_i32 s11, s10, 8
	s_lshl_b32 s23, s14, 10
	s_lshl_b64 s[2:3], s[44:45], 20
	s_lshl_b64 s[6:7], s[26:27], 20
	v_ashrrev_i16_sdwa v2, v224, sext(v2) dst_sel:DWORD dst_unused:UNUSED_PAD src0_sel:DWORD src1_sel:BYTE_0
	s_add_u32 s46, s76, s6
	v_lshlrev_b32_e32 v5, 5, v13
	v_bfe_i32 v15, v2, 0, 16
	v_lshlrev_b32_e32 v2, 1, v3
	v_lshrrev_b32_e32 v4, 2, v3
	s_addc_u32 s47, s22, s7
	s_add_i32 s6, s23, 0
	v_and_b32_e32 v5, 32, v5
	v_and_b32_e32 v2, 24, v2
	v_and_b32_e32 v4, 4, v4
	s_add_i32 m0, s6, 0x10000
	v_or3_b32 v2, v6, v4, v2
	v_add_lshl_u32 v4, v5, v15, 1
	global_load_lds_dwordx4 v180, s[46:47]
	s_add_i32 m0, s6, 0x12000
	v_lshl_add_u32 v196, v2, 12, v4
	s_add_u32 s18, s46, 0x80000
	global_load_lds_dwordx4 v196, s[46:47]
	s_addc_u32 s19, s47, 0
	s_add_i32 m0, s6, 0x14000
	v_lshl_add_u32 v194, v3, 12, v4
	global_load_lds_dwordx4 v180, s[18:19]
	s_add_i32 m0, s6, 0x16000
	s_add_u32 s48, s29, s2
	s_addc_u32 s49, s64, s3
	s_add_i32 s9, s6, 0x2000
	global_load_lds_dwordx4 v196, s[18:19]
	s_mov_b32 m0, s6
	s_add_u32 s2, s48, 0x80000
	global_load_lds_dwordx4 v192, s[48:49]
	s_mov_b32 m0, s9
	s_addc_u32 s3, s49, 0
	s_add_i32 s21, s6, 0x4000
	global_load_lds_dwordx4 v194, s[48:49]
	s_mov_b32 m0, s21
	s_add_i32 s7, s6, 0x6000
	global_load_lds_dwordx4 v192, s[2:3]
	s_mov_b32 m0, s7
	v_writelane_b32 v255, s97, 55
	global_load_lds_dwordx4 v194, s[2:3]
	s_load_dwordx2 s[2:3], s[0:1], s8 offset:0x38
	s_load_dwordx4 s[40:43], s[0:1], s8 offset:0xf8
	v_writelane_b32 v255, s96, 56
	v_mov_b32_e32 v197, v181
	v_mov_b32_e32 v193, v181
	v_mov_b32_e32 v195, v181
	s_cmp_eq_u32 s11, 1
	v_writelane_b32 v255, s70, 57
	v_lshl_add_u64 v[8:9], s[46:47], 0, v[180:181]
	v_lshl_add_u64 v[6:7], s[46:47], 0, v[196:197]
	v_lshl_add_u64 v[2:3], s[48:49], 0, v[192:193]
	s_cselect_b64 s[56:57], -1, 0
	s_cmp_lg_u32 s11, 1
	v_lshl_add_u64 v[4:5], s[48:49], 0, v[194:195]
	s_mov_b32 s8, s15
	s_cbranch_scc0 .LBB0_1675
	s_barrier

.LBB0_1688:
	s_and_b64 vcc, exec, s[30:31]
	s_cbranch_vccnz .LBB0_1690
	s_barrier

.LBB0_1750:
	s_andn2_b64 vcc, exec, s[56:57]
	s_cbranch_vccz .LBB0_1676
	s_barrier
	s_branch .LBB0_1676

.LBB0_1753:
	s_load_dwordx2 s[26:27], s[24:25], 0x118
	v_sub_co_u32_e64 v150, s[2:3], s15, 1
	s_andn2_b64 vcc, exec, s[2:3]
	s_cbranch_vccnz .LBB0_1858
	s_add_i32 s6, s28, s33
	v_readlane_b32 s2, v255, 19
	s_sub_i32 s2, s6, s2
	s_ashr_i32 s3, s2, 31
	s_abs_i32 s2, s2
	v_readlane_b32 s7, v255, 20
	s_mul_hi_u32 s7, s2, s7
	v_readlane_b32 s8, v255, 21
	s_mul_i32 s7, s7, s8
	s_sub_i32 s2, s2, s7
	s_sub_i32 s7, s2, s8
	s_cmp_ge_u32 s2, s8
	s_cselect_b32 s2, s7, s2
	s_sub_i32 s7, s2, s8
	s_cmp_ge_u32 s2, s8
	s_cselect_b32 s2, s7, s2
	s_xor_b32 s2, s2, s3
	v_mov_b32_e32 v16, v0
	s_sub_i32 s7, s2, s3
	s_cmp_gt_i32 s7, 47
	v_readfirstlane_b32 s34, v16
	s_cbranch_scc1 .LBB0_1768
	v_lshlrev_b32_e32 v2, 4, v16
	s_waitcnt lgkmcnt(0)
	v_add_u32_e32 v3, 0x2000, v2
	v_ashrrev_i32_e32 v4, 31, v3
	v_lshrrev_b32_e32 v4, 22, v4
	v_add_u32_e32 v4, v3, v4
	v_ashrrev_i32_e32 v10, 10, v4
	v_mul_i32_i24_e32 v5, 0x400, v10
	v_sub_u32_e32 v3, v3, v5
	v_lshrrev_b32_e32 v5, 4, v3
	v_bitop3_b32 v3, v5, v3, 32 bitop3:0x6c
	v_ashrrev_i32_e32 v5, 31, v3
	v_lshrrev_b32_e32 v5, 26, v5
	v_add_u32_e32 v5, v3, v5
	v_ashrrev_i32_e32 v11, 6, v5
	v_and_b32_e32 v5, 0xc0, v5
	v_sub_u32_e32 v3, v3, v5
	v_lshlrev_b32_e32 v4, 5, v10
	v_ashrrev_i16_sdwa v3, v224, sext(v3) dst_sel:DWORD dst_unused:UNUSED_PAD src0_sel:DWORD src1_sel:BYTE_0
	v_and_b32_e32 v4, 32, v4
	v_bfe_i32 v12, v3, 0, 16
	v_add_u32_e32 v3, v4, v12
	v_lshlrev_b32_e32 v4, 3, v10
	v_and_b32_e32 v4, 0xffff0, v4
	v_add_lshl_u32 v4, v11, v4, 12
	v_lshl_add_u32 v130, v3, 1, v4
	v_bfe_i32 v4, v16, 27, 1
	v_lshrrev_b32_e32 v4, 22, v4
	v_add_u32_e32 v4, v2, v4
	v_and_b32_e32 v4, 0xfffffc00, v4
	v_sub_u32_e32 v2, v2, v4
	v_lshrrev_b32_e32 v4, 4, v2
	v_bitop3_b32 v2, v4, v2, 32 bitop3:0x6c
	v_ashrrev_i32_e32 v4, 31, v2
	s_add_u32 s8, s26, 0x1ff00000
	v_ashrrev_i32_e32 v3, 31, v16
	v_lshrrev_b32_e32 v4, 26, v4
	s_addc_u32 s9, s27, 0
	v_lshrrev_b32_e32 v3, 26, v3
	v_add_u32_e32 v4, v2, v4
	s_add_u32 s21, s26, 0x15800000
	v_add_u32_e32 v3, v16, v3
	v_ashrrev_i32_e32 v14, 6, v4
	v_and_b32_e32 v4, 0xc0, v4
	s_addc_u32 s42, s27, 0
	s_add_i32 s2, s7, 16
	v_ashrrev_i32_e32 v13, 6, v3
	v_sub_u32_e32 v2, v2, v4
	s_ashr_i32 s2, s2, 2
	v_lshlrev_b32_e32 v3, 5, v13
	v_ashrrev_i16_sdwa v2, v224, sext(v2) dst_sel:DWORD dst_unused:UNUSED_PAD src0_sel:DWORD src1_sel:BYTE_0
	s_ashr_i32 s35, s34, 6
	s_and_b32 s44, s7, 3
	v_and_b32_e32 v3, 32, v3
	v_bfe_i32 v15, v2, 0, 16
	s_ashr_i32 s3, s2, 31
	s_ashr_i32 s36, s34, 8
	s_lshl_b32 s43, s35, 10
	v_add_u32_e32 v2, v3, v15
	v_lshlrev_b32_e32 v3, 3, v13
	s_lshl_b32 s18, s44, 20
	s_lshl_b64 s[10:11], s[2:3], 20
	v_and_b32_e32 v3, 0xffff0, v3
	s_add_u32 s10, s21, s10
	v_add_lshl_u32 v3, v14, v3, 12
	s_addc_u32 s11, s42, s11
	s_add_i32 s3, s43, 0
	v_lshl_add_u32 v132, v2, 1, v3
	s_add_i32 m0, s3, 0x10000
	v_mov_b32_e32 v133, v181
	global_load_lds_dwordx4 v132, s[10:11]
	s_add_i32 m0, s3, 0x12000
	s_add_u32 s14, s10, 0x80000
	global_load_lds_dwordx4 v130, s[10:11]
	s_addc_u32 s15, s11, 0
	s_add_i32 m0, s3, 0x14000
	v_mov_b32_e32 v131, v181
	global_load_lds_dwordx4 v132, s[14:15]
	s_add_i32 m0, s3, 0x16000
	s_add_u32 s18, s8, s18
	s_addc_u32 s19, s9, 0
	s_add_i32 s45, s3, 0x2000
	global_load_lds_dwordx4 v130, s[14:15]
	s_mov_b32 m0, s3
	s_add_u32 s14, s18, 0x80000
	global_load_lds_dwordx4 v132, s[18:19]
	s_mov_b32 m0, s45
	s_addc_u32 s15, s19, 0
	s_add_i32 s46, s3, 0x4000
	global_load_lds_dwordx4 v130, s[18:19]
	s_mov_b32 m0, s46
	s_add_i32 s47, s3, 0x6000
	global_load_lds_dwordx4 v132, s[14:15]
	s_mov_b32 m0, s47
	s_cmp_eq_u32 s36, 1
	global_load_lds_dwordx4 v130, s[14:15]
	s_load_dwordx2 s[14:15], s[24:25], 0x110
	v_lshl_add_u64 v[8:9], s[10:11], 0, v[132:133]
	v_lshl_add_u64 v[6:7], s[10:11], 0, v[130:131]
	v_lshl_add_u64 v[2:3], s[18:19], 0, v[132:133]
	s_cselect_b64 s[22:23], -1, 0
	s_cmp_lg_u32 s36, 1
	v_lshl_add_u64 v[4:5], s[18:19], 0, v[130:131]
	s_cbranch_scc0 .LBB0_1757
	s_barrier

.LBB0_1761:
	s_add_u32 s26, s38, 0xfff80080
	s_addc_u32 s27, s39, -1
	s_add_i32 s64, 0, 0x10000
	s_cmp_eq_u32 s63, 28
	s_cselect_b32 s41, s57, s27
	s_cselect_b32 s40, s58, s26
	v_add_u32_e32 v155, s64, v153
	s_cselect_b32 s27, s59, s62
	s_cselect_b32 s26, s60, s61
	s_add_i32 s68, 0, 0x14000
	ds_read_b128 v[138:141], v155
	ds_read_b128 v[142:145], v155 offset:1024
	ds_read_b128 v[146:149], v155 offset:2048
	ds_read_b128 v[156:159], v155 offset:3072
	v_add_u32_e32 v155, s68, v153
	ds_read_b128 v[160:163], v155
	ds_read_b128 v[164:167], v155 offset:1024
	ds_read_b128 v[168:171], v155 offset:2048
	ds_read_b128 v[172:175], v155 offset:3072
	v_lshl_add_u64 v[220:221], s[38:39], 0, v[134:135]
	s_add_i32 m0, s3, 0xc000
	ds_read_b128 v[176:179], v154
	ds_read_b128 v[192:195], v154 offset:1024
	ds_read_b128 v[196:199], v154 offset:2048
	ds_read_b128 v[200:203], v154 offset:3072
	ds_read_b128 v[204:207], v154 offset:4096
	ds_read_b128 v[208:211], v154 offset:5120
	ds_read_b128 v[212:215], v154 offset:6144
	ds_read_b128 v[216:219], v154 offset:7168
	global_load_lds_dwordx4 v[220:221], off
	v_lshl_add_u64 v[220:221], s[38:39], 0, v[136:137]
	s_add_i32 m0, s3, 0xe000
	s_nop 0
	global_load_lds_dwordx4 v[220:221], off
	s_waitcnt vmcnt(8)
	s_waitcnt lgkmcnt(0)
	s_barrier
	s_setprio 1
	s_waitcnt lgkmcnt(0)
	v_mfma_f32_16x16x32_bf16 v[126:129], v[138:141], v[176:179], v[126:129]
	v_mfma_f32_16x16x32_bf16 v[122:125], v[146:149], v[176:179], v[122:125]
	v_mfma_f32_16x16x32_bf16 v[110:113], v[138:141], v[196:199], v[110:113]
	v_mfma_f32_16x16x32_bf16 v[106:109], v[146:149], v[196:199], v[106:109]
	v_mfma_f32_16x16x32_bf16 v[94:97], v[138:141], v[204:207], v[94:97]
	v_mfma_f32_16x16x32_bf16 v[90:93], v[146:149], v[204:207], v[90:93]
	v_mfma_f32_16x16x32_bf16 v[78:81], v[138:141], v[212:215], v[78:81]
	v_mfma_f32_16x16x32_bf16 v[74:77], v[146:149], v[212:215], v[74:77]
	v_mfma_f32_16x16x32_bf16 v[126:129], v[142:145], v[192:195], v[126:129]
	v_mfma_f32_16x16x32_bf16 v[122:125], v[156:159], v[192:195], v[122:125]
	v_mfma_f32_16x16x32_bf16 v[110:113], v[142:145], v[200:203], v[110:113]
	v_mfma_f32_16x16x32_bf16 v[106:109], v[156:159], v[200:203], v[106:109]
	v_mfma_f32_16x16x32_bf16 v[94:97], v[142:145], v[208:211], v[94:97]
	v_mfma_f32_16x16x32_bf16 v[90:93], v[156:159], v[208:211], v[90:93]
	v_mfma_f32_16x16x32_bf16 v[78:81], v[142:145], v[216:219], v[78:81]
	v_mfma_f32_16x16x32_bf16 v[74:77], v[156:159], v[216:219], v[74:77]
	v_mfma_f32_16x16x32_bf16 v[118:121], v[160:163], v[176:179], v[118:121]
	v_mfma_f32_16x16x32_bf16 v[114:117], v[168:171], v[176:179], v[114:117]
	v_mfma_f32_16x16x32_bf16 v[102:105], v[160:163], v[196:199], v[102:105]
	v_mfma_f32_16x16x32_bf16 v[98:101], v[168:171], v[196:199], v[98:101]
	v_mfma_f32_16x16x32_bf16 v[86:89], v[160:163], v[204:207], v[86:89]
	v_mfma_f32_16x16x32_bf16 v[82:85], v[168:171], v[204:207], v[82:85]
	v_mfma_f32_16x16x32_bf16 v[70:73], v[160:163], v[212:215], v[70:73]
	v_mfma_f32_16x16x32_bf16 v[66:69], v[168:171], v[212:215], v[66:69]
	v_mfma_f32_16x16x32_bf16 v[118:121], v[164:167], v[192:195], v[118:121]
	v_mfma_f32_16x16x32_bf16 v[114:117], v[172:175], v[192:195], v[114:117]
	v_mfma_f32_16x16x32_bf16 v[102:105], v[164:167], v[200:203], v[102:105]
	v_mfma_f32_16x16x32_bf16 v[98:101], v[172:175], v[200:203], v[98:101]
	v_mfma_f32_16x16x32_bf16 v[86:89], v[164:167], v[208:211], v[86:89]
	v_mfma_f32_16x16x32_bf16 v[82:85], v[172:175], v[208:211], v[82:85]
	v_mfma_f32_16x16x32_bf16 v[70:73], v[164:167], v[216:219], v[70:73]
	v_mfma_f32_16x16x32_bf16 v[66:69], v[172:175], v[216:219], v[66:69]
	s_setprio 0
	s_barrier
	s_add_i32 s64, s64, s43
	v_lshl_add_u64 v[220:221], s[26:27], 0, v[132:133]
	s_mov_b32 m0, s64
	ds_read_b128 v[176:179], v154 offset:16384
	ds_read_b128 v[192:195], v154 offset:17408
	ds_read_b128 v[196:199], v154 offset:18432
	ds_read_b128 v[200:203], v154 offset:19456
	ds_read_b128 v[204:207], v154 offset:20480
	ds_read_b128 v[208:211], v154 offset:21504
	ds_read_b128 v[212:215], v154 offset:22528
	ds_read_b128 v[216:219], v154 offset:23552
	global_load_lds_dwordx4 v[220:221], off
	s_add_i32 m0, s64, 0x2000
	s_add_u32 s66, s26, 0x80000
	v_lshl_add_u64 v[222:223], s[26:27], 0, v[130:131]
	s_addc_u32 s67, s27, 0
	s_add_i32 s64, s68, s43
	global_load_lds_dwordx4 v[222:223], off
	v_lshl_add_u64 v[238:239], s[66:67], 0, v[132:133]
	s_mov_b32 m0, s64
	v_lshl_add_u64 v[240:241], s[40:41], 0, v[130:131]
	global_load_lds_dwordx4 v[238:239], off
	v_lshl_add_u64 v[238:239], s[66:67], 0, v[130:131]
	s_add_i32 m0, s64, 0x2000
	s_nop 0
	global_load_lds_dwordx4 v[238:239], off
	v_lshl_add_u64 v[238:239], s[40:41], 0, v[132:133]
	s_mov_b32 m0, s3
	s_nop 0
	global_load_lds_dwordx4 v[238:239], off
	s_mov_b32 m0, s45
	s_nop 0
	global_load_lds_dwordx4 v[240:241], off
	s_waitcnt vmcnt(8)
	s_waitcnt lgkmcnt(0)
	s_barrier
	s_setprio 1
	s_waitcnt lgkmcnt(0)
	v_mfma_f32_16x16x32_bf16 v[62:65], v[138:141], v[176:179], v[62:65]
	v_mfma_f32_16x16x32_bf16 v[58:61], v[146:149], v[176:179], v[58:61]
	v_mfma_f32_16x16x32_bf16 v[46:49], v[138:141], v[196:199], v[46:49]
	v_mfma_f32_16x16x32_bf16 v[42:45], v[146:149], v[196:199], v[42:45]
	v_mfma_f32_16x16x32_bf16 v[30:33], v[138:141], v[204:207], v[30:33]
	v_mfma_f32_16x16x32_bf16 v[26:29], v[146:149], v[204:207], v[26:29]
	v_mfma_f32_16x16x32_bf16 v[14:17], v[138:141], v[212:215], v[14:17]
	v_mfma_f32_16x16x32_bf16 v[10:13], v[146:149], v[212:215], v[10:13]
	v_mfma_f32_16x16x32_bf16 v[62:65], v[142:145], v[192:195], v[62:65]
	v_mfma_f32_16x16x32_bf16 v[58:61], v[156:159], v[192:195], v[58:61]
	v_mfma_f32_16x16x32_bf16 v[46:49], v[142:145], v[200:203], v[46:49]
	v_mfma_f32_16x16x32_bf16 v[42:45], v[156:159], v[200:203], v[42:45]
	v_mfma_f32_16x16x32_bf16 v[30:33], v[142:145], v[208:211], v[30:33]
	v_mfma_f32_16x16x32_bf16 v[26:29], v[156:159], v[208:211], v[26:29]
	v_mfma_f32_16x16x32_bf16 v[14:17], v[142:145], v[216:219], v[14:17]
	v_mfma_f32_16x16x32_bf16 v[10:13], v[156:159], v[216:219], v[10:13]
	v_mfma_f32_16x16x32_bf16 v[54:57], v[160:163], v[176:179], v[54:57]
	v_mfma_f32_16x16x32_bf16 v[50:53], v[168:171], v[176:179], v[50:53]
	v_mfma_f32_16x16x32_bf16 v[38:41], v[160:163], v[196:199], v[38:41]
	v_mfma_f32_16x16x32_bf16 v[34:37], v[168:171], v[196:199], v[34:37]
	v_mfma_f32_16x16x32_bf16 v[22:25], v[160:163], v[204:207], v[22:25]
	v_mfma_f32_16x16x32_bf16 v[18:21], v[168:171], v[204:207], v[18:21]
	v_mfma_f32_16x16x32_bf16 v[6:9], v[160:163], v[212:215], v[6:9]
	v_mfma_f32_16x16x32_bf16 v[2:5], v[168:171], v[212:215], v[2:5]
	v_mfma_f32_16x16x32_bf16 v[54:57], v[164:167], v[192:195], v[54:57]
	v_mfma_f32_16x16x32_bf16 v[50:53], v[172:175], v[192:195], v[50:53]
	v_mfma_f32_16x16x32_bf16 v[38:41], v[164:167], v[200:203], v[38:41]
	v_mfma_f32_16x16x32_bf16 v[34:37], v[172:175], v[200:203], v[34:37]
	v_mfma_f32_16x16x32_bf16 v[22:25], v[164:167], v[208:211], v[22:25]
	v_mfma_f32_16x16x32_bf16 v[18:21], v[172:175], v[208:211], v[18:21]
	v_mfma_f32_16x16x32_bf16 v[6:9], v[164:167], v[216:219], v[6:9]
	v_mfma_f32_16x16x32_bf16 v[2:5], v[172:175], v[216:219], v[2:5]
	s_setprio 0
	s_barrier
	s_add_i32 s64, 0, 0x18000
	v_add_u32_e32 v155, s64, v153
	s_add_i32 s66, 0, 0x1c000
	ds_read_b128 v[138:141], v155
	ds_read_b128 v[142:145], v155 offset:1024
	ds_read_b128 v[146:149], v155 offset:2048
	ds_read_b128 v[156:159], v155 offset:3072
	v_add_u32_e32 v155, s66, v153
	ds_read_b128 v[160:163], v155
	ds_read_b128 v[164:167], v155 offset:1024
	ds_read_b128 v[168:171], v155 offset:2048
	ds_read_b128 v[172:175], v155 offset:3072
	s_add_u32 s40, s40, 0x80000
	s_addc_u32 s41, s41, 0
	s_mov_b32 m0, s46
	v_lshl_add_u64 v[242:243], s[40:41], 0, v[132:133]
	ds_read_b128 v[176:179], v154 offset:32768
	ds_read_b128 v[192:195], v154 offset:33792
	ds_read_b128 v[196:199], v154 offset:34816
	ds_read_b128 v[200:203], v154 offset:35840
	ds_read_b128 v[204:207], v154 offset:36864
	ds_read_b128 v[208:211], v154 offset:37888
	ds_read_b128 v[212:215], v154 offset:38912
	ds_read_b128 v[216:219], v154 offset:39936
	global_load_lds_dwordx4 v[242:243], off
	v_lshl_add_u64 v[242:243], s[40:41], 0, v[130:131]
	s_mov_b32 m0, s47
	s_nop 0
	global_load_lds_dwordx4 v[242:243], off
	s_waitcnt vmcnt(8)
	s_waitcnt lgkmcnt(0)
	s_barrier
	s_setprio 1
	s_waitcnt lgkmcnt(0)
	v_mfma_f32_16x16x32_bf16 v[126:129], v[138:141], v[176:179], v[126:129]
	v_mfma_f32_16x16x32_bf16 v[122:125], v[146:149], v[176:179], v[122:125]
	v_mfma_f32_16x16x32_bf16 v[110:113], v[138:141], v[196:199], v[110:113]
	v_mfma_f32_16x16x32_bf16 v[106:109], v[146:149], v[196:199], v[106:109]
	v_mfma_f32_16x16x32_bf16 v[94:97], v[138:141], v[204:207], v[94:97]
	v_mfma_f32_16x16x32_bf16 v[90:93], v[146:149], v[204:207], v[90:93]
	v_mfma_f32_16x16x32_bf16 v[78:81], v[138:141], v[212:215], v[78:81]
	v_mfma_f32_16x16x32_bf16 v[74:77], v[146:149], v[212:215], v[74:77]
	v_mfma_f32_16x16x32_bf16 v[126:129], v[142:145], v[192:195], v[126:129]
	v_mfma_f32_16x16x32_bf16 v[122:125], v[156:159], v[192:195], v[122:125]
	v_mfma_f32_16x16x32_bf16 v[110:113], v[142:145], v[200:203], v[110:113]
	v_mfma_f32_16x16x32_bf16 v[106:109], v[156:159], v[200:203], v[106:109]
	v_mfma_f32_16x16x32_bf16 v[94:97], v[142:145], v[208:211], v[94:97]
	v_mfma_f32_16x16x32_bf16 v[90:93], v[156:159], v[208:211], v[90:93]
	v_mfma_f32_16x16x32_bf16 v[78:81], v[142:145], v[216:219], v[78:81]
	v_mfma_f32_16x16x32_bf16 v[74:77], v[156:159], v[216:219], v[74:77]
	v_mfma_f32_16x16x32_bf16 v[118:121], v[160:163], v[176:179], v[118:121]
	v_mfma_f32_16x16x32_bf16 v[114:117], v[168:171], v[176:179], v[114:117]
	v_mfma_f32_16x16x32_bf16 v[102:105], v[160:163], v[196:199], v[102:105]
	v_mfma_f32_16x16x32_bf16 v[98:101], v[168:171], v[196:199], v[98:101]
	v_mfma_f32_16x16x32_bf16 v[86:89], v[160:163], v[204:207], v[86:89]
	v_mfma_f32_16x16x32_bf16 v[82:85], v[168:171], v[204:207], v[82:85]
	v_mfma_f32_16x16x32_bf16 v[70:73], v[160:163], v[212:215], v[70:73]
	v_mfma_f32_16x16x32_bf16 v[66:69], v[168:171], v[212:215], v[66:69]
	v_mfma_f32_16x16x32_bf16 v[118:121], v[164:167], v[192:195], v[118:121]
	v_mfma_f32_16x16x32_bf16 v[114:117], v[172:175], v[192:195], v[114:117]
	v_mfma_f32_16x16x32_bf16 v[102:105], v[164:167], v[200:203], v[102:105]
	v_mfma_f32_16x16x32_bf16 v[98:101], v[172:175], v[200:203], v[98:101]
	v_mfma_f32_16x16x32_bf16 v[86:89], v[164:167], v[208:211], v[86:89]
	v_mfma_f32_16x16x32_bf16 v[82:85], v[172:175], v[208:211], v[82:85]
	v_mfma_f32_16x16x32_bf16 v[70:73], v[164:167], v[216:219], v[70:73]
	v_mfma_f32_16x16x32_bf16 v[66:69], v[172:175], v[216:219], v[66:69]
	s_setprio 0
	s_barrier
	s_add_i32 s40, s64, s43
	v_lshl_add_u64 v[220:221], v[220:221], 0, s[16:17]
	s_mov_b32 m0, s40
	ds_read_b128 v[176:179], v154 offset:49152
	ds_read_b128 v[192:195], v154 offset:50176
	ds_read_b128 v[196:199], v154 offset:51200
	ds_read_b128 v[200:203], v154 offset:52224
	ds_read_b128 v[204:207], v154 offset:53248
	ds_read_b128 v[208:211], v154 offset:54272
	ds_read_b128 v[212:215], v154 offset:55296
	ds_read_b128 v[216:219], v154 offset:56320
	global_load_lds_dwordx4 v[220:221], off
	s_add_i32 m0, s40, 0x2000
	s_add_u32 s26, s26, 0x80080
	v_lshl_add_u64 v[220:221], v[222:223], 0, s[16:17]
	s_addc_u32 s27, s27, 0
	s_add_i32 s40, s66, s43
	global_load_lds_dwordx4 v[220:221], off
	v_lshl_add_u64 v[220:221], s[26:27], 0, v[132:133]
	s_mov_b32 m0, s40
	s_nop 0
	global_load_lds_dwordx4 v[220:221], off
	v_lshl_add_u64 v[220:221], s[26:27], 0, v[130:131]
	s_add_i32 m0, s40, 0x2000
	s_nop 0
	global_load_lds_dwordx4 v[220:221], off
	v_lshl_add_u64 v[220:221], v[238:239], 0, s[16:17]
	s_mov_b32 m0, s50
	s_nop 0
	global_load_lds_dwordx4 v[220:221], off
	v_lshl_add_u64 v[220:221], v[240:241], 0, s[16:17]
	s_mov_b32 m0, s51
	s_nop 0
	global_load_lds_dwordx4 v[220:221], off
	s_waitcnt vmcnt(8)
	s_waitcnt lgkmcnt(0)
	s_barrier
	s_setprio 1
	s_waitcnt lgkmcnt(0)
	v_mfma_f32_16x16x32_bf16 v[62:65], v[138:141], v[176:179], v[62:65]
	v_mfma_f32_16x16x32_bf16 v[58:61], v[146:149], v[176:179], v[58:61]
	v_mfma_f32_16x16x32_bf16 v[46:49], v[138:141], v[196:199], v[46:49]
	v_mfma_f32_16x16x32_bf16 v[42:45], v[146:149], v[196:199], v[42:45]
	v_mfma_f32_16x16x32_bf16 v[30:33], v[138:141], v[204:207], v[30:33]
	v_mfma_f32_16x16x32_bf16 v[26:29], v[146:149], v[204:207], v[26:29]
	v_mfma_f32_16x16x32_bf16 v[14:17], v[138:141], v[212:215], v[14:17]
	v_mfma_f32_16x16x32_bf16 v[10:13], v[146:149], v[212:215], v[10:13]
	v_mfma_f32_16x16x32_bf16 v[62:65], v[142:145], v[192:195], v[62:65]
	v_mfma_f32_16x16x32_bf16 v[58:61], v[156:159], v[192:195], v[58:61]
	v_mfma_f32_16x16x32_bf16 v[46:49], v[142:145], v[200:203], v[46:49]
	v_mfma_f32_16x16x32_bf16 v[42:45], v[156:159], v[200:203], v[42:45]
	v_mfma_f32_16x16x32_bf16 v[30:33], v[142:145], v[208:211], v[30:33]
	v_mfma_f32_16x16x32_bf16 v[26:29], v[156:159], v[208:211], v[26:29]
	v_mfma_f32_16x16x32_bf16 v[14:17], v[142:145], v[216:219], v[14:17]
	v_mfma_f32_16x16x32_bf16 v[10:13], v[156:159], v[216:219], v[10:13]
	v_mfma_f32_16x16x32_bf16 v[54:57], v[160:163], v[176:179], v[54:57]
	v_mfma_f32_16x16x32_bf16 v[50:53], v[168:171], v[176:179], v[50:53]
	v_mfma_f32_16x16x32_bf16 v[38:41], v[160:163], v[196:199], v[38:41]
	v_mfma_f32_16x16x32_bf16 v[34:37], v[168:171], v[196:199], v[34:37]
	v_mfma_f32_16x16x32_bf16 v[22:25], v[160:163], v[204:207], v[22:25]
	v_mfma_f32_16x16x32_bf16 v[18:21], v[168:171], v[204:207], v[18:21]
	v_mfma_f32_16x16x32_bf16 v[6:9], v[160:163], v[212:215], v[6:9]
	v_mfma_f32_16x16x32_bf16 v[2:5], v[168:171], v[212:215], v[2:5]
	v_mfma_f32_16x16x32_bf16 v[54:57], v[164:167], v[192:195], v[54:57]
	v_mfma_f32_16x16x32_bf16 v[50:53], v[172:175], v[192:195], v[50:53]
	v_mfma_f32_16x16x32_bf16 v[38:41], v[164:167], v[200:203], v[38:41]
	v_mfma_f32_16x16x32_bf16 v[34:37], v[172:175], v[200:203], v[34:37]
	v_mfma_f32_16x16x32_bf16 v[22:25], v[164:167], v[208:211], v[22:25]
	v_mfma_f32_16x16x32_bf16 v[18:21], v[172:175], v[208:211], v[18:21]
	v_mfma_f32_16x16x32_bf16 v[6:9], v[164:167], v[216:219], v[6:9]
	v_mfma_f32_16x16x32_bf16 v[2:5], v[172:175], v[216:219], v[2:5]
	s_setprio 0
	s_barrier
	s_add_i32 s63, s63, 2
	s_add_u32 s38, s38, 0x100
	s_addc_u32 s39, s39, 0
	s_add_u32 s61, s61, 0x100
	s_addc_u32 s62, s62, 0
	s_cmp_gt_u32 s63, 29
	s_cbranch_scc0 .LBB0_1761
	s_and_b64 vcc, exec, s[34:35]
	s_cbranch_vccnz .LBB0_1764
	s_barrier
.LBB0_1764:
	v_mov_b32_e32 v138, v151
	v_mov_b32_e32 v139, v152
	s_lshl_b32 s26, s56, 8
	s_lshl_b32 s27, s55, 8
	s_add_i32 s26, s26, s48
	v_add_u32_e32 v138, s26, v138
	s_or_b32 s26, s27, s49
	v_lshl_add_u32 v147, v139, 2, s26
	v_ashrrev_i32_e32 v139, 31, v138
	v_lshl_add_u64 v[140:141], v[138:139], 3, s[28:29]
	global_load_dwordx2 v[142:143], v[140:141], off
	v_and_b32_e32 v155, 0x3fc, v147
	s_movk_i32 s26, 0x200
	v_and_b32_e32 v156, 0x1fc, v147
	v_add_u32_e32 v158, 16, v147
	v_and_b32_e32 v159, 0x3fc, v158
	v_add_u32_e32 v162, 0x80, v147
	v_and_b32_e32 v163, 0x3fc, v162
	s_mov_b64 s[38:39], -1
	s_mov_b32 s68, 0x2f800000
	s_mov_b32 s64, 0x3f22f983
	s_mov_b32 s66, 0xbfc90fda
	s_waitcnt vmcnt(0)
	v_ffbh_u32_e32 v139, v143
	v_min_u32_e32 v139, 32, v139
	v_lshlrev_b64 v[142:143], v139, v[142:143]
	v_min_u32_e32 v142, 1, v142
	v_or_b32_e32 v142, v143, v142
	v_cvt_f32_u32_e32 v142, v142
	v_sub_u32_e32 v139, 32, v139
	v_ldexp_f32 v139, v142, v139
	v_mul_f32_e32 v139, 0x30800000, v139
	v_fmamk_f32 v139, v139, 0x3a000000, v1
	v_cmp_gt_f32_e32 vcc, s65, v139
	v_mul_f32_e32 v142, 0x4b800000, v139
	s_nop 0
	v_cndmask_b32_e32 v139, v139, v142, vcc
	v_rsq_f32_e32 v139, v139
	s_nop 0
	v_mul_f32_e32 v142, 0x45800000, v139
	v_cndmask_b32_e32 v146, v139, v142, vcc
	v_and_b32_e32 v139, 0xfffffc00, v147
	v_pk_mul_f32 v[144:145], v[128:129], v[146:147] op_sel_hi:[1,0]
	v_cmp_gt_u32_e32 vcc, s26, v155
	v_add_u32_e32 v128, v139, v138
	v_ashrrev_i32_e32 v129, 31, v128
	v_cndmask_b32_e32 v180, v230, v231, vcc
	v_pk_mul_f32 v[142:143], v[126:127], v[146:147] op_sel_hi:[1,0]
	v_lshl_add_u64 v[126:127], s[14:15], 0, v[180:181]
	v_lshlrev_b64 v[128:129], 11, v[128:129]
	v_lshl_add_u64 v[148:149], v[126:127], 0, v[128:129]
	v_lshlrev_b32_e32 v180, 2, v156
	v_lshl_add_u64 v[148:149], v[148:149], 0, v[180:181]
	global_store_dwordx4 v[148:149], v[142:145], off
	v_cmp_gt_u32_e32 vcc, s26, v159
	v_pk_mul_f32 v[160:161], v[120:121], v[146:147] op_sel_hi:[1,0]
	v_cvt_pk_bf16_f32 v142, v142, v143
	v_cvt_pk_bf16_f32 v143, v144, v145
	v_lshl_add_u64 v[144:145], s[30:31], 0, v[128:129]
	v_lshlrev_b32_e32 v128, 1, v155
	v_mov_b32_e32 v129, v181
	v_lshl_add_u64 v[144:145], v[144:145], 0, v[128:129]
	v_and_b32_e32 v155, 0xfffffc00, v158
	global_store_dwordx2 v[144:145], v[142:143], off
	v_pk_mul_f32 v[144:145], v[124:125], v[146:147] op_sel_hi:[1,0]
	v_add_u32_e32 v124, v155, v138
	v_pk_mul_f32 v[142:143], v[122:123], v[146:147] op_sel_hi:[1,0]
	v_cndmask_b32_e32 v122, v230, v231, vcc
	v_mov_b32_e32 v123, v181
	v_ashrrev_i32_e32 v125, 31, v124
	v_lshl_add_u64 v[122:123], s[14:15], 0, v[122:123]
	v_lshlrev_b64 v[148:149], 11, v[124:125]
	v_and_b32_e32 v124, 0x1fc, v158
	v_lshl_add_u64 v[156:157], v[122:123], 0, v[148:149]
	v_lshlrev_b32_e32 v124, 2, v124
	v_mov_b32_e32 v125, v181
	v_lshl_add_u64 v[156:157], v[156:157], 0, v[124:125]
	global_store_dwordx4 v[156:157], v[142:145], off
	v_cvt_pk_bf16_f32 v156, v142, v143
	v_cvt_pk_bf16_f32 v157, v144, v145
	v_cmp_gt_u32_e32 vcc, s26, v163
	v_pk_mul_f32 v[116:117], v[116:117], v[146:147] op_sel_hi:[1,0]
	v_lshl_add_u64 v[144:145], s[30:31], 0, v[148:149]
	v_lshlrev_b32_e32 v142, 1, v159
	v_mov_b32_e32 v143, v181
	v_lshl_add_u64 v[144:145], v[144:145], 0, v[142:143]
	global_store_dwordx2 v[144:145], v[156:157], off
	v_and_b32_e32 v156, 0xfffffc00, v162
	v_add_u32_e32 v120, v156, v138
	v_pk_mul_f32 v[158:159], v[118:119], v[146:147] op_sel_hi:[1,0]
	v_cndmask_b32_e32 v118, v230, v231, vcc
	v_mov_b32_e32 v119, v181
	v_ashrrev_i32_e32 v121, 31, v120
	v_lshl_add_u64 v[118:119], s[14:15], 0, v[118:119]
	v_lshlrev_b64 v[144:145], 11, v[120:121]
	v_and_b32_e32 v120, 0x1fc, v162
	v_lshl_add_u64 v[148:149], v[118:119], 0, v[144:145]
	v_lshlrev_b32_e32 v120, 2, v120
	v_mov_b32_e32 v121, v181
	v_lshl_add_u64 v[148:149], v[148:149], 0, v[120:121]
	global_store_dwordx4 v[148:149], v[158:161], off
	v_cvt_pk_bf16_f32 v148, v158, v159
	v_add_u32_e32 v162, 0x90, v147
	v_and_b32_e32 v157, 0xfffffc00, v162
	v_lshl_add_u64 v[158:159], s[30:31], 0, v[144:145]
	v_lshlrev_b32_e32 v144, 1, v163
	v_mov_b32_e32 v145, v181
	v_lshl_add_u64 v[158:159], v[158:159], 0, v[144:145]
	v_and_b32_e32 v163, 0x3fc, v162
	v_cvt_pk_bf16_f32 v149, v160, v161
	global_store_dwordx2 v[158:159], v[148:149], off
	v_cmp_gt_u32_e32 vcc, s26, v163
	v_add_u32_e32 v148, v157, v138
	v_pk_mul_f32 v[114:115], v[114:115], v[146:147] op_sel_hi:[1,0]
	v_cndmask_b32_e32 v146, v230, v231, vcc
	v_mov_b32_e32 v147, v181
	v_ashrrev_i32_e32 v149, 31, v148
	v_lshl_add_u64 v[146:147], s[14:15], 0, v[146:147]
	v_lshlrev_b64 v[158:159], 11, v[148:149]
	v_and_b32_e32 v148, 0x1fc, v162
	v_lshl_add_u64 v[160:161], v[146:147], 0, v[158:159]
	v_lshlrev_b32_e32 v148, 2, v148
	v_mov_b32_e32 v149, v181
	v_lshl_add_u64 v[160:161], v[160:161], 0, v[148:149]
	global_store_dwordx4 v[160:161], v[114:117], off
	v_cvt_pk_bf16_f32 v160, v114, v115
	v_cvt_pk_bf16_f32 v161, v116, v117
	v_add_u32_e32 v162, 16, v138
	s_nop 0
	v_lshl_add_u64 v[116:117], s[30:31], 0, v[158:159]
	v_lshlrev_b32_e32 v114, 1, v163
	v_mov_b32_e32 v115, v181
	v_lshl_add_u64 v[116:117], v[116:117], 0, v[114:115]
	global_store_dwordx2 v[116:117], v[160:161], off
	global_load_dwordx2 v[116:117], v[140:141], off offset:128
	s_waitcnt vmcnt(0)
	v_ffbh_u32_e32 v158, v117
	v_min_u32_e32 v158, 32, v158
	v_lshlrev_b64 v[116:117], v158, v[116:117]
	v_min_u32_e32 v116, 1, v116
	v_or_b32_e32 v116, v117, v116
	v_cvt_f32_u32_e32 v116, v116
	v_sub_u32_e32 v117, 32, v158
	v_add_u32_e32 v158, v139, v162
	v_ashrrev_i32_e32 v159, 31, v158
	v_ldexp_f32 v116, v116, v117
	v_mul_f32_e32 v116, 0x30800000, v116
	v_fmamk_f32 v116, v116, 0x3a000000, v1
	v_cmp_gt_f32_e32 vcc, s65, v116
	v_mul_f32_e32 v117, 0x4b800000, v116
	v_lshlrev_b64 v[158:159], 11, v[158:159]
	v_cndmask_b32_e32 v116, v116, v117, vcc
	v_rsq_f32_e32 v116, v116
	v_lshl_add_u64 v[160:161], v[126:127], 0, v[158:159]
	v_lshl_add_u64 v[160:161], v[160:161], 0, v[180:181]
	v_mul_f32_e32 v117, 0x45800000, v116
	v_cndmask_b32_e32 v116, v116, v117, vcc
	v_pk_mul_f32 v[112:113], v[112:113], v[116:117] op_sel_hi:[1,0]
	v_pk_mul_f32 v[110:111], v[110:111], v[116:117] op_sel_hi:[1,0]
	global_store_dwordx4 v[160:161], v[110:113], off
	v_pk_mul_f32 v[108:109], v[108:109], v[116:117] op_sel_hi:[1,0]
	v_pk_mul_f32 v[106:107], v[106:107], v[116:117] op_sel_hi:[1,0]
	v_cvt_pk_bf16_f32 v110, v110, v111
	v_cvt_pk_bf16_f32 v111, v112, v113
	v_lshl_add_u64 v[112:113], s[30:31], 0, v[158:159]
	v_lshl_add_u64 v[112:113], v[112:113], 0, v[128:129]
	global_store_dwordx2 v[112:113], v[110:111], off
	v_add_u32_e32 v110, v155, v162
	v_ashrrev_i32_e32 v111, 31, v110
	v_lshlrev_b64 v[110:111], 11, v[110:111]
	v_lshl_add_u64 v[112:113], v[122:123], 0, v[110:111]
	v_lshl_add_u64 v[112:113], v[112:113], 0, v[124:125]
	global_store_dwordx4 v[112:113], v[106:109], off
	v_pk_mul_f32 v[104:105], v[104:105], v[116:117] op_sel_hi:[1,0]
	v_pk_mul_f32 v[102:103], v[102:103], v[116:117] op_sel_hi:[1,0]
	v_cvt_pk_bf16_f32 v106, v106, v107
	v_cvt_pk_bf16_f32 v107, v108, v109
	v_lshl_add_u64 v[108:109], s[30:31], 0, v[110:111]
	v_lshl_add_u64 v[108:109], v[108:109], 0, v[142:143]
	global_store_dwordx2 v[108:109], v[106:107], off
	v_add_u32_e32 v106, v156, v162
	v_ashrrev_i32_e32 v107, 31, v106
	v_lshlrev_b64 v[106:107], 11, v[106:107]
	v_lshl_add_u64 v[108:109], v[118:119], 0, v[106:107]
	v_lshl_add_u64 v[108:109], v[108:109], 0, v[120:121]
	global_store_dwordx4 v[108:109], v[102:105], off
	v_pk_mul_f32 v[100:101], v[100:101], v[116:117] op_sel_hi:[1,0]
	v_pk_mul_f32 v[98:99], v[98:99], v[116:117] op_sel_hi:[1,0]
	v_cvt_pk_bf16_f32 v102, v102, v103
	v_cvt_pk_bf16_f32 v103, v104, v105
	v_lshl_add_u64 v[104:105], s[30:31], 0, v[106:107]
	v_lshl_add_u64 v[104:105], v[104:105], 0, v[144:145]
	global_store_dwordx2 v[104:105], v[102:103], off
	v_add_u32_e32 v102, v157, v162
	v_ashrrev_i32_e32 v103, 31, v102
	v_lshlrev_b64 v[102:103], 11, v[102:103]
	v_lshl_add_u64 v[104:105], v[146:147], 0, v[102:103]
	v_lshl_add_u64 v[104:105], v[104:105], 0, v[148:149]
	global_store_dwordx4 v[104:105], v[98:101], off
	v_add_u32_e32 v104, 32, v138
	s_nop 0
	v_cvt_pk_bf16_f32 v98, v98, v99
	v_cvt_pk_bf16_f32 v99, v100, v101
	v_lshl_add_u64 v[100:101], s[30:31], 0, v[102:103]
	v_lshl_add_u64 v[100:101], v[100:101], 0, v[114:115]
	global_store_dwordx2 v[100:101], v[98:99], off
	global_load_dwordx2 v[98:99], v[140:141], off offset:256
	s_waitcnt vmcnt(0)
	v_ffbh_u32_e32 v100, v99
	v_min_u32_e32 v100, 32, v100
	v_lshlrev_b64 v[98:99], v100, v[98:99]
	v_min_u32_e32 v98, 1, v98
	v_or_b32_e32 v98, v99, v98
	v_cvt_f32_u32_e32 v98, v98
	v_sub_u32_e32 v99, 32, v100
	v_add_u32_e32 v100, v139, v104
	v_ashrrev_i32_e32 v101, 31, v100
	v_ldexp_f32 v98, v98, v99
	v_mul_f32_e32 v98, 0x30800000, v98
	v_fmamk_f32 v98, v98, 0x3a000000, v1
	v_cmp_gt_f32_e32 vcc, s65, v98
	v_mul_f32_e32 v99, 0x4b800000, v98
	v_lshlrev_b64 v[100:101], 11, v[100:101]
	v_cndmask_b32_e32 v98, v98, v99, vcc
	v_rsq_f32_e32 v98, v98
	v_lshl_add_u64 v[102:103], v[126:127], 0, v[100:101]
	v_lshl_add_u64 v[102:103], v[102:103], 0, v[180:181]
	v_mul_f32_e32 v99, 0x45800000, v98
	v_cndmask_b32_e32 v98, v98, v99, vcc
	v_pk_mul_f32 v[96:97], v[96:97], v[98:99] op_sel_hi:[1,0]
	v_pk_mul_f32 v[94:95], v[94:95], v[98:99] op_sel_hi:[1,0]
	global_store_dwordx4 v[102:103], v[94:97], off
	v_pk_mul_f32 v[92:93], v[92:93], v[98:99] op_sel_hi:[1,0]
	v_pk_mul_f32 v[90:91], v[90:91], v[98:99] op_sel_hi:[1,0]
	v_cvt_pk_bf16_f32 v94, v94, v95
	v_cvt_pk_bf16_f32 v95, v96, v97
	v_lshl_add_u64 v[96:97], s[30:31], 0, v[100:101]
	v_lshl_add_u64 v[96:97], v[96:97], 0, v[128:129]
	global_store_dwordx2 v[96:97], v[94:95], off
	v_add_u32_e32 v94, v155, v104
	v_ashrrev_i32_e32 v95, 31, v94
	v_lshlrev_b64 v[94:95], 11, v[94:95]
	v_lshl_add_u64 v[96:97], v[122:123], 0, v[94:95]
	v_lshl_add_u64 v[96:97], v[96:97], 0, v[124:125]
	global_store_dwordx4 v[96:97], v[90:93], off
	v_pk_mul_f32 v[88:89], v[88:89], v[98:99] op_sel_hi:[1,0]
	v_pk_mul_f32 v[86:87], v[86:87], v[98:99] op_sel_hi:[1,0]
	v_cvt_pk_bf16_f32 v90, v90, v91
	v_cvt_pk_bf16_f32 v91, v92, v93
	v_lshl_add_u64 v[92:93], s[30:31], 0, v[94:95]
	v_lshl_add_u64 v[92:93], v[92:93], 0, v[142:143]
	global_store_dwordx2 v[92:93], v[90:91], off
	v_add_u32_e32 v90, v156, v104
	v_ashrrev_i32_e32 v91, 31, v90
	v_lshlrev_b64 v[90:91], 11, v[90:91]
	v_lshl_add_u64 v[92:93], v[118:119], 0, v[90:91]
	v_lshl_add_u64 v[92:93], v[92:93], 0, v[120:121]
	global_store_dwordx4 v[92:93], v[86:89], off
	v_pk_mul_f32 v[84:85], v[84:85], v[98:99] op_sel_hi:[1,0]
	v_pk_mul_f32 v[82:83], v[82:83], v[98:99] op_sel_hi:[1,0]
	v_cvt_pk_bf16_f32 v86, v86, v87
	v_cvt_pk_bf16_f32 v87, v88, v89
	v_lshl_add_u64 v[88:89], s[30:31], 0, v[90:91]
	v_lshl_add_u64 v[88:89], v[88:89], 0, v[144:145]
	global_store_dwordx2 v[88:89], v[86:87], off
	v_add_u32_e32 v86, v157, v104
	v_ashrrev_i32_e32 v87, 31, v86
	v_lshlrev_b64 v[86:87], 11, v[86:87]
	v_lshl_add_u64 v[88:89], v[146:147], 0, v[86:87]
	v_lshl_add_u64 v[88:89], v[88:89], 0, v[148:149]
	global_store_dwordx4 v[88:89], v[82:85], off
	v_add_u32_e32 v88, 48, v138
	s_nop 0
	v_cvt_pk_bf16_f32 v82, v82, v83
	v_cvt_pk_bf16_f32 v83, v84, v85
	v_lshl_add_u64 v[84:85], s[30:31], 0, v[86:87]
	v_lshl_add_u64 v[84:85], v[84:85], 0, v[114:115]
	global_store_dwordx2 v[84:85], v[82:83], off
	global_load_dwordx2 v[82:83], v[140:141], off offset:384
	s_waitcnt vmcnt(0)
	v_ffbh_u32_e32 v84, v83
	v_min_u32_e32 v84, 32, v84
	v_lshlrev_b64 v[82:83], v84, v[82:83]
	v_min_u32_e32 v82, 1, v82
	v_or_b32_e32 v82, v83, v82
	v_cvt_f32_u32_e32 v82, v82
	v_sub_u32_e32 v83, 32, v84
	v_add_u32_e32 v84, v139, v88
	v_ashrrev_i32_e32 v85, 31, v84
	v_ldexp_f32 v82, v82, v83
	v_mul_f32_e32 v82, 0x30800000, v82
	v_fmamk_f32 v82, v82, 0x3a000000, v1
	v_cmp_gt_f32_e32 vcc, s65, v82
	v_mul_f32_e32 v83, 0x4b800000, v82
	v_lshlrev_b64 v[84:85], 11, v[84:85]
	v_cndmask_b32_e32 v82, v82, v83, vcc
	v_rsq_f32_e32 v82, v82
	v_lshl_add_u64 v[86:87], v[126:127], 0, v[84:85]
	v_lshl_add_u64 v[86:87], v[86:87], 0, v[180:181]
	v_mul_f32_e32 v83, 0x45800000, v82
	v_cndmask_b32_e32 v82, v82, v83, vcc
	v_pk_mul_f32 v[80:81], v[80:81], v[82:83] op_sel_hi:[1,0]
	v_pk_mul_f32 v[78:79], v[78:79], v[82:83] op_sel_hi:[1,0]
	global_store_dwordx4 v[86:87], v[78:81], off
	v_pk_mul_f32 v[76:77], v[76:77], v[82:83] op_sel_hi:[1,0]
	v_pk_mul_f32 v[74:75], v[74:75], v[82:83] op_sel_hi:[1,0]
	v_cvt_pk_bf16_f32 v78, v78, v79
	v_cvt_pk_bf16_f32 v79, v80, v81
	v_lshl_add_u64 v[80:81], s[30:31], 0, v[84:85]
	v_lshl_add_u64 v[80:81], v[80:81], 0, v[128:129]
	global_store_dwordx2 v[80:81], v[78:79], off
	v_add_u32_e32 v78, v155, v88
	v_ashrrev_i32_e32 v79, 31, v78
	v_lshlrev_b64 v[78:79], 11, v[78:79]
	v_lshl_add_u64 v[80:81], v[122:123], 0, v[78:79]
	v_lshl_add_u64 v[80:81], v[80:81], 0, v[124:125]
	global_store_dwordx4 v[80:81], v[74:77], off
	v_pk_mul_f32 v[72:73], v[72:73], v[82:83] op_sel_hi:[1,0]
	v_pk_mul_f32 v[70:71], v[70:71], v[82:83] op_sel_hi:[1,0]
	v_cvt_pk_bf16_f32 v74, v74, v75
	v_cvt_pk_bf16_f32 v75, v76, v77
	v_lshl_add_u64 v[76:77], s[30:31], 0, v[78:79]
	v_lshl_add_u64 v[76:77], v[76:77], 0, v[142:143]
	global_store_dwordx2 v[76:77], v[74:75], off
	v_add_u32_e32 v74, v156, v88
	v_ashrrev_i32_e32 v75, 31, v74
	v_lshlrev_b64 v[74:75], 11, v[74:75]
	v_lshl_add_u64 v[76:77], v[118:119], 0, v[74:75]
	v_lshl_add_u64 v[76:77], v[76:77], 0, v[120:121]
	global_store_dwordx4 v[76:77], v[70:73], off
	v_pk_mul_f32 v[68:69], v[68:69], v[82:83] op_sel_hi:[1,0]
	v_pk_mul_f32 v[66:67], v[66:67], v[82:83] op_sel_hi:[1,0]
	v_cvt_pk_bf16_f32 v70, v70, v71
	v_cvt_pk_bf16_f32 v71, v72, v73
	v_lshl_add_u64 v[72:73], s[30:31], 0, v[74:75]
	v_lshl_add_u64 v[72:73], v[72:73], 0, v[144:145]
	global_store_dwordx2 v[72:73], v[70:71], off
	v_add_u32_e32 v70, v157, v88
	v_ashrrev_i32_e32 v71, 31, v70
	v_lshlrev_b64 v[70:71], 11, v[70:71]
	v_lshl_add_u64 v[72:73], v[146:147], 0, v[70:71]
	v_lshl_add_u64 v[72:73], v[72:73], 0, v[148:149]
	global_store_dwordx4 v[72:73], v[66:69], off
	v_add_u32_e32 v72, 0x80, v138
	s_nop 0
	v_cvt_pk_bf16_f32 v66, v66, v67
	v_cvt_pk_bf16_f32 v67, v68, v69
	v_lshl_add_u64 v[68:69], s[30:31], 0, v[70:71]
	v_lshl_add_u64 v[68:69], v[68:69], 0, v[114:115]
	global_store_dwordx2 v[68:69], v[66:67], off
	global_load_dwordx2 v[66:67], v[140:141], off offset:1024
	s_waitcnt vmcnt(0)
	v_ffbh_u32_e32 v68, v67
	v_min_u32_e32 v68, 32, v68
	v_lshlrev_b64 v[66:67], v68, v[66:67]
	v_min_u32_e32 v66, 1, v66
	v_or_b32_e32 v66, v67, v66
	v_cvt_f32_u32_e32 v66, v66
	v_sub_u32_e32 v67, 32, v68
	v_add_u32_e32 v68, v139, v72
	v_ashrrev_i32_e32 v69, 31, v68
	v_ldexp_f32 v66, v66, v67
	v_mul_f32_e32 v66, 0x30800000, v66
	v_fmamk_f32 v66, v66, 0x3a000000, v1
	v_cmp_gt_f32_e32 vcc, s65, v66
	v_mul_f32_e32 v67, 0x4b800000, v66
	v_lshlrev_b64 v[68:69], 11, v[68:69]
	v_cndmask_b32_e32 v66, v66, v67, vcc
	v_rsq_f32_e32 v66, v66
	v_lshl_add_u64 v[70:71], v[126:127], 0, v[68:69]
	v_lshl_add_u64 v[70:71], v[70:71], 0, v[180:181]
	v_mul_f32_e32 v67, 0x45800000, v66
	v_cndmask_b32_e32 v66, v66, v67, vcc
	v_pk_mul_f32 v[64:65], v[64:65], v[66:67] op_sel_hi:[1,0]
	v_pk_mul_f32 v[62:63], v[62:63], v[66:67] op_sel_hi:[1,0]
	global_store_dwordx4 v[70:71], v[62:65], off
	v_pk_mul_f32 v[60:61], v[60:61], v[66:67] op_sel_hi:[1,0]
	v_pk_mul_f32 v[58:59], v[58:59], v[66:67] op_sel_hi:[1,0]
	v_cvt_pk_bf16_f32 v62, v62, v63
	v_cvt_pk_bf16_f32 v63, v64, v65
	v_lshl_add_u64 v[64:65], s[30:31], 0, v[68:69]
	v_lshl_add_u64 v[64:65], v[64:65], 0, v[128:129]
	global_store_dwordx2 v[64:65], v[62:63], off
	v_add_u32_e32 v62, v155, v72
	v_ashrrev_i32_e32 v63, 31, v62
	v_lshlrev_b64 v[62:63], 11, v[62:63]
	v_lshl_add_u64 v[64:65], v[122:123], 0, v[62:63]
	v_lshl_add_u64 v[64:65], v[64:65], 0, v[124:125]
	global_store_dwordx4 v[64:65], v[58:61], off
	v_pk_mul_f32 v[56:57], v[56:57], v[66:67] op_sel_hi:[1,0]
	v_pk_mul_f32 v[54:55], v[54:55], v[66:67] op_sel_hi:[1,0]
	v_cvt_pk_bf16_f32 v58, v58, v59
	v_cvt_pk_bf16_f32 v59, v60, v61
	v_lshl_add_u64 v[60:61], s[30:31], 0, v[62:63]
	v_lshl_add_u64 v[60:61], v[60:61], 0, v[142:143]
	global_store_dwordx2 v[60:61], v[58:59], off
	v_add_u32_e32 v58, v156, v72
	v_ashrrev_i32_e32 v59, 31, v58
	v_lshlrev_b64 v[58:59], 11, v[58:59]
	v_lshl_add_u64 v[60:61], v[118:119], 0, v[58:59]
	v_lshl_add_u64 v[60:61], v[60:61], 0, v[120:121]
	global_store_dwordx4 v[60:61], v[54:57], off
	v_pk_mul_f32 v[52:53], v[52:53], v[66:67] op_sel_hi:[1,0]
	v_pk_mul_f32 v[50:51], v[50:51], v[66:67] op_sel_hi:[1,0]
	v_cvt_pk_bf16_f32 v54, v54, v55
	v_cvt_pk_bf16_f32 v55, v56, v57
	v_lshl_add_u64 v[56:57], s[30:31], 0, v[58:59]
	v_lshl_add_u64 v[56:57], v[56:57], 0, v[144:145]
	global_store_dwordx2 v[56:57], v[54:55], off
	v_add_u32_e32 v54, v157, v72
	v_ashrrev_i32_e32 v55, 31, v54
	v_lshlrev_b64 v[54:55], 11, v[54:55]
	v_lshl_add_u64 v[56:57], v[146:147], 0, v[54:55]
	v_lshl_add_u64 v[56:57], v[56:57], 0, v[148:149]
	global_store_dwordx4 v[56:57], v[50:53], off
	v_add_u32_e32 v56, 0x90, v138
	s_nop 0
	v_cvt_pk_bf16_f32 v50, v50, v51
	v_cvt_pk_bf16_f32 v51, v52, v53
	v_lshl_add_u64 v[52:53], s[30:31], 0, v[54:55]
	v_lshl_add_u64 v[52:53], v[52:53], 0, v[114:115]
	global_store_dwordx2 v[52:53], v[50:51], off
	global_load_dwordx2 v[50:51], v[140:141], off offset:1152
	s_waitcnt vmcnt(0)
	v_ffbh_u32_e32 v52, v51
	v_min_u32_e32 v52, 32, v52
	v_lshlrev_b64 v[50:51], v52, v[50:51]
	v_min_u32_e32 v50, 1, v50
	v_or_b32_e32 v50, v51, v50
	v_cvt_f32_u32_e32 v50, v50
	v_sub_u32_e32 v51, 32, v52
	v_add_u32_e32 v52, v139, v56
	v_ashrrev_i32_e32 v53, 31, v52
	v_ldexp_f32 v50, v50, v51
	v_mul_f32_e32 v50, 0x30800000, v50
	v_fmamk_f32 v50, v50, 0x3a000000, v1
	v_cmp_gt_f32_e32 vcc, s65, v50
	v_mul_f32_e32 v51, 0x4b800000, v50
	v_lshlrev_b64 v[52:53], 11, v[52:53]
	v_cndmask_b32_e32 v50, v50, v51, vcc
	v_rsq_f32_e32 v50, v50
	v_lshl_add_u64 v[54:55], v[126:127], 0, v[52:53]
	v_lshl_add_u64 v[54:55], v[54:55], 0, v[180:181]
	v_mul_f32_e32 v51, 0x45800000, v50
	v_cndmask_b32_e32 v50, v50, v51, vcc
	v_pk_mul_f32 v[48:49], v[48:49], v[50:51] op_sel_hi:[1,0]
	v_pk_mul_f32 v[46:47], v[46:47], v[50:51] op_sel_hi:[1,0]
	global_store_dwordx4 v[54:55], v[46:49], off
	v_pk_mul_f32 v[44:45], v[44:45], v[50:51] op_sel_hi:[1,0]
	v_pk_mul_f32 v[42:43], v[42:43], v[50:51] op_sel_hi:[1,0]
	v_cvt_pk_bf16_f32 v46, v46, v47
	v_cvt_pk_bf16_f32 v47, v48, v49
	v_lshl_add_u64 v[48:49], s[30:31], 0, v[52:53]
	v_lshl_add_u64 v[48:49], v[48:49], 0, v[128:129]
	global_store_dwordx2 v[48:49], v[46:47], off
	v_add_u32_e32 v46, v155, v56
	v_ashrrev_i32_e32 v47, 31, v46
	v_lshlrev_b64 v[46:47], 11, v[46:47]
	v_lshl_add_u64 v[48:49], v[122:123], 0, v[46:47]
	v_lshl_add_u64 v[48:49], v[48:49], 0, v[124:125]
	global_store_dwordx4 v[48:49], v[42:45], off
	v_pk_mul_f32 v[40:41], v[40:41], v[50:51] op_sel_hi:[1,0]
	v_pk_mul_f32 v[38:39], v[38:39], v[50:51] op_sel_hi:[1,0]
	v_cvt_pk_bf16_f32 v42, v42, v43
	v_cvt_pk_bf16_f32 v43, v44, v45
	v_lshl_add_u64 v[44:45], s[30:31], 0, v[46:47]
	v_lshl_add_u64 v[44:45], v[44:45], 0, v[142:143]
	global_store_dwordx2 v[44:45], v[42:43], off
	v_add_u32_e32 v42, v156, v56
	v_ashrrev_i32_e32 v43, 31, v42
	v_lshlrev_b64 v[42:43], 11, v[42:43]
	v_lshl_add_u64 v[44:45], v[118:119], 0, v[42:43]
	v_lshl_add_u64 v[44:45], v[44:45], 0, v[120:121]
	global_store_dwordx4 v[44:45], v[38:41], off
	v_pk_mul_f32 v[36:37], v[36:37], v[50:51] op_sel_hi:[1,0]
	v_pk_mul_f32 v[34:35], v[34:35], v[50:51] op_sel_hi:[1,0]
	v_cvt_pk_bf16_f32 v38, v38, v39
	v_cvt_pk_bf16_f32 v39, v40, v41
	v_lshl_add_u64 v[40:41], s[30:31], 0, v[42:43]
	v_lshl_add_u64 v[40:41], v[40:41], 0, v[144:145]
	global_store_dwordx2 v[40:41], v[38:39], off
	v_add_u32_e32 v38, v157, v56
	v_ashrrev_i32_e32 v39, 31, v38
	v_lshlrev_b64 v[38:39], 11, v[38:39]
	v_lshl_add_u64 v[40:41], v[146:147], 0, v[38:39]
	v_lshl_add_u64 v[40:41], v[40:41], 0, v[148:149]
	global_store_dwordx4 v[40:41], v[34:37], off
	v_add_u32_e32 v40, 0xa0, v138
	s_nop 0
	v_cvt_pk_bf16_f32 v34, v34, v35
	v_cvt_pk_bf16_f32 v35, v36, v37
	v_lshl_add_u64 v[36:37], s[30:31], 0, v[38:39]
	v_lshl_add_u64 v[36:37], v[36:37], 0, v[114:115]
	global_store_dwordx2 v[36:37], v[34:35], off
	global_load_dwordx2 v[34:35], v[140:141], off offset:1280
	s_waitcnt vmcnt(0)
	v_ffbh_u32_e32 v36, v35
	v_min_u32_e32 v36, 32, v36
	v_lshlrev_b64 v[34:35], v36, v[34:35]
	v_min_u32_e32 v34, 1, v34
	v_or_b32_e32 v34, v35, v34
	v_cvt_f32_u32_e32 v34, v34
	v_sub_u32_e32 v35, 32, v36
	v_add_u32_e32 v36, v139, v40
	v_ashrrev_i32_e32 v37, 31, v36
	v_ldexp_f32 v34, v34, v35
	v_mul_f32_e32 v34, 0x30800000, v34
	v_fmamk_f32 v34, v34, 0x3a000000, v1
	v_cmp_gt_f32_e32 vcc, s65, v34
	v_mul_f32_e32 v35, 0x4b800000, v34
	v_lshlrev_b64 v[36:37], 11, v[36:37]
	v_cndmask_b32_e32 v34, v34, v35, vcc
	v_rsq_f32_e32 v34, v34
	v_lshl_add_u64 v[38:39], v[126:127], 0, v[36:37]
	v_lshl_add_u64 v[38:39], v[38:39], 0, v[180:181]
	v_mul_f32_e32 v35, 0x45800000, v34
	v_cndmask_b32_e32 v34, v34, v35, vcc
	v_pk_mul_f32 v[32:33], v[32:33], v[34:35] op_sel_hi:[1,0]
	v_pk_mul_f32 v[30:31], v[30:31], v[34:35] op_sel_hi:[1,0]
	global_store_dwordx4 v[38:39], v[30:33], off
	v_pk_mul_f32 v[28:29], v[28:29], v[34:35] op_sel_hi:[1,0]
	v_pk_mul_f32 v[26:27], v[26:27], v[34:35] op_sel_hi:[1,0]
	v_cvt_pk_bf16_f32 v30, v30, v31
	v_cvt_pk_bf16_f32 v31, v32, v33
	v_lshl_add_u64 v[32:33], s[30:31], 0, v[36:37]
	v_lshl_add_u64 v[32:33], v[32:33], 0, v[128:129]
	global_store_dwordx2 v[32:33], v[30:31], off
	v_add_u32_e32 v30, v155, v40
	v_ashrrev_i32_e32 v31, 31, v30
	v_lshlrev_b64 v[30:31], 11, v[30:31]
	v_lshl_add_u64 v[32:33], v[122:123], 0, v[30:31]
	v_lshl_add_u64 v[32:33], v[32:33], 0, v[124:125]
	global_store_dwordx4 v[32:33], v[26:29], off
	v_pk_mul_f32 v[24:25], v[24:25], v[34:35] op_sel_hi:[1,0]
	v_pk_mul_f32 v[22:23], v[22:23], v[34:35] op_sel_hi:[1,0]
	v_cvt_pk_bf16_f32 v26, v26, v27
	v_cvt_pk_bf16_f32 v27, v28, v29
	v_lshl_add_u64 v[28:29], s[30:31], 0, v[30:31]
	v_lshl_add_u64 v[28:29], v[28:29], 0, v[142:143]
	global_store_dwordx2 v[28:29], v[26:27], off
	v_add_u32_e32 v26, v156, v40
	v_ashrrev_i32_e32 v27, 31, v26
	v_lshlrev_b64 v[26:27], 11, v[26:27]
	v_lshl_add_u64 v[28:29], v[118:119], 0, v[26:27]
	v_lshl_add_u64 v[28:29], v[28:29], 0, v[120:121]
	global_store_dwordx4 v[28:29], v[22:25], off
	v_pk_mul_f32 v[20:21], v[20:21], v[34:35] op_sel_hi:[1,0]
	v_pk_mul_f32 v[18:19], v[18:19], v[34:35] op_sel_hi:[1,0]
	v_cvt_pk_bf16_f32 v22, v22, v23
	v_cvt_pk_bf16_f32 v23, v24, v25
	v_lshl_add_u64 v[24:25], s[30:31], 0, v[26:27]
	v_lshl_add_u64 v[24:25], v[24:25], 0, v[144:145]
	global_store_dwordx2 v[24:25], v[22:23], off
	v_add_u32_e32 v22, v157, v40
	v_ashrrev_i32_e32 v23, 31, v22
	v_lshlrev_b64 v[22:23], 11, v[22:23]
	v_lshl_add_u64 v[24:25], v[146:147], 0, v[22:23]
	v_lshl_add_u64 v[24:25], v[24:25], 0, v[148:149]
	global_store_dwordx4 v[24:25], v[18:21], off
	v_add_u32_e32 v24, 0xb0, v138
	s_nop 0
	v_cvt_pk_bf16_f32 v18, v18, v19
	v_cvt_pk_bf16_f32 v19, v20, v21
	v_lshl_add_u64 v[20:21], s[30:31], 0, v[22:23]
	v_lshl_add_u64 v[20:21], v[20:21], 0, v[114:115]
	global_store_dwordx2 v[20:21], v[18:19], off
	global_load_dwordx2 v[18:19], v[140:141], off offset:1408
	s_waitcnt vmcnt(0)
	v_ffbh_u32_e32 v20, v19
	v_min_u32_e32 v20, 32, v20
	v_lshlrev_b64 v[18:19], v20, v[18:19]
	v_min_u32_e32 v18, 1, v18
	v_or_b32_e32 v18, v19, v18
	v_cvt_f32_u32_e32 v18, v18
	v_sub_u32_e32 v19, 32, v20
	v_add_u32_e32 v20, v139, v24
	v_ashrrev_i32_e32 v21, 31, v20
	v_ldexp_f32 v18, v18, v19
	v_mul_f32_e32 v18, 0x30800000, v18
	v_fmamk_f32 v18, v18, 0x3a000000, v1
	v_cmp_gt_f32_e32 vcc, s65, v18
	v_mul_f32_e32 v19, 0x4b800000, v18
	v_lshlrev_b64 v[20:21], 11, v[20:21]
	v_cndmask_b32_e32 v18, v18, v19, vcc
	v_rsq_f32_e32 v18, v18
	v_lshl_add_u64 v[22:23], v[126:127], 0, v[20:21]
	v_lshl_add_u64 v[22:23], v[22:23], 0, v[180:181]
	v_mul_f32_e32 v19, 0x45800000, v18
	v_cndmask_b32_e32 v18, v18, v19, vcc
	v_pk_mul_f32 v[16:17], v[16:17], v[18:19] op_sel_hi:[1,0]
	v_pk_mul_f32 v[14:15], v[14:15], v[18:19] op_sel_hi:[1,0]
	global_store_dwordx4 v[22:23], v[14:17], off
	v_pk_mul_f32 v[12:13], v[12:13], v[18:19] op_sel_hi:[1,0]
	v_pk_mul_f32 v[10:11], v[10:11], v[18:19] op_sel_hi:[1,0]
	v_cvt_pk_bf16_f32 v14, v14, v15
	v_cvt_pk_bf16_f32 v15, v16, v17
	v_lshl_add_u64 v[16:17], s[30:31], 0, v[20:21]
	v_lshl_add_u64 v[16:17], v[16:17], 0, v[128:129]
	global_store_dwordx2 v[16:17], v[14:15], off
	v_add_u32_e32 v14, v155, v24
	v_ashrrev_i32_e32 v15, 31, v14
	v_lshlrev_b64 v[14:15], 11, v[14:15]
	v_lshl_add_u64 v[16:17], v[122:123], 0, v[14:15]
	v_lshl_add_u64 v[16:17], v[16:17], 0, v[124:125]
	global_store_dwordx4 v[16:17], v[10:13], off
	v_pk_mul_f32 v[8:9], v[8:9], v[18:19] op_sel_hi:[1,0]
	v_pk_mul_f32 v[6:7], v[6:7], v[18:19] op_sel_hi:[1,0]
	v_cvt_pk_bf16_f32 v10, v10, v11
	v_cvt_pk_bf16_f32 v11, v12, v13
	v_lshl_add_u64 v[12:13], s[30:31], 0, v[14:15]
	v_lshl_add_u64 v[12:13], v[12:13], 0, v[142:143]
	global_store_dwordx2 v[12:13], v[10:11], off
	v_add_u32_e32 v10, v156, v24
	v_ashrrev_i32_e32 v11, 31, v10
	v_lshlrev_b64 v[10:11], 11, v[10:11]
	v_lshl_add_u64 v[12:13], v[118:119], 0, v[10:11]
	v_lshl_add_u64 v[12:13], v[12:13], 0, v[120:121]
	global_store_dwordx4 v[12:13], v[6:9], off
	v_pk_mul_f32 v[4:5], v[4:5], v[18:19] op_sel_hi:[1,0]
	v_pk_mul_f32 v[2:3], v[2:3], v[18:19] op_sel_hi:[1,0]
	v_cvt_pk_bf16_f32 v6, v6, v7
	v_cvt_pk_bf16_f32 v7, v8, v9
	v_lshl_add_u64 v[8:9], s[30:31], 0, v[10:11]
	v_lshl_add_u64 v[8:9], v[8:9], 0, v[144:145]
	global_store_dwordx2 v[8:9], v[6:7], off
	v_add_u32_e32 v6, v157, v24
	v_ashrrev_i32_e32 v7, 31, v6
	v_lshlrev_b64 v[6:7], 11, v[6:7]
	v_lshl_add_u64 v[8:9], v[146:147], 0, v[6:7]
	v_lshl_add_u64 v[8:9], v[8:9], 0, v[148:149]
	global_store_dwordx4 v[8:9], v[2:5], off
	s_andn2_b64 vcc, exec, s[36:37]
	s_nop 0
	v_cvt_pk_bf16_f32 v2, v2, v3
	v_cvt_pk_bf16_f32 v3, v4, v5
	v_lshl_add_u64 v[4:5], s[30:31], 0, v[6:7]
	v_lshl_add_u64 v[4:5], v[4:5], 0, v[114:115]
	global_store_dwordx2 v[4:5], v[2:3], off
	s_cbranch_vccnz .LBB0_1759
	s_andn2_b64 vcc, exec, s[22:23]
	s_cbranch_vccz .LBB0_1758
	s_barrier
	s_branch .LBB0_1758

.LBB0_2224:
	s_andn2_b64 vcc, exec, s[14:15]
	s_cbranch_vccnz .LBB0_2264
	v_ashrrev_i32_e32 v4, 31, v2
	v_lshrrev_b32_e32 v4, 26, v4
	v_add_u32_e32 v4, v2, v4
	v_ashrrev_i32_e32 v148, 6, v4
	v_bfe_i32 v4, v2, 27, 1
	v_lshlrev_b32_e32 v3, 4, v2
	v_lshrrev_b32_e32 v4, 22, v4
	v_add_u32_e32 v4, v3, v4
	v_and_b32_e32 v4, 0xfffffc00, v4
	v_sub_u32_e32 v4, v3, v4
	v_lshrrev_b32_e32 v5, 4, v4
	v_bitop3_b32 v4, v5, v4, 32 bitop3:0x6c
	v_ashrrev_i32_e32 v6, 31, v4
	v_lshrrev_b32_e32 v6, 26, v6
	v_lshlrev_b32_e32 v5, 3, v148
	v_add_u32_e32 v6, v4, v6
	v_and_b32_e32 v5, -16, v5
	v_ashrrev_i32_e32 v150, 6, v6
	v_and_b32_e32 v6, 0xc0, v6
	s_mov_b64 s[14:15], 0x1de00000
	v_add_u32_e32 v5, v150, v5
	v_lshlrev_b32_e32 v7, 5, v148
	v_sub_u32_e32 v4, v4, v6
	v_lshl_add_u64 v[132:133], v[130:131], 0, s[14:15]
	v_and_b32_e32 v149, 32, v7
	v_ashrrev_i16_sdwa v4, v224, sext(v4) dst_sel:DWORD dst_unused:UNUSED_PAD src0_sel:DWORD src1_sel:BYTE_0
	v_lshlrev_b32_e32 v6, 1, v5
	v_lshrrev_b32_e32 v7, 2, v5
	v_and_b32_e32 v8, 3, v150
	s_mov_b32 s14, 0x1ffffe0
	v_bfe_i32 v151, v4, 0, 16
	v_and_b32_e32 v6, 24, v6
	v_and_b32_e32 v7, 4, v7
	v_and_or_b32 v8, v5, s14, v8
	s_movk_i32 s12, 0x1580
	v_add_u32_e32 v4, v149, v151
	v_or3_b32 v6, v8, v7, v6
	v_mul_lo_u32 v5, v5, s12
	v_add_lshl_u32 v134, v4, v5, 1
	v_mul_lo_u32 v5, v6, s12
	v_add_u32_e32 v3, 0x2000, v3
	v_add_lshl_u32 v136, v5, v4, 1
	v_ashrrev_i32_e32 v4, 31, v3
	v_lshrrev_b32_e32 v4, 22, v4
	v_add_u32_e32 v4, v3, v4
	v_ashrrev_i32_e32 v157, 10, v4
	v_mul_i32_i24_e32 v4, 0x400, v157
	v_sub_u32_e32 v3, v3, v4
	v_lshrrev_b32_e32 v4, 4, v3
	v_bitop3_b32 v3, v4, v3, 32 bitop3:0x6c
	v_ashrrev_i32_e32 v5, 31, v3
	v_lshrrev_b32_e32 v5, 26, v5
	v_lshlrev_b32_e32 v4, 3, v157
	v_add_u32_e32 v5, v3, v5
	v_and_b32_e32 v4, -16, v4
	v_ashrrev_i32_e32 v159, 6, v5
	v_and_b32_e32 v5, 0xc0, v5
	v_add_u32_e32 v4, v159, v4
	v_lshlrev_b32_e32 v6, 5, v157
	v_sub_u32_e32 v3, v3, v5
	v_and_b32_e32 v158, 32, v6
	v_ashrrev_i16_sdwa v3, v224, sext(v3) dst_sel:DWORD dst_unused:UNUSED_PAD src0_sel:DWORD src1_sel:BYTE_0
	v_lshlrev_b32_e32 v5, 1, v4
	v_lshrrev_b32_e32 v6, 2, v4
	v_and_b32_e32 v7, 3, v159
	v_bfe_i32 v160, v3, 0, 16
	v_and_b32_e32 v5, 24, v5
	v_and_b32_e32 v6, 4, v6
	v_and_or_b32 v7, v4, s14, v7
	v_add_u32_e32 v3, v158, v160
	v_or3_b32 v5, v7, v6, v5
	v_mul_lo_u32 v4, v4, s12
	v_add_lshl_u32 v138, v3, v4, 1
	v_mul_lo_u32 v4, v5, s12
	s_ashr_i32 s12, s22, 6
	s_ashr_i32 s18, s22, 8
	s_lshl_b32 s40, s12, 10
	s_lshl_b32 s12, s12, 5
	s_lshl_b32 s41, s18, 6
	s_and_b32 s42, s12, 0x60
	s_lshl_b32 s12, s56, 8
	v_and_b32_e32 v154, 15, v2
	s_add_i32 s12, s12, s41
	v_bfe_u32 v153, v2, 4, 2
	v_or_b32_e32 v2, s12, v154
	v_add_lshl_u32 v140, v4, v3, 1
	v_ashrrev_i32_e32 v3, 31, v2
	v_lshlrev_b64 v[2:3], 12, v[2:3]
	s_lshl_b32 s14, s55, 8
	v_lshl_add_u64 v[2:3], v[132:133], 0, v[2:3]
	s_ashr_i32 s15, s14, 31
	v_lshl_add_u64 v[2:3], s[14:15], 1, v[2:3]
	s_lshl_b32 s12, s42, 1
	v_lshl_add_u64 v[2:3], v[2:3], 0, s[12:13]
	v_lshlrev_b32_e32 v180, 4, v153
	v_lshl_add_u64 v[2:3], v[2:3], 0, v[180:181]
	s_mov_b32 s14, 0x10000
	v_add_co_u32_e32 v4, vcc, s14, v2
	s_mov_b32 s14, 0x20000
	s_nop 0
	v_addc_co_u32_e32 v5, vcc, 0, v3, vcc
	global_load_dwordx4 v[64:67], v[2:3], off
	global_load_dwordx4 v[60:63], v[2:3], off offset:256
	global_load_dwordx4 v[56:59], v[4:5], off
	global_load_dwordx4 v[52:55], v[4:5], off offset:256
	v_add_co_u32_e32 v4, vcc, s14, v2
	s_mov_b32 s14, 0x30000
	s_nop 0
	v_addc_co_u32_e32 v5, vcc, 0, v3, vcc
	global_load_dwordx4 v[48:51], v[4:5], off
	global_load_dwordx4 v[44:47], v[4:5], off offset:256
	v_add_co_u32_e32 v4, vcc, s14, v2
	s_mov_b32 s14, 0x80000
	s_nop 0
	v_addc_co_u32_e32 v5, vcc, 0, v3, vcc
	global_load_dwordx4 v[40:43], v[4:5], off
	global_load_dwordx4 v[36:39], v[4:5], off offset:256
	v_add_co_u32_e32 v4, vcc, s14, v2
	s_mov_b32 s14, 0x90000
	s_nop 0
	v_addc_co_u32_e32 v5, vcc, 0, v3, vcc
	global_load_dwordx4 v[32:35], v[4:5], off
	global_load_dwordx4 v[28:31], v[4:5], off offset:256
	v_add_co_u32_e32 v4, vcc, s14, v2
	s_mov_b32 s14, 0xa0000
	s_nop 0
	v_addc_co_u32_e32 v5, vcc, 0, v3, vcc
	global_load_dwordx4 v[24:27], v[4:5], off
	global_load_dwordx4 v[18:21], v[4:5], off offset:256
	v_add_co_u32_e32 v4, vcc, s14, v2
	s_mov_b32 s14, 0xb0000
	s_nop 0
	v_addc_co_u32_e32 v5, vcc, 0, v3, vcc
	s_mul_i32 s15, s55, 0x2b0000
	v_add_co_u32_e32 v14, vcc, s14, v2
	s_mul_hi_i32 s14, s55, 0x2b0000
	s_add_u32 s28, s8, s15
	s_addc_u32 s29, s9, s14
	s_add_i32 s43, s40, 0
	v_addc_co_u32_e32 v15, vcc, 0, v3, vcc
	s_add_i32 m0, s43, 0x10000
	global_load_dwordx4 v[10:13], v[4:5], off
	global_load_dwordx4 v[6:9], v[4:5], off offset:256
	s_nop 0
	global_load_dwordx4 v[2:5], v[14:15], off
	s_nop 0
	global_load_dwordx4 v[14:17], v[14:15], off offset:256
	s_mul_i32 s23, s56, 0x2b0000
	global_load_lds_dwordx4 v136, s[28:29]
	s_add_i32 m0, s43, 0x12000
	s_add_u32 s14, s28, 0x158000
	global_load_lds_dwordx4 v140, s[28:29]
	s_addc_u32 s15, s29, 0
	s_add_i32 m0, s43, 0x14000
	s_mul_hi_i32 s19, s56, 0x2b0000
	global_load_lds_dwordx4 v136, s[14:15]
	s_add_i32 m0, s43, 0x16000
	s_add_u32 s26, s6, s23
	s_addc_u32 s27, s7, s19
	s_add_i32 s44, s43, 0x2000
	global_load_lds_dwordx4 v140, s[14:15]
	s_mov_b32 m0, s43
	s_add_u32 s14, s26, 0x158000
	global_load_lds_dwordx4 v134, s[26:27]
	s_mov_b32 m0, s44
	s_addc_u32 s15, s27, 0
	s_add_i32 s45, s43, 0x4000
	global_load_lds_dwordx4 v138, s[26:27]
	s_mov_b32 m0, s45
	s_add_i32 s47, s43, 0x6000
	global_load_lds_dwordx4 v134, s[14:15]
	s_mov_b32 m0, s47
	v_mov_b32_e32 v137, v181
	global_load_lds_dwordx4 v138, s[14:15]
	v_mov_b32_e32 v141, v181
	v_mov_b32_e32 v135, v181
	v_mov_b32_e32 v139, v181
	s_cmp_eq_u32 s18, 1
	v_lshl_add_u64 v[146:147], s[28:29], 0, v[136:137]
	v_lshl_add_u64 v[144:145], s[28:29], 0, v[140:141]
	v_lshl_add_u64 v[68:69], s[26:27], 0, v[134:135]
	s_cselect_b64 s[14:15], -1, 0
	s_cmp_lg_u32 s18, 1
	v_lshl_add_u64 v[142:143], s[26:27], 0, v[138:139]
	s_cbranch_scc0 .LBB0_2227
	s_barrier

.LBB0_2241:
	s_add_u32 s28, s26, 0x100
	s_addc_u32 s29, s27, 0
	s_add_i32 s58, 0, 0x10000
	s_cmpk_eq_i32 s57, 0x52
	s_cselect_b32 s35, s23, s29
	s_cselect_b32 s34, s22, s28
	s_cselect_b32 s31, s25, s39
	s_cselect_b32 s30, s24, s38
	s_add_i32 s59, 0, 0x14000
	v_add_u32_e32 v166, s58, v156
	v_add_u32_e32 v178, s59, v156
	ds_read_b128 v[148:151], v166
	ds_read_b128 v[158:161], v166 offset:1024
	ds_read_b128 v[162:165], v166 offset:2048
	ds_read_b128 v[166:169], v166 offset:3072
	ds_read_b128 v[170:173], v178
	ds_read_b128 v[174:177], v178 offset:1024
	ds_read_b128 v[190:193], v178 offset:2048
	ds_read_b128 v[194:197], v178 offset:3072
	v_lshl_add_u64 v[178:179], s[26:27], 0, v[144:145]
	s_add_i32 m0, s43, 0xc000
	ds_read_b128 v[198:201], v157
	ds_read_b128 v[202:205], v157 offset:1024
	ds_read_b128 v[206:209], v157 offset:2048
	ds_read_b128 v[210:213], v157 offset:3072
	ds_read_b128 v[214:217], v157 offset:4096
	ds_read_b128 v[218:221], v157 offset:5120
	ds_read_b128 v[238:241], v157 offset:6144
	ds_read_b128 v[242:245], v157 offset:7168
	global_load_lds_dwordx4 v[178:179], off
	v_lshl_add_u64 v[178:179], s[26:27], 0, v[146:147]
	s_add_i32 m0, s43, 0xe000
	s_nop 0
	global_load_lds_dwordx4 v[178:179], off
	s_waitcnt vmcnt(8)
	s_waitcnt lgkmcnt(0)
	s_barrier
	s_setprio 1
	s_waitcnt lgkmcnt(0)
	v_mfma_f32_16x16x32_bf16 v[126:129], v[148:151], v[198:201], v[126:129]
	v_mfma_f32_16x16x32_bf16 v[114:117], v[162:165], v[198:201], v[114:117]
	v_mfma_f32_16x16x32_bf16 v[106:109], v[148:151], v[206:209], v[106:109]
	v_mfma_f32_16x16x32_bf16 v[98:101], v[162:165], v[206:209], v[98:101]
	v_mfma_f32_16x16x32_bf16 v[90:93], v[148:151], v[214:217], v[90:93]
	v_mfma_f32_16x16x32_bf16 v[82:85], v[162:165], v[214:217], v[82:85]
	v_mfma_f32_16x16x32_bf16 v[74:77], v[148:151], v[238:241], v[74:77]
	v_mfma_f32_16x16x32_bf16 v[54:57], v[162:165], v[238:241], v[54:57]
	v_mfma_f32_16x16x32_bf16 v[126:129], v[158:161], v[202:205], v[126:129]
	v_mfma_f32_16x16x32_bf16 v[114:117], v[166:169], v[202:205], v[114:117]
	v_mfma_f32_16x16x32_bf16 v[106:109], v[158:161], v[210:213], v[106:109]
	v_mfma_f32_16x16x32_bf16 v[98:101], v[166:169], v[210:213], v[98:101]
	v_mfma_f32_16x16x32_bf16 v[90:93], v[158:161], v[218:221], v[90:93]
	v_mfma_f32_16x16x32_bf16 v[82:85], v[166:169], v[218:221], v[82:85]
	v_mfma_f32_16x16x32_bf16 v[74:77], v[158:161], v[242:245], v[74:77]
	v_mfma_f32_16x16x32_bf16 v[54:57], v[166:169], v[242:245], v[54:57]
	v_mfma_f32_16x16x32_bf16 v[118:121], v[170:173], v[198:201], v[118:121]
	v_mfma_f32_16x16x32_bf16 v[122:125], v[190:193], v[198:201], v[122:125]
	v_mfma_f32_16x16x32_bf16 v[102:105], v[170:173], v[206:209], v[102:105]
	v_mfma_f32_16x16x32_bf16 v[110:113], v[190:193], v[206:209], v[110:113]
	v_mfma_f32_16x16x32_bf16 v[86:89], v[170:173], v[214:217], v[86:89]
	v_mfma_f32_16x16x32_bf16 v[94:97], v[190:193], v[214:217], v[94:97]
	v_mfma_f32_16x16x32_bf16 v[70:73], v[170:173], v[238:241], v[70:73]
	v_mfma_f32_16x16x32_bf16 v[78:81], v[190:193], v[238:241], v[78:81]
	v_mfma_f32_16x16x32_bf16 v[118:121], v[174:177], v[202:205], v[118:121]
	v_mfma_f32_16x16x32_bf16 v[122:125], v[194:197], v[202:205], v[122:125]
	v_mfma_f32_16x16x32_bf16 v[102:105], v[174:177], v[210:213], v[102:105]
	v_mfma_f32_16x16x32_bf16 v[110:113], v[194:197], v[210:213], v[110:113]
	v_mfma_f32_16x16x32_bf16 v[86:89], v[174:177], v[218:221], v[86:89]
	v_mfma_f32_16x16x32_bf16 v[94:97], v[194:197], v[218:221], v[94:97]
	v_mfma_f32_16x16x32_bf16 v[70:73], v[174:177], v[242:245], v[70:73]
	v_mfma_f32_16x16x32_bf16 v[78:81], v[194:197], v[242:245], v[78:81]
	s_setprio 0
	s_barrier
	s_add_i32 s26, s58, s40
	v_lshl_add_u64 v[178:179], s[30:31], 0, v[136:137]
	s_mov_b32 m0, s26
	ds_read_b128 v[198:201], v157 offset:16384
	ds_read_b128 v[202:205], v157 offset:17408
	ds_read_b128 v[206:209], v157 offset:18432
	ds_read_b128 v[210:213], v157 offset:19456
	ds_read_b128 v[214:217], v157 offset:20480
	ds_read_b128 v[218:221], v157 offset:21504
	ds_read_b128 v[238:241], v157 offset:22528
	ds_read_b128 v[242:245], v157 offset:23552
	global_load_lds_dwordx4 v[178:179], off
	s_add_i32 m0, s26, 0x2000
	s_add_u32 s26, s30, 0x158000
	v_lshl_add_u64 v[222:223], s[30:31], 0, v[140:141]
	s_addc_u32 s27, s31, 0
	s_add_i32 s58, s59, s40
	global_load_lds_dwordx4 v[222:223], off
	v_lshl_add_u64 v[246:247], s[26:27], 0, v[136:137]
	s_mov_b32 m0, s58
	v_lshl_add_u64 v[248:249], s[34:35], 0, v[138:139]
	global_load_lds_dwordx4 v[246:247], off
	v_lshl_add_u64 v[246:247], s[26:27], 0, v[140:141]
	s_add_i32 m0, s58, 0x2000
	s_nop 0
	global_load_lds_dwordx4 v[246:247], off
	v_lshl_add_u64 v[246:247], s[34:35], 0, v[134:135]
	s_mov_b32 m0, s43
	s_nop 0
	global_load_lds_dwordx4 v[246:247], off
	s_mov_b32 m0, s44
	s_nop 0
	global_load_lds_dwordx4 v[248:249], off
	s_waitcnt vmcnt(8)
	s_waitcnt lgkmcnt(0)
	s_barrier
	s_setprio 1
	s_waitcnt lgkmcnt(0)
	v_mfma_f32_16x16x32_bf16 v[50:53], v[148:151], v[198:201], v[50:53]
	v_mfma_f32_16x16x32_bf16 v[38:41], v[162:165], v[198:201], v[38:41]
	v_mfma_f32_16x16x32_bf16 v[22:25], v[148:151], v[206:209], v[22:25]
	v_mfma_f32_16x16x32_bf16 v[42:45], v[162:165], v[206:209], v[42:45]
	v_mfma_f32_16x16x32_bf16 v[30:33], v[148:151], v[214:217], v[30:33]
	v_mfma_f32_16x16x32_bf16 v[18:21], v[162:165], v[214:217], v[18:21]
	v_mfma_f32_16x16x32_bf16 v[10:13], v[148:151], v[238:241], v[10:13]
	v_mfma_f32_16x16x32_bf16 v[2:5], v[162:165], v[238:241], v[2:5]
	v_mfma_f32_16x16x32_bf16 v[50:53], v[158:161], v[202:205], v[50:53]
	v_mfma_f32_16x16x32_bf16 v[38:41], v[166:169], v[202:205], v[38:41]
	v_mfma_f32_16x16x32_bf16 v[22:25], v[158:161], v[210:213], v[22:25]
	v_mfma_f32_16x16x32_bf16 v[42:45], v[166:169], v[210:213], v[42:45]
	v_mfma_f32_16x16x32_bf16 v[30:33], v[158:161], v[218:221], v[30:33]
	v_mfma_f32_16x16x32_bf16 v[18:21], v[166:169], v[218:221], v[18:21]
	v_mfma_f32_16x16x32_bf16 v[10:13], v[158:161], v[242:245], v[10:13]
	v_mfma_f32_16x16x32_bf16 v[2:5], v[166:169], v[242:245], v[2:5]
	v_mfma_f32_16x16x32_bf16 v[46:49], v[170:173], v[198:201], v[46:49]
	v_mfma_f32_16x16x32_bf16 v[58:61], v[190:193], v[198:201], v[58:61]
	v_mfma_f32_16x16x32_bf16 v[62:65], v[170:173], v[206:209], v[62:65]
	v_mfma_f32_16x16x32_bf16 v[66:69], v[190:193], v[206:209], v[66:69]
	v_mfma_f32_16x16x32_bf16 v[26:29], v[170:173], v[214:217], v[26:29]
	v_mfma_f32_16x16x32_bf16 v[34:37], v[190:193], v[214:217], v[34:37]
	v_mfma_f32_16x16x32_bf16 v[6:9], v[170:173], v[238:241], v[6:9]
	v_mfma_f32_16x16x32_bf16 v[14:17], v[190:193], v[238:241], v[14:17]
	v_mfma_f32_16x16x32_bf16 v[46:49], v[174:177], v[202:205], v[46:49]
	v_mfma_f32_16x16x32_bf16 v[58:61], v[194:197], v[202:205], v[58:61]
	v_mfma_f32_16x16x32_bf16 v[62:65], v[174:177], v[210:213], v[62:65]
	v_mfma_f32_16x16x32_bf16 v[66:69], v[194:197], v[210:213], v[66:69]
	v_mfma_f32_16x16x32_bf16 v[26:29], v[174:177], v[218:221], v[26:29]
	v_mfma_f32_16x16x32_bf16 v[34:37], v[194:197], v[218:221], v[34:37]
	v_mfma_f32_16x16x32_bf16 v[6:9], v[174:177], v[242:245], v[6:9]
	v_mfma_f32_16x16x32_bf16 v[14:17], v[194:197], v[242:245], v[14:17]
	s_setprio 0
	s_barrier
	s_add_i32 s58, 0, 0x18000
	s_add_i32 s59, 0, 0x1c000
	v_add_u32_e32 v166, s58, v156
	v_add_u32_e32 v194, s59, v156
	ds_read_b128 v[148:151], v166
	ds_read_b128 v[158:161], v166 offset:1024
	ds_read_b128 v[162:165], v166 offset:2048
	ds_read_b128 v[166:169], v166 offset:3072
	ds_read_b128 v[170:173], v194
	ds_read_b128 v[174:177], v194 offset:1024
	ds_read_b128 v[190:193], v194 offset:2048
	ds_read_b128 v[194:197], v194 offset:3072
	s_add_u32 s26, s34, 0x158000
	s_addc_u32 s27, s35, 0
	s_mov_b32 m0, s45
	v_lshl_add_u64 v[250:251], s[26:27], 0, v[134:135]
	ds_read_b128 v[198:201], v157 offset:32768
	ds_read_b128 v[202:205], v157 offset:33792
	ds_read_b128 v[206:209], v157 offset:34816
	ds_read_b128 v[210:213], v157 offset:35840
	ds_read_b128 v[214:217], v157 offset:36864
	ds_read_b128 v[218:221], v157 offset:37888
	ds_read_b128 v[238:241], v157 offset:38912
	ds_read_b128 v[242:245], v157 offset:39936
	global_load_lds_dwordx4 v[250:251], off
	v_lshl_add_u64 v[250:251], s[26:27], 0, v[138:139]
	s_mov_b32 m0, s47
	s_nop 0
	global_load_lds_dwordx4 v[250:251], off
	s_waitcnt vmcnt(8)
	s_waitcnt lgkmcnt(0)
	s_barrier
	s_setprio 1
	s_waitcnt lgkmcnt(0)
	v_mfma_f32_16x16x32_bf16 v[126:129], v[148:151], v[198:201], v[126:129]
	v_mfma_f32_16x16x32_bf16 v[114:117], v[162:165], v[198:201], v[114:117]
	v_mfma_f32_16x16x32_bf16 v[106:109], v[148:151], v[206:209], v[106:109]
	v_mfma_f32_16x16x32_bf16 v[98:101], v[162:165], v[206:209], v[98:101]
	v_mfma_f32_16x16x32_bf16 v[90:93], v[148:151], v[214:217], v[90:93]
	v_mfma_f32_16x16x32_bf16 v[82:85], v[162:165], v[214:217], v[82:85]
	v_mfma_f32_16x16x32_bf16 v[74:77], v[148:151], v[238:241], v[74:77]
	v_mfma_f32_16x16x32_bf16 v[54:57], v[162:165], v[238:241], v[54:57]
	v_mfma_f32_16x16x32_bf16 v[126:129], v[158:161], v[202:205], v[126:129]
	v_mfma_f32_16x16x32_bf16 v[114:117], v[166:169], v[202:205], v[114:117]
	v_mfma_f32_16x16x32_bf16 v[106:109], v[158:161], v[210:213], v[106:109]
	v_mfma_f32_16x16x32_bf16 v[98:101], v[166:169], v[210:213], v[98:101]
	v_mfma_f32_16x16x32_bf16 v[90:93], v[158:161], v[218:221], v[90:93]
	v_mfma_f32_16x16x32_bf16 v[82:85], v[166:169], v[218:221], v[82:85]
	v_mfma_f32_16x16x32_bf16 v[74:77], v[158:161], v[242:245], v[74:77]
	v_mfma_f32_16x16x32_bf16 v[54:57], v[166:169], v[242:245], v[54:57]
	v_mfma_f32_16x16x32_bf16 v[118:121], v[170:173], v[198:201], v[118:121]
	v_mfma_f32_16x16x32_bf16 v[122:125], v[190:193], v[198:201], v[122:125]
	v_mfma_f32_16x16x32_bf16 v[102:105], v[170:173], v[206:209], v[102:105]
	v_mfma_f32_16x16x32_bf16 v[110:113], v[190:193], v[206:209], v[110:113]
	v_mfma_f32_16x16x32_bf16 v[86:89], v[170:173], v[214:217], v[86:89]
	v_mfma_f32_16x16x32_bf16 v[94:97], v[190:193], v[214:217], v[94:97]
	v_mfma_f32_16x16x32_bf16 v[70:73], v[170:173], v[238:241], v[70:73]
	v_mfma_f32_16x16x32_bf16 v[78:81], v[190:193], v[238:241], v[78:81]
	v_mfma_f32_16x16x32_bf16 v[118:121], v[174:177], v[202:205], v[118:121]
	v_mfma_f32_16x16x32_bf16 v[122:125], v[194:197], v[202:205], v[122:125]
	v_mfma_f32_16x16x32_bf16 v[102:105], v[174:177], v[210:213], v[102:105]
	v_mfma_f32_16x16x32_bf16 v[110:113], v[194:197], v[210:213], v[110:113]
	v_mfma_f32_16x16x32_bf16 v[86:89], v[174:177], v[218:221], v[86:89]
	v_mfma_f32_16x16x32_bf16 v[94:97], v[194:197], v[218:221], v[94:97]
	v_mfma_f32_16x16x32_bf16 v[70:73], v[174:177], v[242:245], v[70:73]
	v_mfma_f32_16x16x32_bf16 v[78:81], v[194:197], v[242:245], v[78:81]
	s_setprio 0
	s_barrier
	s_add_i32 s26, s58, s40
	v_lshl_add_u64 v[178:179], v[178:179], 0, s[16:17]
	s_mov_b32 m0, s26
	ds_read_b128 v[198:201], v157 offset:49152
	ds_read_b128 v[202:205], v157 offset:50176
	ds_read_b128 v[206:209], v157 offset:51200
	ds_read_b128 v[210:213], v157 offset:52224
	ds_read_b128 v[214:217], v157 offset:53248
	ds_read_b128 v[218:221], v157 offset:54272
	ds_read_b128 v[238:241], v157 offset:55296
	ds_read_b128 v[242:245], v157 offset:56320
	global_load_lds_dwordx4 v[178:179], off
	s_add_i32 m0, s26, 0x2000
	s_add_u32 s26, s30, 0x158080
	v_lshl_add_u64 v[178:179], v[222:223], 0, s[16:17]
	s_addc_u32 s27, s31, 0
	s_add_i32 s30, s59, s40
	global_load_lds_dwordx4 v[178:179], off
	v_lshl_add_u64 v[178:179], s[26:27], 0, v[136:137]
	s_mov_b32 m0, s30
	s_nop 0
	global_load_lds_dwordx4 v[178:179], off
	v_lshl_add_u64 v[178:179], s[26:27], 0, v[140:141]
	s_add_i32 m0, s30, 0x2000
	s_nop 0
	global_load_lds_dwordx4 v[178:179], off
	v_lshl_add_u64 v[178:179], v[246:247], 0, s[16:17]
	s_mov_b32 m0, s48
	s_nop 0
	global_load_lds_dwordx4 v[178:179], off
	v_lshl_add_u64 v[178:179], v[248:249], 0, s[16:17]
	s_mov_b32 m0, s49
	s_nop 0
	global_load_lds_dwordx4 v[178:179], off
	s_waitcnt vmcnt(8)
	s_waitcnt lgkmcnt(0)
	s_barrier
	s_setprio 1
	s_waitcnt lgkmcnt(0)
	v_mfma_f32_16x16x32_bf16 v[50:53], v[148:151], v[198:201], v[50:53]
	v_mfma_f32_16x16x32_bf16 v[38:41], v[162:165], v[198:201], v[38:41]
	v_mfma_f32_16x16x32_bf16 v[22:25], v[148:151], v[206:209], v[22:25]
	v_mfma_f32_16x16x32_bf16 v[42:45], v[162:165], v[206:209], v[42:45]
	v_mfma_f32_16x16x32_bf16 v[30:33], v[148:151], v[214:217], v[30:33]
	v_mfma_f32_16x16x32_bf16 v[18:21], v[162:165], v[214:217], v[18:21]
	v_mfma_f32_16x16x32_bf16 v[10:13], v[148:151], v[238:241], v[10:13]
	v_mfma_f32_16x16x32_bf16 v[2:5], v[162:165], v[238:241], v[2:5]
	v_mfma_f32_16x16x32_bf16 v[50:53], v[158:161], v[202:205], v[50:53]
	v_mfma_f32_16x16x32_bf16 v[38:41], v[166:169], v[202:205], v[38:41]
	v_mfma_f32_16x16x32_bf16 v[22:25], v[158:161], v[210:213], v[22:25]
	v_mfma_f32_16x16x32_bf16 v[42:45], v[166:169], v[210:213], v[42:45]
	v_mfma_f32_16x16x32_bf16 v[30:33], v[158:161], v[218:221], v[30:33]
	v_mfma_f32_16x16x32_bf16 v[18:21], v[166:169], v[218:221], v[18:21]
	v_mfma_f32_16x16x32_bf16 v[10:13], v[158:161], v[242:245], v[10:13]
	v_mfma_f32_16x16x32_bf16 v[2:5], v[166:169], v[242:245], v[2:5]
	v_mfma_f32_16x16x32_bf16 v[46:49], v[170:173], v[198:201], v[46:49]
	v_mfma_f32_16x16x32_bf16 v[58:61], v[190:193], v[198:201], v[58:61]
	v_mfma_f32_16x16x32_bf16 v[62:65], v[170:173], v[206:209], v[62:65]
	v_mfma_f32_16x16x32_bf16 v[66:69], v[190:193], v[206:209], v[66:69]
	v_mfma_f32_16x16x32_bf16 v[26:29], v[170:173], v[214:217], v[26:29]
	v_mfma_f32_16x16x32_bf16 v[34:37], v[190:193], v[214:217], v[34:37]
	v_mfma_f32_16x16x32_bf16 v[6:9], v[170:173], v[238:241], v[6:9]
	v_mfma_f32_16x16x32_bf16 v[14:17], v[190:193], v[238:241], v[14:17]
	v_mfma_f32_16x16x32_bf16 v[46:49], v[174:177], v[202:205], v[46:49]
	v_mfma_f32_16x16x32_bf16 v[58:61], v[194:197], v[202:205], v[58:61]
	v_mfma_f32_16x16x32_bf16 v[62:65], v[174:177], v[210:213], v[62:65]
	v_mfma_f32_16x16x32_bf16 v[66:69], v[194:197], v[210:213], v[66:69]
	v_mfma_f32_16x16x32_bf16 v[26:29], v[174:177], v[218:221], v[26:29]
	v_mfma_f32_16x16x32_bf16 v[34:37], v[194:197], v[218:221], v[34:37]
	v_mfma_f32_16x16x32_bf16 v[6:9], v[174:177], v[242:245], v[6:9]
	v_mfma_f32_16x16x32_bf16 v[14:17], v[194:197], v[242:245], v[14:17]
	s_setprio 0
	s_barrier
	s_add_i32 s57, s57, 2
	s_add_u32 s38, s38, 0x100
	s_addc_u32 s39, s39, 0
	s_cmpk_gt_u32 s57, 0x53
	s_mov_b64 s[26:27], s[28:29]
	s_cbranch_scc0 .LBB0_2241
	s_and_b64 vcc, exec, s[18:19]
	s_cbranch_vccnz .LBB0_2244
	s_barrier

.LBB0_2260:
	s_or_b64 exec, exec, s[26:27]
	s_and_b64 vcc, exec, s[36:37]
	s_mov_b64 s[26:27], -1
	s_cbranch_vccnz .LBB0_2229
	v_lshl_add_u32 v2, s54, 8, v155
	s_waitcnt lgkmcnt(0)
	v_ashrrev_i32_e32 v3, 31, v2
	v_lshlrev_b64 v[2:3], 12, v[2:3]
	s_lshl_b32 s26, s51, 8
	v_lshl_add_u64 v[2:3], v[132:133], 0, v[2:3]
	s_ashr_i32 s27, s26, 31
	v_lshl_add_u64 v[2:3], s[26:27], 1, v[2:3]
	v_lshl_add_u64 v[2:3], v[2:3], 0, s[12:13]
	v_lshl_add_u64 v[2:3], v[2:3], 0, v[180:181]
	s_mov_b32 s26, 0x10000
	v_add_co_u32_e32 v4, vcc, s26, v2
	s_mov_b32 s26, 0x20000
	s_nop 0
	v_addc_co_u32_e32 v5, vcc, 0, v3, vcc
	global_load_dwordx4 v[62:65], v[2:3], off
	global_load_dwordx4 v[54:57], v[2:3], off offset:256
	global_load_dwordx4 v[58:61], v[4:5], off
	global_load_dwordx4 v[46:49], v[4:5], off offset:256
	v_add_co_u32_e32 v4, vcc, s26, v2
	s_mov_b32 s26, 0x30000
	s_nop 0
	v_addc_co_u32_e32 v5, vcc, 0, v3, vcc
	global_load_dwordx4 v[50:53], v[4:5], off
	global_load_dwordx4 v[38:41], v[4:5], off offset:256
	v_add_co_u32_e32 v4, vcc, s26, v2
	s_mov_b32 s26, 0x80000
	s_nop 0
	v_addc_co_u32_e32 v5, vcc, 0, v3, vcc
	global_load_dwordx4 v[42:45], v[4:5], off
	global_load_dwordx4 v[30:33], v[4:5], off offset:256
	v_add_co_u32_e32 v4, vcc, s26, v2
	s_mov_b32 s26, 0x90000
	s_nop 0
	v_addc_co_u32_e32 v5, vcc, 0, v3, vcc
	global_load_dwordx4 v[34:37], v[4:5], off
	global_load_dwordx4 v[22:25], v[4:5], off offset:256
	v_add_co_u32_e32 v4, vcc, s26, v2
	s_nop 1
	v_addc_co_u32_e32 v5, vcc, 0, v3, vcc
	global_load_dwordx4 v[26:29], v[4:5], off
	global_load_dwordx4 v[18:21], v[4:5], off offset:256
	v_add_co_u32_e32 v4, vcc, 0xa0000, v2
	s_nop 1
	v_addc_co_u32_e32 v5, vcc, 0, v3, vcc
	v_add_co_u32_e32 v14, vcc, 0xb0000, v2
	global_load_dwordx4 v[10:13], v[4:5], off
	global_load_dwordx4 v[6:9], v[4:5], off offset:256
	v_addc_co_u32_e32 v15, vcc, 0, v3, vcc
	global_load_dwordx4 v[2:5], v[14:15], off
	s_nop 0
	global_load_dwordx4 v[14:17], v[14:15], off offset:256
	s_andn2_b64 vcc, exec, s[14:15]
	s_cbranch_vccz .LBB0_2228
	s_barrier
	s_branch .LBB0_2228

.LBB0_2276:
	s_andn2_b64 vcc, exec, s[18:19]
	s_cbranch_vccnz .LBB0_2330
	v_ashrrev_i32_e32 v4, 31, v2
	v_lshrrev_b32_e32 v4, 26, v4
	v_add_u32_e32 v4, v2, v4
	v_ashrrev_i32_e32 v132, 6, v4
	v_bfe_i32 v4, v2, 27, 1
	s_waitcnt lgkmcnt(0)
	v_lshlrev_b32_e32 v3, 4, v2
	v_lshrrev_b32_e32 v4, 22, v4
	v_add_u32_e32 v4, v3, v4
	v_and_b32_e32 v4, 0xfffffc00, v4
	v_sub_u32_e32 v4, v3, v4
	v_lshrrev_b32_e32 v5, 4, v4
	v_bitop3_b32 v4, v5, v4, 32 bitop3:0x6c
	v_ashrrev_i32_e32 v6, 31, v4
	v_lshrrev_b32_e32 v6, 26, v6
	v_lshlrev_b32_e32 v5, 3, v132
	v_add_u32_e32 v6, v4, v6
	v_and_b32_e32 v5, -16, v5
	v_ashrrev_i32_e32 v134, 6, v6
	v_and_b32_e32 v6, 0xc0, v6
	s_mov_b64 s[18:19], 0x1de00000
	v_add_u32_e32 v5, v134, v5
	v_lshlrev_b32_e32 v7, 5, v132
	v_sub_u32_e32 v4, v4, v6
	v_lshl_add_u64 v[146:147], v[130:131], 0, s[18:19]
	v_and_b32_e32 v133, 32, v7
	v_ashrrev_i16_sdwa v4, v224, sext(v4) dst_sel:DWORD dst_unused:UNUSED_PAD src0_sel:DWORD src1_sel:BYTE_0
	v_lshlrev_b32_e32 v6, 1, v5
	v_lshrrev_b32_e32 v7, 2, v5
	v_and_b32_e32 v8, 3, v134
	s_mov_b32 s18, 0x1ffffe0
	v_bfe_i32 v135, v4, 0, 16
	v_and_b32_e32 v6, 24, v6
	v_and_b32_e32 v7, 4, v7
	v_and_or_b32 v8, v5, s18, v8
	s_movk_i32 s12, 0x1580
	v_add_u32_e32 v4, v133, v135
	v_or3_b32 v6, v8, v7, v6
	v_mul_lo_u32 v5, v5, s12
	v_add_lshl_u32 v148, v4, v5, 1
	v_mul_lo_u32 v5, v6, s12
	v_add_u32_e32 v3, 0x2000, v3
	v_add_lshl_u32 v150, v5, v4, 1
	v_ashrrev_i32_e32 v4, 31, v3
	v_lshrrev_b32_e32 v4, 22, v4
	v_add_u32_e32 v4, v3, v4
	v_ashrrev_i32_e32 v136, 10, v4
	v_mul_i32_i24_e32 v4, 0x400, v136
	v_sub_u32_e32 v3, v3, v4
	v_lshrrev_b32_e32 v4, 4, v3
	v_bitop3_b32 v3, v4, v3, 32 bitop3:0x6c
	v_ashrrev_i32_e32 v5, 31, v3
	v_lshrrev_b32_e32 v5, 26, v5
	v_lshlrev_b32_e32 v4, 3, v136
	v_add_u32_e32 v5, v3, v5
	v_and_b32_e32 v4, -16, v4
	v_ashrrev_i32_e32 v138, 6, v5
	v_and_b32_e32 v5, 0xc0, v5
	v_add_u32_e32 v4, v138, v4
	v_lshlrev_b32_e32 v6, 5, v136
	v_sub_u32_e32 v3, v3, v5
	v_and_b32_e32 v137, 32, v6
	v_ashrrev_i16_sdwa v3, v224, sext(v3) dst_sel:DWORD dst_unused:UNUSED_PAD src0_sel:DWORD src1_sel:BYTE_0
	v_lshlrev_b32_e32 v5, 1, v4
	v_lshrrev_b32_e32 v6, 2, v4
	v_and_b32_e32 v7, 3, v138
	v_bfe_i32 v139, v3, 0, 16
	v_and_b32_e32 v5, 24, v5
	v_and_b32_e32 v6, 4, v6
	v_and_or_b32 v7, v4, s18, v7
	v_add_u32_e32 v3, v137, v139
	v_or3_b32 v5, v7, v6, v5
	v_mul_lo_u32 v4, v4, s12
	v_add_lshl_u32 v152, v3, v4, 1
	v_mul_lo_u32 v4, v5, s12
	s_ashr_i32 s12, s24, 6
	s_ashr_i32 s22, s24, 8
	s_lshl_b32 s21, s12, 10
	s_lshl_b32 s12, s12, 5
	s_lshl_b32 s54, s22, 6
	s_and_b32 s55, s12, 0x60
	s_lshl_b32 s12, s42, 8
	v_and_b32_e32 v197, 15, v2
	s_add_i32 s12, s12, s54
	v_bfe_u32 v198, v2, 4, 2
	v_or_b32_e32 v2, s12, v197
	v_add_lshl_u32 v154, v4, v3, 1
	v_ashrrev_i32_e32 v3, 31, v2
	v_lshlrev_b64 v[2:3], 12, v[2:3]
	s_lshl_b32 s18, s66, 8
	v_lshl_add_u64 v[2:3], v[146:147], 0, v[2:3]
	s_ashr_i32 s19, s18, 31
	v_lshl_add_u64 v[2:3], s[18:19], 1, v[2:3]
	s_lshl_b32 s12, s55, 1
	v_lshl_add_u64 v[2:3], v[2:3], 0, s[12:13]
	v_lshlrev_b32_e32 v180, 4, v198
	v_lshl_add_u64 v[6:7], v[2:3], 0, v[180:181]
	s_mov_b32 s18, 0x10000
	v_add_co_u32_e32 v2, vcc, s18, v6
	s_mov_b32 s18, 0x20000
	s_nop 0
	v_addc_co_u32_e32 v3, vcc, 0, v7, vcc
	global_load_dwordx4 v[62:65], v[6:7], off
	global_load_dwordx4 v[58:61], v[6:7], off offset:256
	global_load_dwordx4 v[54:57], v[2:3], off
	global_load_dwordx4 v[50:53], v[2:3], off offset:256
	v_add_co_u32_e32 v2, vcc, s18, v6
	s_mov_b32 s18, 0x30000
	s_nop 0
	v_addc_co_u32_e32 v3, vcc, 0, v7, vcc
	global_load_dwordx4 v[46:49], v[2:3], off
	global_load_dwordx4 v[30:33], v[2:3], off offset:256
	v_add_co_u32_e32 v2, vcc, s18, v6
	s_mov_b32 s18, 0x80000
	s_nop 0
	v_addc_co_u32_e32 v3, vcc, 0, v7, vcc
	global_load_dwordx4 v[34:37], v[2:3], off
	global_load_dwordx4 v[22:25], v[2:3], off offset:256
	v_add_co_u32_e32 v2, vcc, s18, v6
	s_mov_b32 s18, 0x90000
	s_nop 0
	v_addc_co_u32_e32 v3, vcc, 0, v7, vcc
	global_load_dwordx4 v[26:29], v[2:3], off
	global_load_dwordx4 v[10:13], v[2:3], off offset:256
	v_add_co_u32_e32 v2, vcc, s18, v6
	s_mov_b32 s18, 0xa0000
	s_nop 0
	v_addc_co_u32_e32 v3, vcc, 0, v7, vcc
	global_load_dwordx4 v[42:45], v[2:3], off
	global_load_dwordx4 v[38:41], v[2:3], off offset:256
	v_add_co_u32_e32 v2, vcc, s18, v6
	s_mov_b32 s18, 0xb0000
	s_nop 0
	v_addc_co_u32_e32 v3, vcc, 0, v7, vcc
	s_mul_i32 s19, s66, 0x2b0000
	v_add_co_u32_e32 v18, vcc, s18, v6
	s_mul_hi_i32 s18, s66, 0x2b0000
	s_add_u32 s30, s8, s19
	s_addc_u32 s31, s9, s18
	s_add_i32 s56, s21, 0
	v_addc_co_u32_e32 v19, vcc, 0, v7, vcc
	s_add_i32 m0, s56, 0x10000
	global_load_dwordx4 v[14:17], v[2:3], off
	s_nop 0
	global_load_dwordx4 v[2:5], v[2:3], off offset:256
	s_nop 0
	global_load_dwordx4 v[6:9], v[18:19], off
	s_nop 0
	global_load_dwordx4 v[18:21], v[18:19], off offset:256
	s_mul_i32 s25, s42, 0x2b0000
	global_load_lds_dwordx4 v150, s[30:31]
	s_add_i32 m0, s56, 0x12000
	s_add_u32 s18, s30, 0x158000
	global_load_lds_dwordx4 v154, s[30:31]
	s_addc_u32 s19, s31, 0
	s_add_i32 m0, s56, 0x14000
	s_mul_hi_i32 s23, s42, 0x2b0000
	global_load_lds_dwordx4 v150, s[18:19]
	s_add_i32 m0, s56, 0x16000
	s_add_u32 s28, s6, s25
	s_addc_u32 s29, s7, s23
	s_add_i32 s57, s56, 0x2000
	global_load_lds_dwordx4 v154, s[18:19]
	s_mov_b32 m0, s56
	s_add_u32 s18, s28, 0x158000
	global_load_lds_dwordx4 v148, s[28:29]
	s_mov_b32 m0, s57
	s_addc_u32 s19, s29, 0
	s_add_i32 s58, s56, 0x4000
	global_load_lds_dwordx4 v152, s[28:29]
	s_mov_b32 m0, s58
	s_add_i32 s59, s56, 0x6000
	global_load_lds_dwordx4 v148, s[18:19]
	s_mov_b32 m0, s59
	v_mov_b32_e32 v151, v181
	global_load_lds_dwordx4 v152, s[18:19]
	v_mov_b32_e32 v155, v181
	v_mov_b32_e32 v149, v181
	v_mov_b32_e32 v153, v181
	s_cmp_eq_u32 s22, 1
	v_lshl_add_u64 v[80:81], s[30:31], 0, v[150:151]
	v_lshl_add_u64 v[78:79], s[30:31], 0, v[154:155]
	v_lshl_add_u64 v[66:67], s[28:29], 0, v[148:149]
	s_cselect_b64 s[18:19], -1, 0
	s_cmp_lg_u32 s22, 1
	v_lshl_add_u64 v[68:69], s[28:29], 0, v[152:153]
	s_cbranch_scc0 .LBB0_2279
	s_barrier

.LBB0_2293:
	s_add_u32 s30, s28, 0x100
	s_addc_u32 s31, s29, 0
	s_add_i32 s46, 0, 0x10000
	s_cmpk_eq_i32 s45, 0x52
	s_cselect_b32 s39, s25, s31
	s_cselect_b32 s38, s24, s30
	s_cselect_b32 s35, s27, s44
	s_cselect_b32 s34, s26, s43
	s_add_i32 s47, 0, 0x14000
	v_add_u32_e32 v142, s46, v200
	v_add_u32_e32 v176, s47, v200
	ds_read_b128 v[130:133], v142
	ds_read_b128 v[134:137], v142 offset:1024
	ds_read_b128 v[138:141], v142 offset:2048
	ds_read_b128 v[142:145], v142 offset:3072
	ds_read_b128 v[164:167], v176
	ds_read_b128 v[168:171], v176 offset:1024
	ds_read_b128 v[172:175], v176 offset:2048
	ds_read_b128 v[176:179], v176 offset:3072
	v_lshl_add_u64 v[222:223], s[28:29], 0, v[160:161]
	s_add_i32 m0, s56, 0xc000
	ds_read_b128 v[190:193], v201
	ds_read_b128 v[202:205], v201 offset:1024
	ds_read_b128 v[206:209], v201 offset:2048
	ds_read_b128 v[210:213], v201 offset:3072
	ds_read_b128 v[214:217], v201 offset:4096
	ds_read_b128 v[218:221], v201 offset:5120
	ds_read_b128 v[238:241], v201 offset:6144
	ds_read_b128 v[242:245], v201 offset:7168
	global_load_lds_dwordx4 v[222:223], off
	v_lshl_add_u64 v[222:223], s[28:29], 0, v[162:163]
	s_add_i32 m0, s56, 0xe000
	s_nop 0
	global_load_lds_dwordx4 v[222:223], off
	s_waitcnt vmcnt(8)
	s_waitcnt lgkmcnt(0)
	s_barrier
	s_setprio 1
	s_waitcnt lgkmcnt(0)
	v_mfma_f32_16x16x32_bf16 v[118:121], v[130:133], v[190:193], v[118:121]
	v_mfma_f32_16x16x32_bf16 v[114:117], v[138:141], v[190:193], v[114:117]
	v_mfma_f32_16x16x32_bf16 v[98:101], v[130:133], v[206:209], v[98:101]
	v_mfma_f32_16x16x32_bf16 v[102:105], v[138:141], v[206:209], v[102:105]
	v_mfma_f32_16x16x32_bf16 v[70:73], v[130:133], v[214:217], v[70:73]
	v_mfma_f32_16x16x32_bf16 v[74:77], v[138:141], v[214:217], v[74:77]
	v_mfma_f32_16x16x32_bf16 v[30:33], v[130:133], v[238:241], v[30:33]
	v_mfma_f32_16x16x32_bf16 v[34:37], v[138:141], v[238:241], v[34:37]
	v_mfma_f32_16x16x32_bf16 v[118:121], v[134:137], v[202:205], v[118:121]
	v_mfma_f32_16x16x32_bf16 v[114:117], v[142:145], v[202:205], v[114:117]
	v_mfma_f32_16x16x32_bf16 v[98:101], v[134:137], v[210:213], v[98:101]
	v_mfma_f32_16x16x32_bf16 v[102:105], v[142:145], v[210:213], v[102:105]
	v_mfma_f32_16x16x32_bf16 v[70:73], v[134:137], v[218:221], v[70:73]
	v_mfma_f32_16x16x32_bf16 v[74:77], v[142:145], v[218:221], v[74:77]
	v_mfma_f32_16x16x32_bf16 v[30:33], v[134:137], v[242:245], v[30:33]
	v_mfma_f32_16x16x32_bf16 v[34:37], v[142:145], v[242:245], v[34:37]
	v_mfma_f32_16x16x32_bf16 v[126:129], v[164:167], v[190:193], v[126:129]
	v_mfma_f32_16x16x32_bf16 v[122:125], v[172:175], v[190:193], v[122:125]
	v_mfma_f32_16x16x32_bf16 v[106:109], v[164:167], v[206:209], v[106:109]
	v_mfma_f32_16x16x32_bf16 v[110:113], v[172:175], v[206:209], v[110:113]
	v_mfma_f32_16x16x32_bf16 v[82:85], v[164:167], v[214:217], v[82:85]
	v_mfma_f32_16x16x32_bf16 v[86:89], v[172:175], v[214:217], v[86:89]
	v_mfma_f32_16x16x32_bf16 v[54:57], v[164:167], v[238:241], v[54:57]
	v_mfma_f32_16x16x32_bf16 v[58:61], v[172:175], v[238:241], v[58:61]
	v_mfma_f32_16x16x32_bf16 v[126:129], v[168:171], v[202:205], v[126:129]
	v_mfma_f32_16x16x32_bf16 v[122:125], v[176:179], v[202:205], v[122:125]
	v_mfma_f32_16x16x32_bf16 v[106:109], v[168:171], v[210:213], v[106:109]
	v_mfma_f32_16x16x32_bf16 v[110:113], v[176:179], v[210:213], v[110:113]
	v_mfma_f32_16x16x32_bf16 v[82:85], v[168:171], v[218:221], v[82:85]
	v_mfma_f32_16x16x32_bf16 v[86:89], v[176:179], v[218:221], v[86:89]
	v_mfma_f32_16x16x32_bf16 v[54:57], v[168:171], v[242:245], v[54:57]
	v_mfma_f32_16x16x32_bf16 v[58:61], v[176:179], v[242:245], v[58:61]
	s_setprio 0
	s_barrier
	s_add_i32 s28, s46, s21
	v_lshl_add_u64 v[222:223], s[34:35], 0, v[150:151]
	s_mov_b32 m0, s28
	ds_read_b128 v[190:193], v201 offset:16384
	ds_read_b128 v[202:205], v201 offset:17408
	ds_read_b128 v[206:209], v201 offset:18432
	ds_read_b128 v[210:213], v201 offset:19456
	ds_read_b128 v[214:217], v201 offset:20480
	ds_read_b128 v[218:221], v201 offset:21504
	ds_read_b128 v[238:241], v201 offset:22528
	ds_read_b128 v[242:245], v201 offset:23552
	global_load_lds_dwordx4 v[222:223], off
	s_add_i32 m0, s28, 0x2000
	s_add_u32 s28, s34, 0x158000
	v_lshl_add_u64 v[246:247], s[34:35], 0, v[154:155]
	s_addc_u32 s29, s35, 0
	s_add_i32 s46, s47, s21
	global_load_lds_dwordx4 v[246:247], off
	v_lshl_add_u64 v[248:249], s[28:29], 0, v[150:151]
	s_mov_b32 m0, s46
	v_lshl_add_u64 v[250:251], s[38:39], 0, v[152:153]
	global_load_lds_dwordx4 v[248:249], off
	v_lshl_add_u64 v[248:249], s[28:29], 0, v[154:155]
	s_add_i32 m0, s46, 0x2000
	s_nop 0
	global_load_lds_dwordx4 v[248:249], off
	v_lshl_add_u64 v[248:249], s[38:39], 0, v[148:149]
	s_mov_b32 m0, s56
	s_nop 0
	global_load_lds_dwordx4 v[248:249], off
	s_mov_b32 m0, s57
	s_nop 0
	global_load_lds_dwordx4 v[250:251], off
	s_waitcnt vmcnt(8)
	s_waitcnt lgkmcnt(0)
	s_barrier
	s_setprio 1
	s_waitcnt lgkmcnt(0)
	v_mfma_f32_16x16x32_bf16 v[22:25], v[130:133], v[190:193], v[22:25]
	v_mfma_f32_16x16x32_bf16 v[26:29], v[138:141], v[190:193], v[26:29]
	v_mfma_f32_16x16x32_bf16 v[10:13], v[130:133], v[206:209], v[10:13]
	v_mfma_f32_16x16x32_bf16 v[78:81], v[138:141], v[206:209], v[78:81]
	v_mfma_f32_16x16x32_bf16 v[38:41], v[130:133], v[214:217], v[38:41]
	v_mfma_f32_16x16x32_bf16 v[42:45], v[138:141], v[214:217], v[42:45]
	v_mfma_f32_16x16x32_bf16 v[2:5], v[130:133], v[238:241], v[2:5]
	v_mfma_f32_16x16x32_bf16 v[6:9], v[138:141], v[238:241], v[6:9]
	v_mfma_f32_16x16x32_bf16 v[22:25], v[134:137], v[202:205], v[22:25]
	v_mfma_f32_16x16x32_bf16 v[26:29], v[142:145], v[202:205], v[26:29]
	v_mfma_f32_16x16x32_bf16 v[10:13], v[134:137], v[210:213], v[10:13]
	v_mfma_f32_16x16x32_bf16 v[78:81], v[142:145], v[210:213], v[78:81]
	v_mfma_f32_16x16x32_bf16 v[38:41], v[134:137], v[218:221], v[38:41]
	v_mfma_f32_16x16x32_bf16 v[42:45], v[142:145], v[218:221], v[42:45]
	v_mfma_f32_16x16x32_bf16 v[2:5], v[134:137], v[242:245], v[2:5]
	v_mfma_f32_16x16x32_bf16 v[6:9], v[142:145], v[242:245], v[6:9]
	v_mfma_f32_16x16x32_bf16 v[46:49], v[164:167], v[190:193], v[46:49]
	v_mfma_f32_16x16x32_bf16 v[50:53], v[172:175], v[190:193], v[50:53]
	v_mfma_f32_16x16x32_bf16 v[90:93], v[164:167], v[206:209], v[90:93]
	v_mfma_f32_16x16x32_bf16 v[94:97], v[172:175], v[206:209], v[94:97]
	v_mfma_f32_16x16x32_bf16 v[62:65], v[164:167], v[214:217], v[62:65]
	v_mfma_f32_16x16x32_bf16 v[66:69], v[172:175], v[214:217], v[66:69]
	v_mfma_f32_16x16x32_bf16 v[14:17], v[164:167], v[238:241], v[14:17]
	v_mfma_f32_16x16x32_bf16 v[18:21], v[172:175], v[238:241], v[18:21]
	v_mfma_f32_16x16x32_bf16 v[46:49], v[168:171], v[202:205], v[46:49]
	v_mfma_f32_16x16x32_bf16 v[50:53], v[176:179], v[202:205], v[50:53]
	v_mfma_f32_16x16x32_bf16 v[90:93], v[168:171], v[210:213], v[90:93]
	v_mfma_f32_16x16x32_bf16 v[94:97], v[176:179], v[210:213], v[94:97]
	v_mfma_f32_16x16x32_bf16 v[62:65], v[168:171], v[218:221], v[62:65]
	v_mfma_f32_16x16x32_bf16 v[66:69], v[176:179], v[218:221], v[66:69]
	v_mfma_f32_16x16x32_bf16 v[14:17], v[168:171], v[242:245], v[14:17]
	v_mfma_f32_16x16x32_bf16 v[18:21], v[176:179], v[242:245], v[18:21]
	s_setprio 0
	s_barrier
	s_add_i32 s46, 0, 0x18000
	s_add_i32 s47, 0, 0x1c000
	v_add_u32_e32 v142, s46, v200
	v_add_u32_e32 v176, s47, v200
	ds_read_b128 v[130:133], v142
	ds_read_b128 v[134:137], v142 offset:1024
	ds_read_b128 v[138:141], v142 offset:2048
	ds_read_b128 v[142:145], v142 offset:3072
	ds_read_b128 v[164:167], v176
	ds_read_b128 v[168:171], v176 offset:1024
	ds_read_b128 v[172:175], v176 offset:2048
	ds_read_b128 v[176:179], v176 offset:3072
	s_add_u32 s28, s38, 0x158000
	s_addc_u32 s29, s39, 0
	s_mov_b32 m0, s58
	v_lshl_add_u64 v[252:253], s[28:29], 0, v[148:149]
	ds_read_b128 v[190:193], v201 offset:32768
	ds_read_b128 v[202:205], v201 offset:33792
	ds_read_b128 v[206:209], v201 offset:34816
	ds_read_b128 v[210:213], v201 offset:35840
	ds_read_b128 v[214:217], v201 offset:36864
	ds_read_b128 v[218:221], v201 offset:37888
	ds_read_b128 v[238:241], v201 offset:38912
	ds_read_b128 v[242:245], v201 offset:39936
	global_load_lds_dwordx4 v[252:253], off
	v_lshl_add_u64 v[252:253], s[28:29], 0, v[152:153]
	s_mov_b32 m0, s59
	s_nop 0
	global_load_lds_dwordx4 v[252:253], off
	s_waitcnt vmcnt(8)
	s_waitcnt lgkmcnt(0)
	s_barrier
	s_setprio 1
	s_waitcnt lgkmcnt(0)
	v_mfma_f32_16x16x32_bf16 v[118:121], v[130:133], v[190:193], v[118:121]
	v_mfma_f32_16x16x32_bf16 v[114:117], v[138:141], v[190:193], v[114:117]
	v_mfma_f32_16x16x32_bf16 v[98:101], v[130:133], v[206:209], v[98:101]
	v_mfma_f32_16x16x32_bf16 v[102:105], v[138:141], v[206:209], v[102:105]
	v_mfma_f32_16x16x32_bf16 v[70:73], v[130:133], v[214:217], v[70:73]
	v_mfma_f32_16x16x32_bf16 v[74:77], v[138:141], v[214:217], v[74:77]
	v_mfma_f32_16x16x32_bf16 v[30:33], v[130:133], v[238:241], v[30:33]
	v_mfma_f32_16x16x32_bf16 v[34:37], v[138:141], v[238:241], v[34:37]
	v_mfma_f32_16x16x32_bf16 v[118:121], v[134:137], v[202:205], v[118:121]
	v_mfma_f32_16x16x32_bf16 v[114:117], v[142:145], v[202:205], v[114:117]
	v_mfma_f32_16x16x32_bf16 v[98:101], v[134:137], v[210:213], v[98:101]
	v_mfma_f32_16x16x32_bf16 v[102:105], v[142:145], v[210:213], v[102:105]
	v_mfma_f32_16x16x32_bf16 v[70:73], v[134:137], v[218:221], v[70:73]
	v_mfma_f32_16x16x32_bf16 v[74:77], v[142:145], v[218:221], v[74:77]
	v_mfma_f32_16x16x32_bf16 v[30:33], v[134:137], v[242:245], v[30:33]
	v_mfma_f32_16x16x32_bf16 v[34:37], v[142:145], v[242:245], v[34:37]
	v_mfma_f32_16x16x32_bf16 v[126:129], v[164:167], v[190:193], v[126:129]
	v_mfma_f32_16x16x32_bf16 v[122:125], v[172:175], v[190:193], v[122:125]
	v_mfma_f32_16x16x32_bf16 v[106:109], v[164:167], v[206:209], v[106:109]
	v_mfma_f32_16x16x32_bf16 v[110:113], v[172:175], v[206:209], v[110:113]
	v_mfma_f32_16x16x32_bf16 v[82:85], v[164:167], v[214:217], v[82:85]
	v_mfma_f32_16x16x32_bf16 v[86:89], v[172:175], v[214:217], v[86:89]
	v_mfma_f32_16x16x32_bf16 v[54:57], v[164:167], v[238:241], v[54:57]
	v_mfma_f32_16x16x32_bf16 v[58:61], v[172:175], v[238:241], v[58:61]
	v_mfma_f32_16x16x32_bf16 v[126:129], v[168:171], v[202:205], v[126:129]
	v_mfma_f32_16x16x32_bf16 v[122:125], v[176:179], v[202:205], v[122:125]
	v_mfma_f32_16x16x32_bf16 v[106:109], v[168:171], v[210:213], v[106:109]
	v_mfma_f32_16x16x32_bf16 v[110:113], v[176:179], v[210:213], v[110:113]
	v_mfma_f32_16x16x32_bf16 v[82:85], v[168:171], v[218:221], v[82:85]
	v_mfma_f32_16x16x32_bf16 v[86:89], v[176:179], v[218:221], v[86:89]
	v_mfma_f32_16x16x32_bf16 v[54:57], v[168:171], v[242:245], v[54:57]
	v_mfma_f32_16x16x32_bf16 v[58:61], v[176:179], v[242:245], v[58:61]
	s_setprio 0
	s_barrier
	s_add_i32 s28, s46, s21
	v_lshl_add_u64 v[222:223], v[222:223], 0, s[16:17]
	s_mov_b32 m0, s28
	ds_read_b128 v[190:193], v201 offset:49152
	ds_read_b128 v[202:205], v201 offset:50176
	ds_read_b128 v[206:209], v201 offset:51200
	ds_read_b128 v[210:213], v201 offset:52224
	ds_read_b128 v[214:217], v201 offset:53248
	ds_read_b128 v[218:221], v201 offset:54272
	ds_read_b128 v[238:241], v201 offset:55296
	ds_read_b128 v[242:245], v201 offset:56320
	global_load_lds_dwordx4 v[222:223], off
	s_add_i32 m0, s28, 0x2000
	s_add_u32 s28, s34, 0x158080
	v_lshl_add_u64 v[222:223], v[246:247], 0, s[16:17]
	s_addc_u32 s29, s35, 0
	s_add_i32 s34, s47, s21
	global_load_lds_dwordx4 v[222:223], off
	v_lshl_add_u64 v[222:223], s[28:29], 0, v[150:151]
	s_mov_b32 m0, s34
	s_nop 0
	global_load_lds_dwordx4 v[222:223], off
	v_lshl_add_u64 v[222:223], s[28:29], 0, v[154:155]
	s_add_i32 m0, s34, 0x2000
	s_nop 0
	global_load_lds_dwordx4 v[222:223], off
	v_lshl_add_u64 v[222:223], v[248:249], 0, s[16:17]
	s_mov_b32 m0, s60
	s_nop 0
	global_load_lds_dwordx4 v[222:223], off
	v_lshl_add_u64 v[222:223], v[250:251], 0, s[16:17]
	s_mov_b32 m0, s61
	s_nop 0
	global_load_lds_dwordx4 v[222:223], off
	s_waitcnt vmcnt(8)
	s_waitcnt lgkmcnt(0)
	s_barrier
	s_setprio 1
	s_waitcnt lgkmcnt(0)
	v_mfma_f32_16x16x32_bf16 v[22:25], v[130:133], v[190:193], v[22:25]
	v_mfma_f32_16x16x32_bf16 v[26:29], v[138:141], v[190:193], v[26:29]
	v_mfma_f32_16x16x32_bf16 v[10:13], v[130:133], v[206:209], v[10:13]
	v_mfma_f32_16x16x32_bf16 v[78:81], v[138:141], v[206:209], v[78:81]
	v_mfma_f32_16x16x32_bf16 v[38:41], v[130:133], v[214:217], v[38:41]
	v_mfma_f32_16x16x32_bf16 v[42:45], v[138:141], v[214:217], v[42:45]
	v_mfma_f32_16x16x32_bf16 v[2:5], v[130:133], v[238:241], v[2:5]
	v_mfma_f32_16x16x32_bf16 v[6:9], v[138:141], v[238:241], v[6:9]
	v_mfma_f32_16x16x32_bf16 v[22:25], v[134:137], v[202:205], v[22:25]
	v_mfma_f32_16x16x32_bf16 v[26:29], v[142:145], v[202:205], v[26:29]
	v_mfma_f32_16x16x32_bf16 v[10:13], v[134:137], v[210:213], v[10:13]
	v_mfma_f32_16x16x32_bf16 v[78:81], v[142:145], v[210:213], v[78:81]
	v_mfma_f32_16x16x32_bf16 v[38:41], v[134:137], v[218:221], v[38:41]
	v_mfma_f32_16x16x32_bf16 v[42:45], v[142:145], v[218:221], v[42:45]
	v_mfma_f32_16x16x32_bf16 v[2:5], v[134:137], v[242:245], v[2:5]
	v_mfma_f32_16x16x32_bf16 v[6:9], v[142:145], v[242:245], v[6:9]
	v_mfma_f32_16x16x32_bf16 v[46:49], v[164:167], v[190:193], v[46:49]
	v_mfma_f32_16x16x32_bf16 v[50:53], v[172:175], v[190:193], v[50:53]
	v_mfma_f32_16x16x32_bf16 v[90:93], v[164:167], v[206:209], v[90:93]
	v_mfma_f32_16x16x32_bf16 v[94:97], v[172:175], v[206:209], v[94:97]
	v_mfma_f32_16x16x32_bf16 v[62:65], v[164:167], v[214:217], v[62:65]
	v_mfma_f32_16x16x32_bf16 v[66:69], v[172:175], v[214:217], v[66:69]
	v_mfma_f32_16x16x32_bf16 v[14:17], v[164:167], v[238:241], v[14:17]
	v_mfma_f32_16x16x32_bf16 v[18:21], v[172:175], v[238:241], v[18:21]
	v_mfma_f32_16x16x32_bf16 v[46:49], v[168:171], v[202:205], v[46:49]
	v_mfma_f32_16x16x32_bf16 v[50:53], v[176:179], v[202:205], v[50:53]
	v_mfma_f32_16x16x32_bf16 v[90:93], v[168:171], v[210:213], v[90:93]
	v_mfma_f32_16x16x32_bf16 v[94:97], v[176:179], v[210:213], v[94:97]
	v_mfma_f32_16x16x32_bf16 v[62:65], v[168:171], v[218:221], v[62:65]
	v_mfma_f32_16x16x32_bf16 v[66:69], v[176:179], v[218:221], v[66:69]
	v_mfma_f32_16x16x32_bf16 v[14:17], v[168:171], v[242:245], v[14:17]
	v_mfma_f32_16x16x32_bf16 v[18:21], v[176:179], v[242:245], v[18:21]
	s_setprio 0
	s_barrier
	s_add_i32 s45, s45, 2
	s_add_u32 s43, s43, 0x100
	s_addc_u32 s44, s44, 0
	s_cmpk_gt_u32 s45, 0x53
	s_mov_b64 s[28:29], s[30:31]
	s_cbranch_scc0 .LBB0_2293
	s_and_b64 vcc, exec, s[22:23]
	s_cbranch_vccnz .LBB0_2296
	s_barrier

.LBB0_2325:
	s_or_b64 exec, exec, s[28:29]
	s_lshl_b32 s28, s66, 8
	s_or_b32 s28, s28, s55
	v_lshl_add_u32 v130, v132, 3, s28
	s_waitcnt lgkmcnt(0)
	v_ashrrev_i32_e32 v131, 31, v130
	v_lshlrev_b64 v[190:191], 2, v[130:131]
	s_barrier
	v_lshl_add_u64 v[138:139], s[14:15], 0, v[190:191]
	v_lshl_add_u64 v[192:193], v[164:165], 3, v[156:157]
	global_load_dwordx4 v[134:137], v[138:139], off offset:16
	global_load_dwordx4 v[142:145], v[138:139], off
	global_load_dwordx4 v[130:133], v[138:139], off offset:528
	s_nop 0
	global_load_dwordx4 v[138:141], v[138:139], off offset:512
	v_lshlrev_b64 v[164:165], 13, v[164:165]
	global_load_dwordx2 v[202:203], v[192:193], off sc1
	v_lshl_add_u64 v[164:165], s[40:41], 0, v[164:165]
	v_lshl_add_u64 v[164:165], v[164:165], 0, v[190:191]
	s_mov_b64 s[28:29], -1
	s_waitcnt vmcnt(0)
	v_ffbh_u32_e32 v204, v203
	v_min_u32_e32 v204, 32, v204
	v_lshlrev_b64 v[202:203], v204, v[202:203]
	v_min_u32_e32 v202, 1, v202
	v_or_b32_e32 v202, v203, v202
	v_cvt_f32_u32_e32 v202, v202
	v_sub_u32_e32 v203, 32, v204
	v_ldexp_f32 v202, v202, v203
	v_mul_f32_e32 v202, 0x30800000, v202
	v_fmamk_f32 v202, v202, 0x3a000000, v1
	v_mul_f32_e32 v203, 0x4b800000, v202
	v_cmp_gt_f32_e32 vcc, s65, v202
	s_nop 1
	v_cndmask_b32_e32 v202, v202, v203, vcc
	v_rsq_f32_e32 v202, v202
	s_nop 0
	v_mul_f32_e32 v203, 0x45800000, v202
	v_cndmask_b32_e32 v202, v202, v203, vcc
	v_pk_mul_f32 v[118:119], v[118:119], v[202:203] op_sel_hi:[1,0]
	v_pk_mul_f32 v[120:121], v[120:121], v[202:203] op_sel_hi:[1,0]
	v_pk_mul_f32 v[204:205], v[114:115], v[202:203] op_sel_hi:[1,0]
	v_pk_mul_f32 v[206:207], v[116:117], v[202:203] op_sel_hi:[1,0]
	v_pk_mul_f32 v[126:127], v[126:127], v[202:203] op_sel_hi:[1,0]
	v_pk_mul_f32 v[128:129], v[128:129], v[202:203] op_sel_hi:[1,0]
	v_pk_mul_f32 v[208:209], v[122:123], v[202:203] op_sel_hi:[1,0]
	v_pk_mul_f32 v[202:203], v[124:125], v[202:203] op_sel_hi:[1,0]
	v_pk_mul_f32 v[116:117], v[144:145], v[120:121]
	v_pk_mul_f32 v[114:115], v[142:143], v[118:119]
	v_pk_mul_f32 v[120:121], v[136:137], v[206:207]
	v_pk_mul_f32 v[118:119], v[134:135], v[204:205]
	v_pk_mul_f32 v[124:125], v[140:141], v[128:129]
	v_pk_mul_f32 v[122:123], v[138:139], v[126:127]
	v_pk_mul_f32 v[128:129], v[132:133], v[202:203]
	v_pk_mul_f32 v[126:127], v[130:131], v[208:209]
	global_store_dwordx4 v[164:165], v[114:117], off
	global_store_dwordx4 v[164:165], v[118:121], off offset:16
	global_store_dwordx4 v[164:165], v[122:125], off offset:512
	global_store_dwordx4 v[164:165], v[126:129], off offset:528
	global_load_dwordx2 v[114:115], v[192:193], off offset:128 sc1
	s_waitcnt vmcnt(0)
	v_ffbh_u32_e32 v116, v115
	v_min_u32_e32 v116, 32, v116
	v_lshlrev_b64 v[114:115], v116, v[114:115]
	v_min_u32_e32 v114, 1, v114
	v_or_b32_e32 v114, v115, v114
	v_cvt_f32_u32_e32 v114, v114
	v_sub_u32_e32 v115, 32, v116
	v_ldexp_f32 v114, v114, v115
	v_mul_f32_e32 v114, 0x30800000, v114
	v_fmamk_f32 v114, v114, 0x3a000000, v1
	v_mul_f32_e32 v115, 0x4b800000, v114
	v_cmp_gt_f32_e32 vcc, s65, v114
	s_nop 1
	v_cndmask_b32_e32 v114, v114, v115, vcc
	v_rsq_f32_e32 v116, v114
	v_lshlrev_b64 v[114:115], 13, v[178:179]
	v_lshl_add_u64 v[114:115], s[40:41], 0, v[114:115]
	v_lshl_add_u64 v[114:115], v[114:115], 0, v[190:191]
	v_mul_f32_e32 v117, 0x45800000, v116
	v_cndmask_b32_e32 v116, v116, v117, vcc
	v_pk_mul_f32 v[98:99], v[98:99], v[116:117] op_sel_hi:[1,0]
	v_pk_mul_f32 v[100:101], v[100:101], v[116:117] op_sel_hi:[1,0]
	v_pk_mul_f32 v[102:103], v[102:103], v[116:117] op_sel_hi:[1,0]
	v_pk_mul_f32 v[104:105], v[104:105], v[116:117] op_sel_hi:[1,0]
	v_pk_mul_f32 v[106:107], v[106:107], v[116:117] op_sel_hi:[1,0]
	v_pk_mul_f32 v[108:109], v[108:109], v[116:117] op_sel_hi:[1,0]
	v_pk_mul_f32 v[110:111], v[110:111], v[116:117] op_sel_hi:[1,0]
	v_pk_mul_f32 v[112:113], v[112:113], v[116:117] op_sel_hi:[1,0]
	v_pk_mul_f32 v[100:101], v[144:145], v[100:101]
	v_pk_mul_f32 v[98:99], v[142:143], v[98:99]
	v_pk_mul_f32 v[104:105], v[136:137], v[104:105]
	v_pk_mul_f32 v[102:103], v[134:135], v[102:103]
	v_pk_mul_f32 v[108:109], v[140:141], v[108:109]
	v_pk_mul_f32 v[106:107], v[138:139], v[106:107]
	v_pk_mul_f32 v[112:113], v[132:133], v[112:113]
	v_pk_mul_f32 v[110:111], v[130:131], v[110:111]
	global_store_dwordx4 v[114:115], v[98:101], off
	global_store_dwordx4 v[114:115], v[102:105], off offset:16
	global_store_dwordx4 v[114:115], v[106:109], off offset:512
	global_store_dwordx4 v[114:115], v[110:113], off offset:528
	global_load_dwordx2 v[98:99], v[192:193], off offset:256 sc1
	s_waitcnt vmcnt(0)
	v_ffbh_u32_e32 v100, v99
	v_min_u32_e32 v100, 32, v100
	v_lshlrev_b64 v[98:99], v100, v[98:99]
	v_min_u32_e32 v98, 1, v98
	v_or_b32_e32 v98, v99, v98
	v_cvt_f32_u32_e32 v98, v98
	v_sub_u32_e32 v99, 32, v100
	v_ldexp_f32 v98, v98, v99
	v_mul_f32_e32 v98, 0x30800000, v98
	v_fmamk_f32 v98, v98, 0x3a000000, v1
	v_mul_f32_e32 v99, 0x4b800000, v98
	v_cmp_gt_f32_e32 vcc, s65, v98
	s_nop 1
	v_cndmask_b32_e32 v98, v98, v99, vcc
	v_rsq_f32_e32 v100, v98
	v_lshlrev_b64 v[98:99], 13, v[176:177]
	v_lshl_add_u64 v[98:99], s[40:41], 0, v[98:99]
	v_lshl_add_u64 v[98:99], v[98:99], 0, v[190:191]
	v_mul_f32_e32 v101, 0x45800000, v100
	v_cndmask_b32_e32 v100, v100, v101, vcc
	v_pk_mul_f32 v[70:71], v[70:71], v[100:101] op_sel_hi:[1,0]
	v_pk_mul_f32 v[72:73], v[72:73], v[100:101] op_sel_hi:[1,0]
	v_pk_mul_f32 v[74:75], v[74:75], v[100:101] op_sel_hi:[1,0]
	v_pk_mul_f32 v[76:77], v[76:77], v[100:101] op_sel_hi:[1,0]
	v_pk_mul_f32 v[82:83], v[82:83], v[100:101] op_sel_hi:[1,0]
	v_pk_mul_f32 v[84:85], v[84:85], v[100:101] op_sel_hi:[1,0]
	v_pk_mul_f32 v[86:87], v[86:87], v[100:101] op_sel_hi:[1,0]
	v_pk_mul_f32 v[88:89], v[88:89], v[100:101] op_sel_hi:[1,0]
	v_pk_mul_f32 v[72:73], v[144:145], v[72:73]
	v_pk_mul_f32 v[70:71], v[142:143], v[70:71]
	v_pk_mul_f32 v[76:77], v[136:137], v[76:77]
	v_pk_mul_f32 v[74:75], v[134:135], v[74:75]
	v_pk_mul_f32 v[84:85], v[140:141], v[84:85]
	v_pk_mul_f32 v[82:83], v[138:139], v[82:83]
	v_pk_mul_f32 v[88:89], v[132:133], v[88:89]
	v_pk_mul_f32 v[86:87], v[130:131], v[86:87]
	global_store_dwordx4 v[98:99], v[70:73], off
	global_store_dwordx4 v[98:99], v[74:77], off offset:16
	global_store_dwordx4 v[98:99], v[82:85], off offset:512
	global_store_dwordx4 v[98:99], v[86:89], off offset:528
	global_load_dwordx2 v[70:71], v[192:193], off offset:384 sc1
	s_waitcnt vmcnt(0)
	v_ffbh_u32_e32 v72, v71
	v_min_u32_e32 v72, 32, v72
	v_lshlrev_b64 v[70:71], v72, v[70:71]
	v_min_u32_e32 v70, 1, v70
	v_or_b32_e32 v70, v71, v70
	v_cvt_f32_u32_e32 v70, v70
	v_sub_u32_e32 v71, 32, v72
	v_ldexp_f32 v70, v70, v71
	v_mul_f32_e32 v70, 0x30800000, v70
	v_fmamk_f32 v70, v70, 0x3a000000, v1
	v_mul_f32_e32 v71, 0x4b800000, v70
	v_cmp_gt_f32_e32 vcc, s65, v70
	s_nop 1
	v_cndmask_b32_e32 v70, v70, v71, vcc
	v_rsq_f32_e32 v72, v70
	v_lshlrev_b64 v[70:71], 13, v[174:175]
	v_lshl_add_u64 v[70:71], s[40:41], 0, v[70:71]
	v_lshl_add_u64 v[70:71], v[70:71], 0, v[190:191]
	v_mul_f32_e32 v73, 0x45800000, v72
	v_cndmask_b32_e32 v72, v72, v73, vcc
	v_pk_mul_f32 v[30:31], v[30:31], v[72:73] op_sel_hi:[1,0]
	v_pk_mul_f32 v[32:33], v[32:33], v[72:73] op_sel_hi:[1,0]
	v_pk_mul_f32 v[34:35], v[34:35], v[72:73] op_sel_hi:[1,0]
	v_pk_mul_f32 v[36:37], v[36:37], v[72:73] op_sel_hi:[1,0]
	v_pk_mul_f32 v[54:55], v[54:55], v[72:73] op_sel_hi:[1,0]
	v_pk_mul_f32 v[56:57], v[56:57], v[72:73] op_sel_hi:[1,0]
	v_pk_mul_f32 v[58:59], v[58:59], v[72:73] op_sel_hi:[1,0]
	v_pk_mul_f32 v[60:61], v[60:61], v[72:73] op_sel_hi:[1,0]
	v_pk_mul_f32 v[32:33], v[144:145], v[32:33]
	v_pk_mul_f32 v[30:31], v[142:143], v[30:31]
	v_pk_mul_f32 v[36:37], v[136:137], v[36:37]
	v_pk_mul_f32 v[34:35], v[134:135], v[34:35]
	v_pk_mul_f32 v[56:57], v[140:141], v[56:57]
	v_pk_mul_f32 v[54:55], v[138:139], v[54:55]
	v_pk_mul_f32 v[60:61], v[132:133], v[60:61]
	v_pk_mul_f32 v[58:59], v[130:131], v[58:59]
	global_store_dwordx4 v[70:71], v[30:33], off
	global_store_dwordx4 v[70:71], v[34:37], off offset:16
	global_store_dwordx4 v[70:71], v[54:57], off offset:512
	global_store_dwordx4 v[70:71], v[58:61], off offset:528
	global_load_dwordx2 v[30:31], v[192:193], off offset:1024 sc1
	s_waitcnt vmcnt(0)
	v_ffbh_u32_e32 v32, v31
	v_min_u32_e32 v32, 32, v32
	v_lshlrev_b64 v[30:31], v32, v[30:31]
	v_min_u32_e32 v30, 1, v30
	v_or_b32_e32 v30, v31, v30
	v_cvt_f32_u32_e32 v30, v30
	v_sub_u32_e32 v31, 32, v32
	v_ldexp_f32 v30, v30, v31
	v_mul_f32_e32 v30, 0x30800000, v30
	v_fmamk_f32 v30, v30, 0x3a000000, v1
	v_mul_f32_e32 v31, 0x4b800000, v30
	v_cmp_gt_f32_e32 vcc, s65, v30
	s_nop 1
	v_cndmask_b32_e32 v30, v30, v31, vcc
	v_rsq_f32_e32 v32, v30
	v_lshlrev_b64 v[30:31], 13, v[172:173]
	v_lshl_add_u64 v[30:31], s[40:41], 0, v[30:31]
	v_lshl_add_u64 v[54:55], v[30:31], 0, v[190:191]
	v_mul_f32_e32 v30, 0x45800000, v32
	v_cndmask_b32_e32 v30, v32, v30, vcc
	v_pk_mul_f32 v[22:23], v[22:23], v[30:31] op_sel_hi:[1,0]
	v_pk_mul_f32 v[24:25], v[24:25], v[30:31] op_sel_hi:[1,0]
	v_pk_mul_f32 v[26:27], v[26:27], v[30:31] op_sel_hi:[1,0]
	v_pk_mul_f32 v[28:29], v[28:29], v[30:31] op_sel_hi:[1,0]
	v_pk_mul_f32 v[34:35], v[46:47], v[30:31] op_sel_hi:[1,0]
	v_pk_mul_f32 v[32:33], v[48:49], v[30:31] op_sel_hi:[1,0]
	v_pk_mul_f32 v[46:47], v[50:51], v[30:31] op_sel_hi:[1,0]
	v_pk_mul_f32 v[36:37], v[52:53], v[30:31] op_sel_hi:[1,0]
	v_pk_mul_f32 v[24:25], v[144:145], v[24:25]
	v_pk_mul_f32 v[22:23], v[142:143], v[22:23]
	v_pk_mul_f32 v[28:29], v[136:137], v[28:29]
	v_pk_mul_f32 v[26:27], v[134:135], v[26:27]
	v_pk_mul_f32 v[32:33], v[140:141], v[32:33]
	v_pk_mul_f32 v[30:31], v[138:139], v[34:35]
	v_pk_mul_f32 v[36:37], v[132:133], v[36:37]
	v_pk_mul_f32 v[34:35], v[130:131], v[46:47]
	global_store_dwordx4 v[54:55], v[22:25], off
	global_store_dwordx4 v[54:55], v[26:29], off offset:16
	global_store_dwordx4 v[54:55], v[30:33], off offset:512
	global_store_dwordx4 v[54:55], v[34:37], off offset:528
	global_load_dwordx2 v[22:23], v[192:193], off offset:1152 sc1
	s_waitcnt vmcnt(0)
	v_ffbh_u32_e32 v24, v23
	v_min_u32_e32 v24, 32, v24
	v_lshlrev_b64 v[22:23], v24, v[22:23]
	v_min_u32_e32 v22, 1, v22
	v_or_b32_e32 v22, v23, v22
	v_cvt_f32_u32_e32 v22, v22
	v_sub_u32_e32 v23, 32, v24
	v_ldexp_f32 v22, v22, v23
	v_mul_f32_e32 v22, 0x30800000, v22
	v_fmamk_f32 v22, v22, 0x3a000000, v1
	v_mul_f32_e32 v23, 0x4b800000, v22
	v_cmp_gt_f32_e32 vcc, s65, v22
	s_nop 1
	v_cndmask_b32_e32 v22, v22, v23, vcc
	v_rsq_f32_e32 v24, v22
	v_lshlrev_b64 v[22:23], 13, v[170:171]
	v_lshl_add_u64 v[22:23], s[40:41], 0, v[22:23]
	v_lshl_add_u64 v[34:35], v[22:23], 0, v[190:191]
	v_mul_f32_e32 v22, 0x45800000, v24
	v_cndmask_b32_e32 v22, v24, v22, vcc
	v_pk_mul_f32 v[10:11], v[10:11], v[22:23] op_sel_hi:[1,0]
	v_pk_mul_f32 v[12:13], v[12:13], v[22:23] op_sel_hi:[1,0]
	v_pk_mul_f32 v[26:27], v[78:79], v[22:23] op_sel_hi:[1,0]
	v_pk_mul_f32 v[24:25], v[80:81], v[22:23] op_sel_hi:[1,0]
	v_pk_mul_f32 v[30:31], v[90:91], v[22:23] op_sel_hi:[1,0]
	v_pk_mul_f32 v[28:29], v[92:93], v[22:23] op_sel_hi:[1,0]
	v_pk_mul_f32 v[36:37], v[94:95], v[22:23] op_sel_hi:[1,0]
	v_pk_mul_f32 v[32:33], v[96:97], v[22:23] op_sel_hi:[1,0]
	v_pk_mul_f32 v[12:13], v[144:145], v[12:13]
	v_pk_mul_f32 v[10:11], v[142:143], v[10:11]
	v_pk_mul_f32 v[24:25], v[136:137], v[24:25]
	v_pk_mul_f32 v[22:23], v[134:135], v[26:27]
	v_pk_mul_f32 v[28:29], v[140:141], v[28:29]
	v_pk_mul_f32 v[26:27], v[138:139], v[30:31]
	v_pk_mul_f32 v[32:33], v[132:133], v[32:33]
	v_pk_mul_f32 v[30:31], v[130:131], v[36:37]
	global_store_dwordx4 v[34:35], v[10:13], off
	global_store_dwordx4 v[34:35], v[22:25], off offset:16
	global_store_dwordx4 v[34:35], v[26:29], off offset:512
	global_store_dwordx4 v[34:35], v[30:33], off offset:528
	global_load_dwordx2 v[10:11], v[192:193], off offset:1280 sc1
	s_waitcnt vmcnt(0)
	v_ffbh_u32_e32 v12, v11
	v_min_u32_e32 v12, 32, v12
	v_lshlrev_b64 v[10:11], v12, v[10:11]
	v_min_u32_e32 v10, 1, v10
	v_or_b32_e32 v10, v11, v10
	v_cvt_f32_u32_e32 v10, v10
	v_sub_u32_e32 v11, 32, v12
	v_ldexp_f32 v10, v10, v11
	v_mul_f32_e32 v10, 0x30800000, v10
	v_fmamk_f32 v10, v10, 0x3a000000, v1
	v_mul_f32_e32 v11, 0x4b800000, v10
	v_cmp_gt_f32_e32 vcc, s65, v10
	s_nop 1
	v_cndmask_b32_e32 v10, v10, v11, vcc
	v_rsq_f32_e32 v12, v10
	v_lshlrev_b64 v[10:11], 13, v[168:169]
	v_lshl_add_u64 v[10:11], s[40:41], 0, v[10:11]
	v_lshl_add_u64 v[34:35], v[10:11], 0, v[190:191]
	v_mul_f32_e32 v10, 0x45800000, v12
	v_cndmask_b32_e32 v10, v12, v10, vcc
	v_pk_mul_f32 v[22:23], v[38:39], v[10:11] op_sel_hi:[1,0]
	v_pk_mul_f32 v[12:13], v[40:41], v[10:11] op_sel_hi:[1,0]
	v_pk_mul_f32 v[26:27], v[42:43], v[10:11] op_sel_hi:[1,0]
	v_pk_mul_f32 v[24:25], v[44:45], v[10:11] op_sel_hi:[1,0]
	v_pk_mul_f32 v[30:31], v[62:63], v[10:11] op_sel_hi:[1,0]
	v_pk_mul_f32 v[28:29], v[64:65], v[10:11] op_sel_hi:[1,0]
	v_pk_mul_f32 v[36:37], v[66:67], v[10:11] op_sel_hi:[1,0]
	v_pk_mul_f32 v[32:33], v[68:69], v[10:11] op_sel_hi:[1,0]
	v_pk_mul_f32 v[12:13], v[144:145], v[12:13]
	v_pk_mul_f32 v[10:11], v[142:143], v[22:23]
	v_pk_mul_f32 v[24:25], v[136:137], v[24:25]
	v_pk_mul_f32 v[22:23], v[134:135], v[26:27]
	v_pk_mul_f32 v[28:29], v[140:141], v[28:29]
	v_pk_mul_f32 v[26:27], v[138:139], v[30:31]
	v_pk_mul_f32 v[32:33], v[132:133], v[32:33]
	v_pk_mul_f32 v[30:31], v[130:131], v[36:37]
	global_store_dwordx4 v[34:35], v[10:13], off
	global_store_dwordx4 v[34:35], v[22:25], off offset:16
	global_store_dwordx4 v[34:35], v[26:29], off offset:512
	global_store_dwordx4 v[34:35], v[30:33], off offset:528
	global_load_dwordx2 v[10:11], v[192:193], off offset:1408 sc1
	s_and_b64 vcc, exec, s[36:37]
	s_waitcnt vmcnt(0)
	v_ffbh_u32_e32 v12, v11
	v_min_u32_e32 v12, 32, v12
	v_lshlrev_b64 v[10:11], v12, v[10:11]
	v_min_u32_e32 v10, 1, v10
	v_or_b32_e32 v10, v11, v10
	v_cvt_f32_u32_e32 v13, v10
	v_sub_u32_e32 v12, 32, v12
	v_lshlrev_b64 v[10:11], 13, v[166:167]
	v_lshl_add_u64 v[10:11], s[40:41], 0, v[10:11]
	v_ldexp_f32 v12, v13, v12
	v_mul_f32_e32 v12, 0x30800000, v12
	v_fmamk_f32 v12, v12, 0x3a000000, v1
	v_mul_f32_e32 v13, 0x4b800000, v12
	v_cmp_gt_f32_e64 s[38:39], s65, v12
	v_lshl_add_u64 v[22:23], v[10:11], 0, v[190:191]
	s_nop 0
	v_cndmask_b32_e64 v12, v12, v13, s[38:39]
	v_rsq_f32_e32 v12, v12
	s_nop 0
	v_mul_f32_e32 v10, 0x45800000, v12
	v_cndmask_b32_e64 v10, v12, v10, s[38:39]
	v_pk_mul_f32 v[2:3], v[2:3], v[10:11] op_sel_hi:[1,0]
	v_pk_mul_f32 v[4:5], v[4:5], v[10:11] op_sel_hi:[1,0]
	v_pk_mul_f32 v[6:7], v[6:7], v[10:11] op_sel_hi:[1,0]
	v_pk_mul_f32 v[8:9], v[8:9], v[10:11] op_sel_hi:[1,0]
	v_pk_mul_f32 v[14:15], v[14:15], v[10:11] op_sel_hi:[1,0]
	v_pk_mul_f32 v[12:13], v[16:17], v[10:11] op_sel_hi:[1,0]
	v_pk_mul_f32 v[18:19], v[18:19], v[10:11] op_sel_hi:[1,0]
	v_pk_mul_f32 v[16:17], v[20:21], v[10:11] op_sel_hi:[1,0]
	v_pk_mul_f32 v[4:5], v[144:145], v[4:5]
	v_pk_mul_f32 v[2:3], v[142:143], v[2:3]
	v_pk_mul_f32 v[8:9], v[136:137], v[8:9]
	v_pk_mul_f32 v[6:7], v[134:135], v[6:7]
	v_pk_mul_f32 v[12:13], v[140:141], v[12:13]
	v_pk_mul_f32 v[10:11], v[138:139], v[14:15]
	v_pk_mul_f32 v[16:17], v[132:133], v[16:17]
	v_pk_mul_f32 v[14:15], v[130:131], v[18:19]
	global_store_dwordx4 v[22:23], v[2:5], off
	global_store_dwordx4 v[22:23], v[6:9], off offset:16
	global_store_dwordx4 v[22:23], v[10:13], off offset:512
	global_store_dwordx4 v[22:23], v[14:17], off offset:528
	s_cbranch_vccnz .LBB0_2281
	v_lshl_add_u32 v2, s63, 8, v199
	v_ashrrev_i32_e32 v3, 31, v2
	v_lshlrev_b64 v[2:3], 12, v[2:3]
	s_lshl_b32 s28, s64, 8
	v_lshl_add_u64 v[2:3], v[146:147], 0, v[2:3]
	s_ashr_i32 s29, s28, 31
	v_lshl_add_u64 v[2:3], s[28:29], 1, v[2:3]
	v_lshl_add_u64 v[2:3], v[2:3], 0, s[12:13]
	v_lshl_add_u64 v[6:7], v[2:3], 0, v[180:181]
	s_mov_b32 s28, 0x10000
	v_add_co_u32_e32 v2, vcc, s28, v6
	s_mov_b32 s28, 0x20000
	s_nop 0
	v_addc_co_u32_e32 v3, vcc, 0, v7, vcc
	global_load_dwordx4 v[62:65], v[6:7], off
	global_load_dwordx4 v[54:57], v[6:7], off offset:256
	global_load_dwordx4 v[58:61], v[2:3], off
	global_load_dwordx4 v[46:49], v[2:3], off offset:256
	v_add_co_u32_e32 v2, vcc, s28, v6
	s_mov_b32 s28, 0x30000
	s_nop 0
	v_addc_co_u32_e32 v3, vcc, 0, v7, vcc
	global_load_dwordx4 v[50:53], v[2:3], off
	global_load_dwordx4 v[30:33], v[2:3], off offset:256
	v_add_co_u32_e32 v2, vcc, s28, v6
	s_mov_b32 s28, 0x80000
	s_nop 0
	v_addc_co_u32_e32 v3, vcc, 0, v7, vcc
	global_load_dwordx4 v[34:37], v[2:3], off
	global_load_dwordx4 v[22:25], v[2:3], off offset:256
	v_add_co_u32_e32 v2, vcc, s28, v6
	s_mov_b32 s28, 0x90000
	s_nop 0
	v_addc_co_u32_e32 v3, vcc, 0, v7, vcc
	global_load_dwordx4 v[26:29], v[2:3], off
	global_load_dwordx4 v[10:13], v[2:3], off offset:256
	v_add_co_u32_e32 v2, vcc, s28, v6
	s_nop 1
	v_addc_co_u32_e32 v3, vcc, 0, v7, vcc
	global_load_dwordx4 v[42:45], v[2:3], off
	global_load_dwordx4 v[38:41], v[2:3], off offset:256
	v_add_co_u32_e32 v2, vcc, 0xa0000, v6
	s_nop 1
	v_addc_co_u32_e32 v3, vcc, 0, v7, vcc
	v_add_co_u32_e32 v18, vcc, 0xb0000, v6
	global_load_dwordx4 v[14:17], v[2:3], off
	s_nop 0
	global_load_dwordx4 v[2:5], v[2:3], off offset:256
	v_addc_co_u32_e32 v19, vcc, 0, v7, vcc
	global_load_dwordx4 v[6:9], v[18:19], off
	s_nop 0
	global_load_dwordx4 v[18:21], v[18:19], off offset:256
	s_andn2_b64 vcc, exec, s[18:19]
	s_cbranch_vccz .LBB0_2280
	s_barrier
	s_branch .LBB0_2280
